# v053 + attention output stores widened the same way (two dwordx4 per head instead of four dwordx2)
# speedup vs baseline: 1.0076x; 1.0018x over previous
; #define LAS __attribute__((address_space(3)))
; __device__ __forceinline__ void attn_unit(LAS unsigned char* lds, bf16* Q, const bf16* Kg, const bf16* Vg, const float* snk, int unit, int tid) {
;     ...
;     for (int i = 0; i < 2; ++i) { const int idx = tid + 512 * i, j = (idx >> 3) * 2, c = idx & 7, p = n * 128 - 128 + j;
;         v4u w0 = zero4, w1 = zero4;
;         if (p >= 0) { w0 = *(const v4u*)(Vg + (size_t)(b * SEQ + p) * 128 + h * 64 + c * 8); w1 = *(const v4u*)(Vg + (size_t)(b * SEQ + p + 1) * 128 + h * 64 + c * 8); }
;         const unsigned A0[4] = {w0.x, w0.y, w0.z, w0.w}, A1[4] = {w1.x, w1.y, w1.z, w1.w};
; #pragma unroll
;         for (int e = 0; e < 8; ++e) { const unsigned lo = (e & 1) ? (A0[e >> 1] >> 16) : (A0[e >> 1] & 0xffffu), hi = (e & 1) ? (A1[e >> 1] & 0xffff0000u) : (A1[e >> 1] << 16);
;             *(LAS unsigned*)(lds + ATT_VOFF + (8 * c + e) * ATT_VP + j * 2) = lo | hi; } }
;     __syncthreads();
;     const float sink = snk[hq] * 1.4426950408889634f;
;     bool lo_ok[4];
; #pragma unroll
;     for (int i = 0; i < 4; ++i) lo_ok[i] = (4 * fq + i - fr) > 0;
; #pragma unroll
;     for (int mt = 0; mt < 8; ++mt) {
;         f32x4 st[9];
; #pragma unroll
;         for (int kb = 0; kb < 9; ++kb) { const LAS unsigned char* kp = lds + (16 * (mt + kb) + fr) * ATT_KP + 16 * fq;
;             const bf16x8_t k0 = *(const LAS bf16x8_t*)kp, k1 = *(const LAS bf16x8_t*)(kp + 64);
;             f32x4 z = {0.f, 0.f, 0.f, 0.f}; z = __builtin_amdgcn_mfma_f32_16x16x32_bf16(k0, qf[mt][0], z, 0, 0, 0); z = __builtin_amdgcn_mfma_f32_16x16x32_bf16(k1, qf[mt][1], z, 0, 0, 0); st[kb] = z; }
;         float mx = sink;
; #pragma unroll
;         for (int kb = 0; kb < 9; ++kb) {
;             const bool tile_ok = (n > 0) || (mt + kb >= 8);
; #pragma unroll
;             for (int i = 0; i < 4; ++i) { const bool ok = tile_ok && (kb == 0 ? lo_ok[i] : (kb == 8 ? !lo_ok[i] : true));
;                 st[kb][i] = ok ? st[kb][i] : -INFINITY; mx = fmaxf(mx, st[kb][i]); }
;         }
;         mx = fmaxf(mx, __shfl_xor(mx, 16)); mx = fmaxf(mx, __shfl_xor(mx, 32));
.LBB0_493:
	s_or_b64 exec, exec, s[14:15]
	s_waitcnt vmcnt(0)
	v_lshlrev_b32_e32 v74, 16, v66
	v_and_or_b32 v74, v70, s61, v74
	v_lshrrev_b32_e32 v70, 16, v70
	v_and_or_b32 v66, v66, s60, v70
	v_add_u32_e32 v70, 0x9000, v189
	ds_write2_b32 v70, v74, v66 offset1:132
	v_lshlrev_b32_e32 v66, 16, v67
	v_lshrrev_b32_e32 v70, 16, v71
	v_and_or_b32 v66, v71, s61, v66
	v_and_or_b32 v67, v67, s60, v70
	v_add_u32_e32 v70, 0x9400, v189
	ds_write2_b32 v70, v66, v67 offset0:8 offset1:140
	v_lshlrev_b32_e32 v66, 16, v68
	v_lshrrev_b32_e32 v67, 16, v72
	v_and_or_b32 v66, v72, s61, v66
	v_and_or_b32 v67, v68, s60, v67
	v_add_u32_e32 v68, 0x9800, v189
	ds_write2_b32 v68, v66, v67 offset0:16 offset1:148
	v_lshlrev_b32_e32 v66, 16, v69
	v_lshrrev_b32_e32 v67, 16, v73
	v_and_or_b32 v66, v73, s61, v66
	v_and_or_b32 v67, v69, s60, v67
	v_add_u32_e32 v68, 0x9c00, v189
	ds_write2_b32 v68, v66, v67 offset0:24 offset1:156
	s_waitcnt lgkmcnt(0)
	s_barrier
	ds_read_b128 v[66:69], v179
	ds_read_b128 v[70:73], v179 offset:64
	s_waitcnt lgkmcnt(1)
	v_mfma_f32_16x16x32_bf16 v[66:69], v[66:69], v[62:65], 0
	ds_read_b128 v[80:83], v179 offset:2304
	ds_read_b128 v[84:87], v179 offset:4608
	ds_read_b128 v[88:91], v179 offset:6912
	s_waitcnt lgkmcnt(3)
	v_mfma_f32_16x16x32_bf16 v[66:69], v[70:73], v[58:61], v[66:69]
	ds_read_b128 v[70:73], v179 offset:2368
	ds_read_b128 v[92:95], v179 offset:9216
	ds_read_b128 v[96:99], v179 offset:11520
	s_waitcnt lgkmcnt(5)
	v_mfma_f32_16x16x32_bf16 v[80:83], v[80:83], v[62:65], 0
	ds_read_b128 v[100:103], v179 offset:13824
	v_ashrrev_i32_e32 v79, 31, v78
	s_cmp_lg_u32 s64, 0
	s_waitcnt lgkmcnt(3)
	v_mfma_f32_16x16x32_bf16 v[72:75], v[70:73], v[58:61], v[80:83]
	v_lshl_add_u64 v[70:71], v[78:79], 2, s[28:29]
	s_cselect_b64 s[14:15], -1, 0
	s_and_b64 s[18:19], s[14:15], s[6:7]
	ds_read_b128 v[80:83], v179 offset:4672
	v_mfma_f32_16x16x32_bf16 v[84:87], v[84:87], v[62:65], 0
	s_and_b64 s[16:17], s[14:15], s[10:11]
	s_and_b64 s[20:21], s[14:15], s[12:13]
	v_cndmask_b32_e64 v68, v191, v68, s[16:17]
	s_waitcnt lgkmcnt(0)
	v_mfma_f32_16x16x32_bf16 v[80:83], v[80:83], v[58:61], v[84:87]
	s_nop 2
	ds_read_b128 v[84:87], v179 offset:6976
	v_cndmask_b32_e64 v69, v191, v69, s[20:21]
	s_cmp_eq_u32 s64, 0
	v_mfma_f32_16x16x32_bf16 v[88:91], v[88:91], v[62:65], 0
	s_nop 0
	v_cndmask_b32_e64 v78, v191, v80, s[14:15]
	v_cndmask_b32_e64 v79, v191, v81, s[14:15]
	v_cndmask_b32_e64 v80, v191, v82, s[14:15]
	s_waitcnt lgkmcnt(0)
	v_mfma_f32_16x16x32_bf16 v[84:87], v[84:87], v[58:61], v[88:91]
	v_cndmask_b32_e64 v81, v191, v83, s[14:15]
	s_nop 1
	ds_read_b128 v[88:91], v179 offset:9280
	v_mov_b32_e32 v157, v147
	v_mfma_f32_16x16x32_bf16 v[92:95], v[92:95], v[62:65], 0
	s_nop 1
	v_cndmask_b32_e64 v82, v191, v84, s[14:15]
	v_cndmask_b32_e64 v83, v191, v85, s[14:15]
	v_cndmask_b32_e64 v84, v191, v86, s[14:15]
	s_waitcnt lgkmcnt(0)
	v_mfma_f32_16x16x32_bf16 v[88:91], v[88:91], v[58:61], v[92:95]
	v_cndmask_b32_e64 v85, v191, v87, s[14:15]
	s_nop 1
	ds_read_b128 v[92:95], v179 offset:11584
	s_nop 3
	v_cndmask_b32_e64 v86, v191, v88, s[14:15]
	v_mfma_f32_16x16x32_bf16 v[96:99], v[96:99], v[62:65], 0
	v_cndmask_b32_e64 v87, v191, v89, s[14:15]
	v_cndmask_b32_e64 v88, v191, v90, s[14:15]
	v_cndmask_b32_e64 v89, v191, v91, s[14:15]
	s_waitcnt lgkmcnt(0)
	v_mfma_f32_16x16x32_bf16 v[92:95], v[92:95], v[58:61], v[96:99]
	s_nop 2
	ds_read_b128 v[96:99], v179 offset:16128
	ds_read_b128 v[104:107], v179 offset:13888
	ds_read_b128 v[108:111], v179 offset:18432
	ds_read_b128 v[112:115], v179 offset:16192
	ds_read_b128 v[116:119], v179 offset:18496
	v_mfma_f32_16x16x32_bf16 v[100:103], v[100:103], v[62:65], 0
	s_waitcnt lgkmcnt(4)
	v_mfma_f32_16x16x32_bf16 v[96:99], v[96:99], v[62:65], 0
	s_waitcnt lgkmcnt(2)
	v_mfma_f32_16x16x32_bf16 v[108:111], v[108:111], v[62:65], 0
	global_load_dword v64, v[70:71], off
	v_and_b32_e32 v63, 64, v190
	v_xor_b32_e32 v62, 16, v190
	v_add_u32_e32 v63, 64, v63
	v_cmp_lt_i32_e32 vcc, v62, v63
	v_cndmask_b32_e64 v70, v191, v72, s[14:15]
	v_cndmask_b32_e64 v72, v191, v73, s[14:15]
	v_cndmask_b32_e32 v62, v190, v62, vcc
	v_lshlrev_b32_e32 v65, 2, v62
	v_cndmask_b32_e64 v62, v67, v191, s[8:9]
	v_cndmask_b32_e64 v62, v191, v62, s[14:15]
	v_cndmask_b32_e64 v67, v191, v66, s[18:19]
	v_cndmask_b32_e64 v73, v191, v74, s[14:15]
	v_cndmask_b32_e64 v74, v191, v75, s[14:15]
	v_mfma_f32_16x16x32_bf16 v[100:103], v[104:107], v[58:61], v[100:103]
	v_cndmask_b32_e64 v106, v191, v92, s[14:15]
	v_cndmask_b32_e64 v107, v191, v93, s[14:15]
	s_cselect_b64 vcc, -1, 0
	s_waitcnt lgkmcnt(1)
	v_mfma_f32_16x16x32_bf16 v[96:99], v[112:115], v[58:61], v[96:99]
	s_waitcnt vmcnt(0)
; #define LAS __attribute__((address_space(3)))
; __device__ __forceinline__ void attn_unit(LAS unsigned char* lds, bf16* Q, const bf16* Kg, const bf16* Vg, const float* snk, int unit, int tid) {
;     ...
;     for (int mt = 0; mt < 8; ++mt) { qf[mt][0] = *(const bf16x8_t*)(qbase + (size_t)mt * 16 * 1024 + 8 * fq); qf[mt][1] = *(const bf16x8_t*)(qbase + (size_t)mt * 16 * 1024 + 32 + 8 * fq); }
;     ...
;     const float sink = snk[hq] * 1.4426950408889634f;
;     bool lo_ok[4];
; #pragma unroll
;     for (int i = 0; i < 4; ++i) lo_ok[i] = (4 * fq + i - fr) > 0;
; #pragma unroll
;     for (int mt = 0; mt < 8; ++mt) {
;         f32x4 st[9];
; #pragma unroll
;         for (int kb = 0; kb < 9; ++kb) { const LAS unsigned char* kp = lds + (16 * (mt + kb) + fr) * ATT_KP + 16 * fq;
;             const bf16x8_t k0 = *(const LAS bf16x8_t*)kp, k1 = *(const LAS bf16x8_t*)(kp + 64);
;             f32x4 z = {0.f, 0.f, 0.f, 0.f}; z = __builtin_amdgcn_mfma_f32_16x16x32_bf16(k0, qf[mt][0], z, 0, 0, 0); z = __builtin_amdgcn_mfma_f32_16x16x32_bf16(k1, qf[mt][1], z, 0, 0, 0); st[kb] = z; }
;         float mx = sink;
; #pragma unroll
;         for (int kb = 0; kb < 9; ++kb) {
;             const bool tile_ok = (n > 0) || (mt + kb >= 8);
; #pragma unroll
;             for (int i = 0; i < 4; ++i) { const bool ok = tile_ok && (kb == 0 ? lo_ok[i] : (kb == 8 ? !lo_ok[i] : true));
;                 st[kb][i] = ok ? st[kb][i] : -INFINITY; mx = fmaxf(mx, st[kb][i]); }
;         }
;         mx = fmaxf(mx, __shfl_xor(mx, 16)); mx = fmaxf(mx, __shfl_xor(mx, 32));
;         f32x4 ls4 = {0.f, 0.f, 0.f, 0.f};
; #pragma unroll
;         for (int kb = 0; kb < 9; ++kb) { f32x4 d = st[kb] - mx;
; #pragma unroll
;             for (int i = 0; i < 4; ++i) d[i] = __builtin_amdgcn_exp2f(d[i]);
;             st[kb] = d; ls4 = ls4 + d; }
;         float ls = (ls4[0] + ls4[1]) + (ls4[2] + ls4[3]);
;         ls += __shfl_xor(ls, 16); ls += __shfl_xor(ls, 32);
;         const float inv = 1.f / (ls + __builtin_amdgcn_exp2f(sink - mx));
;         f32x4 o[4];
; #pragma unroll
;         for (int dt = 0; dt < 4; ++dt) o[dt] = (f32x4){0.f, 0.f, 0.f, 0.f};
; #pragma unroll
;         for (int kp = 0; kp < 5; ++kp) {
;             v4u pw; pw.x = cvt_pk_bf16(st[2 * kp][0], st[2 * kp][1]); pw.y = cvt_pk_bf16(st[2 * kp][2], st[2 * kp][3]);
	s_cselect_b32 s100, 1, 0
	s_and_b32 s98, s23, 4
	v_add_u32_e32 v254, s98, v165
	v_lshlrev_b32_e32 v254, 7, v254
	v_or_b32_e32 v254, v254, v168
	v_or_b32_e32 v254, v254, v170
	s_and_b32 s98, s25, 0x3f80
	v_lshl_or_b32 v252, s98, 11, v181
	v_mov_b32_e32 v253, 0
	v_lshl_add_u64 v[252:253], s[48:49], 0, v[252:253]
	v_mov_b32_e32 v255, 0
	v_lshl_add_u64 v[252:253], v[254:255], 1, v[252:253]
	global_load_dwordx4 v[206:209], v[252:253], off
	global_load_dwordx4 v[210:213], v[252:253], off offset:2048
	s_mov_b64 s[98:99], 0x8000
	v_lshl_add_u64 v[254:255], v[252:253], 0, s[98:99]
	global_load_dwordx4 v[214:217], v[254:255], off
	global_load_dwordx4 v[218:221], v[254:255], off offset:2048
	s_mov_b64 s[98:99], 0x10000
	v_lshl_add_u64 v[254:255], v[252:253], 0, s[98:99]
	global_load_dwordx4 v[138:141], v[254:255], off
	global_load_dwordx4 v[142:145], v[254:255], off offset:2048
	s_mov_b64 s[98:99], 0x18000
	v_lshl_add_u64 v[254:255], v[252:253], 0, s[98:99]
	global_load_dwordx4 v[130:133], v[254:255], off
	global_load_dwordx4 v[134:137], v[254:255], off offset:2048
	s_mov_b64 s[98:99], 0x20000
	v_lshl_add_u64 v[254:255], v[252:253], 0, s[98:99]
	global_load_dwordx4 v[222:225], v[254:255], off
	global_load_dwordx4 v[226:229], v[254:255], off offset:2048
	s_mov_b64 s[98:99], 0x28000
	v_lshl_add_u64 v[254:255], v[252:253], 0, s[98:99]
	global_load_dwordx4 v[230:233], v[254:255], off
	global_load_dwordx4 v[234:237], v[254:255], off offset:2048
	s_mov_b64 s[98:99], 0x30000
	v_lshl_add_u64 v[254:255], v[252:253], 0, s[98:99]
	global_load_dwordx4 v[238:241], v[254:255], off
	global_load_dwordx4 v[242:245], v[254:255], off offset:2048
	s_mov_b64 s[98:99], 0x38000
	v_lshl_add_u64 v[254:255], v[252:253], 0, s[98:99]
	global_load_dwordx4 v[248:251], v[254:255], off
	global_load_dwordx4 v[252:255], v[254:255], off offset:2048
	s_cmp_lg_u32 s100, 0
	v_mul_f32_e32 v71, 0x3fb8aa3b, v64
	v_max3_f32 v66, v71, v67, v62
	v_max3_f32 v66, v66, v68, v69
	v_max3_f32 v66, v66, v70, v72
	v_max3_f32 v66, v66, v73, v74
	v_max3_f32 v66, v66, v78, v79
	v_max3_f32 v66, v66, v80, v81
	v_max3_f32 v66, v66, v82, v83
	v_max3_f32 v66, v66, v84, v85
	v_max3_f32 v66, v66, v86, v87
	v_max3_f32 v66, v66, v88, v89
	s_waitcnt lgkmcnt(0)
	v_mfma_f32_16x16x32_bf16 v[58:61], v[116:119], v[58:61], v[108:111]
	v_max3_f32 v66, v66, v106, v107
	v_cndmask_b32_e64 v100, v191, v100, s[14:15]
	v_cndmask_b32_e64 v101, v191, v101, s[14:15]
	v_cndmask_b32_e64 v108, v191, v94, s[14:15]
	v_cndmask_b32_e64 v109, v191, v95, s[14:15]
	v_max3_f32 v66, v66, v108, v109
	v_max3_f32 v66, v66, v100, v101
	v_cndmask_b32_e64 v110, v191, v102, s[14:15]
	v_cndmask_b32_e64 v111, v191, v103, s[14:15]
	v_max3_f32 v66, v66, v110, v111
	v_cndmask_b32_e32 v116, v96, v191, vcc
	v_cndmask_b32_e32 v117, v97, v191, vcc
	v_max3_f32 v66, v66, v116, v117
	v_cndmask_b32_e32 v98, v98, v191, vcc
	v_cndmask_b32_e32 v99, v99, v191, vcc
	v_max3_f32 v66, v66, v98, v99
	v_cndmask_b32_e64 v120, v58, v191, s[6:7]
	v_cndmask_b32_e64 v121, v191, v59, s[8:9]
	v_max3_f32 v58, v66, v120, v121
	v_cndmask_b32_e64 v122, v60, v191, s[10:11]
	v_cndmask_b32_e64 v123, v61, v191, s[12:13]
	v_max3_f32 v58, v58, v122, v123
	ds_bpermute_b32 v59, v65, v58
	v_xor_b32_e32 v60, 32, v190
	v_cmp_lt_i32_e32 vcc, v60, v63
	s_waitcnt lgkmcnt(0)
	v_max_f32_e32 v59, v59, v59
	v_cndmask_b32_e32 v60, v190, v60, vcc
	v_lshlrev_b32_e32 v66, 2, v60
	v_max_f32_e32 v58, v58, v59
	ds_bpermute_b32 v59, v66, v58
	s_waitcnt lgkmcnt(0)
	v_max_f32_e32 v59, v59, v59
	v_max_f32_e32 v124, v58, v59
	v_sub_f32_e32 v59, v69, v124
	v_sub_f32_e32 v62, v62, v124
	v_sub_f32_e32 v58, v67, v124
	v_exp_f32_e32 v58, v58
	v_exp_f32_e32 v61, v59
	v_exp_f32_e32 v59, v62
	v_sub_f32_e32 v67, v74, v124
	v_sub_f32_e32 v74, v73, v124
	v_sub_f32_e32 v73, v72, v124
	v_sub_f32_e32 v70, v70, v124
	v_exp_f32_e32 v72, v70
	v_exp_f32_e32 v73, v73
	v_sub_f32_e32 v79, v79, v124
	v_sub_f32_e32 v78, v78, v124
	v_exp_f32_e32 v90, v78
	v_exp_f32_e32 v91, v79
	v_sub_f32_e32 v78, v83, v124
	v_sub_f32_e32 v79, v82, v124
	v_exp_f32_e32 v94, v79
	v_exp_f32_e32 v95, v78
	v_sub_f32_e32 v78, v87, v124
	v_sub_f32_e32 v79, v86, v124
	v_sub_f32_e32 v60, v68, v124
	v_pk_add_f32 v[68:69], v[58:59], 0 op_sel_hi:[1,0]
	v_exp_f32_e32 v102, v79
	v_exp_f32_e32 v103, v78
	v_exp_f32_e32 v75, v67
	v_sub_f32_e32 v67, v81, v124
	v_sub_f32_e32 v70, v80, v124
	v_pk_add_f32 v[68:69], v[72:73], v[68:69]
	v_exp_f32_e32 v60, v60
	v_exp_f32_e32 v92, v70
	v_exp_f32_e32 v93, v67
	v_pk_add_f32 v[68:69], v[90:91], v[68:69]
	v_sub_f32_e32 v67, v85, v124
	v_sub_f32_e32 v70, v84, v124
	v_exp_f32_e32 v74, v74
	v_exp_f32_e32 v96, v70
	v_exp_f32_e32 v97, v67
	v_sub_f32_e32 v67, v89, v124
	v_sub_f32_e32 v70, v88, v124
	v_pk_add_f32 v[68:69], v[94:95], v[68:69]
	v_exp_f32_e32 v104, v70
	v_exp_f32_e32 v105, v67
	v_pk_add_f32 v[82:83], v[102:103], v[68:69]
	v_sub_f32_e32 v67, v109, v124
	v_sub_f32_e32 v69, v107, v124
	v_sub_f32_e32 v70, v106, v124
	v_sub_f32_e32 v68, v108, v124
	v_exp_f32_e32 v106, v70
	v_exp_f32_e32 v107, v69
	v_exp_f32_e32 v109, v67
	v_sub_f32_e32 v67, v101, v124
	v_sub_f32_e32 v70, v100, v124
	v_pk_add_f32 v[62:63], v[60:61], 0 op_sel_hi:[1,0]
	v_exp_f32_e32 v108, v68
	v_sub_f32_e32 v68, v111, v124
	v_sub_f32_e32 v69, v110, v124
	v_exp_f32_e32 v110, v70
	v_exp_f32_e32 v111, v67
	v_add_u32_e32 v67, 0x9000, v180
	v_pk_add_f32 v[62:63], v[74:75], v[62:63]
	v_cvt_pk_bf16_f32 v58, v58, v59
	v_cvt_pk_bf16_f32 v59, v60, v61
	v_cvt_pk_bf16_f32 v60, v72, v73
	v_cvt_pk_bf16_f32 v61, v74, v75
	ds_read2_b64 v[72:75], v67 offset1:4
	v_exp_f32_e32 v112, v69
	v_exp_f32_e32 v113, v68
	v_add_u32_e32 v68, 0xb000, v180
	v_pk_add_f32 v[82:83], v[106:107], v[82:83]
	v_add_u32_e32 v70, 0xd000, v180
	v_add_u32_e32 v69, 0xf000, v180
	v_pk_add_f32 v[62:63], v[92:93], v[62:63]
	ds_read2_b64 v[78:81], v68 offset0:32 offset1:36
	v_pk_add_f32 v[114:115], v[110:111], v[82:83]
	ds_read2_b64 v[82:85], v70 offset0:64 offset1:68
	ds_read2_b64 v[86:89], v69 offset0:96 offset1:100
	v_pk_add_f32 v[62:63], v[96:97], v[62:63]
	v_cvt_pk_bf16_f32 v90, v90, v91
	v_cvt_pk_bf16_f32 v91, v92, v93
	v_cvt_pk_bf16_f32 v92, v94, v95
	v_cvt_pk_bf16_f32 v93, v96, v97
	ds_read2_b64 v[94:97], v67 offset0:8 offset1:12
	s_waitcnt lgkmcnt(4)
; __device__ __forceinline__ unsigned cvt_pk_bf16(float lo, float hi) { unsigned r; asm volatile("v_cvt_pk_bf16_f32 %0, %1, %2" : "=v"(r) : "v"(lo), "v"(hi)); return r; }
; #define LAS __attribute__((address_space(3)))
; __device__ __forceinline__ void attn_unit(LAS unsigned char* lds, bf16* Q, const bf16* Kg, const bf16* Vg, const float* snk, int unit, int tid) {
;     ...
;         f32x4 o[4];
; #pragma unroll
;         for (int dt = 0; dt < 4; ++dt) o[dt] = (f32x4){0.f, 0.f, 0.f, 0.f};
; #pragma unroll
;         for (int kp = 0; kp < 5; ++kp) {
;             v4u pw; pw.x = cvt_pk_bf16(st[2 * kp][0], st[2 * kp][1]); pw.y = cvt_pk_bf16(st[2 * kp][2], st[2 * kp][3]);
;             if (kp < 4) { pw.z = cvt_pk_bf16(st[(2 * kp + 1) % 9][0], st[(2 * kp + 1) % 9][1]); pw.w = cvt_pk_bf16(st[(2 * kp + 1) % 9][2], st[(2 * kp + 1) % 9][3]); } else { pw.z = 0u; pw.w = 0u; }
;             const bf16x8_t pb = __builtin_bit_cast(bf16x8_t, pw);
; #pragma unroll
;             for (int dt = 0; dt < 4; ++dt) { const LAS unsigned char* vp = lds + ATT_VOFF + (16 * dt + fr) * ATT_VP + (16 * (mt + 2 * kp) + 4 * fq) * 2;
;                 const v2u lo = *(const LAS v2u*)vp; v2u hi = {0u, 0u}; if (kp < 4) hi = *(const LAS v2u*)(vp + 32);
;                 v4u aw; aw.x = lo.x; aw.y = lo.y; aw.z = hi.x; aw.w = hi.y;
;                 o[dt] = __builtin_amdgcn_mfma_f32_16x16x32_bf16(__builtin_bit_cast(bf16x8_t, aw), pb, o[dt], 0, 0, 0); }
;         }
; #pragma unroll
;         for (int dt = 0; dt < 4; ++dt) { const f32x4 y = o[dt] * inv; v2u w; w.x = cvt_pk_bf16(y[0], y[1]); w.y = cvt_pk_bf16(y[2], y[3]); *(v2u*)(qbase + (size_t)mt * 16 * 1024 + 16 * dt + 4 * fq) = w; }
	v_mfma_f32_16x16x32_bf16 v[72:75], v[72:75], v[58:61], 0
	v_sub_f32_e32 v119, v99, v124
	v_sub_f32_e32 v118, v98, v124
	ds_read2_b64 v[98:101], v68 offset0:40 offset1:44
	s_waitcnt lgkmcnt(4)
	v_mfma_f32_16x16x32_bf16 v[78:81], v[78:81], v[58:61], 0
	v_add_f32_e64 v62, v104, v62
	v_add_f32_e64 v63, v105, v63
	v_sub_f32_e32 v117, v117, v124
	v_pk_add_f32 v[62:63], v[108:109], v[62:63]
	s_waitcnt lgkmcnt(3)
	v_mfma_f32_16x16x32_bf16 v[82:85], v[82:85], v[58:61], 0
	v_exp_f32_e32 v117, v117
	v_exp_f32_e32 v118, v118
	v_exp_f32_e32 v119, v119
	s_waitcnt lgkmcnt(2)
	v_mfma_f32_16x16x32_bf16 v[58:61], v[86:89], v[58:61], 0
	v_sub_f32_e32 v86, v116, v124
	v_exp_f32_e32 v116, v86
	ds_read2_b64 v[86:89], v70 offset0:72 offset1:76
	s_waitcnt lgkmcnt(2)
	v_mfma_f32_16x16x32_bf16 v[72:75], v[94:97], v[90:93], v[72:75]
	ds_read2_b64 v[94:97], v69 offset0:104 offset1:108
	v_pk_add_f32 v[62:63], v[112:113], v[62:63]
	s_waitcnt lgkmcnt(2)
	v_mfma_f32_16x16x32_bf16 v[78:81], v[98:101], v[90:93], v[78:81]
	v_cvt_pk_bf16_f32 v98, v102, v103
	v_cvt_pk_bf16_f32 v99, v104, v105
	v_cvt_pk_bf16_f32 v100, v106, v107
	v_cvt_pk_bf16_f32 v101, v108, v109
	s_waitcnt lgkmcnt(1)
	v_mfma_f32_16x16x32_bf16 v[82:85], v[86:89], v[90:93], v[82:85]
	ds_read2_b64 v[86:89], v68 offset0:48 offset1:52
	ds_read2_b64 v[102:105], v67 offset0:16 offset1:20
	v_pk_add_f32 v[106:107], v[116:117], v[114:115]
	s_waitcnt lgkmcnt(2)
	v_mfma_f32_16x16x32_bf16 v[58:61], v[94:97], v[90:93], v[58:61]
	ds_read2_b64 v[90:93], v70 offset0:80 offset1:84
	v_sub_f32_e32 v94, v120, v124
	v_exp_f32_e32 v108, v94
	s_waitcnt lgkmcnt(2)
	v_mfma_f32_16x16x32_bf16 v[78:81], v[86:89], v[98:101], v[78:81]
	ds_read2_b64 v[86:89], v69 offset0:112 offset1:116
	v_cvt_pk_bf16_f32 v94, v110, v111
	v_cvt_pk_bf16_f32 v95, v112, v113
	v_cvt_pk_bf16_f32 v96, v116, v117
	v_cvt_pk_bf16_f32 v97, v118, v119
	s_waitcnt lgkmcnt(1)
	v_mfma_f32_16x16x32_bf16 v[82:85], v[90:93], v[98:101], v[82:85]
	ds_read2_b64 v[90:93], v68 offset0:56 offset1:60
	v_sub_f32_e32 v109, v123, v124
	v_sub_f32_e32 v114, v122, v124
	s_waitcnt lgkmcnt(1)
	v_mfma_f32_16x16x32_bf16 v[58:61], v[86:89], v[98:101], v[58:61]
	ds_read2_b64 v[86:89], v70 offset0:88 offset1:92
	v_sub_f32_e32 v115, v121, v124
	v_exp_f32_e32 v110, v114
	s_waitcnt lgkmcnt(1)
	v_mfma_f32_16x16x32_bf16 v[78:81], v[90:93], v[94:97], v[78:81]
	ds_read2_b64 v[90:93], v69 offset0:120 offset1:124
	v_exp_f32_e32 v111, v109
	v_exp_f32_e32 v109, v115
	v_mfma_f32_16x16x32_bf16 v[72:75], v[102:105], v[98:101], v[72:75]
	ds_read2_b64 v[102:105], v67 offset0:24 offset1:28
	v_pk_add_f32 v[62:63], v[118:119], v[62:63]
	v_pk_add_f32 v[98:99], v[108:109], v[106:107]
	v_pk_add_f32 v[62:63], v[110:111], v[62:63]
	s_waitcnt lgkmcnt(2)
	v_mfma_f32_16x16x32_bf16 v[82:85], v[86:89], v[94:97], v[82:85]
	v_pk_mov_b32 v[100:101], v[98:99], v[62:63] op_sel:[1,0]
	v_mov_b32_e32 v99, v63
	v_pk_add_f32 v[62:63], v[100:101], v[98:99]
	s_waitcnt lgkmcnt(1)
	v_mfma_f32_16x16x32_bf16 v[58:61], v[90:93], v[94:97], v[58:61]
	v_cvt_pk_bf16_f32 v86, v108, v109
	v_cvt_pk_bf16_f32 v87, v110, v111
	ds_read_b64 v[90:91], v180 offset:37120
	v_add_f32_e32 v62, v62, v63
	ds_bpermute_b32 v63, v65, v62
	v_mov_b32_e32 v92, v147
	v_mov_b32_e32 v93, v147
	s_waitcnt lgkmcnt(2)
	v_mfma_f32_16x16x32_bf16 v[72:75], v[102:105], v[94:97], v[72:75]
	v_mov_b32_e32 v88, v147
	s_waitcnt lgkmcnt(0)
	v_add_f32_e32 v62, v62, v63
	v_mov_b32_e32 v89, v147
	ds_bpermute_b32 v63, v66, v62
	ds_read_b64 v[94:95], v180 offset:45568
	v_mfma_f32_16x16x32_bf16 v[72:75], v[90:93], v[86:89], v[72:75]
	v_fma_f32 v90, v64, s62, -v124
	v_exp_f32_e32 v90, v90
	s_waitcnt lgkmcnt(1)
	v_add_f32_e32 v62, v62, v63
	v_mov_b32_e32 v96, v147
	v_mov_b32_e32 v97, v147
	v_add_f32_e32 v90, v90, v62
	v_div_scale_f32 v91, s[64:65], v90, v90, 1.0
	v_rcp_f32_e32 v92, v91
	ds_read_b64 v[98:99], v180 offset:54016
	ds_read_b64 v[102:103], v180 offset:62464
	v_mov_b32_e32 v100, v147
	v_mov_b32_e32 v101, v147
	v_mov_b32_e32 v104, v147
	v_mov_b32_e32 v105, v147
	v_lshl_add_u64 v[62:63], v[76:77], 0, v[156:157]
	v_fma_f32 v76, -v91, v92, 1.0
	v_fmac_f32_e32 v92, v76, v92
	v_div_scale_f32 v76, vcc, 1.0, v90, 1.0
	v_mul_f32_e32 v77, v76, v92
	s_waitcnt lgkmcnt(2)
	v_mfma_f32_16x16x32_bf16 v[78:81], v[94:97], v[86:89], v[78:81]
	s_waitcnt lgkmcnt(1)
	v_mfma_f32_16x16x32_bf16 v[82:85], v[98:101], v[86:89], v[82:85]
	s_waitcnt lgkmcnt(0)
	v_mfma_f32_16x16x32_bf16 v[58:61], v[102:105], v[86:89], v[58:61]
	v_fma_f32 v86, -v91, v77, v76
	v_fmac_f32_e32 v77, v86, v92
	v_fma_f32 v76, -v91, v77, v76
	v_div_fmas_f32 v76, v76, v92, v77
	v_div_fixup_f32 v76, v76, v90, 1.0
	v_pk_mul_f32 v[74:75], v[76:77], v[74:75] op_sel_hi:[0,1]
	v_pk_mul_f32 v[72:73], v[76:77], v[72:73] op_sel_hi:[0,1]
	v_cvt_pk_bf16_f32 v72, v72, v73
	v_cvt_pk_bf16_f32 v73, v74, v75
	v_pk_mul_f32 v[74:75], v[76:77], v[78:79] op_sel_hi:[0,1]
	v_lshrrev_b32_e32 v110, 4, v0
	v_and_b32_e32 v110, 1, v110
	v_mul_u32_u24_e32 v110, 24, v110
	v_mov_b32_e32 v111, 0
	v_lshl_add_u64 v[118:119], v[62:63], 0, v[110:111]
	v_mov_b32_e32 v114, v72
	v_mov_b32_e32 v115, v73
	v_pk_mul_f32 v[72:73], v[76:77], v[80:81] op_sel_hi:[0,1]
	v_cvt_pk_bf16_f32 v74, v74, v75
	v_cvt_pk_bf16_f32 v75, v72, v73
	v_mov_b32_e32 v116, v74
	v_mov_b32_e32 v117, v75
	s_nop 1
	v_permlane16_swap_b32_e32 v114, v116
	v_permlane16_swap_b32_e32 v115, v117
	global_store_dwordx4 v[118:119], v[114:117], off
	v_pk_mul_f32 v[74:75], v[76:77], v[82:83] op_sel_hi:[0,1]
	v_pk_mul_f32 v[72:73], v[76:77], v[84:85] op_sel_hi:[0,1]
	v_cvt_pk_bf16_f32 v74, v74, v75
	v_cvt_pk_bf16_f32 v75, v72, v73
	v_pk_mul_f32 v[60:61], v[76:77], v[60:61] op_sel_hi:[0,1]
	v_pk_mul_f32 v[58:59], v[76:77], v[58:59] op_sel_hi:[0,1]
	v_mov_b32_e32 v126, v74
	v_mov_b32_e32 v127, v75
	v_cvt_pk_bf16_f32 v108, v58, v59
	v_cvt_pk_bf16_f32 v109, v60, v61
	ds_read_b128 v[58:61], v179 offset:2304
	ds_read_b128 v[72:75], v179 offset:2368
	s_waitcnt lgkmcnt(1)
; __device__ __forceinline__ unsigned cvt_pk_bf16(float lo, float hi) { unsigned r; asm volatile("v_cvt_pk_bf16_f32 %0, %1, %2" : "=v"(r) : "v"(lo), "v"(hi)); return r; }
; #define LAS __attribute__((address_space(3)))
; __device__ __forceinline__ void attn_unit(LAS unsigned char* lds, bf16* Q, const bf16* Kg, const bf16* Vg, const float* snk, int unit, int tid) {
;     ...
;     for (int mt = 0; mt < 8; ++mt) {
;         f32x4 st[9];
; #pragma unroll
;         for (int kb = 0; kb < 9; ++kb) { const LAS unsigned char* kp = lds + (16 * (mt + kb) + fr) * ATT_KP + 16 * fq;
;             const bf16x8_t k0 = *(const LAS bf16x8_t*)kp, k1 = *(const LAS bf16x8_t*)(kp + 64);
;             f32x4 z = {0.f, 0.f, 0.f, 0.f}; z = __builtin_amdgcn_mfma_f32_16x16x32_bf16(k0, qf[mt][0], z, 0, 0, 0); z = __builtin_amdgcn_mfma_f32_16x16x32_bf16(k1, qf[mt][1], z, 0, 0, 0); st[kb] = z; }
;         float mx = sink;
; #pragma unroll
;         for (int kb = 0; kb < 9; ++kb) {
;             const bool tile_ok = (n > 0) || (mt + kb >= 8);
; #pragma unroll
;             for (int i = 0; i < 4; ++i) { const bool ok = tile_ok && (kb == 0 ? lo_ok[i] : (kb == 8 ? !lo_ok[i] : true));
;                 st[kb][i] = ok ? st[kb][i] : -INFINITY; mx = fmaxf(mx, st[kb][i]); }
;         }
;         mx = fmaxf(mx, __shfl_xor(mx, 16)); mx = fmaxf(mx, __shfl_xor(mx, 32));
;     ...
;         for (int dt = 0; dt < 4; ++dt) { const f32x4 y = o[dt] * inv; v2u w; w.x = cvt_pk_bf16(y[0], y[1]); w.y = cvt_pk_bf16(y[2], y[3]); *(v2u*)(qbase + (size_t)mt * 16 * 1024 + 16 * dt + 4 * fq) = w; }
	v_mfma_f32_16x16x32_bf16 v[58:61], v[58:61], v[50:53], 0
	ds_read_b128 v[76:79], v179 offset:4608
	ds_read_b128 v[80:83], v179 offset:6912
	ds_read_b128 v[84:87], v179 offset:9216
	s_waitcnt lgkmcnt(3)
	v_mfma_f32_16x16x32_bf16 v[72:75], v[72:75], v[54:57], v[58:61]
	ds_read_b128 v[88:91], v179 offset:11520
	ds_read_b128 v[92:95], v179 offset:13824
	ds_read_b128 v[96:99], v179 offset:16128
	ds_read_b128 v[58:61], v179 offset:4672
	s_waitcnt lgkmcnt(6)
	v_mfma_f32_16x16x32_bf16 v[76:79], v[76:79], v[50:53], 0
	ds_read_b128 v[100:103], v179 offset:18432
	ds_read_b128 v[104:107], v179 offset:20736
	v_mov_b32_e32 v128, v108
	v_mov_b32_e32 v129, v109
	s_nop 1
	v_permlane16_swap_b32_e32 v126, v128
	v_permlane16_swap_b32_e32 v127, v129
	global_store_dwordx4 v[118:119], v[126:129], off offset:64
	s_waitcnt lgkmcnt(2)
	v_mfma_f32_16x16x32_bf16 v[76:79], v[58:61], v[54:57], v[76:79]
	ds_read_b128 v[58:61], v179 offset:6976
	v_mfma_f32_16x16x32_bf16 v[80:83], v[80:83], v[50:53], 0
	s_waitcnt lgkmcnt(0)
	v_mfma_f32_16x16x32_bf16 v[80:83], v[58:61], v[54:57], v[80:83]
	ds_read_b128 v[58:61], v179 offset:9280
	v_mfma_f32_16x16x32_bf16 v[84:87], v[84:87], v[50:53], 0
	s_waitcnt lgkmcnt(0)
	v_mfma_f32_16x16x32_bf16 v[84:87], v[58:61], v[54:57], v[84:87]
	ds_read_b128 v[58:61], v179 offset:11584
	v_mfma_f32_16x16x32_bf16 v[88:91], v[88:91], v[50:53], 0
	s_waitcnt lgkmcnt(0)
	v_mfma_f32_16x16x32_bf16 v[88:91], v[58:61], v[54:57], v[88:91]
	ds_read_b128 v[58:61], v179 offset:13888
	v_mfma_f32_16x16x32_bf16 v[92:95], v[92:95], v[50:53], 0
	s_waitcnt lgkmcnt(0)
	v_mfma_f32_16x16x32_bf16 v[92:95], v[58:61], v[54:57], v[92:95]
	ds_read_b128 v[58:61], v179 offset:16192
	v_mfma_f32_16x16x32_bf16 v[96:99], v[96:99], v[50:53], 0
	s_nop 5
	v_cndmask_b32_e64 v92, v191, v92, s[14:15]
	v_cndmask_b32_e64 v93, v191, v93, s[14:15]
	v_cndmask_b32_e64 v94, v191, v94, s[14:15]
	s_waitcnt lgkmcnt(0)
	v_mfma_f32_16x16x32_bf16 v[96:99], v[58:61], v[54:57], v[96:99]
	ds_read_b128 v[58:61], v179 offset:18496
	v_cndmask_b32_e64 v95, v191, v95, s[14:15]
	v_mfma_f32_16x16x32_bf16 v[100:103], v[100:103], v[50:53], 0
	s_nop 4
	v_cndmask_b32_e64 v110, v191, v99, s[14:15]
	s_waitcnt lgkmcnt(0)
	v_mfma_f32_16x16x32_bf16 v[58:61], v[58:61], v[54:57], v[100:103]
	s_nop 2
	ds_read_b128 v[100:103], v179 offset:20800
	v_mfma_f32_16x16x32_bf16 v[50:53], v[104:107], v[50:53], 0
	v_cndmask_b32_e64 v104, v191, v91, s[14:15]
	v_cndmask_b32_e64 v105, v191, v96, s[14:15]
	v_cndmask_b32_e64 v106, v191, v97, s[14:15]
	s_waitcnt lgkmcnt(0)
	v_mfma_f32_16x16x32_bf16 v[50:53], v[100:103], v[54:57], v[50:53]
	v_cndmask_b32_e64 v55, v73, v191, s[8:9]
	v_cndmask_b32_e64 v54, v191, v72, s[18:19]
	v_cndmask_b32_e64 v55, v191, v55, s[14:15]
	v_max3_f32 v56, v71, v54, v55
	v_cndmask_b32_e64 v57, v191, v74, s[16:17]
	v_cndmask_b32_e64 v72, v191, v75, s[20:21]
	v_max3_f32 v56, v56, v57, v72
	v_cndmask_b32_e64 v73, v191, v76, s[14:15]
	v_cndmask_b32_e64 v74, v191, v77, s[14:15]
	v_max3_f32 v56, v56, v73, v74
	v_cndmask_b32_e64 v75, v191, v78, s[14:15]
	v_cndmask_b32_e64 v76, v191, v79, s[14:15]
	v_max3_f32 v56, v56, v75, v76
	v_cndmask_b32_e64 v77, v191, v80, s[14:15]
	v_cndmask_b32_e64 v78, v191, v81, s[14:15]
	v_max3_f32 v56, v56, v77, v78
	v_cndmask_b32_e64 v79, v191, v82, s[14:15]
	v_cndmask_b32_e64 v80, v191, v83, s[14:15]
	v_max3_f32 v56, v56, v79, v80
	v_cndmask_b32_e64 v81, v191, v84, s[14:15]
	v_cndmask_b32_e64 v82, v191, v85, s[14:15]
	v_max3_f32 v56, v56, v81, v82
	v_cndmask_b32_e64 v83, v191, v86, s[14:15]
	v_cndmask_b32_e64 v100, v191, v87, s[14:15]
	v_max3_f32 v56, v56, v83, v100
	v_cndmask_b32_e64 v101, v191, v88, s[14:15]
	v_cndmask_b32_e64 v102, v191, v89, s[14:15]
	v_max3_f32 v56, v56, v101, v102
	v_cndmask_b32_e64 v103, v191, v90, s[14:15]
	v_max3_f32 v56, v56, v103, v104
	v_max3_f32 v56, v56, v92, v93
	v_max3_f32 v56, v56, v94, v95
	v_max3_f32 v56, v56, v105, v106
	v_cndmask_b32_e64 v107, v191, v98, s[14:15]
	v_max3_f32 v56, v56, v107, v110
	v_max3_f32 v56, v56, v58, v59
	v_max3_f32 v56, v56, v60, v61
	v_cndmask_b32_e64 v116, v50, v191, s[6:7]
	v_cndmask_b32_e64 v117, v191, v51, s[8:9]
	v_max3_f32 v50, v56, v116, v117
	v_cndmask_b32_e64 v118, v52, v191, s[10:11]
	v_cndmask_b32_e64 v119, v53, v191, s[12:13]
	v_max3_f32 v50, v50, v118, v119
	ds_bpermute_b32 v51, v65, v50
	s_waitcnt lgkmcnt(0)
	v_max_f32_e32 v51, v51, v51
	v_max_f32_e32 v50, v50, v51
	ds_bpermute_b32 v51, v66, v50
	s_waitcnt lgkmcnt(0)
; __device__ __forceinline__ unsigned cvt_pk_bf16(float lo, float hi) { unsigned r; asm volatile("v_cvt_pk_bf16_f32 %0, %1, %2" : "=v"(r) : "v"(lo), "v"(hi)); return r; }
; #define LAS __attribute__((address_space(3)))
; __device__ __forceinline__ void attn_unit(LAS unsigned char* lds, bf16* Q, const bf16* Kg, const bf16* Vg, const float* snk, int unit, int tid) {
;     ...
;         mx = fmaxf(mx, __shfl_xor(mx, 16)); mx = fmaxf(mx, __shfl_xor(mx, 32));
;         f32x4 ls4 = {0.f, 0.f, 0.f, 0.f};
; #pragma unroll
;         for (int kb = 0; kb < 9; ++kb) { f32x4 d = st[kb] - mx;
; #pragma unroll
;             for (int i = 0; i < 4; ++i) d[i] = __builtin_amdgcn_exp2f(d[i]);
;             st[kb] = d; ls4 = ls4 + d; }
;         float ls = (ls4[0] + ls4[1]) + (ls4[2] + ls4[3]);
;         ls += __shfl_xor(ls, 16); ls += __shfl_xor(ls, 32);
;         const float inv = 1.f / (ls + __builtin_amdgcn_exp2f(sink - mx));
;         f32x4 o[4];
; #pragma unroll
;         for (int dt = 0; dt < 4; ++dt) o[dt] = (f32x4){0.f, 0.f, 0.f, 0.f};
; #pragma unroll
;         for (int kp = 0; kp < 5; ++kp) {
;             v4u pw; pw.x = cvt_pk_bf16(st[2 * kp][0], st[2 * kp][1]); pw.y = cvt_pk_bf16(st[2 * kp][2], st[2 * kp][3]);
;             if (kp < 4) { pw.z = cvt_pk_bf16(st[(2 * kp + 1) % 9][0], st[(2 * kp + 1) % 9][1]); pw.w = cvt_pk_bf16(st[(2 * kp + 1) % 9][2], st[(2 * kp + 1) % 9][3]); } else { pw.z = 0u; pw.w = 0u; }
;             const bf16x8_t pb = __builtin_bit_cast(bf16x8_t, pw);
; #pragma unroll
;             for (int dt = 0; dt < 4; ++dt) { const LAS unsigned char* vp = lds + ATT_VOFF + (16 * dt + fr) * ATT_VP + (16 * (mt + 2 * kp) + 4 * fq) * 2;
;                 const v2u lo = *(const LAS v2u*)vp; v2u hi = {0u, 0u}; if (kp < 4) hi = *(const LAS v2u*)(vp + 32);
;                 v4u aw; aw.x = lo.x; aw.y = lo.y; aw.z = hi.x; aw.w = hi.y;
;                 o[dt] = __builtin_amdgcn_mfma_f32_16x16x32_bf16(__builtin_bit_cast(bf16x8_t, aw), pb, o[dt], 0, 0, 0); }
	v_max_f32_e32 v51, v51, v51
	v_max_f32_e32 v120, v50, v51
	v_sub_f32_e32 v51, v72, v120
	v_sub_f32_e32 v52, v57, v120
	v_sub_f32_e32 v55, v55, v120
	v_sub_f32_e32 v50, v54, v120
	v_exp_f32_e32 v50, v50
	v_exp_f32_e32 v52, v52
	v_exp_f32_e32 v53, v51
	v_exp_f32_e32 v51, v55
	v_sub_f32_e32 v76, v76, v120
	v_sub_f32_e32 v75, v75, v120
	v_sub_f32_e32 v74, v74, v120
	v_sub_f32_e32 v72, v73, v120
	v_exp_f32_e32 v72, v72
	v_exp_f32_e32 v73, v74
	v_exp_f32_e32 v74, v75
	v_exp_f32_e32 v75, v76
	v_sub_f32_e32 v76, v80, v120
	v_sub_f32_e32 v79, v79, v120
	v_sub_f32_e32 v78, v78, v120
	v_sub_f32_e32 v77, v77, v120
	v_exp_f32_e32 v84, v77
	v_exp_f32_e32 v86, v79
	v_exp_f32_e32 v87, v76
	v_exp_f32_e32 v85, v78
	v_sub_f32_e32 v76, v100, v120
	v_sub_f32_e32 v77, v83, v120
	v_sub_f32_e32 v78, v82, v120
	v_sub_f32_e32 v79, v81, v120
	v_exp_f32_e32 v88, v79
	v_exp_f32_e32 v89, v78
	v_exp_f32_e32 v90, v77
	v_exp_f32_e32 v91, v76
	v_sub_f32_e32 v76, v104, v120
	v_sub_f32_e32 v77, v103, v120
	v_sub_f32_e32 v78, v102, v120
	v_sub_f32_e32 v79, v101, v120
	v_pk_add_f32 v[54:55], v[52:53], 0 op_sel_hi:[1,0]
	v_pk_add_f32 v[56:57], v[50:51], 0 op_sel_hi:[1,0]
	v_exp_f32_e32 v96, v79
	v_exp_f32_e32 v98, v77
	v_exp_f32_e32 v99, v76
	v_exp_f32_e32 v97, v78
	v_pk_add_f32 v[56:57], v[72:73], v[56:57]
	v_pk_add_f32 v[54:55], v[74:75], v[54:55]
	v_pk_add_f32 v[56:57], v[84:85], v[56:57]
	v_pk_add_f32 v[54:55], v[86:87], v[54:55]
	v_pk_add_f32 v[56:57], v[88:89], v[56:57]
	v_pk_add_f32 v[54:55], v[90:91], v[54:55]
	v_sub_f32_e32 v78, v92, v120
	v_pk_add_f32 v[76:77], v[98:99], v[54:55]
	v_pk_add_f32 v[54:55], v[96:97], v[56:57]
	v_sub_f32_e32 v57, v93, v120
	v_sub_f32_e32 v56, v95, v120
	v_exp_f32_e32 v101, v57
	v_sub_f32_e32 v57, v94, v120
	v_exp_f32_e32 v100, v78
	v_exp_f32_e32 v102, v57
	v_exp_f32_e32 v103, v56
	v_sub_f32_e32 v80, v110, v120
	v_sub_f32_e32 v81, v107, v120
	v_sub_f32_e32 v82, v106, v120
	v_sub_f32_e32 v83, v105, v120
	v_exp_f32_e32 v104, v81
	v_exp_f32_e32 v105, v80
	v_exp_f32_e32 v106, v83
	v_exp_f32_e32 v107, v82
	v_pk_add_f32 v[78:79], v[100:101], v[54:55]
	v_pk_add_f32 v[76:77], v[102:103], v[76:77]
	v_cvt_pk_bf16_f32 v50, v50, v51
	v_cvt_pk_bf16_f32 v51, v52, v53
	v_cvt_pk_bf16_f32 v52, v72, v73
	v_cvt_pk_bf16_f32 v53, v74, v75
	ds_read2_b64 v[54:57], v67 offset0:4 offset1:8
	ds_read2_b64 v[72:75], v68 offset0:36 offset1:40
	v_pk_add_f32 v[108:109], v[104:105], v[76:77]
	v_pk_add_f32 v[110:111], v[106:107], v[78:79]
	ds_read2_b64 v[76:79], v70 offset0:68 offset1:72
	ds_read2_b64 v[80:83], v69 offset0:100 offset1:104
	v_sub_f32_e32 v60, v60, v120
	v_sub_f32_e32 v59, v59, v120
	v_sub_f32_e32 v58, v58, v120
	v_sub_f32_e32 v115, v61, v120
	v_cvt_pk_bf16_f32 v84, v84, v85
	v_cvt_pk_bf16_f32 v85, v86, v87
	v_cvt_pk_bf16_f32 v86, v88, v89
	v_cvt_pk_bf16_f32 v87, v90, v91
	ds_read2_b64 v[88:91], v67 offset0:12 offset1:16
	v_exp_f32_e32 v112, v58
	v_exp_f32_e32 v113, v59
	v_exp_f32_e32 v114, v60
	ds_read2_b64 v[58:61], v70 offset0:76 offset1:80
	s_waitcnt lgkmcnt(5)
	v_mfma_f32_16x16x32_bf16 v[54:57], v[54:57], v[50:53], 0
	ds_read2_b64 v[92:95], v68 offset0:44 offset1:48
	v_exp_f32_e32 v115, v115
	s_waitcnt lgkmcnt(5)
	v_mfma_f32_16x16x32_bf16 v[72:75], v[72:75], v[50:53], 0
	s_waitcnt lgkmcnt(4)
	v_mfma_f32_16x16x32_bf16 v[76:79], v[76:79], v[50:53], 0
	s_waitcnt lgkmcnt(3)
	v_mfma_f32_16x16x32_bf16 v[50:53], v[80:83], v[50:53], 0
	ds_read2_b64 v[80:83], v69 offset0:108 offset1:112
	s_waitcnt lgkmcnt(3)
	v_mfma_f32_16x16x32_bf16 v[54:57], v[88:91], v[84:87], v[54:57]
	v_cvt_pk_bf16_f32 v88, v96, v97
	v_cvt_pk_bf16_f32 v89, v98, v99
	v_cvt_pk_bf16_f32 v90, v100, v101
	v_cvt_pk_bf16_f32 v91, v102, v103
	s_waitcnt lgkmcnt(2)
	v_mfma_f32_16x16x32_bf16 v[58:61], v[58:61], v[84:87], v[76:79]
	v_add_f32_e64 v98, v114, v108
	v_add_f32_e64 v99, v115, v109
	v_sub_f32_e32 v101, v119, v120
	v_sub_f32_e32 v102, v118, v120
	ds_read2_b64 v[76:79], v68 offset0:52 offset1:56
	s_waitcnt lgkmcnt(2)
	v_mfma_f32_16x16x32_bf16 v[72:75], v[92:95], v[84:87], v[72:75]
	ds_read2_b64 v[92:95], v67 offset0:20 offset1:24
	v_sub_f32_e32 v108, v117, v120
	v_exp_f32_e32 v102, v102
	s_waitcnt lgkmcnt(2)
	v_mfma_f32_16x16x32_bf16 v[50:53], v[80:83], v[84:87], v[50:53]
	ds_read2_b64 v[80:83], v70 offset0:84 offset1:88
	v_sub_f32_e32 v84, v116, v120
	v_exp_f32_e32 v100, v84
	s_waitcnt lgkmcnt(2)
	v_mfma_f32_16x16x32_bf16 v[72:75], v[76:79], v[88:91], v[72:75]
	ds_read2_b64 v[76:79], v69 offset0:116 offset1:120
	v_cvt_pk_bf16_f32 v84, v106, v107
	v_cvt_pk_bf16_f32 v85, v104, v105
	v_cvt_pk_bf16_f32 v86, v112, v113
	v_cvt_pk_bf16_f32 v87, v114, v115
	s_waitcnt lgkmcnt(1)
	v_mfma_f32_16x16x32_bf16 v[58:61], v[80:83], v[88:91], v[58:61]
	ds_read2_b64 v[80:83], v68 offset0:60 offset1:64
	v_exp_f32_e32 v103, v101
	v_exp_f32_e32 v101, v108
	v_mfma_f32_16x16x32_bf16 v[54:57], v[92:95], v[88:91], v[54:57]
	ds_read2_b64 v[92:95], v67 offset0:28 offset1:32
	v_pk_add_f32 v[96:97], v[112:113], v[110:111]
	s_waitcnt lgkmcnt(2)
	v_mfma_f32_16x16x32_bf16 v[50:53], v[76:79], v[88:91], v[50:53]
	ds_read2_b64 v[76:79], v70 offset0:92 offset1:96
	v_pk_add_f32 v[88:89], v[102:103], v[98:99]
	v_pk_add_f32 v[90:91], v[100:101], v[96:97]
	s_waitcnt lgkmcnt(2)
	v_mfma_f32_16x16x32_bf16 v[72:75], v[80:83], v[84:87], v[72:75]
	ds_read2_b64 v[80:83], v69 offset0:124 offset1:128
	s_waitcnt lgkmcnt(2)
	v_mfma_f32_16x16x32_bf16 v[54:57], v[92:95], v[84:87], v[54:57]
	v_pk_mov_b32 v[92:93], v[90:91], v[88:89] op_sel:[1,0]
	v_mov_b32_e32 v91, v89
	v_pk_add_f32 v[88:89], v[92:93], v[90:91]
	s_waitcnt lgkmcnt(1)
	v_mfma_f32_16x16x32_bf16 v[58:61], v[76:79], v[84:87], v[58:61]
	v_add_f32_e32 v88, v88, v89
	ds_bpermute_b32 v76, v65, v88
	v_mov_b32_e32 v78, v147
	s_waitcnt lgkmcnt(1)
; __device__ __forceinline__ unsigned cvt_pk_bf16(float lo, float hi) { unsigned r; asm volatile("v_cvt_pk_bf16_f32 %0, %1, %2" : "=v"(r) : "v"(lo), "v"(hi)); return r; }
; #define LAS __attribute__((address_space(3)))
; __device__ __forceinline__ void attn_unit(LAS unsigned char* lds, bf16* Q, const bf16* Kg, const bf16* Vg, const float* snk, int unit, int tid) {
;     ...
;     for (int mt = 0; mt < 8; ++mt) {
;         f32x4 st[9];
; #pragma unroll
;         for (int kb = 0; kb < 9; ++kb) { const LAS unsigned char* kp = lds + (16 * (mt + kb) + fr) * ATT_KP + 16 * fq;
;             const bf16x8_t k0 = *(const LAS bf16x8_t*)kp, k1 = *(const LAS bf16x8_t*)(kp + 64);
;             f32x4 z = {0.f, 0.f, 0.f, 0.f}; z = __builtin_amdgcn_mfma_f32_16x16x32_bf16(k0, qf[mt][0], z, 0, 0, 0); z = __builtin_amdgcn_mfma_f32_16x16x32_bf16(k1, qf[mt][1], z, 0, 0, 0); st[kb] = z; }
;     ...
;         float ls = (ls4[0] + ls4[1]) + (ls4[2] + ls4[3]);
;         ls += __shfl_xor(ls, 16); ls += __shfl_xor(ls, 32);
;         const float inv = 1.f / (ls + __builtin_amdgcn_exp2f(sink - mx));
;         f32x4 o[4];
; #pragma unroll
;         for (int dt = 0; dt < 4; ++dt) o[dt] = (f32x4){0.f, 0.f, 0.f, 0.f};
; #pragma unroll
;         for (int kp = 0; kp < 5; ++kp) {
;             v4u pw; pw.x = cvt_pk_bf16(st[2 * kp][0], st[2 * kp][1]); pw.y = cvt_pk_bf16(st[2 * kp][2], st[2 * kp][3]);
;             if (kp < 4) { pw.z = cvt_pk_bf16(st[(2 * kp + 1) % 9][0], st[(2 * kp + 1) % 9][1]); pw.w = cvt_pk_bf16(st[(2 * kp + 1) % 9][2], st[(2 * kp + 1) % 9][3]); } else { pw.z = 0u; pw.w = 0u; }
;             const bf16x8_t pb = __builtin_bit_cast(bf16x8_t, pw);
; #pragma unroll
;             for (int dt = 0; dt < 4; ++dt) { const LAS unsigned char* vp = lds + ATT_VOFF + (16 * dt + fr) * ATT_VP + (16 * (mt + 2 * kp) + 4 * fq) * 2;
;                 const v2u lo = *(const LAS v2u*)vp; v2u hi = {0u, 0u}; if (kp < 4) hi = *(const LAS v2u*)(vp + 32);
;                 v4u aw; aw.x = lo.x; aw.y = lo.y; aw.z = hi.x; aw.w = hi.y;
;                 o[dt] = __builtin_amdgcn_mfma_f32_16x16x32_bf16(__builtin_bit_cast(bf16x8_t, aw), pb, o[dt], 0, 0, 0); }
;         }
; #pragma unroll
;         for (int dt = 0; dt < 4; ++dt) { const f32x4 y = o[dt] * inv; v2u w; w.x = cvt_pk_bf16(y[0], y[1]); w.y = cvt_pk_bf16(y[2], y[3]); *(v2u*)(qbase + (size_t)mt * 16 * 1024 + 16 * dt + 4 * fq) = w; }
	v_mfma_f32_16x16x32_bf16 v[50:53], v[80:83], v[84:87], v[50:53]
	v_mov_b32_e32 v82, v147
	v_mov_b32_e32 v83, v147
	s_waitcnt lgkmcnt(0)
	v_add_f32_e32 v94, v88, v76
	v_cvt_pk_bf16_f32 v76, v100, v101
	v_cvt_pk_bf16_f32 v77, v102, v103
	ds_read_b64 v[80:81], v180 offset:37152
	ds_read_b64 v[84:85], v180 offset:45600
	v_mov_b32_e32 v79, v147
	v_mov_b32_e32 v86, v147
	v_mov_b32_e32 v87, v147
	s_waitcnt lgkmcnt(1)
	v_mfma_f32_16x16x32_bf16 v[54:57], v[80:83], v[76:79], v[54:57]
	ds_bpermute_b32 v80, v66, v94
	v_fma_f32 v81, v64, s62, -v120
	v_exp_f32_e32 v81, v81
	ds_read_b64 v[88:89], v180 offset:54048
	ds_read_b64 v[92:93], v180 offset:62496
	v_mov_b32_e32 v90, v147
	s_waitcnt lgkmcnt(2)
	v_add_f32_e32 v80, v94, v80
	v_add_f32_e32 v80, v81, v80
	v_mov_b32_e32 v91, v147
	v_mov_b32_e32 v94, v147
	v_mov_b32_e32 v95, v147
	v_div_scale_f32 v81, s[64:65], v80, v80, 1.0
	v_rcp_f32_e32 v82, v81
	v_mfma_f32_16x16x32_bf16 v[72:75], v[84:87], v[76:79], v[72:75]
	s_waitcnt lgkmcnt(1)
	v_mfma_f32_16x16x32_bf16 v[58:61], v[88:91], v[76:79], v[58:61]
	s_waitcnt lgkmcnt(0)
	v_mfma_f32_16x16x32_bf16 v[50:53], v[92:95], v[76:79], v[50:53]
	v_fma_f32 v76, -v81, v82, 1.0
	v_fmac_f32_e32 v82, v76, v82
	v_div_scale_f32 v76, vcc, 1.0, v80, 1.0
	v_mul_f32_e32 v77, v76, v82
	v_fma_f32 v78, -v81, v77, v76
	v_fmac_f32_e32 v77, v78, v82
	v_fma_f32 v76, -v81, v77, v76
	v_div_fmas_f32 v76, v76, v82, v77
	v_div_fixup_f32 v76, v76, v80, 1.0
	v_pk_mul_f32 v[56:57], v[76:77], v[56:57] op_sel_hi:[0,1]
	v_pk_mul_f32 v[54:55], v[76:77], v[54:55] op_sel_hi:[0,1]
	v_add_co_u32_e32 v100, vcc, s40, v62
	v_cvt_pk_bf16_f32 v54, v54, v55
	v_cvt_pk_bf16_f32 v55, v56, v57
	v_pk_mul_f32 v[56:57], v[76:77], v[72:73] op_sel_hi:[0,1]
	s_nop 0
	v_addc_co_u32_e32 v101, vcc, 0, v63, vcc
	v_lshrrev_b32_e32 v110, 4, v0
	v_and_b32_e32 v110, 1, v110
	v_mul_u32_u24_e32 v110, 24, v110
	v_mov_b32_e32 v111, 0
	v_lshl_add_u64 v[118:119], v[100:101], 0, v[110:111]
	v_mov_b32_e32 v114, v54
	v_mov_b32_e32 v115, v55
	v_pk_mul_f32 v[54:55], v[76:77], v[74:75] op_sel_hi:[0,1]
	v_cvt_pk_bf16_f32 v56, v56, v57
	v_cvt_pk_bf16_f32 v57, v54, v55
	v_mov_b32_e32 v116, v56
	v_mov_b32_e32 v117, v57
	s_nop 1
	v_permlane16_swap_b32_e32 v114, v116
	v_permlane16_swap_b32_e32 v115, v117
	global_store_dwordx4 v[118:119], v[114:117], off
	v_pk_mul_f32 v[56:57], v[76:77], v[58:59] op_sel_hi:[0,1]
	v_pk_mul_f32 v[54:55], v[76:77], v[60:61] op_sel_hi:[0,1]
	v_cvt_pk_bf16_f32 v56, v56, v57
	v_cvt_pk_bf16_f32 v57, v54, v55
	v_pk_mul_f32 v[52:53], v[76:77], v[52:53] op_sel_hi:[0,1]
	v_pk_mul_f32 v[50:51], v[76:77], v[50:51] op_sel_hi:[0,1]
	v_mov_b32_e32 v126, v56
	v_mov_b32_e32 v127, v57
	v_cvt_pk_bf16_f32 v102, v50, v51
	v_cvt_pk_bf16_f32 v103, v52, v53
	ds_read_b128 v[50:53], v179 offset:4608
	ds_read_b128 v[54:57], v179 offset:4672
	s_waitcnt lgkmcnt(1)
	v_mfma_f32_16x16x32_bf16 v[50:53], v[50:53], v[42:45], 0
	ds_read_b128 v[58:61], v179 offset:6912
	ds_read_b128 v[96:99], v179 offset:23040
	v_mov_b32_e32 v128, v102
	v_mov_b32_e32 v129, v103
	s_nop 1
	v_permlane16_swap_b32_e32 v126, v128
	v_permlane16_swap_b32_e32 v127, v129
	global_store_dwordx4 v[118:119], v[126:129], off offset:64
	s_waitcnt lgkmcnt(2)
	v_mfma_f32_16x16x32_bf16 v[72:75], v[54:57], v[46:49], v[50:53]
	s_nop 2
	ds_read_b128 v[50:53], v179 offset:6976
	s_waitcnt lgkmcnt(2)
	v_mfma_f32_16x16x32_bf16 v[54:57], v[58:61], v[42:45], 0
	ds_read_b128 v[58:61], v179 offset:9216
	s_waitcnt lgkmcnt(1)
	v_mfma_f32_16x16x32_bf16 v[76:79], v[50:53], v[46:49], v[54:57]
	ds_read_b128 v[50:53], v179 offset:9280
	s_waitcnt lgkmcnt(1)
	v_mfma_f32_16x16x32_bf16 v[54:57], v[58:61], v[42:45], 0
	ds_read_b128 v[58:61], v179 offset:11520
	s_waitcnt lgkmcnt(1)
	v_mfma_f32_16x16x32_bf16 v[80:83], v[50:53], v[46:49], v[54:57]
	ds_read_b128 v[50:53], v179 offset:11584
	s_waitcnt lgkmcnt(1)
	v_mfma_f32_16x16x32_bf16 v[54:57], v[58:61], v[42:45], 0
	ds_read_b128 v[58:61], v179 offset:13824
	s_waitcnt lgkmcnt(1)
	v_mfma_f32_16x16x32_bf16 v[84:87], v[50:53], v[46:49], v[54:57]
	ds_read_b128 v[50:53], v179 offset:13888
	s_waitcnt lgkmcnt(1)
	v_mfma_f32_16x16x32_bf16 v[54:57], v[58:61], v[42:45], 0
	ds_read_b128 v[58:61], v179 offset:16128
	s_waitcnt lgkmcnt(1)
	v_mfma_f32_16x16x32_bf16 v[88:91], v[50:53], v[46:49], v[54:57]
	ds_read_b128 v[50:53], v179 offset:16192
	s_waitcnt lgkmcnt(1)
	v_mfma_f32_16x16x32_bf16 v[54:57], v[58:61], v[42:45], 0
	ds_read_b128 v[58:61], v179 offset:18432
	s_waitcnt lgkmcnt(1)
	v_mfma_f32_16x16x32_bf16 v[92:95], v[50:53], v[46:49], v[54:57]
	ds_read_b128 v[50:53], v179 offset:18496
	s_waitcnt lgkmcnt(1)
	v_mfma_f32_16x16x32_bf16 v[54:57], v[58:61], v[42:45], 0
	ds_read_b128 v[58:61], v179 offset:20736
	s_nop 3
	v_cndmask_b32_e64 v92, v191, v92, s[14:15]
	v_cndmask_b32_e64 v93, v191, v93, s[14:15]
	s_waitcnt lgkmcnt(1)
	v_mfma_f32_16x16x32_bf16 v[54:57], v[50:53], v[46:49], v[54:57]
	ds_read_b128 v[50:53], v179 offset:20800
	v_cndmask_b32_e64 v94, v191, v94, s[14:15]
	v_cndmask_b32_e64 v95, v191, v95, s[14:15]
	s_waitcnt lgkmcnt(1)
	v_mfma_f32_16x16x32_bf16 v[58:61], v[58:61], v[42:45], 0
	s_waitcnt lgkmcnt(0)
	v_mfma_f32_16x16x32_bf16 v[50:53], v[50:53], v[46:49], v[58:61]
	s_nop 5
	ds_read_b128 v[58:61], v179 offset:23104
	v_mfma_f32_16x16x32_bf16 v[42:45], v[96:99], v[42:45], 0
	s_waitcnt lgkmcnt(0)
; __device__ __forceinline__ void attn_unit(LAS unsigned char* lds, bf16* Q, const bf16* Kg, const bf16* Vg, const float* snk, int unit, int tid) {
;     ...
;         for (int kb = 0; kb < 9; ++kb) { const LAS unsigned char* kp = lds + (16 * (mt + kb) + fr) * ATT_KP + 16 * fq;
;             const bf16x8_t k0 = *(const LAS bf16x8_t*)kp, k1 = *(const LAS bf16x8_t*)(kp + 64);
;             f32x4 z = {0.f, 0.f, 0.f, 0.f}; z = __builtin_amdgcn_mfma_f32_16x16x32_bf16(k0, qf[mt][0], z, 0, 0, 0); z = __builtin_amdgcn_mfma_f32_16x16x32_bf16(k1, qf[mt][1], z, 0, 0, 0); st[kb] = z; }
;         float mx = sink;
; #pragma unroll
;         for (int kb = 0; kb < 9; ++kb) {
;             const bool tile_ok = (n > 0) || (mt + kb >= 8);
; #pragma unroll
;             for (int i = 0; i < 4; ++i) { const bool ok = tile_ok && (kb == 0 ? lo_ok[i] : (kb == 8 ? !lo_ok[i] : true));
;                 st[kb][i] = ok ? st[kb][i] : -INFINITY; mx = fmaxf(mx, st[kb][i]); }
;         }
;         mx = fmaxf(mx, __shfl_xor(mx, 16)); mx = fmaxf(mx, __shfl_xor(mx, 32));
;         f32x4 ls4 = {0.f, 0.f, 0.f, 0.f};
; #pragma unroll
;         for (int kb = 0; kb < 9; ++kb) { f32x4 d = st[kb] - mx;
; #pragma unroll
;             for (int i = 0; i < 4; ++i) d[i] = __builtin_amdgcn_exp2f(d[i]);
;             st[kb] = d; ls4 = ls4 + d; }
;         float ls = (ls4[0] + ls4[1]) + (ls4[2] + ls4[3]);
;         ls += __shfl_xor(ls, 16); ls += __shfl_xor(ls, 32);
;         const float inv = 1.f / (ls + __builtin_amdgcn_exp2f(sink - mx));
;         f32x4 o[4];
; #pragma unroll
;         for (int dt = 0; dt < 4; ++dt) o[dt] = (f32x4){0.f, 0.f, 0.f, 0.f};
; #pragma unroll
;         for (int kp = 0; kp < 5; ++kp) {
;             v4u pw; pw.x = cvt_pk_bf16(st[2 * kp][0], st[2 * kp][1]); pw.y = cvt_pk_bf16(st[2 * kp][2], st[2 * kp][3]);
;             if (kp < 4) { pw.z = cvt_pk_bf16(st[(2 * kp + 1) % 9][0], st[(2 * kp + 1) % 9][1]); pw.w = cvt_pk_bf16(st[(2 * kp + 1) % 9][2], st[(2 * kp + 1) % 9][3]); } else { pw.z = 0u; pw.w = 0u; }
;             const bf16x8_t pb = __builtin_bit_cast(bf16x8_t, pw);
; #pragma unroll
;             for (int dt = 0; dt < 4; ++dt) { const LAS unsigned char* vp = lds + ATT_VOFF + (16 * dt + fr) * ATT_VP + (16 * (mt + 2 * kp) + 4 * fq) * 2;
;                 const v2u lo = *(const LAS v2u*)vp; v2u hi = {0u, 0u}; if (kp < 4) hi = *(const LAS v2u*)(vp + 32);
	v_mfma_f32_16x16x32_bf16 v[42:45], v[58:61], v[46:49], v[42:45]
	v_cndmask_b32_e64 v47, v73, v191, s[8:9]
	v_cndmask_b32_e64 v46, v191, v72, s[18:19]
	v_cndmask_b32_e64 v47, v191, v47, s[14:15]
	v_max3_f32 v48, v71, v46, v47
	v_cndmask_b32_e64 v49, v191, v74, s[16:17]
	v_cndmask_b32_e64 v58, v191, v75, s[20:21]
	v_max3_f32 v48, v48, v49, v58
	v_cndmask_b32_e64 v59, v191, v76, s[14:15]
	v_cndmask_b32_e64 v60, v191, v77, s[14:15]
	v_max3_f32 v48, v48, v59, v60
	v_cndmask_b32_e64 v61, v191, v78, s[14:15]
	v_cndmask_b32_e64 v72, v191, v79, s[14:15]
	v_max3_f32 v48, v48, v61, v72
	v_cndmask_b32_e64 v73, v191, v80, s[14:15]
	v_cndmask_b32_e64 v74, v191, v81, s[14:15]
	v_max3_f32 v48, v48, v73, v74
	v_cndmask_b32_e64 v75, v191, v82, s[14:15]
	v_cndmask_b32_e64 v76, v191, v83, s[14:15]
	v_max3_f32 v48, v48, v75, v76
	v_cndmask_b32_e64 v80, v191, v84, s[14:15]
	v_cndmask_b32_e64 v81, v191, v85, s[14:15]
	v_max3_f32 v48, v48, v80, v81
	v_cndmask_b32_e64 v82, v191, v86, s[14:15]
	v_cndmask_b32_e64 v83, v191, v87, s[14:15]
	v_max3_f32 v48, v48, v82, v83
	v_cndmask_b32_e64 v84, v191, v88, s[14:15]
	v_cndmask_b32_e64 v85, v191, v89, s[14:15]
	v_max3_f32 v48, v48, v84, v85
	v_cndmask_b32_e64 v86, v191, v90, s[14:15]
	v_cndmask_b32_e64 v87, v191, v91, s[14:15]
	v_max3_f32 v48, v48, v86, v87
	v_max3_f32 v48, v48, v92, v93
	v_max3_f32 v48, v48, v94, v95
	v_max3_f32 v48, v48, v54, v55
	v_max3_f32 v48, v48, v56, v57
	v_max3_f32 v48, v48, v50, v51
	v_max3_f32 v48, v48, v52, v53
	v_cndmask_b32_e64 v108, v42, v191, s[6:7]
	v_cndmask_b32_e64 v109, v191, v43, s[8:9]
	v_max3_f32 v42, v48, v108, v109
	v_cndmask_b32_e64 v110, v44, v191, s[10:11]
	v_cndmask_b32_e64 v111, v45, v191, s[12:13]
	v_max3_f32 v42, v42, v110, v111
	ds_bpermute_b32 v43, v65, v42
	s_waitcnt lgkmcnt(0)
	v_max_f32_e32 v43, v43, v43
	v_max_f32_e32 v42, v42, v43
	ds_bpermute_b32 v43, v66, v42
	s_waitcnt lgkmcnt(0)
	v_max_f32_e32 v43, v43, v43
	v_max_f32_e32 v112, v42, v43
	v_sub_f32_e32 v43, v58, v112
	v_sub_f32_e32 v44, v49, v112
	v_sub_f32_e32 v47, v47, v112
	v_sub_f32_e32 v42, v46, v112
	v_exp_f32_e32 v42, v42
	v_exp_f32_e32 v44, v44
	v_exp_f32_e32 v45, v43
	v_exp_f32_e32 v43, v47
	v_sub_f32_e32 v72, v72, v112
	v_sub_f32_e32 v61, v61, v112
	v_sub_f32_e32 v60, v60, v112
	v_sub_f32_e32 v58, v59, v112
	v_exp_f32_e32 v58, v58
	v_exp_f32_e32 v59, v60
	v_exp_f32_e32 v60, v61
	v_exp_f32_e32 v61, v72
	v_sub_f32_e32 v72, v76, v112
	v_sub_f32_e32 v75, v75, v112
	v_sub_f32_e32 v74, v74, v112
	v_sub_f32_e32 v73, v73, v112
	v_exp_f32_e32 v76, v73
	v_exp_f32_e32 v78, v75
	v_exp_f32_e32 v79, v72
	v_exp_f32_e32 v77, v74
	v_sub_f32_e32 v72, v83, v112
	v_sub_f32_e32 v73, v82, v112
	v_sub_f32_e32 v74, v81, v112
	v_sub_f32_e32 v75, v80, v112
	v_exp_f32_e32 v80, v75
	v_exp_f32_e32 v81, v74
	v_exp_f32_e32 v82, v73
	v_exp_f32_e32 v83, v72
	v_sub_f32_e32 v72, v87, v112
	v_sub_f32_e32 v73, v86, v112
	v_sub_f32_e32 v74, v85, v112
	v_sub_f32_e32 v75, v84, v112
	v_pk_add_f32 v[46:47], v[44:45], 0 op_sel_hi:[1,0]
	v_pk_add_f32 v[48:49], v[42:43], 0 op_sel_hi:[1,0]
	v_exp_f32_e32 v88, v75
	v_exp_f32_e32 v90, v73
	v_exp_f32_e32 v91, v72
	v_exp_f32_e32 v89, v74
	v_pk_add_f32 v[48:49], v[58:59], v[48:49]
	v_pk_add_f32 v[46:47], v[60:61], v[46:47]
	v_pk_add_f32 v[48:49], v[76:77], v[48:49]
	v_pk_add_f32 v[46:47], v[78:79], v[46:47]
	v_pk_add_f32 v[48:49], v[80:81], v[48:49]
	v_pk_add_f32 v[46:47], v[82:83], v[46:47]
	v_sub_f32_e32 v74, v92, v112
	v_pk_add_f32 v[72:73], v[90:91], v[46:47]
	v_pk_add_f32 v[46:47], v[88:89], v[48:49]
	v_sub_f32_e32 v49, v93, v112
	v_sub_f32_e32 v48, v95, v112
	v_exp_f32_e32 v93, v49
	v_sub_f32_e32 v49, v94, v112
	v_exp_f32_e32 v92, v74
	v_exp_f32_e32 v94, v49
	v_exp_f32_e32 v95, v48
	v_sub_f32_e32 v57, v57, v112
	v_sub_f32_e32 v56, v56, v112
	v_sub_f32_e32 v84, v55, v112
	v_cvt_pk_bf16_f32 v42, v42, v43
	v_cvt_pk_bf16_f32 v43, v44, v45
	v_cvt_pk_bf16_f32 v44, v58, v59
	v_sub_f32_e32 v58, v54, v112
	v_exp_f32_e32 v96, v56
	v_exp_f32_e32 v97, v57
	v_exp_f32_e32 v98, v58
	v_exp_f32_e32 v99, v84
	v_pk_add_f32 v[74:75], v[92:93], v[46:47]
	v_pk_add_f32 v[58:59], v[94:95], v[72:73]
	v_cvt_pk_bf16_f32 v45, v60, v61
	ds_read2_b64 v[46:49], v67 offset0:8 offset1:12
	ds_read2_b64 v[54:57], v68 offset0:40 offset1:44
	v_pk_add_f32 v[100:101], v[96:97], v[58:59]
	v_pk_add_f32 v[102:103], v[98:99], v[74:75]
	ds_read2_b64 v[58:61], v70 offset0:72 offset1:76
	ds_read2_b64 v[72:75], v69 offset0:104 offset1:108
	v_sub_f32_e32 v52, v52, v112
	v_sub_f32_e32 v51, v51, v112
	v_sub_f32_e32 v50, v50, v112
	v_sub_f32_e32 v107, v53, v112
	v_cvt_pk_bf16_f32 v76, v76, v77
	v_cvt_pk_bf16_f32 v77, v78, v79
	v_cvt_pk_bf16_f32 v78, v80, v81
	v_cvt_pk_bf16_f32 v79, v82, v83
	ds_read2_b64 v[80:83], v67 offset0:16 offset1:20
	v_exp_f32_e32 v104, v50
	v_exp_f32_e32 v105, v51
	v_exp_f32_e32 v106, v52
	ds_read2_b64 v[50:53], v70 offset0:80 offset1:84
	s_waitcnt lgkmcnt(5)
	v_mfma_f32_16x16x32_bf16 v[46:49], v[46:49], v[42:45], 0
	ds_read2_b64 v[84:87], v68 offset0:48 offset1:52
	v_exp_f32_e32 v107, v107
	s_waitcnt lgkmcnt(5)
	v_mfma_f32_16x16x32_bf16 v[54:57], v[54:57], v[42:45], 0
	s_waitcnt lgkmcnt(4)
	v_mfma_f32_16x16x32_bf16 v[58:61], v[58:61], v[42:45], 0
	s_waitcnt lgkmcnt(3)
	v_mfma_f32_16x16x32_bf16 v[42:45], v[72:75], v[42:45], 0
	ds_read2_b64 v[72:75], v69 offset0:112 offset1:116
	s_waitcnt lgkmcnt(3)
	v_mfma_f32_16x16x32_bf16 v[46:49], v[80:83], v[76:79], v[46:49]
	v_cvt_pk_bf16_f32 v80, v88, v89
	v_cvt_pk_bf16_f32 v81, v90, v91
	v_cvt_pk_bf16_f32 v82, v92, v93
	v_cvt_pk_bf16_f32 v83, v94, v95
	s_waitcnt lgkmcnt(2)
; __device__ __forceinline__ unsigned cvt_pk_bf16(float lo, float hi) { unsigned r; asm volatile("v_cvt_pk_bf16_f32 %0, %1, %2" : "=v"(r) : "v"(lo), "v"(hi)); return r; }
; #define LAS __attribute__((address_space(3)))
; __device__ __forceinline__ void attn_unit(LAS unsigned char* lds, bf16* Q, const bf16* Kg, const bf16* Vg, const float* snk, int unit, int tid) {
;     ...
;     for (int mt = 0; mt < 8; ++mt) {
;         f32x4 st[9];
; #pragma unroll
;         for (int kb = 0; kb < 9; ++kb) { const LAS unsigned char* kp = lds + (16 * (mt + kb) + fr) * ATT_KP + 16 * fq;
;             const bf16x8_t k0 = *(const LAS bf16x8_t*)kp, k1 = *(const LAS bf16x8_t*)(kp + 64);
;             f32x4 z = {0.f, 0.f, 0.f, 0.f}; z = __builtin_amdgcn_mfma_f32_16x16x32_bf16(k0, qf[mt][0], z, 0, 0, 0); z = __builtin_amdgcn_mfma_f32_16x16x32_bf16(k1, qf[mt][1], z, 0, 0, 0); st[kb] = z; }
;     ...
; #pragma unroll
;         for (int kp = 0; kp < 5; ++kp) {
;             v4u pw; pw.x = cvt_pk_bf16(st[2 * kp][0], st[2 * kp][1]); pw.y = cvt_pk_bf16(st[2 * kp][2], st[2 * kp][3]);
;             if (kp < 4) { pw.z = cvt_pk_bf16(st[(2 * kp + 1) % 9][0], st[(2 * kp + 1) % 9][1]); pw.w = cvt_pk_bf16(st[(2 * kp + 1) % 9][2], st[(2 * kp + 1) % 9][3]); } else { pw.z = 0u; pw.w = 0u; }
;             const bf16x8_t pb = __builtin_bit_cast(bf16x8_t, pw);
; #pragma unroll
;             for (int dt = 0; dt < 4; ++dt) { const LAS unsigned char* vp = lds + ATT_VOFF + (16 * dt + fr) * ATT_VP + (16 * (mt + 2 * kp) + 4 * fq) * 2;
;                 const v2u lo = *(const LAS v2u*)vp; v2u hi = {0u, 0u}; if (kp < 4) hi = *(const LAS v2u*)(vp + 32);
;                 v4u aw; aw.x = lo.x; aw.y = lo.y; aw.z = hi.x; aw.w = hi.y;
;                 o[dt] = __builtin_amdgcn_mfma_f32_16x16x32_bf16(__builtin_bit_cast(bf16x8_t, aw), pb, o[dt], 0, 0, 0); }
;         }
; #pragma unroll
;         for (int dt = 0; dt < 4; ++dt) { const f32x4 y = o[dt] * inv; v2u w; w.x = cvt_pk_bf16(y[0], y[1]); w.y = cvt_pk_bf16(y[2], y[3]); *(v2u*)(qbase + (size_t)mt * 16 * 1024 + 16 * dt + 4 * fq) = w; }
	v_mfma_f32_16x16x32_bf16 v[50:53], v[50:53], v[76:79], v[58:61]
	v_add_f32_e64 v90, v106, v100
	v_add_f32_e64 v91, v107, v101
	v_sub_f32_e32 v93, v111, v112
	v_sub_f32_e32 v94, v110, v112
	ds_read2_b64 v[58:61], v68 offset0:56 offset1:60
	s_waitcnt lgkmcnt(2)
	v_mfma_f32_16x16x32_bf16 v[54:57], v[84:87], v[76:79], v[54:57]
	ds_read2_b64 v[84:87], v67 offset0:24 offset1:28
	v_sub_f32_e32 v100, v109, v112
	v_exp_f32_e32 v94, v94
	s_waitcnt lgkmcnt(2)
	v_mfma_f32_16x16x32_bf16 v[42:45], v[72:75], v[76:79], v[42:45]
	ds_read2_b64 v[72:75], v70 offset0:88 offset1:92
	v_sub_f32_e32 v76, v108, v112
	v_exp_f32_e32 v92, v76
	s_waitcnt lgkmcnt(2)
	v_mfma_f32_16x16x32_bf16 v[54:57], v[58:61], v[80:83], v[54:57]
	ds_read2_b64 v[58:61], v69 offset0:120 offset1:124
	v_cvt_pk_bf16_f32 v76, v98, v99
	v_cvt_pk_bf16_f32 v77, v96, v97
	v_cvt_pk_bf16_f32 v78, v104, v105
	v_cvt_pk_bf16_f32 v79, v106, v107
	s_waitcnt lgkmcnt(1)
	v_mfma_f32_16x16x32_bf16 v[50:53], v[72:75], v[80:83], v[50:53]
	ds_read2_b64 v[72:75], v68 offset0:64 offset1:68
	v_exp_f32_e32 v95, v93
	v_exp_f32_e32 v93, v100
	v_mfma_f32_16x16x32_bf16 v[46:49], v[84:87], v[80:83], v[46:49]
	ds_read2_b64 v[84:87], v67 offset0:32 offset1:36
	v_pk_add_f32 v[88:89], v[104:105], v[102:103]
	s_waitcnt lgkmcnt(2)
	v_mfma_f32_16x16x32_bf16 v[42:45], v[58:61], v[80:83], v[42:45]
	ds_read2_b64 v[58:61], v70 offset0:96 offset1:100
	v_pk_add_f32 v[80:81], v[94:95], v[90:91]
	v_pk_add_f32 v[82:83], v[92:93], v[88:89]
	s_waitcnt lgkmcnt(2)
	v_mfma_f32_16x16x32_bf16 v[54:57], v[72:75], v[76:79], v[54:57]
	ds_read2_b64 v[72:75], v69 offset0:128 offset1:132
	s_waitcnt lgkmcnt(2)
	v_mfma_f32_16x16x32_bf16 v[46:49], v[84:87], v[76:79], v[46:49]
	v_pk_mov_b32 v[84:85], v[82:83], v[80:81] op_sel:[1,0]
	v_mov_b32_e32 v83, v81
	v_pk_add_f32 v[80:81], v[84:85], v[82:83]
	s_waitcnt lgkmcnt(1)
	v_mfma_f32_16x16x32_bf16 v[50:53], v[58:61], v[76:79], v[50:53]
	v_add_f32_e32 v80, v80, v81
	ds_bpermute_b32 v58, v65, v80
	v_mov_b32_e32 v60, v147
	s_waitcnt lgkmcnt(1)
	v_mfma_f32_16x16x32_bf16 v[42:45], v[72:75], v[76:79], v[42:45]
	v_mov_b32_e32 v74, v147
	v_mov_b32_e32 v75, v147
	s_waitcnt lgkmcnt(0)
	v_add_f32_e32 v86, v80, v58
	v_cvt_pk_bf16_f32 v58, v92, v93
	v_cvt_pk_bf16_f32 v59, v94, v95
	ds_read_b64 v[72:73], v180 offset:37184
	ds_read_b64 v[76:77], v180 offset:45632
	v_mov_b32_e32 v61, v147
	v_mov_b32_e32 v78, v147
	v_mov_b32_e32 v79, v147
	s_waitcnt lgkmcnt(1)
	v_mfma_f32_16x16x32_bf16 v[46:49], v[72:75], v[58:61], v[46:49]
	ds_bpermute_b32 v72, v66, v86
	v_fma_f32 v73, v64, s62, -v112
	v_exp_f32_e32 v73, v73
	ds_read_b64 v[80:81], v180 offset:54080
	ds_read_b64 v[84:85], v180 offset:62528
	v_mov_b32_e32 v82, v147
	s_waitcnt lgkmcnt(2)
	v_add_f32_e32 v72, v86, v72
	v_add_f32_e32 v72, v73, v72
	v_mov_b32_e32 v83, v147
	v_mov_b32_e32 v86, v147
	v_mov_b32_e32 v87, v147
	v_div_scale_f32 v73, s[64:65], v72, v72, 1.0
	v_rcp_f32_e32 v74, v73
	v_mfma_f32_16x16x32_bf16 v[54:57], v[76:79], v[58:61], v[54:57]
	s_waitcnt lgkmcnt(1)
	v_mfma_f32_16x16x32_bf16 v[50:53], v[80:83], v[58:61], v[50:53]
	s_waitcnt lgkmcnt(0)
	v_mfma_f32_16x16x32_bf16 v[42:45], v[84:87], v[58:61], v[42:45]
	v_fma_f32 v58, -v73, v74, 1.0
	v_fmac_f32_e32 v74, v58, v74
	v_div_scale_f32 v58, vcc, 1.0, v72, 1.0
	v_mul_f32_e32 v59, v58, v74
	v_fma_f32 v60, -v73, v59, v58
	v_fmac_f32_e32 v59, v60, v74
	v_fma_f32 v58, -v73, v59, v58
	v_div_fmas_f32 v58, v58, v74, v59
	v_div_fixup_f32 v58, v58, v72, 1.0
	v_pk_mul_f32 v[48:49], v[58:59], v[48:49] op_sel_hi:[0,1]
	v_pk_mul_f32 v[46:47], v[58:59], v[46:47] op_sel_hi:[0,1]
	v_add_co_u32_e32 v92, vcc, s41, v62
	v_cvt_pk_bf16_f32 v46, v46, v47
	v_cvt_pk_bf16_f32 v47, v48, v49
	v_pk_mul_f32 v[48:49], v[58:59], v[54:55] op_sel_hi:[0,1]
	s_nop 0
	v_addc_co_u32_e32 v93, vcc, 0, v63, vcc
	v_lshrrev_b32_e32 v110, 4, v0
	v_and_b32_e32 v110, 1, v110
	v_mul_u32_u24_e32 v110, 24, v110
	v_mov_b32_e32 v111, 0
	v_lshl_add_u64 v[118:119], v[92:93], 0, v[110:111]
	v_mov_b32_e32 v114, v46
	v_mov_b32_e32 v115, v47
	v_pk_mul_f32 v[46:47], v[58:59], v[56:57] op_sel_hi:[0,1]
	v_cvt_pk_bf16_f32 v48, v48, v49
	v_cvt_pk_bf16_f32 v49, v46, v47
	v_mov_b32_e32 v116, v48
	v_mov_b32_e32 v117, v49
	s_nop 1
	v_permlane16_swap_b32_e32 v114, v116
	v_permlane16_swap_b32_e32 v115, v117
	global_store_dwordx4 v[118:119], v[114:117], off
	v_pk_mul_f32 v[48:49], v[58:59], v[50:51] op_sel_hi:[0,1]
	v_pk_mul_f32 v[46:47], v[58:59], v[52:53] op_sel_hi:[0,1]
	v_cvt_pk_bf16_f32 v48, v48, v49
	v_cvt_pk_bf16_f32 v49, v46, v47
	v_pk_mul_f32 v[44:45], v[58:59], v[44:45] op_sel_hi:[0,1]
	v_pk_mul_f32 v[42:43], v[58:59], v[42:43] op_sel_hi:[0,1]
	v_mov_b32_e32 v126, v48
	v_mov_b32_e32 v127, v49
	v_cvt_pk_bf16_f32 v94, v42, v43
	v_cvt_pk_bf16_f32 v95, v44, v45
	ds_read_b128 v[42:45], v179 offset:6912
	ds_read_b128 v[46:49], v179 offset:6976
	s_waitcnt lgkmcnt(1)
	v_mfma_f32_16x16x32_bf16 v[42:45], v[42:45], v[34:37], 0
	ds_read_b128 v[50:53], v179 offset:9216
	ds_read_b128 v[54:57], v179 offset:11520
	ds_read_b128 v[58:61], v179 offset:13824
	s_waitcnt lgkmcnt(3)
	v_mfma_f32_16x16x32_bf16 v[46:49], v[46:49], v[38:41], v[42:45]
	ds_read_b128 v[72:75], v179 offset:16128
	ds_read_b128 v[76:79], v179 offset:18432
	ds_read_b128 v[80:83], v179 offset:20736
	ds_read_b128 v[42:45], v179 offset:9280
	s_waitcnt lgkmcnt(6)
	v_mfma_f32_16x16x32_bf16 v[50:53], v[50:53], v[34:37], 0
	ds_read_b128 v[84:87], v179 offset:23040
	ds_read_b128 v[88:91], v179 offset:25344
	v_mov_b32_e32 v128, v94
	v_mov_b32_e32 v129, v95
	s_nop 1
	v_permlane16_swap_b32_e32 v126, v128
	v_permlane16_swap_b32_e32 v127, v129
	global_store_dwordx4 v[118:119], v[126:129], off offset:64
	s_waitcnt lgkmcnt(2)
; __device__ __forceinline__ void attn_unit(LAS unsigned char* lds, bf16* Q, const bf16* Kg, const bf16* Vg, const float* snk, int unit, int tid) {
;     ...
;         for (int kb = 0; kb < 9; ++kb) { const LAS unsigned char* kp = lds + (16 * (mt + kb) + fr) * ATT_KP + 16 * fq;
;             const bf16x8_t k0 = *(const LAS bf16x8_t*)kp, k1 = *(const LAS bf16x8_t*)(kp + 64);
;             f32x4 z = {0.f, 0.f, 0.f, 0.f}; z = __builtin_amdgcn_mfma_f32_16x16x32_bf16(k0, qf[mt][0], z, 0, 0, 0); z = __builtin_amdgcn_mfma_f32_16x16x32_bf16(k1, qf[mt][1], z, 0, 0, 0); st[kb] = z; }
;         float mx = sink;
; #pragma unroll
;         for (int kb = 0; kb < 9; ++kb) {
;             const bool tile_ok = (n > 0) || (mt + kb >= 8);
; #pragma unroll
;             for (int i = 0; i < 4; ++i) { const bool ok = tile_ok && (kb == 0 ? lo_ok[i] : (kb == 8 ? !lo_ok[i] : true));
;                 st[kb][i] = ok ? st[kb][i] : -INFINITY; mx = fmaxf(mx, st[kb][i]); }
;         }
;         mx = fmaxf(mx, __shfl_xor(mx, 16)); mx = fmaxf(mx, __shfl_xor(mx, 32));
;         f32x4 ls4 = {0.f, 0.f, 0.f, 0.f};
; #pragma unroll
;         for (int kb = 0; kb < 9; ++kb) { f32x4 d = st[kb] - mx;
; #pragma unroll
;             for (int i = 0; i < 4; ++i) d[i] = __builtin_amdgcn_exp2f(d[i]);
;             st[kb] = d; ls4 = ls4 + d; }
;         float ls = (ls4[0] + ls4[1]) + (ls4[2] + ls4[3]);
;         ls += __shfl_xor(ls, 16); ls += __shfl_xor(ls, 32);
;         const float inv = 1.f / (ls + __builtin_amdgcn_exp2f(sink - mx));
;         f32x4 o[4];
; #pragma unroll
;         for (int dt = 0; dt < 4; ++dt) o[dt] = (f32x4){0.f, 0.f, 0.f, 0.f};
; #pragma unroll
;         for (int kp = 0; kp < 5; ++kp) {
;             v4u pw; pw.x = cvt_pk_bf16(st[2 * kp][0], st[2 * kp][1]); pw.y = cvt_pk_bf16(st[2 * kp][2], st[2 * kp][3]);
;             if (kp < 4) { pw.z = cvt_pk_bf16(st[(2 * kp + 1) % 9][0], st[(2 * kp + 1) % 9][1]); pw.w = cvt_pk_bf16(st[(2 * kp + 1) % 9][2], st[(2 * kp + 1) % 9][3]); } else { pw.z = 0u; pw.w = 0u; }
;             const bf16x8_t pb = __builtin_bit_cast(bf16x8_t, pw);
; #pragma unroll
;             for (int dt = 0; dt < 4; ++dt) { const LAS unsigned char* vp = lds + ATT_VOFF + (16 * dt + fr) * ATT_VP + (16 * (mt + 2 * kp) + 4 * fq) * 2;
;                 const v2u lo = *(const LAS v2u*)vp; v2u hi = {0u, 0u}; if (kp < 4) hi = *(const LAS v2u*)(vp + 32);
	v_mfma_f32_16x16x32_bf16 v[50:53], v[42:45], v[38:41], v[50:53]
	ds_read_b128 v[42:45], v179 offset:11584
	v_mfma_f32_16x16x32_bf16 v[54:57], v[54:57], v[34:37], 0
	s_waitcnt lgkmcnt(0)
	v_mfma_f32_16x16x32_bf16 v[54:57], v[42:45], v[38:41], v[54:57]
	ds_read_b128 v[42:45], v179 offset:13888
	v_mfma_f32_16x16x32_bf16 v[58:61], v[58:61], v[34:37], 0
	s_waitcnt lgkmcnt(0)
	v_mfma_f32_16x16x32_bf16 v[58:61], v[42:45], v[38:41], v[58:61]
	ds_read_b128 v[42:45], v179 offset:16192
	v_mfma_f32_16x16x32_bf16 v[72:75], v[72:75], v[34:37], 0
	s_waitcnt lgkmcnt(0)
	v_mfma_f32_16x16x32_bf16 v[72:75], v[42:45], v[38:41], v[72:75]
	ds_read_b128 v[42:45], v179 offset:18496
	v_mfma_f32_16x16x32_bf16 v[76:79], v[76:79], v[34:37], 0
	s_waitcnt lgkmcnt(0)
	v_mfma_f32_16x16x32_bf16 v[76:79], v[42:45], v[38:41], v[76:79]
	ds_read_b128 v[42:45], v179 offset:20800
	v_mfma_f32_16x16x32_bf16 v[80:83], v[80:83], v[34:37], 0
	s_waitcnt lgkmcnt(0)
	v_mfma_f32_16x16x32_bf16 v[80:83], v[42:45], v[38:41], v[80:83]
	ds_read_b128 v[42:45], v179 offset:23104
	v_mfma_f32_16x16x32_bf16 v[84:87], v[84:87], v[34:37], 0
	s_waitcnt lgkmcnt(0)
	v_mfma_f32_16x16x32_bf16 v[42:45], v[42:45], v[38:41], v[84:87]
	s_nop 5
	ds_read_b128 v[84:87], v179 offset:25408
	v_mfma_f32_16x16x32_bf16 v[34:37], v[88:91], v[34:37], 0
	v_cndmask_b32_e64 v88, v191, v75, s[14:15]
	s_waitcnt lgkmcnt(0)
	v_mfma_f32_16x16x32_bf16 v[34:37], v[84:87], v[38:41], v[34:37]
	v_cndmask_b32_e64 v39, v47, v191, s[8:9]
	v_cndmask_b32_e64 v38, v191, v46, s[18:19]
	v_cndmask_b32_e64 v39, v191, v39, s[14:15]
	v_max3_f32 v40, v71, v38, v39
	v_cndmask_b32_e64 v41, v191, v48, s[16:17]
	v_cndmask_b32_e64 v46, v191, v49, s[20:21]
	v_max3_f32 v40, v40, v41, v46
	v_cndmask_b32_e64 v47, v191, v50, s[14:15]
	v_cndmask_b32_e64 v48, v191, v51, s[14:15]
	v_max3_f32 v40, v40, v47, v48
	v_cndmask_b32_e64 v49, v191, v52, s[14:15]
	v_cndmask_b32_e64 v50, v191, v53, s[14:15]
	v_max3_f32 v40, v40, v49, v50
	v_cndmask_b32_e64 v51, v191, v54, s[14:15]
	v_cndmask_b32_e64 v52, v191, v55, s[14:15]
	v_max3_f32 v40, v40, v51, v52
	v_cndmask_b32_e64 v53, v191, v56, s[14:15]
	v_cndmask_b32_e64 v54, v191, v57, s[14:15]
	v_max3_f32 v40, v40, v53, v54
	v_cndmask_b32_e64 v55, v191, v58, s[14:15]
	v_cndmask_b32_e64 v56, v191, v59, s[14:15]
	v_max3_f32 v40, v40, v55, v56
	v_cndmask_b32_e64 v57, v191, v60, s[14:15]
	v_cndmask_b32_e64 v84, v191, v61, s[14:15]
	v_max3_f32 v40, v40, v57, v84
	v_cndmask_b32_e64 v85, v191, v72, s[14:15]
	v_cndmask_b32_e64 v86, v191, v73, s[14:15]
	v_max3_f32 v40, v40, v85, v86
	v_cndmask_b32_e64 v87, v191, v74, s[14:15]
	v_max3_f32 v40, v40, v87, v88
	v_max3_f32 v40, v40, v76, v77
	v_max3_f32 v40, v40, v78, v79
	v_max3_f32 v40, v40, v80, v81
	v_max3_f32 v40, v40, v82, v83
	v_max3_f32 v40, v40, v42, v43
	v_max3_f32 v40, v40, v44, v45
	v_cndmask_b32_e64 v100, v34, v191, s[6:7]
	v_cndmask_b32_e64 v101, v191, v35, s[8:9]
	v_max3_f32 v34, v40, v100, v101
	v_cndmask_b32_e64 v102, v36, v191, s[10:11]
	v_cndmask_b32_e64 v103, v37, v191, s[12:13]
	v_max3_f32 v34, v34, v102, v103
	ds_bpermute_b32 v35, v65, v34
	s_waitcnt lgkmcnt(0)
	v_max_f32_e32 v35, v35, v35
	v_max_f32_e32 v34, v34, v35
	ds_bpermute_b32 v35, v66, v34
	s_waitcnt lgkmcnt(0)
	v_max_f32_e32 v35, v35, v35
	v_max_f32_e32 v104, v34, v35
	v_sub_f32_e32 v35, v46, v104
	v_sub_f32_e32 v36, v41, v104
	v_sub_f32_e32 v39, v39, v104
	v_sub_f32_e32 v34, v38, v104
	v_exp_f32_e32 v34, v34
	v_exp_f32_e32 v36, v36
	v_exp_f32_e32 v37, v35
	v_exp_f32_e32 v35, v39
	v_sub_f32_e32 v50, v50, v104
	v_sub_f32_e32 v49, v49, v104
	v_sub_f32_e32 v48, v48, v104
	v_sub_f32_e32 v46, v47, v104
	v_exp_f32_e32 v46, v46
	v_exp_f32_e32 v47, v48
	v_exp_f32_e32 v48, v49
	v_exp_f32_e32 v49, v50
	v_sub_f32_e32 v50, v54, v104
	v_sub_f32_e32 v53, v53, v104
	v_sub_f32_e32 v52, v52, v104
	v_sub_f32_e32 v51, v51, v104
	v_exp_f32_e32 v58, v51
	v_exp_f32_e32 v60, v53
	v_exp_f32_e32 v61, v50
	v_exp_f32_e32 v59, v52
	v_sub_f32_e32 v50, v84, v104
	v_sub_f32_e32 v51, v57, v104
	v_sub_f32_e32 v52, v56, v104
	v_sub_f32_e32 v53, v55, v104
	v_exp_f32_e32 v72, v53
	v_exp_f32_e32 v73, v52
	v_exp_f32_e32 v74, v51
	v_exp_f32_e32 v75, v50
	v_sub_f32_e32 v50, v88, v104
	v_sub_f32_e32 v51, v87, v104
	v_sub_f32_e32 v52, v86, v104
	v_sub_f32_e32 v53, v85, v104
	v_pk_add_f32 v[38:39], v[36:37], 0 op_sel_hi:[1,0]
	v_pk_add_f32 v[40:41], v[34:35], 0 op_sel_hi:[1,0]
	v_exp_f32_e32 v84, v53
	v_exp_f32_e32 v86, v51
	v_exp_f32_e32 v87, v50
	v_exp_f32_e32 v85, v52
	v_pk_add_f32 v[40:41], v[46:47], v[40:41]
	v_pk_add_f32 v[38:39], v[48:49], v[38:39]
	v_pk_add_f32 v[40:41], v[58:59], v[40:41]
	v_pk_add_f32 v[38:39], v[60:61], v[38:39]
	v_pk_add_f32 v[40:41], v[72:73], v[40:41]
	v_pk_add_f32 v[38:39], v[74:75], v[38:39]
	v_sub_f32_e32 v52, v76, v104
	v_pk_add_f32 v[50:51], v[86:87], v[38:39]
	v_pk_add_f32 v[38:39], v[84:85], v[40:41]
	v_sub_f32_e32 v41, v77, v104
	v_sub_f32_e32 v40, v79, v104
	v_exp_f32_e32 v89, v41
	v_sub_f32_e32 v41, v78, v104
	v_exp_f32_e32 v88, v52
	v_exp_f32_e32 v90, v41
	v_exp_f32_e32 v91, v40
	v_sub_f32_e32 v54, v83, v104
	v_sub_f32_e32 v55, v82, v104
	v_sub_f32_e32 v56, v81, v104
	v_sub_f32_e32 v57, v80, v104
	v_exp_f32_e32 v80, v55
	v_exp_f32_e32 v81, v54
	v_exp_f32_e32 v82, v57
	v_exp_f32_e32 v83, v56
	v_pk_add_f32 v[52:53], v[88:89], v[38:39]
	v_pk_add_f32 v[50:51], v[90:91], v[50:51]
	v_cvt_pk_bf16_f32 v34, v34, v35
	v_cvt_pk_bf16_f32 v35, v36, v37
	v_cvt_pk_bf16_f32 v36, v46, v47
	v_cvt_pk_bf16_f32 v37, v48, v49
	ds_read2_b64 v[38:41], v67 offset0:12 offset1:16
	ds_read2_b64 v[46:49], v68 offset0:44 offset1:48
	v_pk_add_f32 v[92:93], v[80:81], v[50:51]
	v_pk_add_f32 v[94:95], v[82:83], v[52:53]
	ds_read2_b64 v[50:53], v70 offset0:76 offset1:80
	ds_read2_b64 v[54:57], v69 offset0:108 offset1:112
	v_sub_f32_e32 v44, v44, v104
	v_sub_f32_e32 v43, v43, v104
	v_sub_f32_e32 v42, v42, v104
	v_sub_f32_e32 v99, v45, v104
	v_cvt_pk_bf16_f32 v58, v58, v59
	v_cvt_pk_bf16_f32 v59, v60, v61
	v_cvt_pk_bf16_f32 v60, v72, v73
	v_cvt_pk_bf16_f32 v61, v74, v75
	ds_read2_b64 v[72:75], v67 offset0:20 offset1:24
	v_exp_f32_e32 v96, v42
	v_exp_f32_e32 v97, v43
	v_exp_f32_e32 v98, v44
	ds_read2_b64 v[42:45], v70 offset0:84 offset1:88
	s_waitcnt lgkmcnt(5)
; __device__ __forceinline__ unsigned cvt_pk_bf16(float lo, float hi) { unsigned r; asm volatile("v_cvt_pk_bf16_f32 %0, %1, %2" : "=v"(r) : "v"(lo), "v"(hi)); return r; }
; #define LAS __attribute__((address_space(3)))
; __device__ __forceinline__ void attn_unit(LAS unsigned char* lds, bf16* Q, const bf16* Kg, const bf16* Vg, const float* snk, int unit, int tid) {
;     ...
;     for (int mt = 0; mt < 8; ++mt) {
;         f32x4 st[9];
; #pragma unroll
;         for (int kb = 0; kb < 9; ++kb) { const LAS unsigned char* kp = lds + (16 * (mt + kb) + fr) * ATT_KP + 16 * fq;
;             const bf16x8_t k0 = *(const LAS bf16x8_t*)kp, k1 = *(const LAS bf16x8_t*)(kp + 64);
;             f32x4 z = {0.f, 0.f, 0.f, 0.f}; z = __builtin_amdgcn_mfma_f32_16x16x32_bf16(k0, qf[mt][0], z, 0, 0, 0); z = __builtin_amdgcn_mfma_f32_16x16x32_bf16(k1, qf[mt][1], z, 0, 0, 0); st[kb] = z; }
;     ...
; #pragma unroll
;         for (int kp = 0; kp < 5; ++kp) {
;             v4u pw; pw.x = cvt_pk_bf16(st[2 * kp][0], st[2 * kp][1]); pw.y = cvt_pk_bf16(st[2 * kp][2], st[2 * kp][3]);
;             if (kp < 4) { pw.z = cvt_pk_bf16(st[(2 * kp + 1) % 9][0], st[(2 * kp + 1) % 9][1]); pw.w = cvt_pk_bf16(st[(2 * kp + 1) % 9][2], st[(2 * kp + 1) % 9][3]); } else { pw.z = 0u; pw.w = 0u; }
;             const bf16x8_t pb = __builtin_bit_cast(bf16x8_t, pw);
; #pragma unroll
;             for (int dt = 0; dt < 4; ++dt) { const LAS unsigned char* vp = lds + ATT_VOFF + (16 * dt + fr) * ATT_VP + (16 * (mt + 2 * kp) + 4 * fq) * 2;
;                 const v2u lo = *(const LAS v2u*)vp; v2u hi = {0u, 0u}; if (kp < 4) hi = *(const LAS v2u*)(vp + 32);
;                 v4u aw; aw.x = lo.x; aw.y = lo.y; aw.z = hi.x; aw.w = hi.y;
;                 o[dt] = __builtin_amdgcn_mfma_f32_16x16x32_bf16(__builtin_bit_cast(bf16x8_t, aw), pb, o[dt], 0, 0, 0); }
;         }
; #pragma unroll
;         for (int dt = 0; dt < 4; ++dt) { const f32x4 y = o[dt] * inv; v2u w; w.x = cvt_pk_bf16(y[0], y[1]); w.y = cvt_pk_bf16(y[2], y[3]); *(v2u*)(qbase + (size_t)mt * 16 * 1024 + 16 * dt + 4 * fq) = w; }
	v_mfma_f32_16x16x32_bf16 v[38:41], v[38:41], v[34:37], 0
	ds_read2_b64 v[76:79], v68 offset0:52 offset1:56
	v_exp_f32_e32 v99, v99
	s_waitcnt lgkmcnt(5)
	v_mfma_f32_16x16x32_bf16 v[46:49], v[46:49], v[34:37], 0
	s_waitcnt lgkmcnt(4)
	v_mfma_f32_16x16x32_bf16 v[50:53], v[50:53], v[34:37], 0
	s_waitcnt lgkmcnt(3)
	v_mfma_f32_16x16x32_bf16 v[34:37], v[54:57], v[34:37], 0
	ds_read2_b64 v[54:57], v69 offset0:116 offset1:120
	s_waitcnt lgkmcnt(3)
	v_mfma_f32_16x16x32_bf16 v[38:41], v[72:75], v[58:61], v[38:41]
	v_cvt_pk_bf16_f32 v72, v84, v85
	v_cvt_pk_bf16_f32 v73, v86, v87
	v_cvt_pk_bf16_f32 v74, v88, v89
	v_cvt_pk_bf16_f32 v75, v90, v91
	s_waitcnt lgkmcnt(2)
	v_mfma_f32_16x16x32_bf16 v[42:45], v[42:45], v[58:61], v[50:53]
	v_sub_f32_e32 v89, v103, v104
	v_sub_f32_e32 v90, v102, v104
	v_sub_f32_e32 v91, v101, v104
	ds_read2_b64 v[50:53], v68 offset0:60 offset1:64
	s_waitcnt lgkmcnt(2)
	v_mfma_f32_16x16x32_bf16 v[46:49], v[76:79], v[58:61], v[46:49]
	ds_read2_b64 v[76:79], v67 offset0:28 offset1:32
	v_pk_add_f32 v[84:85], v[96:97], v[94:95]
	v_pk_add_f32 v[86:87], v[98:99], v[92:93]
	s_waitcnt lgkmcnt(2)
	v_mfma_f32_16x16x32_bf16 v[34:37], v[54:57], v[58:61], v[34:37]
	ds_read2_b64 v[54:57], v70 offset0:92 offset1:96
	v_sub_f32_e32 v58, v100, v104
	v_exp_f32_e32 v88, v58
	s_waitcnt lgkmcnt(2)
	v_mfma_f32_16x16x32_bf16 v[46:49], v[50:53], v[72:75], v[46:49]
	ds_read2_b64 v[50:53], v69 offset0:124 offset1:128
	v_cvt_pk_bf16_f32 v58, v82, v83
	v_cvt_pk_bf16_f32 v59, v80, v81
	v_cvt_pk_bf16_f32 v60, v96, v97
	v_cvt_pk_bf16_f32 v61, v98, v99
	s_waitcnt lgkmcnt(1)
	v_mfma_f32_16x16x32_bf16 v[42:45], v[54:57], v[72:75], v[42:45]
	ds_read2_b64 v[54:57], v68 offset0:68 offset1:72
	v_exp_f32_e32 v80, v90
	v_exp_f32_e32 v81, v89
	v_mfma_f32_16x16x32_bf16 v[38:41], v[76:79], v[72:75], v[38:41]
	ds_read2_b64 v[76:79], v67 offset0:36 offset1:40
	v_exp_f32_e32 v89, v91
	s_waitcnt lgkmcnt(2)
	v_mfma_f32_16x16x32_bf16 v[34:37], v[50:53], v[72:75], v[34:37]
	ds_read2_b64 v[50:53], v70 offset0:100 offset1:104
	v_pk_add_f32 v[72:73], v[80:81], v[86:87]
	v_pk_add_f32 v[74:75], v[88:89], v[84:85]
	s_waitcnt lgkmcnt(2)
	v_mfma_f32_16x16x32_bf16 v[46:49], v[54:57], v[58:61], v[46:49]
	ds_read2_b64 v[54:57], v69 offset0:132 offset1:136
	s_waitcnt lgkmcnt(2)
	v_mfma_f32_16x16x32_bf16 v[38:41], v[76:79], v[58:61], v[38:41]
	v_pk_mov_b32 v[76:77], v[74:75], v[72:73] op_sel:[1,0]
	v_mov_b32_e32 v75, v73
	v_pk_add_f32 v[72:73], v[76:77], v[74:75]
	s_waitcnt lgkmcnt(1)
	v_mfma_f32_16x16x32_bf16 v[42:45], v[50:53], v[58:61], v[42:45]
	v_add_f32_e32 v72, v72, v73
	ds_bpermute_b32 v50, v65, v72
	v_mov_b32_e32 v52, v147
	s_waitcnt lgkmcnt(1)
	v_mfma_f32_16x16x32_bf16 v[34:37], v[54:57], v[58:61], v[34:37]
	v_mov_b32_e32 v56, v147
	v_mov_b32_e32 v57, v147
	s_waitcnt lgkmcnt(0)
	v_add_f32_e32 v78, v72, v50
	v_cvt_pk_bf16_f32 v50, v88, v89
	v_cvt_pk_bf16_f32 v51, v80, v81
	ds_read_b64 v[54:55], v180 offset:37216
	ds_read_b64 v[58:59], v180 offset:45664
	v_mov_b32_e32 v53, v147
	v_mov_b32_e32 v60, v147
	v_mov_b32_e32 v61, v147
	s_waitcnt lgkmcnt(1)
	v_mfma_f32_16x16x32_bf16 v[38:41], v[54:57], v[50:53], v[38:41]
	ds_bpermute_b32 v54, v66, v78
	v_fma_f32 v55, v64, s62, -v104
	v_exp_f32_e32 v55, v55
	ds_read_b64 v[72:73], v180 offset:54112
	ds_read_b64 v[76:77], v180 offset:62560
	v_mov_b32_e32 v74, v147
	s_waitcnt lgkmcnt(2)
	v_add_f32_e32 v54, v78, v54
	v_add_f32_e32 v54, v55, v54
	v_mov_b32_e32 v75, v147
	v_mov_b32_e32 v78, v147
	v_mov_b32_e32 v79, v147
	v_div_scale_f32 v55, s[64:65], v54, v54, 1.0
	v_rcp_f32_e32 v56, v55
	v_mfma_f32_16x16x32_bf16 v[46:49], v[58:61], v[50:53], v[46:49]
	s_waitcnt lgkmcnt(1)
	v_mfma_f32_16x16x32_bf16 v[42:45], v[72:75], v[50:53], v[42:45]
	s_waitcnt lgkmcnt(0)
	v_mfma_f32_16x16x32_bf16 v[34:37], v[76:79], v[50:53], v[34:37]
	v_fma_f32 v50, -v55, v56, 1.0
	v_fmac_f32_e32 v56, v50, v56
	v_div_scale_f32 v50, vcc, 1.0, v54, 1.0
	v_mul_f32_e32 v51, v50, v56
	v_fma_f32 v52, -v55, v51, v50
	v_fmac_f32_e32 v51, v52, v56
	v_fma_f32 v50, -v55, v51, v50
	v_div_fmas_f32 v50, v50, v56, v51
	v_div_fixup_f32 v50, v50, v54, 1.0
	v_pk_mul_f32 v[40:41], v[50:51], v[40:41] op_sel_hi:[0,1]
	v_pk_mul_f32 v[38:39], v[50:51], v[38:39] op_sel_hi:[0,1]
	v_add_co_u32_e32 v84, vcc, s44, v62
	v_cvt_pk_bf16_f32 v38, v38, v39
	v_cvt_pk_bf16_f32 v39, v40, v41
	v_pk_mul_f32 v[40:41], v[50:51], v[46:47] op_sel_hi:[0,1]
	s_nop 0
	v_addc_co_u32_e32 v85, vcc, 0, v63, vcc
	v_lshrrev_b32_e32 v110, 4, v0
	v_and_b32_e32 v110, 1, v110
	v_mul_u32_u24_e32 v110, 24, v110
	v_mov_b32_e32 v111, 0
	v_lshl_add_u64 v[118:119], v[84:85], 0, v[110:111]
	v_mov_b32_e32 v114, v38
	v_mov_b32_e32 v115, v39
	v_pk_mul_f32 v[38:39], v[50:51], v[48:49] op_sel_hi:[0,1]
	v_cvt_pk_bf16_f32 v40, v40, v41
	v_cvt_pk_bf16_f32 v41, v38, v39
	v_mov_b32_e32 v116, v40
	v_mov_b32_e32 v117, v41
	s_nop 1
	v_permlane16_swap_b32_e32 v114, v116
	v_permlane16_swap_b32_e32 v115, v117
	global_store_dwordx4 v[118:119], v[114:117], off
	v_pk_mul_f32 v[40:41], v[50:51], v[42:43] op_sel_hi:[0,1]
	v_pk_mul_f32 v[38:39], v[50:51], v[44:45] op_sel_hi:[0,1]
	v_cvt_pk_bf16_f32 v40, v40, v41
	v_cvt_pk_bf16_f32 v41, v38, v39
	v_pk_mul_f32 v[36:37], v[50:51], v[36:37] op_sel_hi:[0,1]
	v_pk_mul_f32 v[34:35], v[50:51], v[34:35] op_sel_hi:[0,1]
	v_mov_b32_e32 v126, v40
	v_mov_b32_e32 v127, v41
	v_cvt_pk_bf16_f32 v86, v34, v35
	v_cvt_pk_bf16_f32 v87, v36, v37
	ds_read_b128 v[34:37], v179 offset:9216
	ds_read_b128 v[38:41], v179 offset:9280
	s_waitcnt lgkmcnt(1)
	v_mfma_f32_16x16x32_bf16 v[34:37], v[34:37], v[26:29], 0
	ds_read_b128 v[42:45], v179 offset:11520
	ds_read_b128 v[46:49], v179 offset:13824
	ds_read_b128 v[50:53], v179 offset:16128
	s_waitcnt lgkmcnt(3)
; __device__ __forceinline__ void attn_unit(LAS unsigned char* lds, bf16* Q, const bf16* Kg, const bf16* Vg, const float* snk, int unit, int tid) {
;     ...
;         for (int kb = 0; kb < 9; ++kb) { const LAS unsigned char* kp = lds + (16 * (mt + kb) + fr) * ATT_KP + 16 * fq;
;             const bf16x8_t k0 = *(const LAS bf16x8_t*)kp, k1 = *(const LAS bf16x8_t*)(kp + 64);
;             f32x4 z = {0.f, 0.f, 0.f, 0.f}; z = __builtin_amdgcn_mfma_f32_16x16x32_bf16(k0, qf[mt][0], z, 0, 0, 0); z = __builtin_amdgcn_mfma_f32_16x16x32_bf16(k1, qf[mt][1], z, 0, 0, 0); st[kb] = z; }
;         float mx = sink;
; #pragma unroll
;         for (int kb = 0; kb < 9; ++kb) {
;             const bool tile_ok = (n > 0) || (mt + kb >= 8);
; #pragma unroll
;             for (int i = 0; i < 4; ++i) { const bool ok = tile_ok && (kb == 0 ? lo_ok[i] : (kb == 8 ? !lo_ok[i] : true));
;                 st[kb][i] = ok ? st[kb][i] : -INFINITY; mx = fmaxf(mx, st[kb][i]); }
;         }
;         mx = fmaxf(mx, __shfl_xor(mx, 16)); mx = fmaxf(mx, __shfl_xor(mx, 32));
;         f32x4 ls4 = {0.f, 0.f, 0.f, 0.f};
; #pragma unroll
;         for (int kb = 0; kb < 9; ++kb) { f32x4 d = st[kb] - mx;
; #pragma unroll
;             for (int i = 0; i < 4; ++i) d[i] = __builtin_amdgcn_exp2f(d[i]);
;             st[kb] = d; ls4 = ls4 + d; }
;         float ls = (ls4[0] + ls4[1]) + (ls4[2] + ls4[3]);
;         ls += __shfl_xor(ls, 16); ls += __shfl_xor(ls, 32);
;         const float inv = 1.f / (ls + __builtin_amdgcn_exp2f(sink - mx));
;         f32x4 o[4];
; #pragma unroll
;         for (int dt = 0; dt < 4; ++dt) o[dt] = (f32x4){0.f, 0.f, 0.f, 0.f};
; #pragma unroll
;         for (int kp = 0; kp < 5; ++kp) {
;             v4u pw; pw.x = cvt_pk_bf16(st[2 * kp][0], st[2 * kp][1]); pw.y = cvt_pk_bf16(st[2 * kp][2], st[2 * kp][3]);
;             if (kp < 4) { pw.z = cvt_pk_bf16(st[(2 * kp + 1) % 9][0], st[(2 * kp + 1) % 9][1]); pw.w = cvt_pk_bf16(st[(2 * kp + 1) % 9][2], st[(2 * kp + 1) % 9][3]); } else { pw.z = 0u; pw.w = 0u; }
;             const bf16x8_t pb = __builtin_bit_cast(bf16x8_t, pw);
; #pragma unroll
;             for (int dt = 0; dt < 4; ++dt) { const LAS unsigned char* vp = lds + ATT_VOFF + (16 * dt + fr) * ATT_VP + (16 * (mt + 2 * kp) + 4 * fq) * 2;
;                 const v2u lo = *(const LAS v2u*)vp; v2u hi = {0u, 0u}; if (kp < 4) hi = *(const LAS v2u*)(vp + 32);
	v_mfma_f32_16x16x32_bf16 v[38:41], v[38:41], v[30:33], v[34:37]
	ds_read_b128 v[54:57], v179 offset:18432
	ds_read_b128 v[58:61], v179 offset:20736
	ds_read_b128 v[72:75], v179 offset:23040
	ds_read_b128 v[34:37], v179 offset:11584
	s_waitcnt lgkmcnt(6)
	v_mfma_f32_16x16x32_bf16 v[42:45], v[42:45], v[26:29], 0
	ds_read_b128 v[76:79], v179 offset:25344
	ds_read_b128 v[80:83], v179 offset:27648
	v_mov_b32_e32 v128, v86
	v_mov_b32_e32 v129, v87
	s_nop 1
	v_permlane16_swap_b32_e32 v126, v128
	v_permlane16_swap_b32_e32 v127, v129
	global_store_dwordx4 v[118:119], v[126:129], off offset:64
	s_waitcnt lgkmcnt(2)
	v_mfma_f32_16x16x32_bf16 v[42:45], v[34:37], v[30:33], v[42:45]
	ds_read_b128 v[34:37], v179 offset:13888
	v_mfma_f32_16x16x32_bf16 v[46:49], v[46:49], v[26:29], 0
	s_waitcnt lgkmcnt(0)
	v_mfma_f32_16x16x32_bf16 v[46:49], v[34:37], v[30:33], v[46:49]
	ds_read_b128 v[34:37], v179 offset:16192
	v_mfma_f32_16x16x32_bf16 v[50:53], v[50:53], v[26:29], 0
	s_waitcnt lgkmcnt(0)
	v_mfma_f32_16x16x32_bf16 v[50:53], v[34:37], v[30:33], v[50:53]
	ds_read_b128 v[34:37], v179 offset:18496
	v_mfma_f32_16x16x32_bf16 v[54:57], v[54:57], v[26:29], 0
	s_waitcnt lgkmcnt(0)
	v_mfma_f32_16x16x32_bf16 v[54:57], v[34:37], v[30:33], v[54:57]
	ds_read_b128 v[34:37], v179 offset:20800
	v_mfma_f32_16x16x32_bf16 v[58:61], v[58:61], v[26:29], 0
	s_waitcnt lgkmcnt(0)
	v_mfma_f32_16x16x32_bf16 v[58:61], v[34:37], v[30:33], v[58:61]
	ds_read_b128 v[34:37], v179 offset:23104
	v_mfma_f32_16x16x32_bf16 v[72:75], v[72:75], v[26:29], 0
	s_waitcnt lgkmcnt(0)
	v_mfma_f32_16x16x32_bf16 v[72:75], v[34:37], v[30:33], v[72:75]
	ds_read_b128 v[34:37], v179 offset:25408
	v_mfma_f32_16x16x32_bf16 v[76:79], v[76:79], v[26:29], 0
	s_waitcnt lgkmcnt(0)
	v_mfma_f32_16x16x32_bf16 v[34:37], v[34:37], v[30:33], v[76:79]
	s_nop 5
	ds_read_b128 v[76:79], v179 offset:27712
	v_mfma_f32_16x16x32_bf16 v[26:29], v[80:83], v[26:29], 0
	s_waitcnt lgkmcnt(0)
	v_mfma_f32_16x16x32_bf16 v[26:29], v[76:79], v[30:33], v[26:29]
	v_cndmask_b32_e64 v31, v39, v191, s[8:9]
	v_cndmask_b32_e64 v30, v191, v38, s[18:19]
	v_cndmask_b32_e64 v31, v191, v31, s[14:15]
	v_max3_f32 v32, v71, v30, v31
	v_cndmask_b32_e64 v33, v191, v40, s[16:17]
	v_cndmask_b32_e64 v38, v191, v41, s[20:21]
	v_max3_f32 v32, v32, v33, v38
	v_cndmask_b32_e64 v39, v191, v42, s[14:15]
	v_cndmask_b32_e64 v40, v191, v43, s[14:15]
	v_max3_f32 v32, v32, v39, v40
	v_cndmask_b32_e64 v41, v191, v44, s[14:15]
	v_cndmask_b32_e64 v42, v191, v45, s[14:15]
	v_max3_f32 v32, v32, v41, v42
	v_cndmask_b32_e64 v43, v191, v46, s[14:15]
	v_cndmask_b32_e64 v44, v191, v47, s[14:15]
	v_max3_f32 v32, v32, v43, v44
	v_cndmask_b32_e64 v45, v191, v48, s[14:15]
	v_cndmask_b32_e64 v46, v191, v49, s[14:15]
	v_max3_f32 v32, v32, v45, v46
	v_cndmask_b32_e64 v47, v191, v50, s[14:15]
	v_cndmask_b32_e64 v48, v191, v51, s[14:15]
	v_max3_f32 v32, v32, v47, v48
	v_cndmask_b32_e64 v49, v191, v52, s[14:15]
	v_cndmask_b32_e64 v76, v191, v53, s[14:15]
	v_max3_f32 v32, v32, v49, v76
	v_max3_f32 v32, v32, v54, v55
	v_max3_f32 v32, v32, v56, v57
	v_max3_f32 v32, v32, v58, v59
	v_max3_f32 v32, v32, v60, v61
	v_max3_f32 v32, v32, v72, v73
	v_max3_f32 v32, v32, v74, v75
	v_max3_f32 v32, v32, v34, v35
	v_max3_f32 v32, v32, v36, v37
	v_cndmask_b32_e64 v92, v26, v191, s[6:7]
	v_cndmask_b32_e64 v93, v191, v27, s[8:9]
	v_max3_f32 v26, v32, v92, v93
	v_cndmask_b32_e64 v94, v28, v191, s[10:11]
	v_cndmask_b32_e64 v95, v29, v191, s[12:13]
	v_max3_f32 v26, v26, v94, v95
	ds_bpermute_b32 v27, v65, v26
	s_waitcnt lgkmcnt(0)
	v_max_f32_e32 v27, v27, v27
	v_max_f32_e32 v26, v26, v27
	ds_bpermute_b32 v27, v66, v26
	s_waitcnt lgkmcnt(0)
	v_max_f32_e32 v27, v27, v27
	v_max_f32_e32 v96, v26, v27
	v_sub_f32_e32 v27, v38, v96
	v_sub_f32_e32 v28, v33, v96
	v_sub_f32_e32 v31, v31, v96
	v_sub_f32_e32 v26, v30, v96
	v_exp_f32_e32 v26, v26
	v_exp_f32_e32 v28, v28
	v_exp_f32_e32 v29, v27
	v_exp_f32_e32 v27, v31
	v_sub_f32_e32 v42, v42, v96
	v_sub_f32_e32 v41, v41, v96
	v_sub_f32_e32 v40, v40, v96
	v_sub_f32_e32 v38, v39, v96
	v_exp_f32_e32 v38, v38
	v_exp_f32_e32 v39, v40
	v_exp_f32_e32 v40, v41
	v_exp_f32_e32 v41, v42
	v_sub_f32_e32 v42, v46, v96
	v_sub_f32_e32 v45, v45, v96
	v_sub_f32_e32 v44, v44, v96
	v_sub_f32_e32 v43, v43, v96
	v_exp_f32_e32 v50, v43
	v_exp_f32_e32 v52, v45
	v_exp_f32_e32 v53, v42
	v_exp_f32_e32 v51, v44
	v_sub_f32_e32 v42, v76, v96
	v_sub_f32_e32 v43, v49, v96
	v_sub_f32_e32 v44, v48, v96
	v_sub_f32_e32 v45, v47, v96
	v_exp_f32_e32 v76, v45
	v_exp_f32_e32 v77, v44
	v_exp_f32_e32 v78, v43
	v_exp_f32_e32 v79, v42
	v_sub_f32_e32 v42, v57, v96
	v_sub_f32_e32 v43, v56, v96
	v_sub_f32_e32 v44, v55, v96
	v_sub_f32_e32 v45, v54, v96
	v_pk_add_f32 v[30:31], v[28:29], 0 op_sel_hi:[1,0]
	v_pk_add_f32 v[32:33], v[26:27], 0 op_sel_hi:[1,0]
	v_exp_f32_e32 v80, v45
	v_exp_f32_e32 v82, v43
	v_exp_f32_e32 v83, v42
	v_exp_f32_e32 v81, v44
	v_pk_add_f32 v[32:33], v[38:39], v[32:33]
	v_pk_add_f32 v[30:31], v[40:41], v[30:31]
	v_pk_add_f32 v[32:33], v[50:51], v[32:33]
	v_pk_add_f32 v[30:31], v[52:53], v[30:31]
	v_pk_add_f32 v[32:33], v[76:77], v[32:33]
	v_pk_add_f32 v[30:31], v[78:79], v[30:31]
	v_sub_f32_e32 v44, v58, v96
	v_pk_add_f32 v[42:43], v[82:83], v[30:31]
	v_pk_add_f32 v[30:31], v[80:81], v[32:33]
	v_sub_f32_e32 v33, v59, v96
	v_sub_f32_e32 v32, v61, v96
	v_exp_f32_e32 v85, v33
	v_sub_f32_e32 v33, v60, v96
	v_exp_f32_e32 v84, v44
	v_exp_f32_e32 v86, v33
	v_exp_f32_e32 v87, v32
	v_sub_f32_e32 v46, v75, v96
	v_sub_f32_e32 v47, v74, v96
	v_sub_f32_e32 v48, v73, v96
	v_sub_f32_e32 v49, v72, v96
	v_exp_f32_e32 v72, v47
	v_exp_f32_e32 v73, v46
	v_exp_f32_e32 v74, v49
	v_exp_f32_e32 v75, v48
	v_pk_add_f32 v[44:45], v[84:85], v[30:31]
	v_pk_add_f32 v[42:43], v[86:87], v[42:43]
	v_cvt_pk_bf16_f32 v26, v26, v27
	v_cvt_pk_bf16_f32 v27, v28, v29
	v_cvt_pk_bf16_f32 v28, v38, v39
	v_cvt_pk_bf16_f32 v29, v40, v41
	ds_read2_b64 v[30:33], v67 offset0:16 offset1:20
	ds_read2_b64 v[38:41], v68 offset0:48 offset1:52
	v_pk_add_f32 v[88:89], v[72:73], v[42:43]
	v_pk_add_f32 v[90:91], v[74:75], v[44:45]
	ds_read2_b64 v[42:45], v70 offset0:80 offset1:84
	ds_read2_b64 v[46:49], v69 offset0:112 offset1:116
	v_sub_f32_e32 v36, v36, v96
	v_sub_f32_e32 v35, v35, v96
	v_sub_f32_e32 v34, v34, v96
	v_sub_f32_e32 v97, v37, v96
	v_cvt_pk_bf16_f32 v50, v50, v51
	v_cvt_pk_bf16_f32 v51, v52, v53
	v_cvt_pk_bf16_f32 v52, v76, v77
	v_cvt_pk_bf16_f32 v53, v78, v79
	ds_read2_b64 v[54:57], v67 offset0:24 offset1:28
	v_exp_f32_e32 v76, v34
	v_exp_f32_e32 v77, v35
	v_exp_f32_e32 v78, v36
	ds_read2_b64 v[34:37], v70 offset0:88 offset1:92
	s_waitcnt lgkmcnt(5)
; __device__ __forceinline__ unsigned cvt_pk_bf16(float lo, float hi) { unsigned r; asm volatile("v_cvt_pk_bf16_f32 %0, %1, %2" : "=v"(r) : "v"(lo), "v"(hi)); return r; }
; #define LAS __attribute__((address_space(3)))
; __device__ __forceinline__ void attn_unit(LAS unsigned char* lds, bf16* Q, const bf16* Kg, const bf16* Vg, const float* snk, int unit, int tid) {
;     ...
;     for (int mt = 0; mt < 8; ++mt) {
;         f32x4 st[9];
; #pragma unroll
;         for (int kb = 0; kb < 9; ++kb) { const LAS unsigned char* kp = lds + (16 * (mt + kb) + fr) * ATT_KP + 16 * fq;
;             const bf16x8_t k0 = *(const LAS bf16x8_t*)kp, k1 = *(const LAS bf16x8_t*)(kp + 64);
;             f32x4 z = {0.f, 0.f, 0.f, 0.f}; z = __builtin_amdgcn_mfma_f32_16x16x32_bf16(k0, qf[mt][0], z, 0, 0, 0); z = __builtin_amdgcn_mfma_f32_16x16x32_bf16(k1, qf[mt][1], z, 0, 0, 0); st[kb] = z; }
;     ...
; #pragma unroll
;         for (int kp = 0; kp < 5; ++kp) {
;             v4u pw; pw.x = cvt_pk_bf16(st[2 * kp][0], st[2 * kp][1]); pw.y = cvt_pk_bf16(st[2 * kp][2], st[2 * kp][3]);
;             if (kp < 4) { pw.z = cvt_pk_bf16(st[(2 * kp + 1) % 9][0], st[(2 * kp + 1) % 9][1]); pw.w = cvt_pk_bf16(st[(2 * kp + 1) % 9][2], st[(2 * kp + 1) % 9][3]); } else { pw.z = 0u; pw.w = 0u; }
;             const bf16x8_t pb = __builtin_bit_cast(bf16x8_t, pw);
; #pragma unroll
;             for (int dt = 0; dt < 4; ++dt) { const LAS unsigned char* vp = lds + ATT_VOFF + (16 * dt + fr) * ATT_VP + (16 * (mt + 2 * kp) + 4 * fq) * 2;
;                 const v2u lo = *(const LAS v2u*)vp; v2u hi = {0u, 0u}; if (kp < 4) hi = *(const LAS v2u*)(vp + 32);
;                 v4u aw; aw.x = lo.x; aw.y = lo.y; aw.z = hi.x; aw.w = hi.y;
;                 o[dt] = __builtin_amdgcn_mfma_f32_16x16x32_bf16(__builtin_bit_cast(bf16x8_t, aw), pb, o[dt], 0, 0, 0); }
;         }
; #pragma unroll
;         for (int dt = 0; dt < 4; ++dt) { const f32x4 y = o[dt] * inv; v2u w; w.x = cvt_pk_bf16(y[0], y[1]); w.y = cvt_pk_bf16(y[2], y[3]); *(v2u*)(qbase + (size_t)mt * 16 * 1024 + 16 * dt + 4 * fq) = w; }
	v_mfma_f32_16x16x32_bf16 v[30:33], v[30:33], v[26:29], 0
	ds_read2_b64 v[58:61], v68 offset0:56 offset1:60
	v_exp_f32_e32 v79, v97
	s_waitcnt lgkmcnt(5)
	v_mfma_f32_16x16x32_bf16 v[38:41], v[38:41], v[26:29], 0
	s_waitcnt lgkmcnt(4)
	v_mfma_f32_16x16x32_bf16 v[42:45], v[42:45], v[26:29], 0
	s_waitcnt lgkmcnt(3)
	v_mfma_f32_16x16x32_bf16 v[26:29], v[46:49], v[26:29], 0
	ds_read2_b64 v[46:49], v69 offset0:120 offset1:124
	s_waitcnt lgkmcnt(3)
	v_mfma_f32_16x16x32_bf16 v[30:33], v[54:57], v[50:53], v[30:33]
	v_cvt_pk_bf16_f32 v54, v80, v81
	v_cvt_pk_bf16_f32 v55, v82, v83
	v_cvt_pk_bf16_f32 v56, v84, v85
	v_cvt_pk_bf16_f32 v57, v86, v87
	s_waitcnt lgkmcnt(2)
	v_mfma_f32_16x16x32_bf16 v[34:37], v[34:37], v[50:53], v[42:45]
	v_sub_f32_e32 v85, v95, v96
	v_sub_f32_e32 v86, v94, v96
	v_sub_f32_e32 v87, v93, v96
	ds_read2_b64 v[42:45], v68 offset0:64 offset1:68
	s_waitcnt lgkmcnt(2)
	v_mfma_f32_16x16x32_bf16 v[38:41], v[58:61], v[50:53], v[38:41]
	ds_read2_b64 v[58:61], v67 offset0:32 offset1:36
	v_pk_add_f32 v[80:81], v[76:77], v[90:91]
	v_pk_add_f32 v[82:83], v[78:79], v[88:89]
	s_waitcnt lgkmcnt(2)
	v_mfma_f32_16x16x32_bf16 v[26:29], v[46:49], v[50:53], v[26:29]
	ds_read2_b64 v[46:49], v70 offset0:96 offset1:100
	v_sub_f32_e32 v50, v92, v96
	v_exp_f32_e32 v84, v50
	s_waitcnt lgkmcnt(2)
	v_mfma_f32_16x16x32_bf16 v[38:41], v[42:45], v[54:57], v[38:41]
	ds_read2_b64 v[42:45], v69 offset0:128 offset1:132
	v_cvt_pk_bf16_f32 v50, v74, v75
	v_cvt_pk_bf16_f32 v51, v72, v73
	v_cvt_pk_bf16_f32 v52, v76, v77
	v_cvt_pk_bf16_f32 v53, v78, v79
	s_waitcnt lgkmcnt(1)
	v_mfma_f32_16x16x32_bf16 v[34:37], v[46:49], v[54:57], v[34:37]
	ds_read2_b64 v[46:49], v68 offset0:72 offset1:76
	v_exp_f32_e32 v72, v86
	v_exp_f32_e32 v73, v85
	v_mfma_f32_16x16x32_bf16 v[30:33], v[58:61], v[54:57], v[30:33]
	ds_read2_b64 v[58:61], v67 offset0:40 offset1:44
	v_exp_f32_e32 v85, v87
	s_waitcnt lgkmcnt(2)
	v_mfma_f32_16x16x32_bf16 v[26:29], v[42:45], v[54:57], v[26:29]
	ds_read2_b64 v[42:45], v70 offset0:104 offset1:108
	v_pk_add_f32 v[54:55], v[72:73], v[82:83]
	v_pk_add_f32 v[56:57], v[84:85], v[80:81]
	s_waitcnt lgkmcnt(2)
	v_mfma_f32_16x16x32_bf16 v[38:41], v[46:49], v[50:53], v[38:41]
	ds_read2_b64 v[46:49], v69 offset0:136 offset1:140
	s_waitcnt lgkmcnt(2)
	v_mfma_f32_16x16x32_bf16 v[30:33], v[58:61], v[50:53], v[30:33]
	v_pk_mov_b32 v[58:59], v[56:57], v[54:55] op_sel:[1,0]
	v_mov_b32_e32 v57, v55
	v_pk_add_f32 v[54:55], v[58:59], v[56:57]
	s_waitcnt lgkmcnt(1)
	v_mfma_f32_16x16x32_bf16 v[34:37], v[42:45], v[50:53], v[34:37]
	v_add_f32_e32 v54, v54, v55
	ds_bpermute_b32 v42, v65, v54
	v_mov_b32_e32 v44, v147
	s_waitcnt lgkmcnt(1)
	v_mfma_f32_16x16x32_bf16 v[26:29], v[46:49], v[50:53], v[26:29]
	v_mov_b32_e32 v48, v147
	v_mov_b32_e32 v49, v147
	s_waitcnt lgkmcnt(0)
	v_add_f32_e32 v60, v54, v42
	v_cvt_pk_bf16_f32 v42, v84, v85
	v_cvt_pk_bf16_f32 v43, v72, v73
	ds_read_b64 v[46:47], v180 offset:37248
	ds_read_b64 v[50:51], v180 offset:45696
	v_mov_b32_e32 v45, v147
	v_mov_b32_e32 v52, v147
	v_mov_b32_e32 v53, v147
	s_waitcnt lgkmcnt(1)
	v_mfma_f32_16x16x32_bf16 v[30:33], v[46:49], v[42:45], v[30:33]
	ds_bpermute_b32 v46, v66, v60
	v_fma_f32 v47, v64, s62, -v96
	v_exp_f32_e32 v47, v47
	ds_read_b64 v[54:55], v180 offset:54144
	ds_read_b64 v[58:59], v180 offset:62592
	v_mov_b32_e32 v56, v147
	s_waitcnt lgkmcnt(2)
	v_add_f32_e32 v46, v60, v46
	v_add_f32_e32 v46, v47, v46
	v_mov_b32_e32 v57, v147
	v_mov_b32_e32 v60, v147
	v_mov_b32_e32 v61, v147
	v_div_scale_f32 v47, s[64:65], v46, v46, 1.0
	v_rcp_f32_e32 v48, v47
	v_mfma_f32_16x16x32_bf16 v[38:41], v[50:53], v[42:45], v[38:41]
	s_waitcnt lgkmcnt(1)
	v_mfma_f32_16x16x32_bf16 v[34:37], v[54:57], v[42:45], v[34:37]
	s_waitcnt lgkmcnt(0)
	v_mfma_f32_16x16x32_bf16 v[26:29], v[58:61], v[42:45], v[26:29]
	v_fma_f32 v42, -v47, v48, 1.0
	v_fmac_f32_e32 v48, v42, v48
	v_div_scale_f32 v42, vcc, 1.0, v46, 1.0
	v_mul_f32_e32 v43, v42, v48
	v_fma_f32 v44, -v47, v43, v42
	v_fmac_f32_e32 v43, v44, v48
	v_fma_f32 v42, -v47, v43, v42
	v_div_fmas_f32 v42, v42, v48, v43
	v_div_fixup_f32 v42, v42, v46, 1.0
	v_pk_mul_f32 v[32:33], v[42:43], v[32:33] op_sel_hi:[0,1]
	v_pk_mul_f32 v[30:31], v[42:43], v[30:31] op_sel_hi:[0,1]
	v_add_co_u32_e32 v76, vcc, s45, v62
	v_cvt_pk_bf16_f32 v30, v30, v31
	v_cvt_pk_bf16_f32 v31, v32, v33
	v_pk_mul_f32 v[32:33], v[42:43], v[38:39] op_sel_hi:[0,1]
	s_nop 0
	v_addc_co_u32_e32 v77, vcc, 0, v63, vcc
	v_lshrrev_b32_e32 v110, 4, v0
	v_and_b32_e32 v110, 1, v110
	v_mul_u32_u24_e32 v110, 24, v110
	v_mov_b32_e32 v111, 0
	v_lshl_add_u64 v[118:119], v[76:77], 0, v[110:111]
	v_mov_b32_e32 v114, v30
	v_mov_b32_e32 v115, v31
	v_pk_mul_f32 v[30:31], v[42:43], v[40:41] op_sel_hi:[0,1]
	v_cvt_pk_bf16_f32 v32, v32, v33
	v_cvt_pk_bf16_f32 v33, v30, v31
	v_mov_b32_e32 v116, v32
	v_mov_b32_e32 v117, v33
	s_nop 1
	v_permlane16_swap_b32_e32 v114, v116
	v_permlane16_swap_b32_e32 v115, v117
	global_store_dwordx4 v[118:119], v[114:117], off
	v_pk_mul_f32 v[32:33], v[42:43], v[34:35] op_sel_hi:[0,1]
	v_pk_mul_f32 v[30:31], v[42:43], v[36:37] op_sel_hi:[0,1]
	v_cvt_pk_bf16_f32 v32, v32, v33
	v_cvt_pk_bf16_f32 v33, v30, v31
	v_pk_mul_f32 v[28:29], v[42:43], v[28:29] op_sel_hi:[0,1]
	v_pk_mul_f32 v[26:27], v[42:43], v[26:27] op_sel_hi:[0,1]
	v_mov_b32_e32 v126, v32
	v_mov_b32_e32 v127, v33
	v_cvt_pk_bf16_f32 v78, v26, v27
	v_cvt_pk_bf16_f32 v79, v28, v29
	ds_read_b128 v[26:29], v179 offset:11520
	ds_read_b128 v[30:33], v179 offset:11584
	s_waitcnt lgkmcnt(1)
	v_mfma_f32_16x16x32_bf16 v[26:29], v[26:29], v[18:21], 0
	ds_read_b128 v[34:37], v179 offset:13824
	ds_read_b128 v[38:41], v179 offset:16128
	ds_read_b128 v[42:45], v179 offset:18432
	s_waitcnt lgkmcnt(3)
; __device__ __forceinline__ void attn_unit(LAS unsigned char* lds, bf16* Q, const bf16* Kg, const bf16* Vg, const float* snk, int unit, int tid) {
;     ...
;         for (int kb = 0; kb < 9; ++kb) { const LAS unsigned char* kp = lds + (16 * (mt + kb) + fr) * ATT_KP + 16 * fq;
;             const bf16x8_t k0 = *(const LAS bf16x8_t*)kp, k1 = *(const LAS bf16x8_t*)(kp + 64);
;             f32x4 z = {0.f, 0.f, 0.f, 0.f}; z = __builtin_amdgcn_mfma_f32_16x16x32_bf16(k0, qf[mt][0], z, 0, 0, 0); z = __builtin_amdgcn_mfma_f32_16x16x32_bf16(k1, qf[mt][1], z, 0, 0, 0); st[kb] = z; }
;         float mx = sink;
; #pragma unroll
;         for (int kb = 0; kb < 9; ++kb) {
;             const bool tile_ok = (n > 0) || (mt + kb >= 8);
; #pragma unroll
;             for (int i = 0; i < 4; ++i) { const bool ok = tile_ok && (kb == 0 ? lo_ok[i] : (kb == 8 ? !lo_ok[i] : true));
;                 st[kb][i] = ok ? st[kb][i] : -INFINITY; mx = fmaxf(mx, st[kb][i]); }
;         }
;         mx = fmaxf(mx, __shfl_xor(mx, 16)); mx = fmaxf(mx, __shfl_xor(mx, 32));
;         f32x4 ls4 = {0.f, 0.f, 0.f, 0.f};
; #pragma unroll
;         for (int kb = 0; kb < 9; ++kb) { f32x4 d = st[kb] - mx;
; #pragma unroll
;             for (int i = 0; i < 4; ++i) d[i] = __builtin_amdgcn_exp2f(d[i]);
;             st[kb] = d; ls4 = ls4 + d; }
;         float ls = (ls4[0] + ls4[1]) + (ls4[2] + ls4[3]);
;         ls += __shfl_xor(ls, 16); ls += __shfl_xor(ls, 32);
;         const float inv = 1.f / (ls + __builtin_amdgcn_exp2f(sink - mx));
;         f32x4 o[4];
; #pragma unroll
;         for (int dt = 0; dt < 4; ++dt) o[dt] = (f32x4){0.f, 0.f, 0.f, 0.f};
; #pragma unroll
;         for (int kp = 0; kp < 5; ++kp) {
;             v4u pw; pw.x = cvt_pk_bf16(st[2 * kp][0], st[2 * kp][1]); pw.y = cvt_pk_bf16(st[2 * kp][2], st[2 * kp][3]);
;             if (kp < 4) { pw.z = cvt_pk_bf16(st[(2 * kp + 1) % 9][0], st[(2 * kp + 1) % 9][1]); pw.w = cvt_pk_bf16(st[(2 * kp + 1) % 9][2], st[(2 * kp + 1) % 9][3]); } else { pw.z = 0u; pw.w = 0u; }
;             const bf16x8_t pb = __builtin_bit_cast(bf16x8_t, pw);
; #pragma unroll
;             for (int dt = 0; dt < 4; ++dt) { const LAS unsigned char* vp = lds + ATT_VOFF + (16 * dt + fr) * ATT_VP + (16 * (mt + 2 * kp) + 4 * fq) * 2;
;                 const v2u lo = *(const LAS v2u*)vp; v2u hi = {0u, 0u}; if (kp < 4) hi = *(const LAS v2u*)(vp + 32);
	v_mfma_f32_16x16x32_bf16 v[30:33], v[30:33], v[22:25], v[26:29]
	ds_read_b128 v[46:49], v179 offset:20736
	ds_read_b128 v[50:53], v179 offset:23040
	ds_read_b128 v[54:57], v179 offset:25344
	ds_read_b128 v[26:29], v179 offset:13888
	s_waitcnt lgkmcnt(6)
	v_mfma_f32_16x16x32_bf16 v[34:37], v[34:37], v[18:21], 0
	ds_read_b128 v[58:61], v179 offset:27648
	ds_read_b128 v[72:75], v179 offset:29952
	v_mov_b32_e32 v128, v78
	v_mov_b32_e32 v129, v79
	s_nop 1
	v_permlane16_swap_b32_e32 v126, v128
	v_permlane16_swap_b32_e32 v127, v129
	global_store_dwordx4 v[118:119], v[126:129], off offset:64
	s_waitcnt lgkmcnt(2)
	v_mfma_f32_16x16x32_bf16 v[34:37], v[26:29], v[22:25], v[34:37]
	ds_read_b128 v[26:29], v179 offset:16192
	v_mfma_f32_16x16x32_bf16 v[38:41], v[38:41], v[18:21], 0
	s_waitcnt lgkmcnt(0)
	v_mfma_f32_16x16x32_bf16 v[38:41], v[26:29], v[22:25], v[38:41]
	ds_read_b128 v[26:29], v179 offset:18496
	v_mfma_f32_16x16x32_bf16 v[42:45], v[42:45], v[18:21], 0
	s_waitcnt lgkmcnt(0)
	v_mfma_f32_16x16x32_bf16 v[42:45], v[26:29], v[22:25], v[42:45]
	ds_read_b128 v[26:29], v179 offset:20800
	v_mfma_f32_16x16x32_bf16 v[46:49], v[46:49], v[18:21], 0
	s_waitcnt lgkmcnt(0)
	v_mfma_f32_16x16x32_bf16 v[46:49], v[26:29], v[22:25], v[46:49]
	ds_read_b128 v[26:29], v179 offset:23104
	v_mfma_f32_16x16x32_bf16 v[50:53], v[50:53], v[18:21], 0
	s_waitcnt lgkmcnt(0)
	v_mfma_f32_16x16x32_bf16 v[50:53], v[26:29], v[22:25], v[50:53]
	ds_read_b128 v[26:29], v179 offset:25408
	v_mfma_f32_16x16x32_bf16 v[54:57], v[54:57], v[18:21], 0
	s_waitcnt lgkmcnt(0)
	v_mfma_f32_16x16x32_bf16 v[54:57], v[26:29], v[22:25], v[54:57]
	ds_read_b128 v[26:29], v179 offset:27712
	v_mfma_f32_16x16x32_bf16 v[58:61], v[58:61], v[18:21], 0
	s_waitcnt lgkmcnt(0)
	v_mfma_f32_16x16x32_bf16 v[26:29], v[26:29], v[22:25], v[58:61]
	s_nop 5
	ds_read_b128 v[58:61], v179 offset:30016
	v_mfma_f32_16x16x32_bf16 v[18:21], v[72:75], v[18:21], 0
	s_waitcnt lgkmcnt(0)
	v_mfma_f32_16x16x32_bf16 v[18:21], v[58:61], v[22:25], v[18:21]
	v_cndmask_b32_e64 v23, v31, v191, s[8:9]
	v_cndmask_b32_e64 v22, v191, v30, s[18:19]
	v_cndmask_b32_e64 v23, v191, v23, s[14:15]
	v_max3_f32 v24, v71, v22, v23
	v_cndmask_b32_e64 v25, v191, v32, s[16:17]
	v_cndmask_b32_e64 v30, v191, v33, s[20:21]
	v_max3_f32 v24, v24, v25, v30
	v_cndmask_b32_e64 v31, v191, v34, s[14:15]
	v_cndmask_b32_e64 v32, v191, v35, s[14:15]
	v_max3_f32 v24, v24, v31, v32
	v_cndmask_b32_e64 v33, v191, v36, s[14:15]
	v_cndmask_b32_e64 v34, v191, v37, s[14:15]
	v_max3_f32 v24, v24, v33, v34
	v_cndmask_b32_e64 v35, v191, v38, s[14:15]
	v_cndmask_b32_e64 v36, v191, v39, s[14:15]
	v_max3_f32 v24, v24, v35, v36
	v_cndmask_b32_e64 v37, v191, v40, s[14:15]
	v_cndmask_b32_e64 v38, v191, v41, s[14:15]
	v_max3_f32 v24, v24, v37, v38
	v_max3_f32 v24, v24, v42, v43
	v_max3_f32 v24, v24, v44, v45
	v_max3_f32 v24, v24, v46, v47
	v_max3_f32 v24, v24, v48, v49
	v_max3_f32 v24, v24, v50, v51
	v_max3_f32 v24, v24, v52, v53
	v_max3_f32 v24, v24, v54, v55
	v_max3_f32 v24, v24, v56, v57
	v_max3_f32 v24, v24, v26, v27
	v_max3_f32 v24, v24, v28, v29
	v_cndmask_b32_e64 v86, v18, v191, s[6:7]
	v_cndmask_b32_e64 v87, v191, v19, s[8:9]
	v_max3_f32 v18, v24, v86, v87
	v_cndmask_b32_e64 v88, v20, v191, s[10:11]
	v_cndmask_b32_e64 v89, v21, v191, s[12:13]
	v_max3_f32 v18, v18, v88, v89
	ds_bpermute_b32 v19, v65, v18
	s_waitcnt lgkmcnt(0)
	v_max_f32_e32 v19, v19, v19
	v_max_f32_e32 v18, v18, v19
	ds_bpermute_b32 v19, v66, v18
	s_waitcnt lgkmcnt(0)
	v_max_f32_e32 v19, v19, v19
	v_max_f32_e32 v90, v18, v19
	v_sub_f32_e32 v19, v30, v90
	v_sub_f32_e32 v20, v25, v90
	v_sub_f32_e32 v23, v23, v90
	v_sub_f32_e32 v18, v22, v90
	v_exp_f32_e32 v18, v18
	v_exp_f32_e32 v20, v20
	v_exp_f32_e32 v21, v19
	v_exp_f32_e32 v19, v23
	v_sub_f32_e32 v34, v34, v90
	v_sub_f32_e32 v33, v33, v90
	v_sub_f32_e32 v32, v32, v90
	v_sub_f32_e32 v30, v31, v90
	v_exp_f32_e32 v30, v30
	v_exp_f32_e32 v31, v32
	v_exp_f32_e32 v32, v33
	v_exp_f32_e32 v33, v34
	v_sub_f32_e32 v34, v38, v90
	v_sub_f32_e32 v37, v37, v90
	v_sub_f32_e32 v36, v36, v90
	v_sub_f32_e32 v35, v35, v90
	v_exp_f32_e32 v58, v35
	v_exp_f32_e32 v60, v37
	v_exp_f32_e32 v61, v34
	v_exp_f32_e32 v59, v36
	v_sub_f32_e32 v34, v45, v90
	v_sub_f32_e32 v35, v44, v90
	v_sub_f32_e32 v36, v43, v90
	v_sub_f32_e32 v37, v42, v90
	v_exp_f32_e32 v44, v37
	v_exp_f32_e32 v45, v36
	v_exp_f32_e32 v72, v35
	v_exp_f32_e32 v73, v34
	v_sub_f32_e32 v34, v49, v90
	v_sub_f32_e32 v35, v48, v90
	v_sub_f32_e32 v36, v47, v90
	v_sub_f32_e32 v37, v46, v90
	v_pk_add_f32 v[22:23], v[20:21], 0 op_sel_hi:[1,0]
	v_pk_add_f32 v[24:25], v[18:19], 0 op_sel_hi:[1,0]
	v_exp_f32_e32 v74, v37
	v_exp_f32_e32 v76, v35
	v_exp_f32_e32 v77, v34
	v_exp_f32_e32 v75, v36
	v_pk_add_f32 v[24:25], v[30:31], v[24:25]
	v_pk_add_f32 v[22:23], v[32:33], v[22:23]
	v_pk_add_f32 v[24:25], v[58:59], v[24:25]
	v_pk_add_f32 v[22:23], v[60:61], v[22:23]
	v_pk_add_f32 v[24:25], v[44:45], v[24:25]
	v_pk_add_f32 v[22:23], v[72:73], v[22:23]
	v_sub_f32_e32 v36, v50, v90
	v_pk_add_f32 v[34:35], v[76:77], v[22:23]
	v_pk_add_f32 v[22:23], v[74:75], v[24:25]
	v_sub_f32_e32 v25, v51, v90
	v_sub_f32_e32 v24, v53, v90
	v_exp_f32_e32 v79, v25
	v_sub_f32_e32 v25, v52, v90
	v_exp_f32_e32 v78, v36
	v_exp_f32_e32 v80, v25
	v_exp_f32_e32 v81, v24
	v_sub_f32_e32 v38, v57, v90
	v_sub_f32_e32 v39, v56, v90
	v_sub_f32_e32 v40, v55, v90
	v_sub_f32_e32 v41, v54, v90
	v_exp_f32_e32 v54, v39
	v_exp_f32_e32 v55, v38
	v_exp_f32_e32 v56, v41
	v_exp_f32_e32 v57, v40
	v_pk_add_f32 v[36:37], v[78:79], v[22:23]
	v_pk_add_f32 v[34:35], v[80:81], v[34:35]
	v_cvt_pk_bf16_f32 v18, v18, v19
	v_cvt_pk_bf16_f32 v19, v20, v21
	v_cvt_pk_bf16_f32 v20, v30, v31
	v_cvt_pk_bf16_f32 v21, v32, v33
	ds_read2_b64 v[22:25], v67 offset0:20 offset1:24
	ds_read2_b64 v[30:33], v68 offset0:52 offset1:56
	v_pk_add_f32 v[82:83], v[54:55], v[34:35]
	v_pk_add_f32 v[84:85], v[56:57], v[36:37]
	ds_read2_b64 v[34:37], v70 offset0:84 offset1:88
	ds_read2_b64 v[38:41], v69 offset0:116 offset1:120
	v_sub_f32_e32 v28, v28, v90
	v_sub_f32_e32 v27, v27, v90
	v_sub_f32_e32 v26, v26, v90
	v_sub_f32_e32 v91, v29, v90
	v_cvt_pk_bf16_f32 v42, v58, v59
	v_cvt_pk_bf16_f32 v43, v60, v61
	v_cvt_pk_bf16_f32 v44, v44, v45
	v_cvt_pk_bf16_f32 v45, v72, v73
	ds_read2_b64 v[46:49], v67 offset0:28 offset1:32
	v_exp_f32_e32 v58, v26
	v_exp_f32_e32 v59, v27
	v_exp_f32_e32 v60, v28
	ds_read2_b64 v[26:29], v70 offset0:92 offset1:96
	s_waitcnt lgkmcnt(5)
; __device__ __forceinline__ unsigned cvt_pk_bf16(float lo, float hi) { unsigned r; asm volatile("v_cvt_pk_bf16_f32 %0, %1, %2" : "=v"(r) : "v"(lo), "v"(hi)); return r; }
; #define LAS __attribute__((address_space(3)))
; __device__ __forceinline__ void attn_unit(LAS unsigned char* lds, bf16* Q, const bf16* Kg, const bf16* Vg, const float* snk, int unit, int tid) {
;     ...
;     for (int mt = 0; mt < 8; ++mt) {
;         f32x4 st[9];
; #pragma unroll
;         for (int kb = 0; kb < 9; ++kb) { const LAS unsigned char* kp = lds + (16 * (mt + kb) + fr) * ATT_KP + 16 * fq;
;             const bf16x8_t k0 = *(const LAS bf16x8_t*)kp, k1 = *(const LAS bf16x8_t*)(kp + 64);
;             f32x4 z = {0.f, 0.f, 0.f, 0.f}; z = __builtin_amdgcn_mfma_f32_16x16x32_bf16(k0, qf[mt][0], z, 0, 0, 0); z = __builtin_amdgcn_mfma_f32_16x16x32_bf16(k1, qf[mt][1], z, 0, 0, 0); st[kb] = z; }
;     ...
; #pragma unroll
;         for (int kp = 0; kp < 5; ++kp) {
;             v4u pw; pw.x = cvt_pk_bf16(st[2 * kp][0], st[2 * kp][1]); pw.y = cvt_pk_bf16(st[2 * kp][2], st[2 * kp][3]);
;             if (kp < 4) { pw.z = cvt_pk_bf16(st[(2 * kp + 1) % 9][0], st[(2 * kp + 1) % 9][1]); pw.w = cvt_pk_bf16(st[(2 * kp + 1) % 9][2], st[(2 * kp + 1) % 9][3]); } else { pw.z = 0u; pw.w = 0u; }
;             const bf16x8_t pb = __builtin_bit_cast(bf16x8_t, pw);
; #pragma unroll
;             for (int dt = 0; dt < 4; ++dt) { const LAS unsigned char* vp = lds + ATT_VOFF + (16 * dt + fr) * ATT_VP + (16 * (mt + 2 * kp) + 4 * fq) * 2;
;                 const v2u lo = *(const LAS v2u*)vp; v2u hi = {0u, 0u}; if (kp < 4) hi = *(const LAS v2u*)(vp + 32);
;                 v4u aw; aw.x = lo.x; aw.y = lo.y; aw.z = hi.x; aw.w = hi.y;
;                 o[dt] = __builtin_amdgcn_mfma_f32_16x16x32_bf16(__builtin_bit_cast(bf16x8_t, aw), pb, o[dt], 0, 0, 0); }
;         }
; #pragma unroll
;         for (int dt = 0; dt < 4; ++dt) { const f32x4 y = o[dt] * inv; v2u w; w.x = cvt_pk_bf16(y[0], y[1]); w.y = cvt_pk_bf16(y[2], y[3]); *(v2u*)(qbase + (size_t)mt * 16 * 1024 + 16 * dt + 4 * fq) = w; }
	v_mfma_f32_16x16x32_bf16 v[22:25], v[22:25], v[18:21], 0
	ds_read2_b64 v[50:53], v68 offset0:60 offset1:64
	v_exp_f32_e32 v61, v91
	v_pk_add_f32 v[72:73], v[58:59], v[84:85]
	s_waitcnt lgkmcnt(5)
	v_mfma_f32_16x16x32_bf16 v[30:33], v[30:33], v[18:21], 0
	s_waitcnt lgkmcnt(4)
	v_mfma_f32_16x16x32_bf16 v[34:37], v[34:37], v[18:21], 0
	s_waitcnt lgkmcnt(3)
	v_mfma_f32_16x16x32_bf16 v[18:21], v[38:41], v[18:21], 0
	ds_read2_b64 v[38:41], v69 offset0:124 offset1:128
	s_waitcnt lgkmcnt(3)
	v_mfma_f32_16x16x32_bf16 v[22:25], v[46:49], v[42:45], v[22:25]
	v_cvt_pk_bf16_f32 v46, v74, v75
	v_cvt_pk_bf16_f32 v47, v76, v77
	v_cvt_pk_bf16_f32 v48, v78, v79
	v_cvt_pk_bf16_f32 v49, v80, v81
	s_waitcnt lgkmcnt(2)
	v_mfma_f32_16x16x32_bf16 v[26:29], v[26:29], v[42:45], v[34:37]
	v_sub_f32_e32 v77, v89, v90
	v_sub_f32_e32 v78, v88, v90
	v_sub_f32_e32 v79, v87, v90
	ds_read2_b64 v[34:37], v68 offset0:68 offset1:72
	s_waitcnt lgkmcnt(2)
	v_mfma_f32_16x16x32_bf16 v[30:33], v[50:53], v[42:45], v[30:33]
	ds_read2_b64 v[50:53], v67 offset0:36 offset1:40
	v_pk_add_f32 v[74:75], v[60:61], v[82:83]
	s_waitcnt lgkmcnt(2)
	v_mfma_f32_16x16x32_bf16 v[18:21], v[38:41], v[42:45], v[18:21]
	ds_read2_b64 v[38:41], v70 offset0:100 offset1:104
	v_sub_f32_e32 v42, v86, v90
	v_exp_f32_e32 v76, v42
	s_waitcnt lgkmcnt(2)
	v_mfma_f32_16x16x32_bf16 v[30:33], v[34:37], v[46:49], v[30:33]
	ds_read2_b64 v[34:37], v69 offset0:132 offset1:136
	v_cvt_pk_bf16_f32 v42, v56, v57
	v_cvt_pk_bf16_f32 v43, v54, v55
	v_cvt_pk_bf16_f32 v44, v58, v59
	v_cvt_pk_bf16_f32 v45, v60, v61
	s_waitcnt lgkmcnt(1)
	v_mfma_f32_16x16x32_bf16 v[26:29], v[38:41], v[46:49], v[26:29]
	ds_read2_b64 v[38:41], v68 offset0:76 offset1:80
	v_exp_f32_e32 v54, v78
	v_exp_f32_e32 v55, v77
	v_mfma_f32_16x16x32_bf16 v[22:25], v[50:53], v[46:49], v[22:25]
	ds_read2_b64 v[50:53], v67 offset0:44 offset1:48
	v_exp_f32_e32 v77, v79
	s_waitcnt lgkmcnt(2)
	v_mfma_f32_16x16x32_bf16 v[18:21], v[34:37], v[46:49], v[18:21]
	ds_read2_b64 v[34:37], v70 offset0:108 offset1:112
	v_pk_add_f32 v[46:47], v[54:55], v[74:75]
	v_pk_add_f32 v[48:49], v[76:77], v[72:73]
	s_waitcnt lgkmcnt(2)
	v_mfma_f32_16x16x32_bf16 v[30:33], v[38:41], v[42:45], v[30:33]
	ds_read2_b64 v[38:41], v69 offset0:140 offset1:144
	s_waitcnt lgkmcnt(2)
	v_mfma_f32_16x16x32_bf16 v[22:25], v[50:53], v[42:45], v[22:25]
	v_pk_mov_b32 v[50:51], v[48:49], v[46:47] op_sel:[1,0]
	v_mov_b32_e32 v49, v47
	v_pk_add_f32 v[46:47], v[50:51], v[48:49]
	s_waitcnt lgkmcnt(1)
	v_mfma_f32_16x16x32_bf16 v[26:29], v[34:37], v[42:45], v[26:29]
	v_add_f32_e32 v46, v46, v47
	ds_bpermute_b32 v34, v65, v46
	v_mov_b32_e32 v36, v147
	s_waitcnt lgkmcnt(1)
	v_mfma_f32_16x16x32_bf16 v[18:21], v[38:41], v[42:45], v[18:21]
	v_mov_b32_e32 v40, v147
	v_mov_b32_e32 v41, v147
	s_waitcnt lgkmcnt(0)
	v_add_f32_e32 v52, v46, v34
	v_cvt_pk_bf16_f32 v34, v76, v77
	v_cvt_pk_bf16_f32 v35, v54, v55
	ds_read_b64 v[38:39], v180 offset:37280
	ds_read_b64 v[42:43], v180 offset:45728
	v_mov_b32_e32 v37, v147
	v_mov_b32_e32 v44, v147
	v_mov_b32_e32 v45, v147
	s_waitcnt lgkmcnt(1)
	v_mfma_f32_16x16x32_bf16 v[22:25], v[38:41], v[34:37], v[22:25]
	ds_bpermute_b32 v38, v66, v52
	v_fma_f32 v39, v64, s62, -v90
	v_exp_f32_e32 v39, v39
	ds_read_b64 v[46:47], v180 offset:54176
	ds_read_b64 v[50:51], v180 offset:62624
	v_mov_b32_e32 v48, v147
	s_waitcnt lgkmcnt(2)
	v_add_f32_e32 v38, v52, v38
	v_add_f32_e32 v38, v39, v38
	v_mov_b32_e32 v49, v147
	v_mov_b32_e32 v52, v147
	v_mov_b32_e32 v53, v147
	v_div_scale_f32 v39, s[64:65], v38, v38, 1.0
	v_rcp_f32_e32 v40, v39
	v_mfma_f32_16x16x32_bf16 v[30:33], v[42:45], v[34:37], v[30:33]
	s_waitcnt lgkmcnt(1)
	v_mfma_f32_16x16x32_bf16 v[26:29], v[46:49], v[34:37], v[26:29]
	s_waitcnt lgkmcnt(0)
	v_mfma_f32_16x16x32_bf16 v[18:21], v[50:53], v[34:37], v[18:21]
	v_fma_f32 v34, -v39, v40, 1.0
	v_fmac_f32_e32 v40, v34, v40
	v_div_scale_f32 v34, vcc, 1.0, v38, 1.0
	v_mul_f32_e32 v35, v34, v40
	v_fma_f32 v36, -v39, v35, v34
	v_fmac_f32_e32 v35, v36, v40
	v_fma_f32 v34, -v39, v35, v34
	v_div_fmas_f32 v34, v34, v40, v35
	v_div_fixup_f32 v34, v34, v38, 1.0
	v_pk_mul_f32 v[24:25], v[34:35], v[24:25] op_sel_hi:[0,1]
	v_pk_mul_f32 v[22:23], v[34:35], v[22:23] op_sel_hi:[0,1]
	v_add_co_u32_e32 v58, vcc, s46, v62
	v_cvt_pk_bf16_f32 v22, v22, v23
	v_cvt_pk_bf16_f32 v23, v24, v25
	v_pk_mul_f32 v[24:25], v[34:35], v[30:31] op_sel_hi:[0,1]
	s_nop 0
	v_addc_co_u32_e32 v59, vcc, 0, v63, vcc
	v_lshrrev_b32_e32 v110, 4, v0
	v_and_b32_e32 v110, 1, v110
	v_mul_u32_u24_e32 v110, 24, v110
	v_mov_b32_e32 v111, 0
	v_lshl_add_u64 v[118:119], v[58:59], 0, v[110:111]
	v_mov_b32_e32 v114, v22
	v_mov_b32_e32 v115, v23
	v_pk_mul_f32 v[22:23], v[34:35], v[32:33] op_sel_hi:[0,1]
	v_cvt_pk_bf16_f32 v24, v24, v25
	v_cvt_pk_bf16_f32 v25, v22, v23
	v_mov_b32_e32 v116, v24
	v_mov_b32_e32 v117, v25
	s_nop 1
	v_permlane16_swap_b32_e32 v114, v116
	v_permlane16_swap_b32_e32 v115, v117
	global_store_dwordx4 v[118:119], v[114:117], off
	v_pk_mul_f32 v[24:25], v[34:35], v[26:27] op_sel_hi:[0,1]
	v_pk_mul_f32 v[22:23], v[34:35], v[28:29] op_sel_hi:[0,1]
	v_cvt_pk_bf16_f32 v24, v24, v25
	v_cvt_pk_bf16_f32 v25, v22, v23
	v_pk_mul_f32 v[20:21], v[34:35], v[20:21] op_sel_hi:[0,1]
	v_pk_mul_f32 v[18:19], v[34:35], v[18:19] op_sel_hi:[0,1]
	v_mov_b32_e32 v126, v24
	v_mov_b32_e32 v127, v25
	v_cvt_pk_bf16_f32 v60, v18, v19
	v_cvt_pk_bf16_f32 v61, v20, v21
	ds_read_b128 v[18:21], v179 offset:13824
	ds_read_b128 v[22:25], v179 offset:13888
	s_waitcnt lgkmcnt(1)
	v_mfma_f32_16x16x32_bf16 v[18:21], v[18:21], v[10:13], 0
	ds_read_b128 v[26:29], v179 offset:16128
	ds_read_b128 v[30:33], v179 offset:18432
	ds_read_b128 v[34:37], v179 offset:20736
	s_waitcnt lgkmcnt(3)
; __device__ __forceinline__ void attn_unit(LAS unsigned char* lds, bf16* Q, const bf16* Kg, const bf16* Vg, const float* snk, int unit, int tid) {
;     ...
;         for (int kb = 0; kb < 9; ++kb) { const LAS unsigned char* kp = lds + (16 * (mt + kb) + fr) * ATT_KP + 16 * fq;
;             const bf16x8_t k0 = *(const LAS bf16x8_t*)kp, k1 = *(const LAS bf16x8_t*)(kp + 64);
;             f32x4 z = {0.f, 0.f, 0.f, 0.f}; z = __builtin_amdgcn_mfma_f32_16x16x32_bf16(k0, qf[mt][0], z, 0, 0, 0); z = __builtin_amdgcn_mfma_f32_16x16x32_bf16(k1, qf[mt][1], z, 0, 0, 0); st[kb] = z; }
;         float mx = sink;
; #pragma unroll
;         for (int kb = 0; kb < 9; ++kb) {
;             const bool tile_ok = (n > 0) || (mt + kb >= 8);
; #pragma unroll
;             for (int i = 0; i < 4; ++i) { const bool ok = tile_ok && (kb == 0 ? lo_ok[i] : (kb == 8 ? !lo_ok[i] : true));
;                 st[kb][i] = ok ? st[kb][i] : -INFINITY; mx = fmaxf(mx, st[kb][i]); }
;         }
;         mx = fmaxf(mx, __shfl_xor(mx, 16)); mx = fmaxf(mx, __shfl_xor(mx, 32));
;         f32x4 ls4 = {0.f, 0.f, 0.f, 0.f};
; #pragma unroll
;         for (int kb = 0; kb < 9; ++kb) { f32x4 d = st[kb] - mx;
; #pragma unroll
;             for (int i = 0; i < 4; ++i) d[i] = __builtin_amdgcn_exp2f(d[i]);
;             st[kb] = d; ls4 = ls4 + d; }
;         float ls = (ls4[0] + ls4[1]) + (ls4[2] + ls4[3]);
;         ls += __shfl_xor(ls, 16); ls += __shfl_xor(ls, 32);
;         const float inv = 1.f / (ls + __builtin_amdgcn_exp2f(sink - mx));
;         f32x4 o[4];
; #pragma unroll
;         for (int dt = 0; dt < 4; ++dt) o[dt] = (f32x4){0.f, 0.f, 0.f, 0.f};
; #pragma unroll
;         for (int kp = 0; kp < 5; ++kp) {
;             v4u pw; pw.x = cvt_pk_bf16(st[2 * kp][0], st[2 * kp][1]); pw.y = cvt_pk_bf16(st[2 * kp][2], st[2 * kp][3]);
;             if (kp < 4) { pw.z = cvt_pk_bf16(st[(2 * kp + 1) % 9][0], st[(2 * kp + 1) % 9][1]); pw.w = cvt_pk_bf16(st[(2 * kp + 1) % 9][2], st[(2 * kp + 1) % 9][3]); } else { pw.z = 0u; pw.w = 0u; }
;             const bf16x8_t pb = __builtin_bit_cast(bf16x8_t, pw);
; #pragma unroll
;             for (int dt = 0; dt < 4; ++dt) { const LAS unsigned char* vp = lds + ATT_VOFF + (16 * dt + fr) * ATT_VP + (16 * (mt + 2 * kp) + 4 * fq) * 2;
;                 const v2u lo = *(const LAS v2u*)vp; v2u hi = {0u, 0u}; if (kp < 4) hi = *(const LAS v2u*)(vp + 32);
	v_mfma_f32_16x16x32_bf16 v[22:25], v[22:25], v[14:17], v[18:21]
	ds_read_b128 v[38:41], v179 offset:23040
	ds_read_b128 v[42:45], v179 offset:25344
	ds_read_b128 v[46:49], v179 offset:27648
	ds_read_b128 v[18:21], v179 offset:16192
	s_waitcnt lgkmcnt(6)
	v_mfma_f32_16x16x32_bf16 v[26:29], v[26:29], v[10:13], 0
	ds_read_b128 v[50:53], v179 offset:29952
	ds_read_b128 v[54:57], v179 offset:32256
	v_mov_b32_e32 v128, v60
	v_mov_b32_e32 v129, v61
	s_nop 1
	v_permlane16_swap_b32_e32 v126, v128
	v_permlane16_swap_b32_e32 v127, v129
	global_store_dwordx4 v[118:119], v[126:129], off offset:64
	s_waitcnt lgkmcnt(2)
	v_mfma_f32_16x16x32_bf16 v[26:29], v[18:21], v[14:17], v[26:29]
	ds_read_b128 v[18:21], v179 offset:18496
	v_mfma_f32_16x16x32_bf16 v[30:33], v[30:33], v[10:13], 0
	s_waitcnt lgkmcnt(0)
	v_mfma_f32_16x16x32_bf16 v[30:33], v[18:21], v[14:17], v[30:33]
	ds_read_b128 v[18:21], v179 offset:20800
	v_mfma_f32_16x16x32_bf16 v[34:37], v[34:37], v[10:13], 0
	s_waitcnt lgkmcnt(0)
	v_mfma_f32_16x16x32_bf16 v[34:37], v[18:21], v[14:17], v[34:37]
	ds_read_b128 v[18:21], v179 offset:23104
	v_mfma_f32_16x16x32_bf16 v[38:41], v[38:41], v[10:13], 0
	s_waitcnt lgkmcnt(0)
	v_mfma_f32_16x16x32_bf16 v[38:41], v[18:21], v[14:17], v[38:41]
	ds_read_b128 v[18:21], v179 offset:25408
	v_mfma_f32_16x16x32_bf16 v[42:45], v[42:45], v[10:13], 0
	s_waitcnt lgkmcnt(0)
	v_mfma_f32_16x16x32_bf16 v[42:45], v[18:21], v[14:17], v[42:45]
	ds_read_b128 v[18:21], v179 offset:27712
	v_mfma_f32_16x16x32_bf16 v[46:49], v[46:49], v[10:13], 0
	s_waitcnt lgkmcnt(0)
	v_mfma_f32_16x16x32_bf16 v[46:49], v[18:21], v[14:17], v[46:49]
	ds_read_b128 v[18:21], v179 offset:30016
	v_mfma_f32_16x16x32_bf16 v[50:53], v[50:53], v[10:13], 0
	s_waitcnt lgkmcnt(0)
	v_mfma_f32_16x16x32_bf16 v[18:21], v[18:21], v[14:17], v[50:53]
	s_nop 5
	ds_read_b128 v[50:53], v179 offset:32320
	v_mfma_f32_16x16x32_bf16 v[10:13], v[54:57], v[10:13], 0
	s_waitcnt lgkmcnt(0)
	v_mfma_f32_16x16x32_bf16 v[10:13], v[50:53], v[14:17], v[10:13]
	v_cndmask_b32_e64 v15, v23, v191, s[8:9]
	v_cndmask_b32_e64 v14, v191, v22, s[18:19]
	v_cndmask_b32_e64 v15, v191, v15, s[14:15]
	v_max3_f32 v16, v71, v14, v15
	v_cndmask_b32_e64 v17, v191, v24, s[16:17]
	v_cndmask_b32_e64 v22, v191, v25, s[20:21]
	v_max3_f32 v16, v16, v17, v22
	v_cndmask_b32_e64 v23, v191, v26, s[14:15]
	v_cndmask_b32_e64 v24, v191, v27, s[14:15]
	v_max3_f32 v16, v16, v23, v24
	v_cndmask_b32_e64 v25, v191, v28, s[14:15]
	v_cndmask_b32_e64 v26, v191, v29, s[14:15]
	v_max3_f32 v16, v16, v25, v26
	v_max3_f32 v16, v16, v30, v31
	v_max3_f32 v16, v16, v32, v33
	v_max3_f32 v16, v16, v34, v35
	v_max3_f32 v16, v16, v36, v37
	v_max3_f32 v16, v16, v38, v39
	v_max3_f32 v16, v16, v40, v41
	v_max3_f32 v16, v16, v42, v43
	v_max3_f32 v16, v16, v44, v45
	v_max3_f32 v16, v16, v46, v47
	v_max3_f32 v16, v16, v48, v49
	v_max3_f32 v16, v16, v18, v19
	v_max3_f32 v16, v16, v20, v21
	v_cndmask_b32_e64 v78, v10, v191, s[6:7]
	v_cndmask_b32_e64 v79, v191, v11, s[8:9]
	v_max3_f32 v10, v16, v78, v79
	v_cndmask_b32_e64 v80, v12, v191, s[10:11]
	v_cndmask_b32_e64 v81, v13, v191, s[12:13]
	v_max3_f32 v10, v10, v80, v81
	ds_bpermute_b32 v11, v65, v10
	s_waitcnt lgkmcnt(0)
	v_max_f32_e32 v11, v11, v11
	v_max_f32_e32 v10, v10, v11
	ds_bpermute_b32 v11, v66, v10
	s_waitcnt lgkmcnt(0)
	v_max_f32_e32 v11, v11, v11
	v_max_f32_e32 v82, v10, v11
	v_sub_f32_e32 v11, v22, v82
	v_sub_f32_e32 v12, v17, v82
	v_sub_f32_e32 v15, v15, v82
	v_sub_f32_e32 v10, v14, v82
	v_exp_f32_e32 v10, v10
	v_exp_f32_e32 v12, v12
	v_exp_f32_e32 v13, v11
	v_exp_f32_e32 v11, v15
	v_sub_f32_e32 v26, v26, v82
	v_sub_f32_e32 v25, v25, v82
	v_sub_f32_e32 v24, v24, v82
	v_sub_f32_e32 v22, v23, v82
	v_exp_f32_e32 v22, v22
	v_exp_f32_e32 v23, v24
	v_exp_f32_e32 v24, v25
	v_exp_f32_e32 v25, v26
	v_sub_f32_e32 v26, v33, v82
	v_sub_f32_e32 v27, v32, v82
	v_sub_f32_e32 v28, v31, v82
	v_sub_f32_e32 v29, v30, v82
	v_exp_f32_e32 v50, v29
	v_exp_f32_e32 v52, v27
	v_exp_f32_e32 v53, v26
	v_exp_f32_e32 v51, v28
	v_sub_f32_e32 v26, v37, v82
	v_sub_f32_e32 v27, v36, v82
	v_sub_f32_e32 v28, v35, v82
	v_sub_f32_e32 v29, v34, v82
	v_exp_f32_e32 v36, v29
	v_exp_f32_e32 v37, v28
	v_exp_f32_e32 v54, v27
	v_exp_f32_e32 v55, v26
	v_sub_f32_e32 v26, v41, v82
	v_sub_f32_e32 v27, v40, v82
	v_sub_f32_e32 v28, v39, v82
	v_sub_f32_e32 v29, v38, v82
	v_pk_add_f32 v[14:15], v[12:13], 0 op_sel_hi:[1,0]
	v_pk_add_f32 v[16:17], v[10:11], 0 op_sel_hi:[1,0]
	v_exp_f32_e32 v56, v29
	v_exp_f32_e32 v58, v27
	v_exp_f32_e32 v59, v26
	v_exp_f32_e32 v57, v28
	v_pk_add_f32 v[16:17], v[22:23], v[16:17]
	v_pk_add_f32 v[14:15], v[24:25], v[14:15]
	v_pk_add_f32 v[16:17], v[50:51], v[16:17]
	v_pk_add_f32 v[14:15], v[52:53], v[14:15]
	v_pk_add_f32 v[16:17], v[36:37], v[16:17]
	v_pk_add_f32 v[14:15], v[54:55], v[14:15]
	v_sub_f32_e32 v28, v42, v82
	v_pk_add_f32 v[26:27], v[58:59], v[14:15]
	v_pk_add_f32 v[14:15], v[56:57], v[16:17]
	v_sub_f32_e32 v17, v43, v82
	v_sub_f32_e32 v16, v45, v82
	v_exp_f32_e32 v61, v17
	v_sub_f32_e32 v17, v44, v82
	v_exp_f32_e32 v60, v28
	v_exp_f32_e32 v72, v17
	v_exp_f32_e32 v73, v16
	v_sub_f32_e32 v30, v49, v82
	v_sub_f32_e32 v31, v48, v82
	v_sub_f32_e32 v32, v47, v82
	v_sub_f32_e32 v33, v46, v82
	v_exp_f32_e32 v46, v31
	v_exp_f32_e32 v47, v30
	v_exp_f32_e32 v48, v33
	v_exp_f32_e32 v49, v32
	v_pk_add_f32 v[28:29], v[60:61], v[14:15]
	v_pk_add_f32 v[26:27], v[72:73], v[26:27]
	v_cvt_pk_bf16_f32 v10, v10, v11
	v_cvt_pk_bf16_f32 v11, v12, v13
	v_cvt_pk_bf16_f32 v12, v22, v23
	v_cvt_pk_bf16_f32 v13, v24, v25
	ds_read2_b64 v[14:17], v67 offset0:24 offset1:28
	ds_read2_b64 v[22:25], v68 offset0:56 offset1:60
	v_pk_add_f32 v[74:75], v[46:47], v[26:27]
	v_pk_add_f32 v[76:77], v[48:49], v[28:29]
	ds_read2_b64 v[26:29], v70 offset0:88 offset1:92
	ds_read2_b64 v[30:33], v69 offset0:120 offset1:124
	v_sub_f32_e32 v20, v20, v82
	v_sub_f32_e32 v19, v19, v82
	v_sub_f32_e32 v18, v18, v82
	v_sub_f32_e32 v83, v21, v82
	v_cvt_pk_bf16_f32 v34, v50, v51
	v_cvt_pk_bf16_f32 v35, v52, v53
	v_cvt_pk_bf16_f32 v36, v36, v37
	v_cvt_pk_bf16_f32 v37, v54, v55
	ds_read2_b64 v[38:41], v67 offset0:32 offset1:36
	v_exp_f32_e32 v50, v18
	v_exp_f32_e32 v51, v19
	v_exp_f32_e32 v52, v20
	ds_read2_b64 v[18:21], v70 offset0:96 offset1:100
	s_waitcnt lgkmcnt(5)
; __device__ __forceinline__ unsigned cvt_pk_bf16(float lo, float hi) { unsigned r; asm volatile("v_cvt_pk_bf16_f32 %0, %1, %2" : "=v"(r) : "v"(lo), "v"(hi)); return r; }
; #define LAS __attribute__((address_space(3)))
; __device__ __forceinline__ void attn_unit(LAS unsigned char* lds, bf16* Q, const bf16* Kg, const bf16* Vg, const float* snk, int unit, int tid) {
;     ...
;     for (int mt = 0; mt < 8; ++mt) {
;         f32x4 st[9];
; #pragma unroll
;         for (int kb = 0; kb < 9; ++kb) { const LAS unsigned char* kp = lds + (16 * (mt + kb) + fr) * ATT_KP + 16 * fq;
;             const bf16x8_t k0 = *(const LAS bf16x8_t*)kp, k1 = *(const LAS bf16x8_t*)(kp + 64);
;             f32x4 z = {0.f, 0.f, 0.f, 0.f}; z = __builtin_amdgcn_mfma_f32_16x16x32_bf16(k0, qf[mt][0], z, 0, 0, 0); z = __builtin_amdgcn_mfma_f32_16x16x32_bf16(k1, qf[mt][1], z, 0, 0, 0); st[kb] = z; }
;     ...
; #pragma unroll
;         for (int kp = 0; kp < 5; ++kp) {
;             v4u pw; pw.x = cvt_pk_bf16(st[2 * kp][0], st[2 * kp][1]); pw.y = cvt_pk_bf16(st[2 * kp][2], st[2 * kp][3]);
;             if (kp < 4) { pw.z = cvt_pk_bf16(st[(2 * kp + 1) % 9][0], st[(2 * kp + 1) % 9][1]); pw.w = cvt_pk_bf16(st[(2 * kp + 1) % 9][2], st[(2 * kp + 1) % 9][3]); } else { pw.z = 0u; pw.w = 0u; }
;             const bf16x8_t pb = __builtin_bit_cast(bf16x8_t, pw);
; #pragma unroll
;             for (int dt = 0; dt < 4; ++dt) { const LAS unsigned char* vp = lds + ATT_VOFF + (16 * dt + fr) * ATT_VP + (16 * (mt + 2 * kp) + 4 * fq) * 2;
;                 const v2u lo = *(const LAS v2u*)vp; v2u hi = {0u, 0u}; if (kp < 4) hi = *(const LAS v2u*)(vp + 32);
;                 v4u aw; aw.x = lo.x; aw.y = lo.y; aw.z = hi.x; aw.w = hi.y;
;                 o[dt] = __builtin_amdgcn_mfma_f32_16x16x32_bf16(__builtin_bit_cast(bf16x8_t, aw), pb, o[dt], 0, 0, 0); }
;         }
; #pragma unroll
;         for (int dt = 0; dt < 4; ++dt) { const f32x4 y = o[dt] * inv; v2u w; w.x = cvt_pk_bf16(y[0], y[1]); w.y = cvt_pk_bf16(y[2], y[3]); *(v2u*)(qbase + (size_t)mt * 16 * 1024 + 16 * dt + 4 * fq) = w; }
	v_mfma_f32_16x16x32_bf16 v[14:17], v[14:17], v[10:13], 0
	ds_read2_b64 v[42:45], v68 offset0:64 offset1:68
	v_exp_f32_e32 v53, v83
	v_pk_add_f32 v[54:55], v[50:51], v[76:77]
	s_waitcnt lgkmcnt(5)
	v_mfma_f32_16x16x32_bf16 v[22:25], v[22:25], v[10:13], 0
	s_waitcnt lgkmcnt(4)
	v_mfma_f32_16x16x32_bf16 v[26:29], v[26:29], v[10:13], 0
	s_waitcnt lgkmcnt(3)
	v_mfma_f32_16x16x32_bf16 v[10:13], v[30:33], v[10:13], 0
	ds_read2_b64 v[30:33], v69 offset0:128 offset1:132
	s_waitcnt lgkmcnt(3)
	v_mfma_f32_16x16x32_bf16 v[14:17], v[38:41], v[34:37], v[14:17]
	v_cvt_pk_bf16_f32 v38, v56, v57
	v_cvt_pk_bf16_f32 v39, v58, v59
	v_cvt_pk_bf16_f32 v40, v60, v61
	v_cvt_pk_bf16_f32 v41, v72, v73
	s_waitcnt lgkmcnt(2)
	v_mfma_f32_16x16x32_bf16 v[18:21], v[18:21], v[34:37], v[26:29]
	v_sub_f32_e32 v59, v81, v82
	v_sub_f32_e32 v60, v80, v82
	v_sub_f32_e32 v61, v79, v82
	ds_read2_b64 v[26:29], v68 offset0:72 offset1:76
	s_waitcnt lgkmcnt(2)
	v_mfma_f32_16x16x32_bf16 v[22:25], v[42:45], v[34:37], v[22:25]
	ds_read2_b64 v[42:45], v67 offset0:40 offset1:44
	v_pk_add_f32 v[56:57], v[52:53], v[74:75]
	s_waitcnt lgkmcnt(2)
	v_mfma_f32_16x16x32_bf16 v[10:13], v[30:33], v[34:37], v[10:13]
	ds_read2_b64 v[30:33], v70 offset0:104 offset1:108
	v_sub_f32_e32 v34, v78, v82
	v_exp_f32_e32 v58, v34
	s_waitcnt lgkmcnt(2)
	v_mfma_f32_16x16x32_bf16 v[22:25], v[26:29], v[38:41], v[22:25]
	ds_read2_b64 v[26:29], v69 offset0:136 offset1:140
	v_cvt_pk_bf16_f32 v34, v48, v49
	v_cvt_pk_bf16_f32 v35, v46, v47
	v_cvt_pk_bf16_f32 v36, v50, v51
	v_cvt_pk_bf16_f32 v37, v52, v53
	s_waitcnt lgkmcnt(1)
	v_mfma_f32_16x16x32_bf16 v[18:21], v[30:33], v[38:41], v[18:21]
	ds_read2_b64 v[30:33], v68 offset0:80 offset1:84
	v_exp_f32_e32 v46, v60
	v_exp_f32_e32 v47, v59
	v_mfma_f32_16x16x32_bf16 v[14:17], v[42:45], v[38:41], v[14:17]
	ds_read2_b64 v[42:45], v67 offset0:48 offset1:52
	v_exp_f32_e32 v59, v61
	s_waitcnt lgkmcnt(2)
	v_mfma_f32_16x16x32_bf16 v[10:13], v[26:29], v[38:41], v[10:13]
	ds_read2_b64 v[26:29], v70 offset0:112 offset1:116
	v_pk_add_f32 v[38:39], v[46:47], v[56:57]
	v_pk_add_f32 v[40:41], v[58:59], v[54:55]
	s_waitcnt lgkmcnt(2)
	v_mfma_f32_16x16x32_bf16 v[22:25], v[30:33], v[34:37], v[22:25]
	ds_read2_b64 v[30:33], v69 offset0:144 offset1:148
	s_waitcnt lgkmcnt(2)
	v_mfma_f32_16x16x32_bf16 v[14:17], v[42:45], v[34:37], v[14:17]
	v_pk_mov_b32 v[42:43], v[40:41], v[38:39] op_sel:[1,0]
	v_mov_b32_e32 v41, v39
	v_pk_add_f32 v[38:39], v[42:43], v[40:41]
	s_waitcnt lgkmcnt(1)
	v_mfma_f32_16x16x32_bf16 v[18:21], v[26:29], v[34:37], v[18:21]
	v_add_f32_e32 v38, v38, v39
	ds_bpermute_b32 v26, v65, v38
	v_mov_b32_e32 v28, v147
	s_waitcnt lgkmcnt(1)
	v_mfma_f32_16x16x32_bf16 v[10:13], v[30:33], v[34:37], v[10:13]
	v_mov_b32_e32 v32, v147
	v_mov_b32_e32 v33, v147
	s_waitcnt lgkmcnt(0)
	v_add_f32_e32 v44, v38, v26
	v_cvt_pk_bf16_f32 v26, v58, v59
	v_cvt_pk_bf16_f32 v27, v46, v47
	ds_read_b64 v[30:31], v180 offset:37312
	ds_read_b64 v[34:35], v180 offset:45760
	v_mov_b32_e32 v29, v147
	v_mov_b32_e32 v36, v147
	v_mov_b32_e32 v37, v147
	s_waitcnt lgkmcnt(1)
	v_mfma_f32_16x16x32_bf16 v[14:17], v[30:33], v[26:29], v[14:17]
	ds_bpermute_b32 v30, v66, v44
	v_fma_f32 v31, v64, s62, -v82
	v_exp_f32_e32 v31, v31
	ds_read_b64 v[38:39], v180 offset:54208
	ds_read_b64 v[42:43], v180 offset:62656
	v_mov_b32_e32 v40, v147
	s_waitcnt lgkmcnt(2)
	v_add_f32_e32 v30, v44, v30
	v_add_f32_e32 v30, v31, v30
	v_mov_b32_e32 v41, v147
	v_mov_b32_e32 v44, v147
	v_mov_b32_e32 v45, v147
	v_div_scale_f32 v31, s[64:65], v30, v30, 1.0
	v_rcp_f32_e32 v32, v31
	v_mfma_f32_16x16x32_bf16 v[22:25], v[34:37], v[26:29], v[22:25]
	s_waitcnt lgkmcnt(1)
	v_mfma_f32_16x16x32_bf16 v[18:21], v[38:41], v[26:29], v[18:21]
	s_waitcnt lgkmcnt(0)
	v_mfma_f32_16x16x32_bf16 v[10:13], v[42:45], v[26:29], v[10:13]
	v_fma_f32 v26, -v31, v32, 1.0
	v_fmac_f32_e32 v32, v26, v32
	v_div_scale_f32 v26, vcc, 1.0, v30, 1.0
	v_mul_f32_e32 v27, v26, v32
	v_fma_f32 v28, -v31, v27, v26
	v_fmac_f32_e32 v27, v28, v32
	v_fma_f32 v26, -v31, v27, v26
	v_div_fmas_f32 v26, v26, v32, v27
	v_div_fixup_f32 v26, v26, v30, 1.0
	v_pk_mul_f32 v[16:17], v[26:27], v[16:17] op_sel_hi:[0,1]
	v_pk_mul_f32 v[14:15], v[26:27], v[14:15] op_sel_hi:[0,1]
	v_add_co_u32_e32 v50, vcc, s47, v62
	v_cvt_pk_bf16_f32 v14, v14, v15
	v_cvt_pk_bf16_f32 v15, v16, v17
	v_pk_mul_f32 v[16:17], v[26:27], v[22:23] op_sel_hi:[0,1]
	s_nop 0
	v_addc_co_u32_e32 v51, vcc, 0, v63, vcc
	v_lshrrev_b32_e32 v110, 4, v0
	v_and_b32_e32 v110, 1, v110
	v_mul_u32_u24_e32 v110, 24, v110
	v_mov_b32_e32 v111, 0
	v_lshl_add_u64 v[118:119], v[50:51], 0, v[110:111]
	v_mov_b32_e32 v114, v14
	v_mov_b32_e32 v115, v15
	v_pk_mul_f32 v[14:15], v[26:27], v[24:25] op_sel_hi:[0,1]
	v_cvt_pk_bf16_f32 v16, v16, v17
	v_cvt_pk_bf16_f32 v17, v14, v15
	v_mov_b32_e32 v116, v16
	v_mov_b32_e32 v117, v17
	s_nop 1
	v_permlane16_swap_b32_e32 v114, v116
	v_permlane16_swap_b32_e32 v115, v117
	global_store_dwordx4 v[118:119], v[114:117], off
	v_pk_mul_f32 v[16:17], v[26:27], v[18:19] op_sel_hi:[0,1]
	v_pk_mul_f32 v[14:15], v[26:27], v[20:21] op_sel_hi:[0,1]
	v_cvt_pk_bf16_f32 v16, v16, v17
	v_cvt_pk_bf16_f32 v17, v14, v15
	v_pk_mul_f32 v[12:13], v[26:27], v[12:13] op_sel_hi:[0,1]
	v_pk_mul_f32 v[10:11], v[26:27], v[10:11] op_sel_hi:[0,1]
	v_mov_b32_e32 v126, v16
	v_mov_b32_e32 v127, v17
	v_cvt_pk_bf16_f32 v52, v10, v11
	v_cvt_pk_bf16_f32 v53, v12, v13
	ds_read_b128 v[10:13], v179 offset:16128
	ds_read_b128 v[14:17], v179 offset:16192
	s_waitcnt lgkmcnt(1)
	v_mfma_f32_16x16x32_bf16 v[10:13], v[10:13], v[2:5], 0
	ds_read_b128 v[18:21], v179 offset:18432
	ds_read_b128 v[22:25], v179 offset:20736
	ds_read_b128 v[26:29], v179 offset:23040
	s_waitcnt lgkmcnt(3)
; __device__ __forceinline__ void attn_unit(LAS unsigned char* lds, bf16* Q, const bf16* Kg, const bf16* Vg, const float* snk, int unit, int tid) {
;     ...
;         for (int kb = 0; kb < 9; ++kb) { const LAS unsigned char* kp = lds + (16 * (mt + kb) + fr) * ATT_KP + 16 * fq;
;             const bf16x8_t k0 = *(const LAS bf16x8_t*)kp, k1 = *(const LAS bf16x8_t*)(kp + 64);
;             f32x4 z = {0.f, 0.f, 0.f, 0.f}; z = __builtin_amdgcn_mfma_f32_16x16x32_bf16(k0, qf[mt][0], z, 0, 0, 0); z = __builtin_amdgcn_mfma_f32_16x16x32_bf16(k1, qf[mt][1], z, 0, 0, 0); st[kb] = z; }
;         float mx = sink;
; #pragma unroll
;         for (int kb = 0; kb < 9; ++kb) {
;             const bool tile_ok = (n > 0) || (mt + kb >= 8);
; #pragma unroll
;             for (int i = 0; i < 4; ++i) { const bool ok = tile_ok && (kb == 0 ? lo_ok[i] : (kb == 8 ? !lo_ok[i] : true));
;                 st[kb][i] = ok ? st[kb][i] : -INFINITY; mx = fmaxf(mx, st[kb][i]); }
;         }
;         mx = fmaxf(mx, __shfl_xor(mx, 16)); mx = fmaxf(mx, __shfl_xor(mx, 32));
;         f32x4 ls4 = {0.f, 0.f, 0.f, 0.f};
; #pragma unroll
;         for (int kb = 0; kb < 9; ++kb) { f32x4 d = st[kb] - mx;
; #pragma unroll
;             for (int i = 0; i < 4; ++i) d[i] = __builtin_amdgcn_exp2f(d[i]);
;             st[kb] = d; ls4 = ls4 + d; }
;         float ls = (ls4[0] + ls4[1]) + (ls4[2] + ls4[3]);
;         ls += __shfl_xor(ls, 16); ls += __shfl_xor(ls, 32);
;         const float inv = 1.f / (ls + __builtin_amdgcn_exp2f(sink - mx));
;         f32x4 o[4];
; #pragma unroll
;         for (int dt = 0; dt < 4; ++dt) o[dt] = (f32x4){0.f, 0.f, 0.f, 0.f};
; #pragma unroll
;         for (int kp = 0; kp < 5; ++kp) {
;             v4u pw; pw.x = cvt_pk_bf16(st[2 * kp][0], st[2 * kp][1]); pw.y = cvt_pk_bf16(st[2 * kp][2], st[2 * kp][3]);
;             if (kp < 4) { pw.z = cvt_pk_bf16(st[(2 * kp + 1) % 9][0], st[(2 * kp + 1) % 9][1]); pw.w = cvt_pk_bf16(st[(2 * kp + 1) % 9][2], st[(2 * kp + 1) % 9][3]); } else { pw.z = 0u; pw.w = 0u; }
;             const bf16x8_t pb = __builtin_bit_cast(bf16x8_t, pw);
; #pragma unroll
;             for (int dt = 0; dt < 4; ++dt) { const LAS unsigned char* vp = lds + ATT_VOFF + (16 * dt + fr) * ATT_VP + (16 * (mt + 2 * kp) + 4 * fq) * 2;
;                 const v2u lo = *(const LAS v2u*)vp; v2u hi = {0u, 0u}; if (kp < 4) hi = *(const LAS v2u*)(vp + 32);
	v_mfma_f32_16x16x32_bf16 v[14:17], v[14:17], v[6:9], v[10:13]
	ds_read_b128 v[30:33], v179 offset:25344
	ds_read_b128 v[34:37], v179 offset:27648
	ds_read_b128 v[38:41], v179 offset:29952
	ds_read_b128 v[10:13], v179 offset:18496
	s_waitcnt lgkmcnt(6)
	v_mfma_f32_16x16x32_bf16 v[18:21], v[18:21], v[2:5], 0
	ds_read_b128 v[42:45], v179 offset:32256
	ds_read_b128 v[46:49], v179 offset:34560
	v_mov_b32_e32 v128, v52
	v_mov_b32_e32 v129, v53
	s_nop 1
	v_permlane16_swap_b32_e32 v126, v128
	v_permlane16_swap_b32_e32 v127, v129
	global_store_dwordx4 v[118:119], v[126:129], off offset:64
	s_waitcnt lgkmcnt(2)
	v_mfma_f32_16x16x32_bf16 v[18:21], v[10:13], v[6:9], v[18:21]
	ds_read_b128 v[10:13], v179 offset:20800
	v_mfma_f32_16x16x32_bf16 v[22:25], v[22:25], v[2:5], 0
	s_waitcnt lgkmcnt(0)
	v_mfma_f32_16x16x32_bf16 v[22:25], v[10:13], v[6:9], v[22:25]
	ds_read_b128 v[10:13], v179 offset:23104
	v_mfma_f32_16x16x32_bf16 v[26:29], v[26:29], v[2:5], 0
	s_waitcnt lgkmcnt(0)
	v_mfma_f32_16x16x32_bf16 v[26:29], v[10:13], v[6:9], v[26:29]
	ds_read_b128 v[10:13], v179 offset:25408
	v_mfma_f32_16x16x32_bf16 v[30:33], v[30:33], v[2:5], 0
	s_waitcnt lgkmcnt(0)
	v_mfma_f32_16x16x32_bf16 v[30:33], v[10:13], v[6:9], v[30:33]
	ds_read_b128 v[10:13], v179 offset:27712
	v_mfma_f32_16x16x32_bf16 v[34:37], v[34:37], v[2:5], 0
	s_waitcnt lgkmcnt(0)
	v_mfma_f32_16x16x32_bf16 v[34:37], v[10:13], v[6:9], v[34:37]
	ds_read_b128 v[10:13], v179 offset:30016
	v_mfma_f32_16x16x32_bf16 v[38:41], v[38:41], v[2:5], 0
	s_waitcnt lgkmcnt(0)
	v_mfma_f32_16x16x32_bf16 v[38:41], v[10:13], v[6:9], v[38:41]
	ds_read_b128 v[10:13], v179 offset:32320
	v_mfma_f32_16x16x32_bf16 v[42:45], v[42:45], v[2:5], 0
	s_waitcnt lgkmcnt(0)
	v_mfma_f32_16x16x32_bf16 v[10:13], v[10:13], v[6:9], v[42:45]
	s_nop 5
	ds_read_b128 v[42:45], v179 offset:34624
	v_mfma_f32_16x16x32_bf16 v[2:5], v[46:49], v[2:5], 0
	s_waitcnt lgkmcnt(0)
	v_mfma_f32_16x16x32_bf16 v[2:5], v[42:45], v[6:9], v[2:5]
	v_cndmask_b32_e64 v7, v15, v191, s[8:9]
	v_cndmask_b32_e64 v6, v191, v14, s[18:19]
	v_cndmask_b32_e64 v7, v191, v7, s[14:15]
	v_max3_f32 v8, v71, v6, v7
	v_cndmask_b32_e64 v9, v191, v16, s[16:17]
	v_cndmask_b32_e64 v14, v191, v17, s[20:21]
	v_max3_f32 v8, v8, v9, v14
	v_max3_f32 v8, v8, v18, v19
	v_max3_f32 v8, v8, v20, v21
	v_max3_f32 v8, v8, v22, v23
	v_max3_f32 v8, v8, v24, v25
	v_max3_f32 v8, v8, v26, v27
	v_max3_f32 v8, v8, v28, v29
	v_max3_f32 v8, v8, v30, v31
	v_max3_f32 v8, v8, v32, v33
	v_max3_f32 v8, v8, v34, v35
	v_max3_f32 v8, v8, v36, v37
	v_max3_f32 v8, v8, v38, v39
	v_max3_f32 v8, v8, v40, v41
	v_max3_f32 v8, v8, v10, v11
	v_max3_f32 v8, v8, v12, v13
	v_cndmask_b32_e64 v60, v2, v191, s[6:7]
	v_cndmask_b32_e64 v61, v191, v3, s[8:9]
	v_max3_f32 v2, v8, v60, v61
	v_cndmask_b32_e64 v71, v4, v191, s[10:11]
	v_cndmask_b32_e64 v72, v5, v191, s[12:13]
	v_max3_f32 v2, v2, v71, v72
	ds_bpermute_b32 v3, v65, v2
	s_waitcnt lgkmcnt(0)
	v_max_f32_e32 v3, v3, v3
	v_max_f32_e32 v2, v2, v3
	ds_bpermute_b32 v3, v66, v2
	s_waitcnt lgkmcnt(0)
	v_max_f32_e32 v3, v3, v3
	v_max_f32_e32 v73, v2, v3
	v_sub_f32_e32 v3, v14, v73
	v_sub_f32_e32 v4, v9, v73
	v_sub_f32_e32 v7, v7, v73
	v_sub_f32_e32 v2, v6, v73
	v_exp_f32_e32 v2, v2
	v_exp_f32_e32 v4, v4
	v_exp_f32_e32 v5, v3
	v_exp_f32_e32 v3, v7
	v_sub_f32_e32 v17, v21, v73
	v_sub_f32_e32 v16, v20, v73
	v_sub_f32_e32 v15, v19, v73
	v_sub_f32_e32 v14, v18, v73
	v_exp_f32_e32 v14, v14
	v_exp_f32_e32 v15, v15
	v_exp_f32_e32 v16, v16
	v_exp_f32_e32 v17, v17
	v_sub_f32_e32 v18, v25, v73
	v_sub_f32_e32 v19, v24, v73
	v_sub_f32_e32 v20, v23, v73
	v_sub_f32_e32 v21, v22, v73
	v_exp_f32_e32 v42, v21
	v_exp_f32_e32 v44, v19
	v_exp_f32_e32 v45, v18
	v_exp_f32_e32 v43, v20
	v_sub_f32_e32 v18, v29, v73
	v_sub_f32_e32 v19, v28, v73
	v_sub_f32_e32 v20, v27, v73
	v_sub_f32_e32 v21, v26, v73
	v_exp_f32_e32 v28, v21
	v_exp_f32_e32 v29, v20
	v_exp_f32_e32 v46, v19
	v_exp_f32_e32 v47, v18
	v_sub_f32_e32 v18, v33, v73
	v_sub_f32_e32 v19, v32, v73
	v_sub_f32_e32 v20, v31, v73
	v_sub_f32_e32 v21, v30, v73
	v_pk_add_f32 v[6:7], v[4:5], 0 op_sel_hi:[1,0]
	v_pk_add_f32 v[8:9], v[2:3], 0 op_sel_hi:[1,0]
	v_exp_f32_e32 v48, v21
	v_exp_f32_e32 v50, v19
	v_exp_f32_e32 v51, v18
	v_exp_f32_e32 v49, v20
	v_pk_add_f32 v[8:9], v[14:15], v[8:9]
	v_pk_add_f32 v[6:7], v[16:17], v[6:7]
	v_pk_add_f32 v[8:9], v[42:43], v[8:9]
	v_pk_add_f32 v[6:7], v[44:45], v[6:7]
	v_pk_add_f32 v[8:9], v[28:29], v[8:9]
	v_pk_add_f32 v[6:7], v[46:47], v[6:7]
	v_sub_f32_e32 v20, v34, v73
	v_pk_add_f32 v[18:19], v[50:51], v[6:7]
	v_pk_add_f32 v[6:7], v[48:49], v[8:9]
	v_sub_f32_e32 v9, v35, v73
	v_sub_f32_e32 v8, v37, v73
	v_exp_f32_e32 v53, v9
	v_sub_f32_e32 v9, v36, v73
	v_exp_f32_e32 v52, v20
	v_exp_f32_e32 v54, v9
	v_exp_f32_e32 v55, v8
	v_sub_f32_e32 v22, v41, v73
	v_sub_f32_e32 v23, v40, v73
	v_sub_f32_e32 v24, v39, v73
	v_sub_f32_e32 v25, v38, v73
	v_exp_f32_e32 v38, v23
	v_exp_f32_e32 v39, v22
	v_exp_f32_e32 v40, v25
	v_exp_f32_e32 v41, v24
	v_pk_add_f32 v[20:21], v[52:53], v[6:7]
	v_pk_add_f32 v[18:19], v[54:55], v[18:19]
	v_cvt_pk_bf16_f32 v2, v2, v3
	v_cvt_pk_bf16_f32 v3, v4, v5
	v_cvt_pk_bf16_f32 v4, v14, v15
	v_cvt_pk_bf16_f32 v5, v16, v17
	ds_read2_b64 v[6:9], v67 offset0:28 offset1:32
	ds_read2_b64 v[14:17], v68 offset0:60 offset1:64
	v_pk_add_f32 v[56:57], v[38:39], v[18:19]
	v_pk_add_f32 v[58:59], v[40:41], v[20:21]
	ds_read2_b64 v[18:21], v70 offset0:92 offset1:96
	ds_read2_b64 v[22:25], v69 offset0:124 offset1:128
	v_sub_f32_e32 v12, v12, v73
	v_sub_f32_e32 v11, v11, v73
	v_sub_f32_e32 v10, v10, v73
	v_sub_f32_e32 v74, v13, v73
	v_cvt_pk_bf16_f32 v26, v42, v43
	v_cvt_pk_bf16_f32 v27, v44, v45
	v_cvt_pk_bf16_f32 v28, v28, v29
	v_cvt_pk_bf16_f32 v29, v46, v47
	ds_read2_b64 v[30:33], v67 offset0:36 offset1:40
	v_exp_f32_e32 v42, v10
	v_exp_f32_e32 v43, v11
	v_exp_f32_e32 v44, v12
	ds_read2_b64 v[10:13], v70 offset0:100 offset1:104
	s_waitcnt lgkmcnt(5)
; __device__ __forceinline__ unsigned cvt_pk_bf16(float lo, float hi) { unsigned r; asm volatile("v_cvt_pk_bf16_f32 %0, %1, %2" : "=v"(r) : "v"(lo), "v"(hi)); return r; }
; #define LAS __attribute__((address_space(3)))
; __device__ __forceinline__ void attn_unit(LAS unsigned char* lds, bf16* Q, const bf16* Kg, const bf16* Vg, const float* snk, int unit, int tid) {
;     ...
; #pragma unroll
;         for (int kp = 0; kp < 5; ++kp) {
;             v4u pw; pw.x = cvt_pk_bf16(st[2 * kp][0], st[2 * kp][1]); pw.y = cvt_pk_bf16(st[2 * kp][2], st[2 * kp][3]);
;             if (kp < 4) { pw.z = cvt_pk_bf16(st[(2 * kp + 1) % 9][0], st[(2 * kp + 1) % 9][1]); pw.w = cvt_pk_bf16(st[(2 * kp + 1) % 9][2], st[(2 * kp + 1) % 9][3]); } else { pw.z = 0u; pw.w = 0u; }
;             const bf16x8_t pb = __builtin_bit_cast(bf16x8_t, pw);
; #pragma unroll
;             for (int dt = 0; dt < 4; ++dt) { const LAS unsigned char* vp = lds + ATT_VOFF + (16 * dt + fr) * ATT_VP + (16 * (mt + 2 * kp) + 4 * fq) * 2;
;                 const v2u lo = *(const LAS v2u*)vp; v2u hi = {0u, 0u}; if (kp < 4) hi = *(const LAS v2u*)(vp + 32);
;                 v4u aw; aw.x = lo.x; aw.y = lo.y; aw.z = hi.x; aw.w = hi.y;
;                 o[dt] = __builtin_amdgcn_mfma_f32_16x16x32_bf16(__builtin_bit_cast(bf16x8_t, aw), pb, o[dt], 0, 0, 0); }
;         }
; #pragma unroll
;         for (int dt = 0; dt < 4; ++dt) { const f32x4 y = o[dt] * inv; v2u w; w.x = cvt_pk_bf16(y[0], y[1]); w.y = cvt_pk_bf16(y[2], y[3]); *(v2u*)(qbase + (size_t)mt * 16 * 1024 + 16 * dt + 4 * fq) = w; }
;     }
;     __syncthreads();
	v_mfma_f32_16x16x32_bf16 v[6:9], v[6:9], v[2:5], 0
	ds_read2_b64 v[34:37], v68 offset0:68 offset1:72
	v_exp_f32_e32 v45, v74
	v_pk_add_f32 v[46:47], v[42:43], v[58:59]
	s_waitcnt lgkmcnt(5)
	v_mfma_f32_16x16x32_bf16 v[14:17], v[14:17], v[2:5], 0
	s_waitcnt lgkmcnt(4)
	v_mfma_f32_16x16x32_bf16 v[18:21], v[18:21], v[2:5], 0
	s_waitcnt lgkmcnt(3)
	v_mfma_f32_16x16x32_bf16 v[2:5], v[22:25], v[2:5], 0
	ds_read2_b64 v[22:25], v69 offset0:132 offset1:136
	s_waitcnt lgkmcnt(3)
	v_mfma_f32_16x16x32_bf16 v[6:9], v[30:33], v[26:29], v[6:9]
	v_cvt_pk_bf16_f32 v30, v48, v49
	v_cvt_pk_bf16_f32 v31, v50, v51
	v_cvt_pk_bf16_f32 v32, v52, v53
	v_cvt_pk_bf16_f32 v33, v54, v55
	s_waitcnt lgkmcnt(2)
	v_mfma_f32_16x16x32_bf16 v[10:13], v[10:13], v[26:29], v[18:21]
	v_sub_f32_e32 v51, v72, v73
	v_sub_f32_e32 v52, v71, v73
	v_sub_f32_e32 v53, v61, v73
	ds_read2_b64 v[18:21], v68 offset0:76 offset1:80
	s_waitcnt lgkmcnt(2)
	v_mfma_f32_16x16x32_bf16 v[14:17], v[34:37], v[26:29], v[14:17]
	ds_read2_b64 v[34:37], v67 offset0:44 offset1:48
	v_pk_add_f32 v[48:49], v[44:45], v[56:57]
	s_waitcnt lgkmcnt(2)
	v_mfma_f32_16x16x32_bf16 v[2:5], v[22:25], v[26:29], v[2:5]
	ds_read2_b64 v[22:25], v70 offset0:108 offset1:112
	v_sub_f32_e32 v26, v60, v73
	v_exp_f32_e32 v50, v26
	s_waitcnt lgkmcnt(2)
	v_mfma_f32_16x16x32_bf16 v[14:17], v[18:21], v[30:33], v[14:17]
	ds_read2_b64 v[18:21], v69 offset0:140 offset1:144
	v_cvt_pk_bf16_f32 v26, v40, v41
	v_cvt_pk_bf16_f32 v27, v38, v39
	v_cvt_pk_bf16_f32 v28, v42, v43
	v_cvt_pk_bf16_f32 v29, v44, v45
	s_waitcnt lgkmcnt(1)
	v_mfma_f32_16x16x32_bf16 v[10:13], v[22:25], v[30:33], v[10:13]
	ds_read2_b64 v[22:25], v68 offset0:84 offset1:88
	v_exp_f32_e32 v38, v52
	v_exp_f32_e32 v39, v51
	v_mfma_f32_16x16x32_bf16 v[6:9], v[34:37], v[30:33], v[6:9]
	ds_read2_b64 v[34:37], v67 offset0:52 offset1:56
	v_exp_f32_e32 v51, v53
	s_waitcnt lgkmcnt(2)
	v_mfma_f32_16x16x32_bf16 v[2:5], v[18:21], v[30:33], v[2:5]
	ds_read2_b64 v[18:21], v70 offset0:116 offset1:120
	v_pk_add_f32 v[30:31], v[38:39], v[48:49]
	v_pk_add_f32 v[32:33], v[50:51], v[46:47]
	s_waitcnt lgkmcnt(2)
	v_mfma_f32_16x16x32_bf16 v[14:17], v[22:25], v[26:29], v[14:17]
	ds_read2_b64 v[22:25], v69 offset0:148 offset1:152
	s_waitcnt lgkmcnt(2)
	v_mfma_f32_16x16x32_bf16 v[6:9], v[34:37], v[26:29], v[6:9]
	v_pk_mov_b32 v[34:35], v[32:33], v[30:31] op_sel:[1,0]
	v_mov_b32_e32 v33, v31
	v_pk_add_f32 v[30:31], v[34:35], v[32:33]
	s_waitcnt lgkmcnt(1)
	v_mfma_f32_16x16x32_bf16 v[10:13], v[18:21], v[26:29], v[10:13]
	v_add_f32_e32 v30, v30, v31
	ds_bpermute_b32 v18, v65, v30
	v_mov_b32_e32 v20, v147
	s_waitcnt lgkmcnt(1)
	v_mfma_f32_16x16x32_bf16 v[2:5], v[22:25], v[26:29], v[2:5]
	v_mov_b32_e32 v24, v147
	v_mov_b32_e32 v25, v147
	s_waitcnt lgkmcnt(0)
	v_add_f32_e32 v36, v30, v18
	v_cvt_pk_bf16_f32 v18, v50, v51
	v_cvt_pk_bf16_f32 v19, v38, v39
	ds_read_b64 v[22:23], v180 offset:37344
	ds_read_b64 v[26:27], v180 offset:45792
	v_mov_b32_e32 v21, v147
	v_mov_b32_e32 v28, v147
	v_mov_b32_e32 v29, v147
	s_waitcnt lgkmcnt(1)
	v_mfma_f32_16x16x32_bf16 v[6:9], v[22:25], v[18:21], v[6:9]
	ds_bpermute_b32 v22, v66, v36
	v_fma_f32 v23, v64, s62, -v73
	v_exp_f32_e32 v23, v23
	ds_read_b64 v[30:31], v180 offset:54240
	ds_read_b64 v[34:35], v180 offset:62688
	v_mov_b32_e32 v32, v147
	s_waitcnt lgkmcnt(2)
	v_add_f32_e32 v22, v36, v22
	v_add_f32_e32 v22, v23, v22
	v_mov_b32_e32 v33, v147
	v_mov_b32_e32 v36, v147
	v_mov_b32_e32 v37, v147
	v_div_scale_f32 v23, s[14:15], v22, v22, 1.0
	v_rcp_f32_e32 v24, v23
	v_mfma_f32_16x16x32_bf16 v[14:17], v[26:29], v[18:21], v[14:17]
	s_waitcnt lgkmcnt(1)
	v_mfma_f32_16x16x32_bf16 v[10:13], v[30:33], v[18:21], v[10:13]
	s_waitcnt lgkmcnt(0)
	v_mfma_f32_16x16x32_bf16 v[2:5], v[34:37], v[18:21], v[2:5]
	v_fma_f32 v18, -v23, v24, 1.0
	v_fmac_f32_e32 v24, v18, v24
	v_div_scale_f32 v18, vcc, 1.0, v22, 1.0
	v_mul_f32_e32 v19, v18, v24
	v_fma_f32 v20, -v23, v19, v18
	v_fmac_f32_e32 v19, v20, v24
	v_fma_f32 v18, -v23, v19, v18
	v_div_fmas_f32 v18, v18, v24, v19
	v_div_fixup_f32 v18, v18, v22, 1.0
	v_pk_mul_f32 v[8:9], v[18:19], v[8:9] op_sel_hi:[0,1]
	v_pk_mul_f32 v[6:7], v[18:19], v[6:7] op_sel_hi:[0,1]
	v_cvt_pk_bf16_f32 v6, v6, v7
	v_cvt_pk_bf16_f32 v7, v8, v9
	v_add_co_u32_e32 v8, vcc, s59, v62
	v_pk_mul_f32 v[14:15], v[18:19], v[14:15] op_sel_hi:[0,1]
	s_nop 0
	v_addc_co_u32_e32 v9, vcc, 0, v63, vcc
	v_lshrrev_b32_e32 v110, 4, v0
	v_and_b32_e32 v110, 1, v110
	v_mul_u32_u24_e32 v110, 24, v110
	v_mov_b32_e32 v111, 0
	v_lshl_add_u64 v[118:119], v[8:9], 0, v[110:111]
	v_mov_b32_e32 v114, v6
	v_mov_b32_e32 v115, v7
	v_pk_mul_f32 v[6:7], v[18:19], v[16:17] op_sel_hi:[0,1]
	v_pk_mul_f32 v[10:11], v[18:19], v[10:11] op_sel_hi:[0,1]
	v_pk_mul_f32 v[2:3], v[18:19], v[2:3] op_sel_hi:[0,1]
	v_cvt_pk_bf16_f32 v14, v14, v15
	v_cvt_pk_bf16_f32 v15, v6, v7
	v_mov_b32_e32 v116, v14
	v_mov_b32_e32 v117, v15
	s_nop 1
	v_permlane16_swap_b32_e32 v114, v116
	v_permlane16_swap_b32_e32 v115, v117
	global_store_dwordx4 v[118:119], v[114:117], off
	v_pk_mul_f32 v[6:7], v[18:19], v[12:13] op_sel_hi:[0,1]
	v_cvt_pk_bf16_f32 v10, v10, v11
	v_cvt_pk_bf16_f32 v11, v6, v7
	v_mov_b32_e32 v126, v10
	v_mov_b32_e32 v127, v11
	v_pk_mul_f32 v[4:5], v[18:19], v[4:5] op_sel_hi:[0,1]
	v_cvt_pk_bf16_f32 v2, v2, v3
	v_cvt_pk_bf16_f32 v3, v4, v5
	v_mov_b32_e32 v128, v2
	v_mov_b32_e32 v129, v3
	s_nop 1
	v_permlane16_swap_b32_e32 v126, v128
	v_permlane16_swap_b32_e32 v127, v129
	global_store_dwordx4 v[118:119], v[126:129], off offset:64
	s_barrier

; #define LAS __attribute__((address_space(3)))
; __device__ __forceinline__ void attn_unit(LAS unsigned char* lds, bf16* Q, const bf16* Kg, const bf16* Vg, const float* snk, int unit, int tid) {
;     ...
;     for (int i = 0; i < 2; ++i) { const int idx = tid + 512 * i, j = (idx >> 3) * 2, c = idx & 7, p = n * 128 - 128 + j;
;         v4u w0 = zero4, w1 = zero4;
;         if (p >= 0) { w0 = *(const v4u*)(Vg + (size_t)(b * SEQ + p) * 128 + h * 64 + c * 8); w1 = *(const v4u*)(Vg + (size_t)(b * SEQ + p + 1) * 128 + h * 64 + c * 8); }
;         const unsigned A0[4] = {w0.x, w0.y, w0.z, w0.w}, A1[4] = {w1.x, w1.y, w1.z, w1.w};
; #pragma unroll
;         for (int e = 0; e < 8; ++e) { const unsigned lo = (e & 1) ? (A0[e >> 1] >> 16) : (A0[e >> 1] & 0xffffu), hi = (e & 1) ? (A1[e >> 1] & 0xffff0000u) : (A1[e >> 1] << 16);
;             *(LAS unsigned*)(lds + ATT_VOFF + (8 * c + e) * ATT_VP + j * 2) = lo | hi; } }
;     __syncthreads();
;     const float sink = snk[hq] * 1.4426950408889634f;
;     bool lo_ok[4];
; #pragma unroll
;     for (int i = 0; i < 4; ++i) lo_ok[i] = (4 * fq + i - fr) > 0;
; #pragma unroll
;     for (int mt = 0; mt < 8; ++mt) {
;         f32x4 st[9];
; #pragma unroll
;         for (int kb = 0; kb < 9; ++kb) { const LAS unsigned char* kp = lds + (16 * (mt + kb) + fr) * ATT_KP + 16 * fq;
;             const bf16x8_t k0 = *(const LAS bf16x8_t*)kp, k1 = *(const LAS bf16x8_t*)(kp + 64);
;             f32x4 z = {0.f, 0.f, 0.f, 0.f}; z = __builtin_amdgcn_mfma_f32_16x16x32_bf16(k0, qf[mt][0], z, 0, 0, 0); z = __builtin_amdgcn_mfma_f32_16x16x32_bf16(k1, qf[mt][1], z, 0, 0, 0); st[kb] = z; }
;         float mx = sink;
; #pragma unroll
;         for (int kb = 0; kb < 9; ++kb) {
;             const bool tile_ok = (n > 0) || (mt + kb >= 8);
; #pragma unroll
;             for (int i = 0; i < 4; ++i) { const bool ok = tile_ok && (kb == 0 ? lo_ok[i] : (kb == 8 ? !lo_ok[i] : true));
;                 st[kb][i] = ok ? st[kb][i] : -INFINITY; mx = fmaxf(mx, st[kb][i]); }
;         }
;         mx = fmaxf(mx, __shfl_xor(mx, 16)); mx = fmaxf(mx, __shfl_xor(mx, 32));
.LBB0_1396:
	s_or_b64 exec, exec, s[16:17]
	s_waitcnt vmcnt(0)
	v_lshlrev_b32_e32 v74, 16, v66
	v_and_or_b32 v74, v70, s60, v74
	v_lshrrev_b32_e32 v70, 16, v70
	v_and_or_b32 v66, v66, s59, v70
	v_add_u32_e32 v70, 0x9000, v188
	ds_write2_b32 v70, v74, v66 offset1:132
	v_lshlrev_b32_e32 v66, 16, v67
	v_lshrrev_b32_e32 v70, 16, v71
	v_and_or_b32 v66, v71, s60, v66
	v_and_or_b32 v67, v67, s59, v70
	v_add_u32_e32 v70, 0x9400, v188
	ds_write2_b32 v70, v66, v67 offset0:8 offset1:140
	v_lshlrev_b32_e32 v66, 16, v68
	v_lshrrev_b32_e32 v67, 16, v72
	v_and_or_b32 v66, v72, s60, v66
	v_and_or_b32 v67, v68, s59, v67
	v_add_u32_e32 v68, 0x9800, v188
	ds_write2_b32 v68, v66, v67 offset0:16 offset1:148
	v_lshlrev_b32_e32 v66, 16, v69
	v_lshrrev_b32_e32 v67, 16, v73
	v_and_or_b32 v66, v73, s60, v66
	v_and_or_b32 v67, v69, s59, v67
	v_add_u32_e32 v68, 0x9c00, v188
	ds_write2_b32 v68, v66, v67 offset0:24 offset1:156
	s_waitcnt lgkmcnt(0)
	s_barrier
	ds_read_b128 v[66:69], v178
	ds_read_b128 v[70:73], v178 offset:64
	s_waitcnt lgkmcnt(1)
	v_mfma_f32_16x16x32_bf16 v[66:69], v[66:69], v[62:65], 0
	ds_read_b128 v[80:83], v178 offset:2304
	ds_read_b128 v[84:87], v178 offset:4608
	ds_read_b128 v[88:91], v178 offset:6912
	s_waitcnt lgkmcnt(3)
	v_mfma_f32_16x16x32_bf16 v[66:69], v[70:73], v[58:61], v[66:69]
	ds_read_b128 v[70:73], v178 offset:2368
	ds_read_b128 v[92:95], v178 offset:9216
	ds_read_b128 v[96:99], v178 offset:11520
	s_waitcnt lgkmcnt(5)
	v_mfma_f32_16x16x32_bf16 v[80:83], v[80:83], v[62:65], 0
	ds_read_b128 v[100:103], v178 offset:13824
	v_ashrrev_i32_e32 v79, 31, v78
	s_cmp_lg_u32 s63, 0
	s_waitcnt lgkmcnt(3)
	v_mfma_f32_16x16x32_bf16 v[72:75], v[70:73], v[58:61], v[80:83]
	v_lshl_add_u64 v[70:71], v[78:79], 2, s[28:29]
	s_cselect_b64 s[16:17], -1, 0
	s_and_b64 s[20:21], s[16:17], s[8:9]
	ds_read_b128 v[80:83], v178 offset:4672
	v_mfma_f32_16x16x32_bf16 v[84:87], v[84:87], v[62:65], 0
	s_and_b64 s[18:19], s[16:17], s[12:13]
	s_and_b64 s[22:23], s[16:17], s[14:15]
	v_cndmask_b32_e64 v68, v190, v68, s[18:19]
	s_waitcnt lgkmcnt(0)
	v_mfma_f32_16x16x32_bf16 v[80:83], v[80:83], v[58:61], v[84:87]
	s_nop 2
	ds_read_b128 v[84:87], v178 offset:6976
	v_cndmask_b32_e64 v69, v190, v69, s[22:23]
	s_cmp_eq_u32 s63, 0
	v_mfma_f32_16x16x32_bf16 v[88:91], v[88:91], v[62:65], 0
	s_nop 0
	v_cndmask_b32_e64 v78, v190, v80, s[16:17]
	v_cndmask_b32_e64 v79, v190, v81, s[16:17]
	v_cndmask_b32_e64 v80, v190, v82, s[16:17]
	s_waitcnt lgkmcnt(0)
	v_mfma_f32_16x16x32_bf16 v[84:87], v[84:87], v[58:61], v[88:91]
	v_cndmask_b32_e64 v81, v190, v83, s[16:17]
	s_nop 1
	ds_read_b128 v[88:91], v178 offset:9280
	v_mov_b32_e32 v157, v147
	v_mfma_f32_16x16x32_bf16 v[92:95], v[92:95], v[62:65], 0
	s_nop 1
	v_cndmask_b32_e64 v82, v190, v84, s[16:17]
	v_cndmask_b32_e64 v83, v190, v85, s[16:17]
	v_cndmask_b32_e64 v84, v190, v86, s[16:17]
	s_waitcnt lgkmcnt(0)
	v_mfma_f32_16x16x32_bf16 v[88:91], v[88:91], v[58:61], v[92:95]
	v_cndmask_b32_e64 v85, v190, v87, s[16:17]
	s_nop 1
	ds_read_b128 v[92:95], v178 offset:11584
	s_nop 3
	v_cndmask_b32_e64 v86, v190, v88, s[16:17]
	v_mfma_f32_16x16x32_bf16 v[96:99], v[96:99], v[62:65], 0
	v_cndmask_b32_e64 v87, v190, v89, s[16:17]
	v_cndmask_b32_e64 v88, v190, v90, s[16:17]
	v_cndmask_b32_e64 v89, v190, v91, s[16:17]
	s_waitcnt lgkmcnt(0)
	v_mfma_f32_16x16x32_bf16 v[92:95], v[92:95], v[58:61], v[96:99]
	s_nop 2
	ds_read_b128 v[96:99], v178 offset:16128
	ds_read_b128 v[104:107], v178 offset:13888
	ds_read_b128 v[108:111], v178 offset:18432
	ds_read_b128 v[112:115], v178 offset:16192
	ds_read_b128 v[116:119], v178 offset:18496
	v_mfma_f32_16x16x32_bf16 v[100:103], v[100:103], v[62:65], 0
	s_waitcnt lgkmcnt(4)
	v_mfma_f32_16x16x32_bf16 v[96:99], v[96:99], v[62:65], 0
	s_waitcnt lgkmcnt(2)
	v_mfma_f32_16x16x32_bf16 v[108:111], v[108:111], v[62:65], 0
	global_load_dword v64, v[70:71], off offset:64
	v_and_b32_e32 v63, 64, v189
	v_xor_b32_e32 v62, 16, v189
	v_add_u32_e32 v63, 64, v63
	v_cmp_lt_i32_e32 vcc, v62, v63
	v_cndmask_b32_e64 v70, v190, v72, s[16:17]
	v_cndmask_b32_e64 v72, v190, v73, s[16:17]
	v_cndmask_b32_e32 v62, v189, v62, vcc
	v_lshlrev_b32_e32 v65, 2, v62
	v_cndmask_b32_e64 v62, v67, v190, s[10:11]
	v_cndmask_b32_e64 v62, v190, v62, s[16:17]
	v_cndmask_b32_e64 v67, v190, v66, s[20:21]
	v_cndmask_b32_e64 v73, v190, v74, s[16:17]
	v_cndmask_b32_e64 v74, v190, v75, s[16:17]
	v_mfma_f32_16x16x32_bf16 v[100:103], v[104:107], v[58:61], v[100:103]
	v_cndmask_b32_e64 v106, v190, v92, s[16:17]
	v_cndmask_b32_e64 v107, v190, v93, s[16:17]
	s_cselect_b64 vcc, -1, 0
	s_waitcnt lgkmcnt(1)
	v_mfma_f32_16x16x32_bf16 v[96:99], v[112:115], v[58:61], v[96:99]
	s_waitcnt vmcnt(0)
; #define LAS __attribute__((address_space(3)))
; __device__ __forceinline__ void attn_unit(LAS unsigned char* lds, bf16* Q, const bf16* Kg, const bf16* Vg, const float* snk, int unit, int tid) {
;     ...
;     for (int mt = 0; mt < 8; ++mt) { qf[mt][0] = *(const bf16x8_t*)(qbase + (size_t)mt * 16 * 1024 + 8 * fq); qf[mt][1] = *(const bf16x8_t*)(qbase + (size_t)mt * 16 * 1024 + 32 + 8 * fq); }
;     ...
;     const float sink = snk[hq] * 1.4426950408889634f;
;     bool lo_ok[4];
; #pragma unroll
;     for (int i = 0; i < 4; ++i) lo_ok[i] = (4 * fq + i - fr) > 0;
; #pragma unroll
;     for (int mt = 0; mt < 8; ++mt) {
;         f32x4 st[9];
; #pragma unroll
;         for (int kb = 0; kb < 9; ++kb) { const LAS unsigned char* kp = lds + (16 * (mt + kb) + fr) * ATT_KP + 16 * fq;
;             const bf16x8_t k0 = *(const LAS bf16x8_t*)kp, k1 = *(const LAS bf16x8_t*)(kp + 64);
;             f32x4 z = {0.f, 0.f, 0.f, 0.f}; z = __builtin_amdgcn_mfma_f32_16x16x32_bf16(k0, qf[mt][0], z, 0, 0, 0); z = __builtin_amdgcn_mfma_f32_16x16x32_bf16(k1, qf[mt][1], z, 0, 0, 0); st[kb] = z; }
;         float mx = sink;
; #pragma unroll
;         for (int kb = 0; kb < 9; ++kb) {
;             const bool tile_ok = (n > 0) || (mt + kb >= 8);
; #pragma unroll
;             for (int i = 0; i < 4; ++i) { const bool ok = tile_ok && (kb == 0 ? lo_ok[i] : (kb == 8 ? !lo_ok[i] : true));
;                 st[kb][i] = ok ? st[kb][i] : -INFINITY; mx = fmaxf(mx, st[kb][i]); }
;         }
;         mx = fmaxf(mx, __shfl_xor(mx, 16)); mx = fmaxf(mx, __shfl_xor(mx, 32));
;         f32x4 ls4 = {0.f, 0.f, 0.f, 0.f};
; #pragma unroll
;         for (int kb = 0; kb < 9; ++kb) { f32x4 d = st[kb] - mx;
; #pragma unroll
;             for (int i = 0; i < 4; ++i) d[i] = __builtin_amdgcn_exp2f(d[i]);
;             st[kb] = d; ls4 = ls4 + d; }
;         float ls = (ls4[0] + ls4[1]) + (ls4[2] + ls4[3]);
;         ls += __shfl_xor(ls, 16); ls += __shfl_xor(ls, 32);
;         const float inv = 1.f / (ls + __builtin_amdgcn_exp2f(sink - mx));
;         f32x4 o[4];
; #pragma unroll
;         for (int dt = 0; dt < 4; ++dt) o[dt] = (f32x4){0.f, 0.f, 0.f, 0.f};
; #pragma unroll
;         for (int kp = 0; kp < 5; ++kp) {
;             v4u pw; pw.x = cvt_pk_bf16(st[2 * kp][0], st[2 * kp][1]); pw.y = cvt_pk_bf16(st[2 * kp][2], st[2 * kp][3]);
	s_cselect_b32 s100, 1, 0
	s_and_b32 s98, s4, 4
	v_add_u32_e32 v254, s98, v165
	v_lshlrev_b32_e32 v254, 7, v254
	v_or_b32_e32 v254, v254, v168
	v_or_b32_e32 v254, v254, v170
	s_and_b32 s98, s24, 0x3f80
	v_lshl_or_b32 v252, s98, 11, v180
	v_mov_b32_e32 v253, 0
	v_lshl_add_u64 v[252:253], s[38:39], 0, v[252:253]
	v_mov_b32_e32 v255, 0
	v_lshl_add_u64 v[252:253], v[254:255], 1, v[252:253]
	global_load_dwordx4 v[198:201], v[252:253], off
	global_load_dwordx4 v[202:205], v[252:253], off offset:2048
	s_mov_b64 s[98:99], 0x8000
	v_lshl_add_u64 v[254:255], v[252:253], 0, s[98:99]
	global_load_dwordx4 v[206:209], v[254:255], off
	global_load_dwordx4 v[210:213], v[254:255], off offset:2048
	s_mov_b64 s[98:99], 0x10000
	v_lshl_add_u64 v[254:255], v[252:253], 0, s[98:99]
	global_load_dwordx4 v[138:141], v[254:255], off
	global_load_dwordx4 v[142:145], v[254:255], off offset:2048
	s_mov_b64 s[98:99], 0x18000
	v_lshl_add_u64 v[254:255], v[252:253], 0, s[98:99]
	global_load_dwordx4 v[130:133], v[254:255], off
	global_load_dwordx4 v[134:137], v[254:255], off offset:2048
	s_mov_b64 s[98:99], 0x20000
	v_lshl_add_u64 v[254:255], v[252:253], 0, s[98:99]
	global_load_dwordx4 v[214:217], v[254:255], off
	global_load_dwordx4 v[218:221], v[254:255], off offset:2048
	s_mov_b64 s[98:99], 0x28000
	v_lshl_add_u64 v[254:255], v[252:253], 0, s[98:99]
	global_load_dwordx4 v[222:225], v[254:255], off
	global_load_dwordx4 v[226:229], v[254:255], off offset:2048
	s_mov_b64 s[98:99], 0x30000
	v_lshl_add_u64 v[254:255], v[252:253], 0, s[98:99]
	global_load_dwordx4 v[230:233], v[254:255], off
	global_load_dwordx4 v[234:237], v[254:255], off offset:2048
	s_mov_b64 s[98:99], 0x38000
	v_lshl_add_u64 v[254:255], v[252:253], 0, s[98:99]
	global_load_dwordx4 v[248:251], v[254:255], off
	global_load_dwordx4 v[252:255], v[254:255], off offset:2048
	s_cmp_lg_u32 s100, 0
	v_mul_f32_e32 v71, 0x3fb8aa3b, v64
	v_max3_f32 v66, v71, v67, v62
	v_max3_f32 v66, v66, v68, v69
	v_max3_f32 v66, v66, v70, v72
	v_max3_f32 v66, v66, v73, v74
	v_max3_f32 v66, v66, v78, v79
	v_max3_f32 v66, v66, v80, v81
	v_max3_f32 v66, v66, v82, v83
	v_max3_f32 v66, v66, v84, v85
	v_max3_f32 v66, v66, v86, v87
	v_max3_f32 v66, v66, v88, v89
	s_waitcnt lgkmcnt(0)
	v_mfma_f32_16x16x32_bf16 v[58:61], v[116:119], v[58:61], v[108:111]
	v_max3_f32 v66, v66, v106, v107
	v_cndmask_b32_e64 v100, v190, v100, s[16:17]
	v_cndmask_b32_e64 v101, v190, v101, s[16:17]
	v_cndmask_b32_e64 v108, v190, v94, s[16:17]
	v_cndmask_b32_e64 v109, v190, v95, s[16:17]
	v_max3_f32 v66, v66, v108, v109
	v_max3_f32 v66, v66, v100, v101
	v_cndmask_b32_e64 v110, v190, v102, s[16:17]
	v_cndmask_b32_e64 v111, v190, v103, s[16:17]
	v_max3_f32 v66, v66, v110, v111
	v_cndmask_b32_e32 v116, v96, v190, vcc
	v_cndmask_b32_e32 v117, v97, v190, vcc
	v_max3_f32 v66, v66, v116, v117
	v_cndmask_b32_e32 v98, v98, v190, vcc
	v_cndmask_b32_e32 v99, v99, v190, vcc
	v_max3_f32 v66, v66, v98, v99
	v_cndmask_b32_e64 v120, v58, v190, s[8:9]
	v_cndmask_b32_e64 v121, v190, v59, s[10:11]
	v_max3_f32 v58, v66, v120, v121
	v_cndmask_b32_e64 v122, v60, v190, s[12:13]
	v_cndmask_b32_e64 v123, v61, v190, s[14:15]
	v_max3_f32 v58, v58, v122, v123
	ds_bpermute_b32 v59, v65, v58
	v_xor_b32_e32 v60, 32, v189
	v_cmp_lt_i32_e32 vcc, v60, v63
	s_waitcnt lgkmcnt(0)
	v_max_f32_e32 v59, v59, v59
	v_cndmask_b32_e32 v60, v189, v60, vcc
	v_lshlrev_b32_e32 v66, 2, v60
	v_max_f32_e32 v58, v58, v59
	ds_bpermute_b32 v59, v66, v58
	s_waitcnt lgkmcnt(0)
	v_max_f32_e32 v59, v59, v59
	v_max_f32_e32 v124, v58, v59
	v_sub_f32_e32 v59, v69, v124
	v_sub_f32_e32 v62, v62, v124
	v_sub_f32_e32 v58, v67, v124
	v_exp_f32_e32 v58, v58
	v_exp_f32_e32 v61, v59
	v_exp_f32_e32 v59, v62
	v_sub_f32_e32 v67, v74, v124
	v_sub_f32_e32 v74, v73, v124
	v_sub_f32_e32 v73, v72, v124
	v_sub_f32_e32 v70, v70, v124
	v_exp_f32_e32 v72, v70
	v_exp_f32_e32 v73, v73
	v_sub_f32_e32 v79, v79, v124
	v_sub_f32_e32 v78, v78, v124
	v_exp_f32_e32 v90, v78
	v_exp_f32_e32 v91, v79
	v_sub_f32_e32 v78, v83, v124
	v_sub_f32_e32 v79, v82, v124
	v_exp_f32_e32 v94, v79
	v_exp_f32_e32 v95, v78
	v_sub_f32_e32 v78, v87, v124
	v_sub_f32_e32 v79, v86, v124
	v_sub_f32_e32 v60, v68, v124
	v_pk_add_f32 v[68:69], v[58:59], 0 op_sel_hi:[1,0]
	v_exp_f32_e32 v102, v79
	v_exp_f32_e32 v103, v78
	v_exp_f32_e32 v75, v67
	v_sub_f32_e32 v67, v81, v124
	v_sub_f32_e32 v70, v80, v124
	v_pk_add_f32 v[68:69], v[72:73], v[68:69]
	v_exp_f32_e32 v60, v60
	v_exp_f32_e32 v92, v70
	v_exp_f32_e32 v93, v67
	v_pk_add_f32 v[68:69], v[90:91], v[68:69]
	v_sub_f32_e32 v67, v85, v124
	v_sub_f32_e32 v70, v84, v124
	v_exp_f32_e32 v74, v74
	v_exp_f32_e32 v96, v70
	v_exp_f32_e32 v97, v67
	v_sub_f32_e32 v67, v89, v124
	v_sub_f32_e32 v70, v88, v124
	v_pk_add_f32 v[68:69], v[94:95], v[68:69]
	v_exp_f32_e32 v104, v70
	v_exp_f32_e32 v105, v67
	v_pk_add_f32 v[82:83], v[102:103], v[68:69]
	v_sub_f32_e32 v67, v109, v124
	v_sub_f32_e32 v69, v107, v124
	v_sub_f32_e32 v70, v106, v124
	v_sub_f32_e32 v68, v108, v124
	v_exp_f32_e32 v106, v70
	v_exp_f32_e32 v107, v69
	v_exp_f32_e32 v109, v67
	v_sub_f32_e32 v67, v101, v124
	v_sub_f32_e32 v70, v100, v124
	v_pk_add_f32 v[62:63], v[60:61], 0 op_sel_hi:[1,0]
	v_exp_f32_e32 v108, v68
	v_sub_f32_e32 v68, v111, v124
	v_sub_f32_e32 v69, v110, v124
	v_exp_f32_e32 v110, v70
	v_exp_f32_e32 v111, v67
	v_add_u32_e32 v67, 0x9000, v179
	v_pk_add_f32 v[62:63], v[74:75], v[62:63]
	v_cvt_pk_bf16_f32 v58, v58, v59
	v_cvt_pk_bf16_f32 v59, v60, v61
	v_cvt_pk_bf16_f32 v60, v72, v73
	v_cvt_pk_bf16_f32 v61, v74, v75
	ds_read2_b64 v[72:75], v67 offset1:4
	v_exp_f32_e32 v112, v69
	v_exp_f32_e32 v113, v68
	v_add_u32_e32 v68, 0xb000, v179
	v_pk_add_f32 v[82:83], v[106:107], v[82:83]
	v_add_u32_e32 v70, 0xd000, v179
	v_add_u32_e32 v69, 0xf000, v179
	v_pk_add_f32 v[62:63], v[92:93], v[62:63]
	ds_read2_b64 v[78:81], v68 offset0:32 offset1:36
	v_pk_add_f32 v[114:115], v[110:111], v[82:83]
	ds_read2_b64 v[82:85], v70 offset0:64 offset1:68
	ds_read2_b64 v[86:89], v69 offset0:96 offset1:100
	v_pk_add_f32 v[62:63], v[96:97], v[62:63]
	v_cvt_pk_bf16_f32 v90, v90, v91
	v_cvt_pk_bf16_f32 v91, v92, v93
	v_cvt_pk_bf16_f32 v92, v94, v95
	v_cvt_pk_bf16_f32 v93, v96, v97
	ds_read2_b64 v[94:97], v67 offset0:8 offset1:12
	s_waitcnt lgkmcnt(4)
; __device__ __forceinline__ unsigned cvt_pk_bf16(float lo, float hi) { unsigned r; asm volatile("v_cvt_pk_bf16_f32 %0, %1, %2" : "=v"(r) : "v"(lo), "v"(hi)); return r; }
; #define LAS __attribute__((address_space(3)))
; __device__ __forceinline__ void attn_unit(LAS unsigned char* lds, bf16* Q, const bf16* Kg, const bf16* Vg, const float* snk, int unit, int tid) {
;     ...
;         for (int kb = 0; kb < 9; ++kb) { const LAS unsigned char* kp = lds + (16 * (mt + kb) + fr) * ATT_KP + 16 * fq;
;             const bf16x8_t k0 = *(const LAS bf16x8_t*)kp, k1 = *(const LAS bf16x8_t*)(kp + 64);
;             f32x4 z = {0.f, 0.f, 0.f, 0.f}; z = __builtin_amdgcn_mfma_f32_16x16x32_bf16(k0, qf[mt][0], z, 0, 0, 0); z = __builtin_amdgcn_mfma_f32_16x16x32_bf16(k1, qf[mt][1], z, 0, 0, 0); st[kb] = z; }
;     ...
;         float ls = (ls4[0] + ls4[1]) + (ls4[2] + ls4[3]);
;         ls += __shfl_xor(ls, 16); ls += __shfl_xor(ls, 32);
;         const float inv = 1.f / (ls + __builtin_amdgcn_exp2f(sink - mx));
;         f32x4 o[4];
; #pragma unroll
;         for (int dt = 0; dt < 4; ++dt) o[dt] = (f32x4){0.f, 0.f, 0.f, 0.f};
; #pragma unroll
;         for (int kp = 0; kp < 5; ++kp) {
;             v4u pw; pw.x = cvt_pk_bf16(st[2 * kp][0], st[2 * kp][1]); pw.y = cvt_pk_bf16(st[2 * kp][2], st[2 * kp][3]);
;             if (kp < 4) { pw.z = cvt_pk_bf16(st[(2 * kp + 1) % 9][0], st[(2 * kp + 1) % 9][1]); pw.w = cvt_pk_bf16(st[(2 * kp + 1) % 9][2], st[(2 * kp + 1) % 9][3]); } else { pw.z = 0u; pw.w = 0u; }
;             const bf16x8_t pb = __builtin_bit_cast(bf16x8_t, pw);
; #pragma unroll
;             for (int dt = 0; dt < 4; ++dt) { const LAS unsigned char* vp = lds + ATT_VOFF + (16 * dt + fr) * ATT_VP + (16 * (mt + 2 * kp) + 4 * fq) * 2;
;                 const v2u lo = *(const LAS v2u*)vp; v2u hi = {0u, 0u}; if (kp < 4) hi = *(const LAS v2u*)(vp + 32);
;                 v4u aw; aw.x = lo.x; aw.y = lo.y; aw.z = hi.x; aw.w = hi.y;
;                 o[dt] = __builtin_amdgcn_mfma_f32_16x16x32_bf16(__builtin_bit_cast(bf16x8_t, aw), pb, o[dt], 0, 0, 0); }
;         }
; #pragma unroll
;         for (int dt = 0; dt < 4; ++dt) { const f32x4 y = o[dt] * inv; v2u w; w.x = cvt_pk_bf16(y[0], y[1]); w.y = cvt_pk_bf16(y[2], y[3]); *(v2u*)(qbase + (size_t)mt * 16 * 1024 + 16 * dt + 4 * fq) = w; }
	v_mfma_f32_16x16x32_bf16 v[72:75], v[72:75], v[58:61], 0
	v_sub_f32_e32 v119, v99, v124
	v_sub_f32_e32 v118, v98, v124
	ds_read2_b64 v[98:101], v68 offset0:40 offset1:44
	s_waitcnt lgkmcnt(4)
	v_mfma_f32_16x16x32_bf16 v[78:81], v[78:81], v[58:61], 0
	v_add_f32_e64 v62, v104, v62
	v_add_f32_e64 v63, v105, v63
	v_sub_f32_e32 v117, v117, v124
	v_pk_add_f32 v[62:63], v[108:109], v[62:63]
	s_waitcnt lgkmcnt(3)
	v_mfma_f32_16x16x32_bf16 v[82:85], v[82:85], v[58:61], 0
	v_exp_f32_e32 v117, v117
	v_exp_f32_e32 v118, v118
	v_exp_f32_e32 v119, v119
	s_waitcnt lgkmcnt(2)
	v_mfma_f32_16x16x32_bf16 v[58:61], v[86:89], v[58:61], 0
	v_sub_f32_e32 v86, v116, v124
	v_exp_f32_e32 v116, v86
	ds_read2_b64 v[86:89], v70 offset0:72 offset1:76
	s_waitcnt lgkmcnt(2)
	v_mfma_f32_16x16x32_bf16 v[72:75], v[94:97], v[90:93], v[72:75]
	ds_read2_b64 v[94:97], v69 offset0:104 offset1:108
	v_pk_add_f32 v[62:63], v[112:113], v[62:63]
	s_waitcnt lgkmcnt(2)
	v_mfma_f32_16x16x32_bf16 v[78:81], v[98:101], v[90:93], v[78:81]
	v_cvt_pk_bf16_f32 v98, v102, v103
	v_cvt_pk_bf16_f32 v99, v104, v105
	v_cvt_pk_bf16_f32 v100, v106, v107
	v_cvt_pk_bf16_f32 v101, v108, v109
	s_waitcnt lgkmcnt(1)
	v_mfma_f32_16x16x32_bf16 v[82:85], v[86:89], v[90:93], v[82:85]
	ds_read2_b64 v[86:89], v68 offset0:48 offset1:52
	ds_read2_b64 v[102:105], v67 offset0:16 offset1:20
	v_pk_add_f32 v[106:107], v[116:117], v[114:115]
	s_waitcnt lgkmcnt(2)
	v_mfma_f32_16x16x32_bf16 v[58:61], v[94:97], v[90:93], v[58:61]
	ds_read2_b64 v[90:93], v70 offset0:80 offset1:84
	v_sub_f32_e32 v94, v120, v124
	v_exp_f32_e32 v108, v94
	s_waitcnt lgkmcnt(2)
	v_mfma_f32_16x16x32_bf16 v[78:81], v[86:89], v[98:101], v[78:81]
	ds_read2_b64 v[86:89], v69 offset0:112 offset1:116
	v_cvt_pk_bf16_f32 v94, v110, v111
	v_cvt_pk_bf16_f32 v95, v112, v113
	v_cvt_pk_bf16_f32 v96, v116, v117
	v_cvt_pk_bf16_f32 v97, v118, v119
	s_waitcnt lgkmcnt(1)
	v_mfma_f32_16x16x32_bf16 v[82:85], v[90:93], v[98:101], v[82:85]
	ds_read2_b64 v[90:93], v68 offset0:56 offset1:60
	v_sub_f32_e32 v109, v123, v124
	v_sub_f32_e32 v114, v122, v124
	s_waitcnt lgkmcnt(1)
	v_mfma_f32_16x16x32_bf16 v[58:61], v[86:89], v[98:101], v[58:61]
	ds_read2_b64 v[86:89], v70 offset0:88 offset1:92
	v_sub_f32_e32 v115, v121, v124
	v_exp_f32_e32 v110, v114
	s_waitcnt lgkmcnt(1)
	v_mfma_f32_16x16x32_bf16 v[78:81], v[90:93], v[94:97], v[78:81]
	ds_read2_b64 v[90:93], v69 offset0:120 offset1:124
	v_exp_f32_e32 v111, v109
	v_exp_f32_e32 v109, v115
	v_mfma_f32_16x16x32_bf16 v[72:75], v[102:105], v[98:101], v[72:75]
	ds_read2_b64 v[102:105], v67 offset0:24 offset1:28
	v_pk_add_f32 v[62:63], v[118:119], v[62:63]
	v_pk_add_f32 v[98:99], v[108:109], v[106:107]
	v_pk_add_f32 v[62:63], v[110:111], v[62:63]
	s_waitcnt lgkmcnt(2)
	v_mfma_f32_16x16x32_bf16 v[82:85], v[86:89], v[94:97], v[82:85]
	v_pk_mov_b32 v[100:101], v[98:99], v[62:63] op_sel:[1,0]
	v_mov_b32_e32 v99, v63
	v_pk_add_f32 v[62:63], v[100:101], v[98:99]
	s_waitcnt lgkmcnt(1)
	v_mfma_f32_16x16x32_bf16 v[58:61], v[90:93], v[94:97], v[58:61]
	v_cvt_pk_bf16_f32 v86, v108, v109
	v_cvt_pk_bf16_f32 v87, v110, v111
	ds_read_b64 v[90:91], v179 offset:37120
	v_add_f32_e32 v62, v62, v63
	ds_bpermute_b32 v63, v65, v62
	v_mov_b32_e32 v92, v147
	v_mov_b32_e32 v93, v147
	s_waitcnt lgkmcnt(2)
	v_mfma_f32_16x16x32_bf16 v[72:75], v[102:105], v[94:97], v[72:75]
	v_mov_b32_e32 v88, v147
	s_waitcnt lgkmcnt(0)
	v_add_f32_e32 v62, v62, v63
	v_mov_b32_e32 v89, v147
	ds_bpermute_b32 v63, v66, v62
	ds_read_b64 v[94:95], v179 offset:45568
	v_mfma_f32_16x16x32_bf16 v[72:75], v[90:93], v[86:89], v[72:75]
	v_fma_f32 v90, v64, s61, -v124
	v_exp_f32_e32 v90, v90
	s_waitcnt lgkmcnt(1)
	v_add_f32_e32 v62, v62, v63
	v_mov_b32_e32 v96, v147
	v_mov_b32_e32 v97, v147
	v_add_f32_e32 v90, v90, v62
	v_div_scale_f32 v91, s[68:69], v90, v90, 1.0
	v_rcp_f32_e32 v92, v91
	ds_read_b64 v[98:99], v179 offset:54016
	ds_read_b64 v[102:103], v179 offset:62464
	v_mov_b32_e32 v100, v147
	v_mov_b32_e32 v101, v147
	v_mov_b32_e32 v104, v147
	v_mov_b32_e32 v105, v147
	v_lshl_add_u64 v[62:63], v[76:77], 0, v[156:157]
	v_fma_f32 v76, -v91, v92, 1.0
	v_fmac_f32_e32 v92, v76, v92
	v_div_scale_f32 v76, vcc, 1.0, v90, 1.0
	v_mul_f32_e32 v77, v76, v92
	s_waitcnt lgkmcnt(2)
	v_mfma_f32_16x16x32_bf16 v[78:81], v[94:97], v[86:89], v[78:81]
	s_waitcnt lgkmcnt(1)
	v_mfma_f32_16x16x32_bf16 v[82:85], v[98:101], v[86:89], v[82:85]
	s_waitcnt lgkmcnt(0)
	v_mfma_f32_16x16x32_bf16 v[58:61], v[102:105], v[86:89], v[58:61]
	v_fma_f32 v86, -v91, v77, v76
	v_fmac_f32_e32 v77, v86, v92
	v_fma_f32 v76, -v91, v77, v76
	v_div_fmas_f32 v76, v76, v92, v77
	v_div_fixup_f32 v76, v76, v90, 1.0
	v_pk_mul_f32 v[74:75], v[76:77], v[74:75] op_sel_hi:[0,1]
	v_pk_mul_f32 v[72:73], v[76:77], v[72:73] op_sel_hi:[0,1]
	v_cvt_pk_bf16_f32 v72, v72, v73
	v_cvt_pk_bf16_f32 v73, v74, v75
	v_pk_mul_f32 v[74:75], v[76:77], v[78:79] op_sel_hi:[0,1]
	v_lshrrev_b32_e32 v110, 4, v0
	v_and_b32_e32 v110, 1, v110
	v_mul_u32_u24_e32 v110, 24, v110
	v_mov_b32_e32 v111, 0
	v_lshl_add_u64 v[118:119], v[62:63], 0, v[110:111]
	v_mov_b32_e32 v114, v72
	v_mov_b32_e32 v115, v73
	v_pk_mul_f32 v[72:73], v[76:77], v[80:81] op_sel_hi:[0,1]
	v_cvt_pk_bf16_f32 v74, v74, v75
	v_cvt_pk_bf16_f32 v75, v72, v73
	v_mov_b32_e32 v116, v74
	v_mov_b32_e32 v117, v75
	s_nop 1
	v_permlane16_swap_b32_e32 v114, v116
	v_permlane16_swap_b32_e32 v115, v117
	global_store_dwordx4 v[118:119], v[114:117], off
	v_pk_mul_f32 v[74:75], v[76:77], v[82:83] op_sel_hi:[0,1]
	v_pk_mul_f32 v[72:73], v[76:77], v[84:85] op_sel_hi:[0,1]
	v_cvt_pk_bf16_f32 v74, v74, v75
	v_cvt_pk_bf16_f32 v75, v72, v73
	v_pk_mul_f32 v[60:61], v[76:77], v[60:61] op_sel_hi:[0,1]
	v_pk_mul_f32 v[58:59], v[76:77], v[58:59] op_sel_hi:[0,1]
	v_mov_b32_e32 v126, v74
	v_mov_b32_e32 v127, v75
	v_cvt_pk_bf16_f32 v108, v58, v59
	v_cvt_pk_bf16_f32 v109, v60, v61
	ds_read_b128 v[58:61], v178 offset:2304
	ds_read_b128 v[72:75], v178 offset:2368
	s_waitcnt lgkmcnt(1)
; __device__ __forceinline__ unsigned cvt_pk_bf16(float lo, float hi) { unsigned r; asm volatile("v_cvt_pk_bf16_f32 %0, %1, %2" : "=v"(r) : "v"(lo), "v"(hi)); return r; }
; #define LAS __attribute__((address_space(3)))
; __device__ __forceinline__ void attn_unit(LAS unsigned char* lds, bf16* Q, const bf16* Kg, const bf16* Vg, const float* snk, int unit, int tid) {
;     ...
;         for (int kb = 0; kb < 9; ++kb) { const LAS unsigned char* kp = lds + (16 * (mt + kb) + fr) * ATT_KP + 16 * fq;
;             const bf16x8_t k0 = *(const LAS bf16x8_t*)kp, k1 = *(const LAS bf16x8_t*)(kp + 64);
;             f32x4 z = {0.f, 0.f, 0.f, 0.f}; z = __builtin_amdgcn_mfma_f32_16x16x32_bf16(k0, qf[mt][0], z, 0, 0, 0); z = __builtin_amdgcn_mfma_f32_16x16x32_bf16(k1, qf[mt][1], z, 0, 0, 0); st[kb] = z; }
;         float mx = sink;
; #pragma unroll
;         for (int kb = 0; kb < 9; ++kb) {
;             const bool tile_ok = (n > 0) || (mt + kb >= 8);
; #pragma unroll
;             for (int i = 0; i < 4; ++i) { const bool ok = tile_ok && (kb == 0 ? lo_ok[i] : (kb == 8 ? !lo_ok[i] : true));
;                 st[kb][i] = ok ? st[kb][i] : -INFINITY; mx = fmaxf(mx, st[kb][i]); }
;         }
;         mx = fmaxf(mx, __shfl_xor(mx, 16)); mx = fmaxf(mx, __shfl_xor(mx, 32));
;     ...
;         for (int dt = 0; dt < 4; ++dt) { const f32x4 y = o[dt] * inv; v2u w; w.x = cvt_pk_bf16(y[0], y[1]); w.y = cvt_pk_bf16(y[2], y[3]); *(v2u*)(qbase + (size_t)mt * 16 * 1024 + 16 * dt + 4 * fq) = w; }
	v_mfma_f32_16x16x32_bf16 v[58:61], v[58:61], v[50:53], 0
	ds_read_b128 v[76:79], v178 offset:4608
	ds_read_b128 v[80:83], v178 offset:6912
	ds_read_b128 v[84:87], v178 offset:9216
	s_waitcnt lgkmcnt(3)
	v_mfma_f32_16x16x32_bf16 v[72:75], v[72:75], v[54:57], v[58:61]
	ds_read_b128 v[88:91], v178 offset:11520
	ds_read_b128 v[92:95], v178 offset:13824
	ds_read_b128 v[96:99], v178 offset:16128
	ds_read_b128 v[58:61], v178 offset:4672
	s_waitcnt lgkmcnt(6)
	v_mfma_f32_16x16x32_bf16 v[76:79], v[76:79], v[50:53], 0
	ds_read_b128 v[100:103], v178 offset:18432
	ds_read_b128 v[104:107], v178 offset:20736
	v_mov_b32_e32 v128, v108
	v_mov_b32_e32 v129, v109
	s_nop 1
	v_permlane16_swap_b32_e32 v126, v128
	v_permlane16_swap_b32_e32 v127, v129
	global_store_dwordx4 v[118:119], v[126:129], off offset:64
	s_waitcnt lgkmcnt(2)
	v_mfma_f32_16x16x32_bf16 v[76:79], v[58:61], v[54:57], v[76:79]
	ds_read_b128 v[58:61], v178 offset:6976
	v_mfma_f32_16x16x32_bf16 v[80:83], v[80:83], v[50:53], 0
	s_waitcnt lgkmcnt(0)
	v_mfma_f32_16x16x32_bf16 v[80:83], v[58:61], v[54:57], v[80:83]
	ds_read_b128 v[58:61], v178 offset:9280
	v_mfma_f32_16x16x32_bf16 v[84:87], v[84:87], v[50:53], 0
	s_waitcnt lgkmcnt(0)
	v_mfma_f32_16x16x32_bf16 v[84:87], v[58:61], v[54:57], v[84:87]
	ds_read_b128 v[58:61], v178 offset:11584
	v_mfma_f32_16x16x32_bf16 v[88:91], v[88:91], v[50:53], 0
	s_waitcnt lgkmcnt(0)
	v_mfma_f32_16x16x32_bf16 v[88:91], v[58:61], v[54:57], v[88:91]
	ds_read_b128 v[58:61], v178 offset:13888
	v_mfma_f32_16x16x32_bf16 v[92:95], v[92:95], v[50:53], 0
	s_waitcnt lgkmcnt(0)
	v_mfma_f32_16x16x32_bf16 v[92:95], v[58:61], v[54:57], v[92:95]
	ds_read_b128 v[58:61], v178 offset:16192
	v_mfma_f32_16x16x32_bf16 v[96:99], v[96:99], v[50:53], 0
	s_nop 5
	v_cndmask_b32_e64 v92, v190, v92, s[16:17]
	v_cndmask_b32_e64 v93, v190, v93, s[16:17]
	v_cndmask_b32_e64 v94, v190, v94, s[16:17]
	s_waitcnt lgkmcnt(0)
	v_mfma_f32_16x16x32_bf16 v[96:99], v[58:61], v[54:57], v[96:99]
	ds_read_b128 v[58:61], v178 offset:18496
	v_cndmask_b32_e64 v95, v190, v95, s[16:17]
	v_mfma_f32_16x16x32_bf16 v[100:103], v[100:103], v[50:53], 0
	s_nop 4
	v_cndmask_b32_e64 v110, v190, v99, s[16:17]
	s_waitcnt lgkmcnt(0)
	v_mfma_f32_16x16x32_bf16 v[58:61], v[58:61], v[54:57], v[100:103]
	s_nop 2
	ds_read_b128 v[100:103], v178 offset:20800
	v_mfma_f32_16x16x32_bf16 v[50:53], v[104:107], v[50:53], 0
	v_cndmask_b32_e64 v104, v190, v91, s[16:17]
	v_cndmask_b32_e64 v105, v190, v96, s[16:17]
	v_cndmask_b32_e64 v106, v190, v97, s[16:17]
	s_waitcnt lgkmcnt(0)
	v_mfma_f32_16x16x32_bf16 v[50:53], v[100:103], v[54:57], v[50:53]
	v_cndmask_b32_e64 v55, v73, v190, s[10:11]
	v_cndmask_b32_e64 v54, v190, v72, s[20:21]
	v_cndmask_b32_e64 v55, v190, v55, s[16:17]
	v_max3_f32 v56, v71, v54, v55
	v_cndmask_b32_e64 v57, v190, v74, s[18:19]
	v_cndmask_b32_e64 v72, v190, v75, s[22:23]
	v_max3_f32 v56, v56, v57, v72
	v_cndmask_b32_e64 v73, v190, v76, s[16:17]
	v_cndmask_b32_e64 v74, v190, v77, s[16:17]
	v_max3_f32 v56, v56, v73, v74
	v_cndmask_b32_e64 v75, v190, v78, s[16:17]
	v_cndmask_b32_e64 v76, v190, v79, s[16:17]
	v_max3_f32 v56, v56, v75, v76
	v_cndmask_b32_e64 v77, v190, v80, s[16:17]
	v_cndmask_b32_e64 v78, v190, v81, s[16:17]
	v_max3_f32 v56, v56, v77, v78
	v_cndmask_b32_e64 v79, v190, v82, s[16:17]
	v_cndmask_b32_e64 v80, v190, v83, s[16:17]
	v_max3_f32 v56, v56, v79, v80
	v_cndmask_b32_e64 v81, v190, v84, s[16:17]
	v_cndmask_b32_e64 v82, v190, v85, s[16:17]
	v_max3_f32 v56, v56, v81, v82
	v_cndmask_b32_e64 v83, v190, v86, s[16:17]
	v_cndmask_b32_e64 v100, v190, v87, s[16:17]
	v_max3_f32 v56, v56, v83, v100
	v_cndmask_b32_e64 v101, v190, v88, s[16:17]
	v_cndmask_b32_e64 v102, v190, v89, s[16:17]
	v_max3_f32 v56, v56, v101, v102
	v_cndmask_b32_e64 v103, v190, v90, s[16:17]
	v_max3_f32 v56, v56, v103, v104
	v_max3_f32 v56, v56, v92, v93
	v_max3_f32 v56, v56, v94, v95
	v_max3_f32 v56, v56, v105, v106
	v_cndmask_b32_e64 v107, v190, v98, s[16:17]
	v_max3_f32 v56, v56, v107, v110
	v_max3_f32 v56, v56, v58, v59
	v_max3_f32 v56, v56, v60, v61
	v_cndmask_b32_e64 v116, v50, v190, s[8:9]
	v_cndmask_b32_e64 v117, v190, v51, s[10:11]
	v_max3_f32 v50, v56, v116, v117
	v_cndmask_b32_e64 v118, v52, v190, s[12:13]
	v_cndmask_b32_e64 v119, v53, v190, s[14:15]
	v_max3_f32 v50, v50, v118, v119
	ds_bpermute_b32 v51, v65, v50
	s_waitcnt lgkmcnt(0)
	v_max_f32_e32 v51, v51, v51
	v_max_f32_e32 v50, v50, v51
	ds_bpermute_b32 v51, v66, v50
	s_waitcnt lgkmcnt(0)
; __device__ __forceinline__ unsigned cvt_pk_bf16(float lo, float hi) { unsigned r; asm volatile("v_cvt_pk_bf16_f32 %0, %1, %2" : "=v"(r) : "v"(lo), "v"(hi)); return r; }
; #define LAS __attribute__((address_space(3)))
; __device__ __forceinline__ void attn_unit(LAS unsigned char* lds, bf16* Q, const bf16* Kg, const bf16* Vg, const float* snk, int unit, int tid) {
;     ...
;         mx = fmaxf(mx, __shfl_xor(mx, 16)); mx = fmaxf(mx, __shfl_xor(mx, 32));
;         f32x4 ls4 = {0.f, 0.f, 0.f, 0.f};
; #pragma unroll
;         for (int kb = 0; kb < 9; ++kb) { f32x4 d = st[kb] - mx;
; #pragma unroll
;             for (int i = 0; i < 4; ++i) d[i] = __builtin_amdgcn_exp2f(d[i]);
;             st[kb] = d; ls4 = ls4 + d; }
;         float ls = (ls4[0] + ls4[1]) + (ls4[2] + ls4[3]);
;         ls += __shfl_xor(ls, 16); ls += __shfl_xor(ls, 32);
;         const float inv = 1.f / (ls + __builtin_amdgcn_exp2f(sink - mx));
;         f32x4 o[4];
; #pragma unroll
;         for (int dt = 0; dt < 4; ++dt) o[dt] = (f32x4){0.f, 0.f, 0.f, 0.f};
; #pragma unroll
;         for (int kp = 0; kp < 5; ++kp) {
;             v4u pw; pw.x = cvt_pk_bf16(st[2 * kp][0], st[2 * kp][1]); pw.y = cvt_pk_bf16(st[2 * kp][2], st[2 * kp][3]);
;             if (kp < 4) { pw.z = cvt_pk_bf16(st[(2 * kp + 1) % 9][0], st[(2 * kp + 1) % 9][1]); pw.w = cvt_pk_bf16(st[(2 * kp + 1) % 9][2], st[(2 * kp + 1) % 9][3]); } else { pw.z = 0u; pw.w = 0u; }
;             const bf16x8_t pb = __builtin_bit_cast(bf16x8_t, pw);
; #pragma unroll
;             for (int dt = 0; dt < 4; ++dt) { const LAS unsigned char* vp = lds + ATT_VOFF + (16 * dt + fr) * ATT_VP + (16 * (mt + 2 * kp) + 4 * fq) * 2;
;                 const v2u lo = *(const LAS v2u*)vp; v2u hi = {0u, 0u}; if (kp < 4) hi = *(const LAS v2u*)(vp + 32);
;                 v4u aw; aw.x = lo.x; aw.y = lo.y; aw.z = hi.x; aw.w = hi.y;
;                 o[dt] = __builtin_amdgcn_mfma_f32_16x16x32_bf16(__builtin_bit_cast(bf16x8_t, aw), pb, o[dt], 0, 0, 0); }
;         }
	v_max_f32_e32 v51, v51, v51
	v_max_f32_e32 v120, v50, v51
	v_sub_f32_e32 v51, v72, v120
	v_sub_f32_e32 v52, v57, v120
	v_sub_f32_e32 v55, v55, v120
	v_sub_f32_e32 v50, v54, v120
	v_exp_f32_e32 v50, v50
	v_exp_f32_e32 v52, v52
	v_exp_f32_e32 v53, v51
	v_exp_f32_e32 v51, v55
	v_sub_f32_e32 v76, v76, v120
	v_sub_f32_e32 v75, v75, v120
	v_sub_f32_e32 v74, v74, v120
	v_sub_f32_e32 v72, v73, v120
	v_exp_f32_e32 v72, v72
	v_exp_f32_e32 v73, v74
	v_exp_f32_e32 v74, v75
	v_exp_f32_e32 v75, v76
	v_sub_f32_e32 v76, v80, v120
	v_sub_f32_e32 v79, v79, v120
	v_sub_f32_e32 v78, v78, v120
	v_sub_f32_e32 v77, v77, v120
	v_exp_f32_e32 v84, v77
	v_exp_f32_e32 v86, v79
	v_exp_f32_e32 v87, v76
	v_exp_f32_e32 v85, v78
	v_sub_f32_e32 v76, v100, v120
	v_sub_f32_e32 v77, v83, v120
	v_sub_f32_e32 v78, v82, v120
	v_sub_f32_e32 v79, v81, v120
	v_exp_f32_e32 v88, v79
	v_exp_f32_e32 v89, v78
	v_exp_f32_e32 v90, v77
	v_exp_f32_e32 v91, v76
	v_sub_f32_e32 v76, v104, v120
	v_sub_f32_e32 v77, v103, v120
	v_sub_f32_e32 v78, v102, v120
	v_sub_f32_e32 v79, v101, v120
	v_pk_add_f32 v[54:55], v[52:53], 0 op_sel_hi:[1,0]
	v_pk_add_f32 v[56:57], v[50:51], 0 op_sel_hi:[1,0]
	v_exp_f32_e32 v96, v79
	v_exp_f32_e32 v98, v77
	v_exp_f32_e32 v99, v76
	v_exp_f32_e32 v97, v78
	v_pk_add_f32 v[56:57], v[72:73], v[56:57]
	v_pk_add_f32 v[54:55], v[74:75], v[54:55]
	v_pk_add_f32 v[56:57], v[84:85], v[56:57]
	v_pk_add_f32 v[54:55], v[86:87], v[54:55]
	v_pk_add_f32 v[56:57], v[88:89], v[56:57]
	v_pk_add_f32 v[54:55], v[90:91], v[54:55]
	v_sub_f32_e32 v78, v92, v120
	v_pk_add_f32 v[76:77], v[98:99], v[54:55]
	v_pk_add_f32 v[54:55], v[96:97], v[56:57]
	v_sub_f32_e32 v57, v93, v120
	v_sub_f32_e32 v56, v95, v120
	v_exp_f32_e32 v101, v57
	v_sub_f32_e32 v57, v94, v120
	v_exp_f32_e32 v100, v78
	v_exp_f32_e32 v102, v57
	v_exp_f32_e32 v103, v56
	v_sub_f32_e32 v80, v110, v120
	v_sub_f32_e32 v81, v107, v120
	v_sub_f32_e32 v82, v106, v120
	v_sub_f32_e32 v83, v105, v120
	v_exp_f32_e32 v104, v81
	v_exp_f32_e32 v105, v80
	v_exp_f32_e32 v106, v83
	v_exp_f32_e32 v107, v82
	v_pk_add_f32 v[78:79], v[100:101], v[54:55]
	v_pk_add_f32 v[76:77], v[102:103], v[76:77]
	v_cvt_pk_bf16_f32 v50, v50, v51
	v_cvt_pk_bf16_f32 v51, v52, v53
	v_cvt_pk_bf16_f32 v52, v72, v73
	v_cvt_pk_bf16_f32 v53, v74, v75
	ds_read2_b64 v[54:57], v67 offset0:4 offset1:8
	ds_read2_b64 v[72:75], v68 offset0:36 offset1:40
	v_pk_add_f32 v[108:109], v[104:105], v[76:77]
	v_pk_add_f32 v[110:111], v[106:107], v[78:79]
	ds_read2_b64 v[76:79], v70 offset0:68 offset1:72
	ds_read2_b64 v[80:83], v69 offset0:100 offset1:104
	v_sub_f32_e32 v60, v60, v120
	v_sub_f32_e32 v59, v59, v120
	v_sub_f32_e32 v58, v58, v120
	v_sub_f32_e32 v115, v61, v120
	v_cvt_pk_bf16_f32 v84, v84, v85
	v_cvt_pk_bf16_f32 v85, v86, v87
	v_cvt_pk_bf16_f32 v86, v88, v89
	v_cvt_pk_bf16_f32 v87, v90, v91
	ds_read2_b64 v[88:91], v67 offset0:12 offset1:16
	v_exp_f32_e32 v112, v58
	v_exp_f32_e32 v113, v59
	v_exp_f32_e32 v114, v60
	ds_read2_b64 v[58:61], v70 offset0:76 offset1:80
	s_waitcnt lgkmcnt(5)
	v_mfma_f32_16x16x32_bf16 v[54:57], v[54:57], v[50:53], 0
	ds_read2_b64 v[92:95], v68 offset0:44 offset1:48
	v_exp_f32_e32 v115, v115
	s_waitcnt lgkmcnt(5)
	v_mfma_f32_16x16x32_bf16 v[72:75], v[72:75], v[50:53], 0
	s_waitcnt lgkmcnt(4)
	v_mfma_f32_16x16x32_bf16 v[76:79], v[76:79], v[50:53], 0
	s_waitcnt lgkmcnt(3)
	v_mfma_f32_16x16x32_bf16 v[50:53], v[80:83], v[50:53], 0
	ds_read2_b64 v[80:83], v69 offset0:108 offset1:112
	s_waitcnt lgkmcnt(3)
	v_mfma_f32_16x16x32_bf16 v[54:57], v[88:91], v[84:87], v[54:57]
	v_cvt_pk_bf16_f32 v88, v96, v97
	v_cvt_pk_bf16_f32 v89, v98, v99
	v_cvt_pk_bf16_f32 v90, v100, v101
	v_cvt_pk_bf16_f32 v91, v102, v103
	s_waitcnt lgkmcnt(2)
	v_mfma_f32_16x16x32_bf16 v[58:61], v[58:61], v[84:87], v[76:79]
	v_add_f32_e64 v98, v114, v108
	v_add_f32_e64 v99, v115, v109
	v_sub_f32_e32 v101, v119, v120
	v_sub_f32_e32 v102, v118, v120
	ds_read2_b64 v[76:79], v68 offset0:52 offset1:56
	s_waitcnt lgkmcnt(2)
	v_mfma_f32_16x16x32_bf16 v[72:75], v[92:95], v[84:87], v[72:75]
	ds_read2_b64 v[92:95], v67 offset0:20 offset1:24
	v_sub_f32_e32 v108, v117, v120
	v_exp_f32_e32 v102, v102
	s_waitcnt lgkmcnt(2)
	v_mfma_f32_16x16x32_bf16 v[50:53], v[80:83], v[84:87], v[50:53]
	ds_read2_b64 v[80:83], v70 offset0:84 offset1:88
	v_sub_f32_e32 v84, v116, v120
	v_exp_f32_e32 v100, v84
	s_waitcnt lgkmcnt(2)
	v_mfma_f32_16x16x32_bf16 v[72:75], v[76:79], v[88:91], v[72:75]
	ds_read2_b64 v[76:79], v69 offset0:116 offset1:120
	v_cvt_pk_bf16_f32 v84, v106, v107
	v_cvt_pk_bf16_f32 v85, v104, v105
	v_cvt_pk_bf16_f32 v86, v112, v113
	v_cvt_pk_bf16_f32 v87, v114, v115
	s_waitcnt lgkmcnt(1)
	v_mfma_f32_16x16x32_bf16 v[58:61], v[80:83], v[88:91], v[58:61]
	ds_read2_b64 v[80:83], v68 offset0:60 offset1:64
	v_exp_f32_e32 v103, v101
	v_exp_f32_e32 v101, v108
	v_mfma_f32_16x16x32_bf16 v[54:57], v[92:95], v[88:91], v[54:57]
	ds_read2_b64 v[92:95], v67 offset0:28 offset1:32
	v_pk_add_f32 v[96:97], v[112:113], v[110:111]
	s_waitcnt lgkmcnt(2)
	v_mfma_f32_16x16x32_bf16 v[50:53], v[76:79], v[88:91], v[50:53]
	ds_read2_b64 v[76:79], v70 offset0:92 offset1:96
	v_pk_add_f32 v[88:89], v[102:103], v[98:99]
	v_pk_add_f32 v[90:91], v[100:101], v[96:97]
	s_waitcnt lgkmcnt(2)
	v_mfma_f32_16x16x32_bf16 v[72:75], v[80:83], v[84:87], v[72:75]
	ds_read2_b64 v[80:83], v69 offset0:124 offset1:128
	s_waitcnt lgkmcnt(2)
	v_mfma_f32_16x16x32_bf16 v[54:57], v[92:95], v[84:87], v[54:57]
	v_pk_mov_b32 v[92:93], v[90:91], v[88:89] op_sel:[1,0]
	v_mov_b32_e32 v91, v89
	v_pk_add_f32 v[88:89], v[92:93], v[90:91]
	s_waitcnt lgkmcnt(1)
	v_mfma_f32_16x16x32_bf16 v[58:61], v[76:79], v[84:87], v[58:61]
	v_add_f32_e32 v88, v88, v89
	ds_bpermute_b32 v76, v65, v88
	v_mov_b32_e32 v78, v147
	s_waitcnt lgkmcnt(1)
; __device__ __forceinline__ unsigned cvt_pk_bf16(float lo, float hi) { unsigned r; asm volatile("v_cvt_pk_bf16_f32 %0, %1, %2" : "=v"(r) : "v"(lo), "v"(hi)); return r; }
; #define LAS __attribute__((address_space(3)))
; __device__ __forceinline__ void attn_unit(LAS unsigned char* lds, bf16* Q, const bf16* Kg, const bf16* Vg, const float* snk, int unit, int tid) {
;     ...
;         for (int kb = 0; kb < 9; ++kb) { const LAS unsigned char* kp = lds + (16 * (mt + kb) + fr) * ATT_KP + 16 * fq;
;             const bf16x8_t k0 = *(const LAS bf16x8_t*)kp, k1 = *(const LAS bf16x8_t*)(kp + 64);
;             f32x4 z = {0.f, 0.f, 0.f, 0.f}; z = __builtin_amdgcn_mfma_f32_16x16x32_bf16(k0, qf[mt][0], z, 0, 0, 0); z = __builtin_amdgcn_mfma_f32_16x16x32_bf16(k1, qf[mt][1], z, 0, 0, 0); st[kb] = z; }
;     ...
; #pragma unroll
;         for (int kp = 0; kp < 5; ++kp) {
;             v4u pw; pw.x = cvt_pk_bf16(st[2 * kp][0], st[2 * kp][1]); pw.y = cvt_pk_bf16(st[2 * kp][2], st[2 * kp][3]);
;             if (kp < 4) { pw.z = cvt_pk_bf16(st[(2 * kp + 1) % 9][0], st[(2 * kp + 1) % 9][1]); pw.w = cvt_pk_bf16(st[(2 * kp + 1) % 9][2], st[(2 * kp + 1) % 9][3]); } else { pw.z = 0u; pw.w = 0u; }
;             const bf16x8_t pb = __builtin_bit_cast(bf16x8_t, pw);
; #pragma unroll
;             for (int dt = 0; dt < 4; ++dt) { const LAS unsigned char* vp = lds + ATT_VOFF + (16 * dt + fr) * ATT_VP + (16 * (mt + 2 * kp) + 4 * fq) * 2;
;                 const v2u lo = *(const LAS v2u*)vp; v2u hi = {0u, 0u}; if (kp < 4) hi = *(const LAS v2u*)(vp + 32);
;                 v4u aw; aw.x = lo.x; aw.y = lo.y; aw.z = hi.x; aw.w = hi.y;
;                 o[dt] = __builtin_amdgcn_mfma_f32_16x16x32_bf16(__builtin_bit_cast(bf16x8_t, aw), pb, o[dt], 0, 0, 0); }
;         }
; #pragma unroll
;         for (int dt = 0; dt < 4; ++dt) { const f32x4 y = o[dt] * inv; v2u w; w.x = cvt_pk_bf16(y[0], y[1]); w.y = cvt_pk_bf16(y[2], y[3]); *(v2u*)(qbase + (size_t)mt * 16 * 1024 + 16 * dt + 4 * fq) = w; }
	v_mfma_f32_16x16x32_bf16 v[50:53], v[80:83], v[84:87], v[50:53]
	v_mov_b32_e32 v82, v147
	v_mov_b32_e32 v83, v147
	s_waitcnt lgkmcnt(0)
	v_add_f32_e32 v94, v88, v76
	v_cvt_pk_bf16_f32 v76, v100, v101
	v_cvt_pk_bf16_f32 v77, v102, v103
	ds_read_b64 v[80:81], v179 offset:37152
	ds_read_b64 v[84:85], v179 offset:45600
	v_mov_b32_e32 v79, v147
	v_mov_b32_e32 v86, v147
	v_mov_b32_e32 v87, v147
	s_waitcnt lgkmcnt(1)
	v_mfma_f32_16x16x32_bf16 v[54:57], v[80:83], v[76:79], v[54:57]
	ds_bpermute_b32 v80, v66, v94
	v_fma_f32 v81, v64, s61, -v120
	v_exp_f32_e32 v81, v81
	ds_read_b64 v[88:89], v179 offset:54048
	ds_read_b64 v[92:93], v179 offset:62496
	v_mov_b32_e32 v90, v147
	s_waitcnt lgkmcnt(2)
	v_add_f32_e32 v80, v94, v80
	v_add_f32_e32 v80, v81, v80
	v_mov_b32_e32 v91, v147
	v_mov_b32_e32 v94, v147
	v_mov_b32_e32 v95, v147
	v_div_scale_f32 v81, s[68:69], v80, v80, 1.0
	v_rcp_f32_e32 v82, v81
	v_mfma_f32_16x16x32_bf16 v[72:75], v[84:87], v[76:79], v[72:75]
	s_waitcnt lgkmcnt(1)
	v_mfma_f32_16x16x32_bf16 v[58:61], v[88:91], v[76:79], v[58:61]
	s_waitcnt lgkmcnt(0)
	v_mfma_f32_16x16x32_bf16 v[50:53], v[92:95], v[76:79], v[50:53]
	v_fma_f32 v76, -v81, v82, 1.0
	v_fmac_f32_e32 v82, v76, v82
	v_div_scale_f32 v76, vcc, 1.0, v80, 1.0
	v_mul_f32_e32 v77, v76, v82
	v_fma_f32 v78, -v81, v77, v76
	v_fmac_f32_e32 v77, v78, v82
	v_fma_f32 v76, -v81, v77, v76
	v_div_fmas_f32 v76, v76, v82, v77
	v_div_fixup_f32 v76, v76, v80, 1.0
	v_pk_mul_f32 v[56:57], v[76:77], v[56:57] op_sel_hi:[0,1]
	v_pk_mul_f32 v[54:55], v[76:77], v[54:55] op_sel_hi:[0,1]
	v_add_co_u32_e32 v100, vcc, s43, v62
	v_cvt_pk_bf16_f32 v54, v54, v55
	v_cvt_pk_bf16_f32 v55, v56, v57
	v_pk_mul_f32 v[56:57], v[76:77], v[72:73] op_sel_hi:[0,1]
	s_nop 0
	v_addc_co_u32_e32 v101, vcc, 0, v63, vcc
	v_lshrrev_b32_e32 v110, 4, v0
	v_and_b32_e32 v110, 1, v110
	v_mul_u32_u24_e32 v110, 24, v110
	v_mov_b32_e32 v111, 0
	v_lshl_add_u64 v[118:119], v[100:101], 0, v[110:111]
	v_mov_b32_e32 v114, v54
	v_mov_b32_e32 v115, v55
	v_pk_mul_f32 v[54:55], v[76:77], v[74:75] op_sel_hi:[0,1]
	v_cvt_pk_bf16_f32 v56, v56, v57
	v_cvt_pk_bf16_f32 v57, v54, v55
	v_mov_b32_e32 v116, v56
	v_mov_b32_e32 v117, v57
	s_nop 1
	v_permlane16_swap_b32_e32 v114, v116
	v_permlane16_swap_b32_e32 v115, v117
	global_store_dwordx4 v[118:119], v[114:117], off
	v_pk_mul_f32 v[56:57], v[76:77], v[58:59] op_sel_hi:[0,1]
	v_pk_mul_f32 v[54:55], v[76:77], v[60:61] op_sel_hi:[0,1]
	v_cvt_pk_bf16_f32 v56, v56, v57
	v_cvt_pk_bf16_f32 v57, v54, v55
	v_pk_mul_f32 v[52:53], v[76:77], v[52:53] op_sel_hi:[0,1]
	v_pk_mul_f32 v[50:51], v[76:77], v[50:51] op_sel_hi:[0,1]
	v_mov_b32_e32 v126, v56
	v_mov_b32_e32 v127, v57
	v_cvt_pk_bf16_f32 v102, v50, v51
	v_cvt_pk_bf16_f32 v103, v52, v53
	ds_read_b128 v[50:53], v178 offset:4608
	ds_read_b128 v[54:57], v178 offset:4672
	s_waitcnt lgkmcnt(1)
	v_mfma_f32_16x16x32_bf16 v[50:53], v[50:53], v[42:45], 0
	ds_read_b128 v[58:61], v178 offset:6912
	ds_read_b128 v[96:99], v178 offset:23040
	v_mov_b32_e32 v128, v102
	v_mov_b32_e32 v129, v103
	s_nop 1
	v_permlane16_swap_b32_e32 v126, v128
	v_permlane16_swap_b32_e32 v127, v129
	global_store_dwordx4 v[118:119], v[126:129], off offset:64
	s_waitcnt lgkmcnt(2)
	v_mfma_f32_16x16x32_bf16 v[72:75], v[54:57], v[46:49], v[50:53]
	s_nop 2
	ds_read_b128 v[50:53], v178 offset:6976
	s_waitcnt lgkmcnt(2)
	v_mfma_f32_16x16x32_bf16 v[54:57], v[58:61], v[42:45], 0
	ds_read_b128 v[58:61], v178 offset:9216
	s_waitcnt lgkmcnt(1)
	v_mfma_f32_16x16x32_bf16 v[76:79], v[50:53], v[46:49], v[54:57]
	ds_read_b128 v[50:53], v178 offset:9280
	s_waitcnt lgkmcnt(1)
	v_mfma_f32_16x16x32_bf16 v[54:57], v[58:61], v[42:45], 0
	ds_read_b128 v[58:61], v178 offset:11520
	s_waitcnt lgkmcnt(1)
	v_mfma_f32_16x16x32_bf16 v[80:83], v[50:53], v[46:49], v[54:57]
	ds_read_b128 v[50:53], v178 offset:11584
	s_waitcnt lgkmcnt(1)
	v_mfma_f32_16x16x32_bf16 v[54:57], v[58:61], v[42:45], 0
	ds_read_b128 v[58:61], v178 offset:13824
	s_waitcnt lgkmcnt(1)
	v_mfma_f32_16x16x32_bf16 v[84:87], v[50:53], v[46:49], v[54:57]
	ds_read_b128 v[50:53], v178 offset:13888
	s_waitcnt lgkmcnt(1)
	v_mfma_f32_16x16x32_bf16 v[54:57], v[58:61], v[42:45], 0
	ds_read_b128 v[58:61], v178 offset:16128
	s_waitcnt lgkmcnt(1)
	v_mfma_f32_16x16x32_bf16 v[88:91], v[50:53], v[46:49], v[54:57]
	ds_read_b128 v[50:53], v178 offset:16192
	s_waitcnt lgkmcnt(1)
	v_mfma_f32_16x16x32_bf16 v[54:57], v[58:61], v[42:45], 0
	ds_read_b128 v[58:61], v178 offset:18432
	s_waitcnt lgkmcnt(1)
	v_mfma_f32_16x16x32_bf16 v[92:95], v[50:53], v[46:49], v[54:57]
	ds_read_b128 v[50:53], v178 offset:18496
	s_waitcnt lgkmcnt(1)
	v_mfma_f32_16x16x32_bf16 v[54:57], v[58:61], v[42:45], 0
	ds_read_b128 v[58:61], v178 offset:20736
	s_nop 3
	v_cndmask_b32_e64 v92, v190, v92, s[16:17]
	v_cndmask_b32_e64 v93, v190, v93, s[16:17]
	s_waitcnt lgkmcnt(1)
	v_mfma_f32_16x16x32_bf16 v[54:57], v[50:53], v[46:49], v[54:57]
	ds_read_b128 v[50:53], v178 offset:20800
	v_cndmask_b32_e64 v94, v190, v94, s[16:17]
	v_cndmask_b32_e64 v95, v190, v95, s[16:17]
	s_waitcnt lgkmcnt(1)
	v_mfma_f32_16x16x32_bf16 v[58:61], v[58:61], v[42:45], 0
	s_waitcnt lgkmcnt(0)
	v_mfma_f32_16x16x32_bf16 v[50:53], v[50:53], v[46:49], v[58:61]
	s_nop 5
	ds_read_b128 v[58:61], v178 offset:23104
	v_mfma_f32_16x16x32_bf16 v[42:45], v[96:99], v[42:45], 0
	s_waitcnt lgkmcnt(0)
; __device__ __forceinline__ void attn_unit(LAS unsigned char* lds, bf16* Q, const bf16* Kg, const bf16* Vg, const float* snk, int unit, int tid) {
;     ...
;             f32x4 z = {0.f, 0.f, 0.f, 0.f}; z = __builtin_amdgcn_mfma_f32_16x16x32_bf16(k0, qf[mt][0], z, 0, 0, 0); z = __builtin_amdgcn_mfma_f32_16x16x32_bf16(k1, qf[mt][1], z, 0, 0, 0); st[kb] = z; }
;         float mx = sink;
; #pragma unroll
;         for (int kb = 0; kb < 9; ++kb) {
;             const bool tile_ok = (n > 0) || (mt + kb >= 8);
; #pragma unroll
;             for (int i = 0; i < 4; ++i) { const bool ok = tile_ok && (kb == 0 ? lo_ok[i] : (kb == 8 ? !lo_ok[i] : true));
;                 st[kb][i] = ok ? st[kb][i] : -INFINITY; mx = fmaxf(mx, st[kb][i]); }
;         }
;         mx = fmaxf(mx, __shfl_xor(mx, 16)); mx = fmaxf(mx, __shfl_xor(mx, 32));
;         f32x4 ls4 = {0.f, 0.f, 0.f, 0.f};
; #pragma unroll
;         for (int kb = 0; kb < 9; ++kb) { f32x4 d = st[kb] - mx;
; #pragma unroll
;             for (int i = 0; i < 4; ++i) d[i] = __builtin_amdgcn_exp2f(d[i]);
;             st[kb] = d; ls4 = ls4 + d; }
;         float ls = (ls4[0] + ls4[1]) + (ls4[2] + ls4[3]);
;         ls += __shfl_xor(ls, 16); ls += __shfl_xor(ls, 32);
;         const float inv = 1.f / (ls + __builtin_amdgcn_exp2f(sink - mx));
;         f32x4 o[4];
; #pragma unroll
;         for (int dt = 0; dt < 4; ++dt) o[dt] = (f32x4){0.f, 0.f, 0.f, 0.f};
; #pragma unroll
;         for (int kp = 0; kp < 5; ++kp) {
;             v4u pw; pw.x = cvt_pk_bf16(st[2 * kp][0], st[2 * kp][1]); pw.y = cvt_pk_bf16(st[2 * kp][2], st[2 * kp][3]);
;             if (kp < 4) { pw.z = cvt_pk_bf16(st[(2 * kp + 1) % 9][0], st[(2 * kp + 1) % 9][1]); pw.w = cvt_pk_bf16(st[(2 * kp + 1) % 9][2], st[(2 * kp + 1) % 9][3]); } else { pw.z = 0u; pw.w = 0u; }
;             const bf16x8_t pb = __builtin_bit_cast(bf16x8_t, pw);
; #pragma unroll
;             for (int dt = 0; dt < 4; ++dt) { const LAS unsigned char* vp = lds + ATT_VOFF + (16 * dt + fr) * ATT_VP + (16 * (mt + 2 * kp) + 4 * fq) * 2;
;                 const v2u lo = *(const LAS v2u*)vp; v2u hi = {0u, 0u}; if (kp < 4) hi = *(const LAS v2u*)(vp + 32);
;                 v4u aw; aw.x = lo.x; aw.y = lo.y; aw.z = hi.x; aw.w = hi.y;
;                 o[dt] = __builtin_amdgcn_mfma_f32_16x16x32_bf16(__builtin_bit_cast(bf16x8_t, aw), pb, o[dt], 0, 0, 0); }
;         }
	v_mfma_f32_16x16x32_bf16 v[42:45], v[58:61], v[46:49], v[42:45]
	v_cndmask_b32_e64 v47, v73, v190, s[10:11]
	v_cndmask_b32_e64 v46, v190, v72, s[20:21]
	v_cndmask_b32_e64 v47, v190, v47, s[16:17]
	v_max3_f32 v48, v71, v46, v47
	v_cndmask_b32_e64 v49, v190, v74, s[18:19]
	v_cndmask_b32_e64 v58, v190, v75, s[22:23]
	v_max3_f32 v48, v48, v49, v58
	v_cndmask_b32_e64 v59, v190, v76, s[16:17]
	v_cndmask_b32_e64 v60, v190, v77, s[16:17]
	v_max3_f32 v48, v48, v59, v60
	v_cndmask_b32_e64 v61, v190, v78, s[16:17]
	v_cndmask_b32_e64 v72, v190, v79, s[16:17]
	v_max3_f32 v48, v48, v61, v72
	v_cndmask_b32_e64 v73, v190, v80, s[16:17]
	v_cndmask_b32_e64 v74, v190, v81, s[16:17]
	v_max3_f32 v48, v48, v73, v74
	v_cndmask_b32_e64 v75, v190, v82, s[16:17]
	v_cndmask_b32_e64 v76, v190, v83, s[16:17]
	v_max3_f32 v48, v48, v75, v76
	v_cndmask_b32_e64 v80, v190, v84, s[16:17]
	v_cndmask_b32_e64 v81, v190, v85, s[16:17]
	v_max3_f32 v48, v48, v80, v81
	v_cndmask_b32_e64 v82, v190, v86, s[16:17]
	v_cndmask_b32_e64 v83, v190, v87, s[16:17]
	v_max3_f32 v48, v48, v82, v83
	v_cndmask_b32_e64 v84, v190, v88, s[16:17]
	v_cndmask_b32_e64 v85, v190, v89, s[16:17]
	v_max3_f32 v48, v48, v84, v85
	v_cndmask_b32_e64 v86, v190, v90, s[16:17]
	v_cndmask_b32_e64 v87, v190, v91, s[16:17]
	v_max3_f32 v48, v48, v86, v87
	v_max3_f32 v48, v48, v92, v93
	v_max3_f32 v48, v48, v94, v95
	v_max3_f32 v48, v48, v54, v55
	v_max3_f32 v48, v48, v56, v57
	v_max3_f32 v48, v48, v50, v51
	v_max3_f32 v48, v48, v52, v53
	v_cndmask_b32_e64 v108, v42, v190, s[8:9]
	v_cndmask_b32_e64 v109, v190, v43, s[10:11]
	v_max3_f32 v42, v48, v108, v109
	v_cndmask_b32_e64 v110, v44, v190, s[12:13]
	v_cndmask_b32_e64 v111, v45, v190, s[14:15]
	v_max3_f32 v42, v42, v110, v111
	ds_bpermute_b32 v43, v65, v42
	s_waitcnt lgkmcnt(0)
	v_max_f32_e32 v43, v43, v43
	v_max_f32_e32 v42, v42, v43
	ds_bpermute_b32 v43, v66, v42
	s_waitcnt lgkmcnt(0)
	v_max_f32_e32 v43, v43, v43
	v_max_f32_e32 v112, v42, v43
	v_sub_f32_e32 v43, v58, v112
	v_sub_f32_e32 v44, v49, v112
	v_sub_f32_e32 v47, v47, v112
	v_sub_f32_e32 v42, v46, v112
	v_exp_f32_e32 v42, v42
	v_exp_f32_e32 v44, v44
	v_exp_f32_e32 v45, v43
	v_exp_f32_e32 v43, v47
	v_sub_f32_e32 v72, v72, v112
	v_sub_f32_e32 v61, v61, v112
	v_sub_f32_e32 v60, v60, v112
	v_sub_f32_e32 v58, v59, v112
	v_exp_f32_e32 v58, v58
	v_exp_f32_e32 v59, v60
	v_exp_f32_e32 v60, v61
	v_exp_f32_e32 v61, v72
	v_sub_f32_e32 v72, v76, v112
	v_sub_f32_e32 v75, v75, v112
	v_sub_f32_e32 v74, v74, v112
	v_sub_f32_e32 v73, v73, v112
	v_exp_f32_e32 v76, v73
	v_exp_f32_e32 v78, v75
	v_exp_f32_e32 v79, v72
	v_exp_f32_e32 v77, v74
	v_sub_f32_e32 v72, v83, v112
	v_sub_f32_e32 v73, v82, v112
	v_sub_f32_e32 v74, v81, v112
	v_sub_f32_e32 v75, v80, v112
	v_exp_f32_e32 v80, v75
	v_exp_f32_e32 v81, v74
	v_exp_f32_e32 v82, v73
	v_exp_f32_e32 v83, v72
	v_sub_f32_e32 v72, v87, v112
	v_sub_f32_e32 v73, v86, v112
	v_sub_f32_e32 v74, v85, v112
	v_sub_f32_e32 v75, v84, v112
	v_pk_add_f32 v[46:47], v[44:45], 0 op_sel_hi:[1,0]
	v_pk_add_f32 v[48:49], v[42:43], 0 op_sel_hi:[1,0]
	v_exp_f32_e32 v88, v75
	v_exp_f32_e32 v90, v73
	v_exp_f32_e32 v91, v72
	v_exp_f32_e32 v89, v74
	v_pk_add_f32 v[48:49], v[58:59], v[48:49]
	v_pk_add_f32 v[46:47], v[60:61], v[46:47]
	v_pk_add_f32 v[48:49], v[76:77], v[48:49]
	v_pk_add_f32 v[46:47], v[78:79], v[46:47]
	v_pk_add_f32 v[48:49], v[80:81], v[48:49]
	v_pk_add_f32 v[46:47], v[82:83], v[46:47]
	v_sub_f32_e32 v74, v92, v112
	v_pk_add_f32 v[72:73], v[90:91], v[46:47]
	v_pk_add_f32 v[46:47], v[88:89], v[48:49]
	v_sub_f32_e32 v49, v93, v112
	v_sub_f32_e32 v48, v95, v112
	v_exp_f32_e32 v93, v49
	v_sub_f32_e32 v49, v94, v112
	v_exp_f32_e32 v92, v74
	v_exp_f32_e32 v94, v49
	v_exp_f32_e32 v95, v48
	v_sub_f32_e32 v57, v57, v112
	v_sub_f32_e32 v56, v56, v112
	v_sub_f32_e32 v84, v55, v112
	v_cvt_pk_bf16_f32 v42, v42, v43
	v_cvt_pk_bf16_f32 v43, v44, v45
	v_cvt_pk_bf16_f32 v44, v58, v59
	v_sub_f32_e32 v58, v54, v112
	v_exp_f32_e32 v96, v56
	v_exp_f32_e32 v97, v57
	v_exp_f32_e32 v98, v58
	v_exp_f32_e32 v99, v84
	v_pk_add_f32 v[74:75], v[92:93], v[46:47]
	v_pk_add_f32 v[58:59], v[94:95], v[72:73]
	v_cvt_pk_bf16_f32 v45, v60, v61
	ds_read2_b64 v[46:49], v67 offset0:8 offset1:12
	ds_read2_b64 v[54:57], v68 offset0:40 offset1:44
	v_pk_add_f32 v[100:101], v[96:97], v[58:59]
	v_pk_add_f32 v[102:103], v[98:99], v[74:75]
	ds_read2_b64 v[58:61], v70 offset0:72 offset1:76
	ds_read2_b64 v[72:75], v69 offset0:104 offset1:108
	v_sub_f32_e32 v52, v52, v112
	v_sub_f32_e32 v51, v51, v112
	v_sub_f32_e32 v50, v50, v112
	v_sub_f32_e32 v107, v53, v112
	v_cvt_pk_bf16_f32 v76, v76, v77
	v_cvt_pk_bf16_f32 v77, v78, v79
	v_cvt_pk_bf16_f32 v78, v80, v81
	v_cvt_pk_bf16_f32 v79, v82, v83
	ds_read2_b64 v[80:83], v67 offset0:16 offset1:20
	v_exp_f32_e32 v104, v50
	v_exp_f32_e32 v105, v51
	v_exp_f32_e32 v106, v52
	ds_read2_b64 v[50:53], v70 offset0:80 offset1:84
	s_waitcnt lgkmcnt(5)
	v_mfma_f32_16x16x32_bf16 v[46:49], v[46:49], v[42:45], 0
	ds_read2_b64 v[84:87], v68 offset0:48 offset1:52
	v_exp_f32_e32 v107, v107
	s_waitcnt lgkmcnt(5)
	v_mfma_f32_16x16x32_bf16 v[54:57], v[54:57], v[42:45], 0
	s_waitcnt lgkmcnt(4)
	v_mfma_f32_16x16x32_bf16 v[58:61], v[58:61], v[42:45], 0
	s_waitcnt lgkmcnt(3)
	v_mfma_f32_16x16x32_bf16 v[42:45], v[72:75], v[42:45], 0
	ds_read2_b64 v[72:75], v69 offset0:112 offset1:116
	s_waitcnt lgkmcnt(3)
	v_mfma_f32_16x16x32_bf16 v[46:49], v[80:83], v[76:79], v[46:49]
	v_cvt_pk_bf16_f32 v80, v88, v89
	v_cvt_pk_bf16_f32 v81, v90, v91
	v_cvt_pk_bf16_f32 v82, v92, v93
	v_cvt_pk_bf16_f32 v83, v94, v95
	s_waitcnt lgkmcnt(2)
; __device__ __forceinline__ unsigned cvt_pk_bf16(float lo, float hi) { unsigned r; asm volatile("v_cvt_pk_bf16_f32 %0, %1, %2" : "=v"(r) : "v"(lo), "v"(hi)); return r; }
; #define LAS __attribute__((address_space(3)))
; __device__ __forceinline__ void attn_unit(LAS unsigned char* lds, bf16* Q, const bf16* Kg, const bf16* Vg, const float* snk, int unit, int tid) {
;     ...
;         for (int kb = 0; kb < 9; ++kb) { const LAS unsigned char* kp = lds + (16 * (mt + kb) + fr) * ATT_KP + 16 * fq;
;             const bf16x8_t k0 = *(const LAS bf16x8_t*)kp, k1 = *(const LAS bf16x8_t*)(kp + 64);
;             f32x4 z = {0.f, 0.f, 0.f, 0.f}; z = __builtin_amdgcn_mfma_f32_16x16x32_bf16(k0, qf[mt][0], z, 0, 0, 0); z = __builtin_amdgcn_mfma_f32_16x16x32_bf16(k1, qf[mt][1], z, 0, 0, 0); st[kb] = z; }
;     ...
;         for (int kp = 0; kp < 5; ++kp) {
;             v4u pw; pw.x = cvt_pk_bf16(st[2 * kp][0], st[2 * kp][1]); pw.y = cvt_pk_bf16(st[2 * kp][2], st[2 * kp][3]);
;             if (kp < 4) { pw.z = cvt_pk_bf16(st[(2 * kp + 1) % 9][0], st[(2 * kp + 1) % 9][1]); pw.w = cvt_pk_bf16(st[(2 * kp + 1) % 9][2], st[(2 * kp + 1) % 9][3]); } else { pw.z = 0u; pw.w = 0u; }
;             const bf16x8_t pb = __builtin_bit_cast(bf16x8_t, pw);
; #pragma unroll
;             for (int dt = 0; dt < 4; ++dt) { const LAS unsigned char* vp = lds + ATT_VOFF + (16 * dt + fr) * ATT_VP + (16 * (mt + 2 * kp) + 4 * fq) * 2;
;                 const v2u lo = *(const LAS v2u*)vp; v2u hi = {0u, 0u}; if (kp < 4) hi = *(const LAS v2u*)(vp + 32);
;                 v4u aw; aw.x = lo.x; aw.y = lo.y; aw.z = hi.x; aw.w = hi.y;
;                 o[dt] = __builtin_amdgcn_mfma_f32_16x16x32_bf16(__builtin_bit_cast(bf16x8_t, aw), pb, o[dt], 0, 0, 0); }
;         }
; #pragma unroll
;         for (int dt = 0; dt < 4; ++dt) { const f32x4 y = o[dt] * inv; v2u w; w.x = cvt_pk_bf16(y[0], y[1]); w.y = cvt_pk_bf16(y[2], y[3]); *(v2u*)(qbase + (size_t)mt * 16 * 1024 + 16 * dt + 4 * fq) = w; }
	v_mfma_f32_16x16x32_bf16 v[50:53], v[50:53], v[76:79], v[58:61]
	v_add_f32_e64 v90, v106, v100
	v_add_f32_e64 v91, v107, v101
	v_sub_f32_e32 v93, v111, v112
	v_sub_f32_e32 v94, v110, v112
	ds_read2_b64 v[58:61], v68 offset0:56 offset1:60
	s_waitcnt lgkmcnt(2)
	v_mfma_f32_16x16x32_bf16 v[54:57], v[84:87], v[76:79], v[54:57]
	ds_read2_b64 v[84:87], v67 offset0:24 offset1:28
	v_sub_f32_e32 v100, v109, v112
	v_exp_f32_e32 v94, v94
	s_waitcnt lgkmcnt(2)
	v_mfma_f32_16x16x32_bf16 v[42:45], v[72:75], v[76:79], v[42:45]
	ds_read2_b64 v[72:75], v70 offset0:88 offset1:92
	v_sub_f32_e32 v76, v108, v112
	v_exp_f32_e32 v92, v76
	s_waitcnt lgkmcnt(2)
	v_mfma_f32_16x16x32_bf16 v[54:57], v[58:61], v[80:83], v[54:57]
	ds_read2_b64 v[58:61], v69 offset0:120 offset1:124
	v_cvt_pk_bf16_f32 v76, v98, v99
	v_cvt_pk_bf16_f32 v77, v96, v97
	v_cvt_pk_bf16_f32 v78, v104, v105
	v_cvt_pk_bf16_f32 v79, v106, v107
	s_waitcnt lgkmcnt(1)
	v_mfma_f32_16x16x32_bf16 v[50:53], v[72:75], v[80:83], v[50:53]
	ds_read2_b64 v[72:75], v68 offset0:64 offset1:68
	v_exp_f32_e32 v95, v93
	v_exp_f32_e32 v93, v100
	v_mfma_f32_16x16x32_bf16 v[46:49], v[84:87], v[80:83], v[46:49]
	ds_read2_b64 v[84:87], v67 offset0:32 offset1:36
	v_pk_add_f32 v[88:89], v[104:105], v[102:103]
	s_waitcnt lgkmcnt(2)
	v_mfma_f32_16x16x32_bf16 v[42:45], v[58:61], v[80:83], v[42:45]
	ds_read2_b64 v[58:61], v70 offset0:96 offset1:100
	v_pk_add_f32 v[80:81], v[94:95], v[90:91]
	v_pk_add_f32 v[82:83], v[92:93], v[88:89]
	s_waitcnt lgkmcnt(2)
	v_mfma_f32_16x16x32_bf16 v[54:57], v[72:75], v[76:79], v[54:57]
	ds_read2_b64 v[72:75], v69 offset0:128 offset1:132
	s_waitcnt lgkmcnt(2)
	v_mfma_f32_16x16x32_bf16 v[46:49], v[84:87], v[76:79], v[46:49]
	v_pk_mov_b32 v[84:85], v[82:83], v[80:81] op_sel:[1,0]
	v_mov_b32_e32 v83, v81
	v_pk_add_f32 v[80:81], v[84:85], v[82:83]
	s_waitcnt lgkmcnt(1)
	v_mfma_f32_16x16x32_bf16 v[50:53], v[58:61], v[76:79], v[50:53]
	v_add_f32_e32 v80, v80, v81
	ds_bpermute_b32 v58, v65, v80
	v_mov_b32_e32 v60, v147
	s_waitcnt lgkmcnt(1)
	v_mfma_f32_16x16x32_bf16 v[42:45], v[72:75], v[76:79], v[42:45]
	v_mov_b32_e32 v74, v147
	v_mov_b32_e32 v75, v147
	s_waitcnt lgkmcnt(0)
	v_add_f32_e32 v86, v80, v58
	v_cvt_pk_bf16_f32 v58, v92, v93
	v_cvt_pk_bf16_f32 v59, v94, v95
	ds_read_b64 v[72:73], v179 offset:37184
	ds_read_b64 v[76:77], v179 offset:45632
	v_mov_b32_e32 v61, v147
	v_mov_b32_e32 v78, v147
	v_mov_b32_e32 v79, v147
	s_waitcnt lgkmcnt(1)
	v_mfma_f32_16x16x32_bf16 v[46:49], v[72:75], v[58:61], v[46:49]
	ds_bpermute_b32 v72, v66, v86
	v_fma_f32 v73, v64, s61, -v112
	v_exp_f32_e32 v73, v73
	ds_read_b64 v[80:81], v179 offset:54080
	ds_read_b64 v[84:85], v179 offset:62528
	v_mov_b32_e32 v82, v147
	s_waitcnt lgkmcnt(2)
	v_add_f32_e32 v72, v86, v72
	v_add_f32_e32 v72, v73, v72
	v_mov_b32_e32 v83, v147
	v_mov_b32_e32 v86, v147
	v_mov_b32_e32 v87, v147
	v_div_scale_f32 v73, s[68:69], v72, v72, 1.0
	v_rcp_f32_e32 v74, v73
	v_mfma_f32_16x16x32_bf16 v[54:57], v[76:79], v[58:61], v[54:57]
	s_waitcnt lgkmcnt(1)
	v_mfma_f32_16x16x32_bf16 v[50:53], v[80:83], v[58:61], v[50:53]
	s_waitcnt lgkmcnt(0)
	v_mfma_f32_16x16x32_bf16 v[42:45], v[84:87], v[58:61], v[42:45]
	v_fma_f32 v58, -v73, v74, 1.0
	v_fmac_f32_e32 v74, v58, v74
	v_div_scale_f32 v58, vcc, 1.0, v72, 1.0
	v_mul_f32_e32 v59, v58, v74
	v_fma_f32 v60, -v73, v59, v58
	v_fmac_f32_e32 v59, v60, v74
	v_fma_f32 v58, -v73, v59, v58
	v_div_fmas_f32 v58, v58, v74, v59
	v_div_fixup_f32 v58, v58, v72, 1.0
	v_pk_mul_f32 v[48:49], v[58:59], v[48:49] op_sel_hi:[0,1]
	v_pk_mul_f32 v[46:47], v[58:59], v[46:47] op_sel_hi:[0,1]
	v_add_co_u32_e32 v92, vcc, s53, v62
	v_cvt_pk_bf16_f32 v46, v46, v47
	v_cvt_pk_bf16_f32 v47, v48, v49
	v_pk_mul_f32 v[48:49], v[58:59], v[54:55] op_sel_hi:[0,1]
	s_nop 0
	v_addc_co_u32_e32 v93, vcc, 0, v63, vcc
	v_lshrrev_b32_e32 v110, 4, v0
	v_and_b32_e32 v110, 1, v110
	v_mul_u32_u24_e32 v110, 24, v110
	v_mov_b32_e32 v111, 0
	v_lshl_add_u64 v[118:119], v[92:93], 0, v[110:111]
	v_mov_b32_e32 v114, v46
	v_mov_b32_e32 v115, v47
	v_pk_mul_f32 v[46:47], v[58:59], v[56:57] op_sel_hi:[0,1]
	v_cvt_pk_bf16_f32 v48, v48, v49
	v_cvt_pk_bf16_f32 v49, v46, v47
	v_mov_b32_e32 v116, v48
	v_mov_b32_e32 v117, v49
	s_nop 1
	v_permlane16_swap_b32_e32 v114, v116
	v_permlane16_swap_b32_e32 v115, v117
	global_store_dwordx4 v[118:119], v[114:117], off
	v_pk_mul_f32 v[48:49], v[58:59], v[50:51] op_sel_hi:[0,1]
	v_pk_mul_f32 v[46:47], v[58:59], v[52:53] op_sel_hi:[0,1]
	v_cvt_pk_bf16_f32 v48, v48, v49
	v_cvt_pk_bf16_f32 v49, v46, v47
	v_pk_mul_f32 v[44:45], v[58:59], v[44:45] op_sel_hi:[0,1]
	v_pk_mul_f32 v[42:43], v[58:59], v[42:43] op_sel_hi:[0,1]
	v_mov_b32_e32 v126, v48
	v_mov_b32_e32 v127, v49
	v_cvt_pk_bf16_f32 v94, v42, v43
	v_cvt_pk_bf16_f32 v95, v44, v45
	ds_read_b128 v[42:45], v178 offset:6912
	ds_read_b128 v[46:49], v178 offset:6976
	s_waitcnt lgkmcnt(1)
	v_mfma_f32_16x16x32_bf16 v[42:45], v[42:45], v[34:37], 0
	ds_read_b128 v[50:53], v178 offset:9216
	ds_read_b128 v[54:57], v178 offset:11520
	ds_read_b128 v[58:61], v178 offset:13824
	s_waitcnt lgkmcnt(3)
	v_mfma_f32_16x16x32_bf16 v[46:49], v[46:49], v[38:41], v[42:45]
	ds_read_b128 v[72:75], v178 offset:16128
	ds_read_b128 v[76:79], v178 offset:18432
	ds_read_b128 v[80:83], v178 offset:20736
	ds_read_b128 v[42:45], v178 offset:9280
	s_waitcnt lgkmcnt(6)
	v_mfma_f32_16x16x32_bf16 v[50:53], v[50:53], v[34:37], 0
	ds_read_b128 v[84:87], v178 offset:23040
	ds_read_b128 v[88:91], v178 offset:25344
	v_mov_b32_e32 v128, v94
	v_mov_b32_e32 v129, v95
	s_nop 1
	v_permlane16_swap_b32_e32 v126, v128
	v_permlane16_swap_b32_e32 v127, v129
	global_store_dwordx4 v[118:119], v[126:129], off offset:64
	s_waitcnt lgkmcnt(2)
; __device__ __forceinline__ void attn_unit(LAS unsigned char* lds, bf16* Q, const bf16* Kg, const bf16* Vg, const float* snk, int unit, int tid) {
;     ...
;             f32x4 z = {0.f, 0.f, 0.f, 0.f}; z = __builtin_amdgcn_mfma_f32_16x16x32_bf16(k0, qf[mt][0], z, 0, 0, 0); z = __builtin_amdgcn_mfma_f32_16x16x32_bf16(k1, qf[mt][1], z, 0, 0, 0); st[kb] = z; }
;         float mx = sink;
; #pragma unroll
;         for (int kb = 0; kb < 9; ++kb) {
;             const bool tile_ok = (n > 0) || (mt + kb >= 8);
; #pragma unroll
;             for (int i = 0; i < 4; ++i) { const bool ok = tile_ok && (kb == 0 ? lo_ok[i] : (kb == 8 ? !lo_ok[i] : true));
;                 st[kb][i] = ok ? st[kb][i] : -INFINITY; mx = fmaxf(mx, st[kb][i]); }
;         }
;         mx = fmaxf(mx, __shfl_xor(mx, 16)); mx = fmaxf(mx, __shfl_xor(mx, 32));
;         f32x4 ls4 = {0.f, 0.f, 0.f, 0.f};
; #pragma unroll
;         for (int kb = 0; kb < 9; ++kb) { f32x4 d = st[kb] - mx;
; #pragma unroll
;             for (int i = 0; i < 4; ++i) d[i] = __builtin_amdgcn_exp2f(d[i]);
;             st[kb] = d; ls4 = ls4 + d; }
;         float ls = (ls4[0] + ls4[1]) + (ls4[2] + ls4[3]);
;         ls += __shfl_xor(ls, 16); ls += __shfl_xor(ls, 32);
;         const float inv = 1.f / (ls + __builtin_amdgcn_exp2f(sink - mx));
;         f32x4 o[4];
; #pragma unroll
;         for (int dt = 0; dt < 4; ++dt) o[dt] = (f32x4){0.f, 0.f, 0.f, 0.f};
; #pragma unroll
;         for (int kp = 0; kp < 5; ++kp) {
;             v4u pw; pw.x = cvt_pk_bf16(st[2 * kp][0], st[2 * kp][1]); pw.y = cvt_pk_bf16(st[2 * kp][2], st[2 * kp][3]);
;             if (kp < 4) { pw.z = cvt_pk_bf16(st[(2 * kp + 1) % 9][0], st[(2 * kp + 1) % 9][1]); pw.w = cvt_pk_bf16(st[(2 * kp + 1) % 9][2], st[(2 * kp + 1) % 9][3]); } else { pw.z = 0u; pw.w = 0u; }
;             const bf16x8_t pb = __builtin_bit_cast(bf16x8_t, pw);
; #pragma unroll
;             for (int dt = 0; dt < 4; ++dt) { const LAS unsigned char* vp = lds + ATT_VOFF + (16 * dt + fr) * ATT_VP + (16 * (mt + 2 * kp) + 4 * fq) * 2;
;                 const v2u lo = *(const LAS v2u*)vp; v2u hi = {0u, 0u}; if (kp < 4) hi = *(const LAS v2u*)(vp + 32);
;                 v4u aw; aw.x = lo.x; aw.y = lo.y; aw.z = hi.x; aw.w = hi.y;
;                 o[dt] = __builtin_amdgcn_mfma_f32_16x16x32_bf16(__builtin_bit_cast(bf16x8_t, aw), pb, o[dt], 0, 0, 0); }
;         }
	v_mfma_f32_16x16x32_bf16 v[50:53], v[42:45], v[38:41], v[50:53]
	ds_read_b128 v[42:45], v178 offset:11584
	v_mfma_f32_16x16x32_bf16 v[54:57], v[54:57], v[34:37], 0
	s_waitcnt lgkmcnt(0)
	v_mfma_f32_16x16x32_bf16 v[54:57], v[42:45], v[38:41], v[54:57]
	ds_read_b128 v[42:45], v178 offset:13888
	v_mfma_f32_16x16x32_bf16 v[58:61], v[58:61], v[34:37], 0
	s_waitcnt lgkmcnt(0)
	v_mfma_f32_16x16x32_bf16 v[58:61], v[42:45], v[38:41], v[58:61]
	ds_read_b128 v[42:45], v178 offset:16192
	v_mfma_f32_16x16x32_bf16 v[72:75], v[72:75], v[34:37], 0
	s_waitcnt lgkmcnt(0)
	v_mfma_f32_16x16x32_bf16 v[72:75], v[42:45], v[38:41], v[72:75]
	ds_read_b128 v[42:45], v178 offset:18496
	v_mfma_f32_16x16x32_bf16 v[76:79], v[76:79], v[34:37], 0
	s_waitcnt lgkmcnt(0)
	v_mfma_f32_16x16x32_bf16 v[76:79], v[42:45], v[38:41], v[76:79]
	ds_read_b128 v[42:45], v178 offset:20800
	v_mfma_f32_16x16x32_bf16 v[80:83], v[80:83], v[34:37], 0
	s_waitcnt lgkmcnt(0)
	v_mfma_f32_16x16x32_bf16 v[80:83], v[42:45], v[38:41], v[80:83]
	ds_read_b128 v[42:45], v178 offset:23104
	v_mfma_f32_16x16x32_bf16 v[84:87], v[84:87], v[34:37], 0
	s_waitcnt lgkmcnt(0)
	v_mfma_f32_16x16x32_bf16 v[42:45], v[42:45], v[38:41], v[84:87]
	s_nop 5
	ds_read_b128 v[84:87], v178 offset:25408
	v_mfma_f32_16x16x32_bf16 v[34:37], v[88:91], v[34:37], 0
	v_cndmask_b32_e64 v88, v190, v75, s[16:17]
	s_waitcnt lgkmcnt(0)
	v_mfma_f32_16x16x32_bf16 v[34:37], v[84:87], v[38:41], v[34:37]
	v_cndmask_b32_e64 v39, v47, v190, s[10:11]
	v_cndmask_b32_e64 v38, v190, v46, s[20:21]
	v_cndmask_b32_e64 v39, v190, v39, s[16:17]
	v_max3_f32 v40, v71, v38, v39
	v_cndmask_b32_e64 v41, v190, v48, s[18:19]
	v_cndmask_b32_e64 v46, v190, v49, s[22:23]
	v_max3_f32 v40, v40, v41, v46
	v_cndmask_b32_e64 v47, v190, v50, s[16:17]
	v_cndmask_b32_e64 v48, v190, v51, s[16:17]
	v_max3_f32 v40, v40, v47, v48
	v_cndmask_b32_e64 v49, v190, v52, s[16:17]
	v_cndmask_b32_e64 v50, v190, v53, s[16:17]
	v_max3_f32 v40, v40, v49, v50
	v_cndmask_b32_e64 v51, v190, v54, s[16:17]
	v_cndmask_b32_e64 v52, v190, v55, s[16:17]
	v_max3_f32 v40, v40, v51, v52
	v_cndmask_b32_e64 v53, v190, v56, s[16:17]
	v_cndmask_b32_e64 v54, v190, v57, s[16:17]
	v_max3_f32 v40, v40, v53, v54
	v_cndmask_b32_e64 v55, v190, v58, s[16:17]
	v_cndmask_b32_e64 v56, v190, v59, s[16:17]
	v_max3_f32 v40, v40, v55, v56
	v_cndmask_b32_e64 v57, v190, v60, s[16:17]
	v_cndmask_b32_e64 v84, v190, v61, s[16:17]
	v_max3_f32 v40, v40, v57, v84
	v_cndmask_b32_e64 v85, v190, v72, s[16:17]
	v_cndmask_b32_e64 v86, v190, v73, s[16:17]
	v_max3_f32 v40, v40, v85, v86
	v_cndmask_b32_e64 v87, v190, v74, s[16:17]
	v_max3_f32 v40, v40, v87, v88
	v_max3_f32 v40, v40, v76, v77
	v_max3_f32 v40, v40, v78, v79
	v_max3_f32 v40, v40, v80, v81
	v_max3_f32 v40, v40, v82, v83
	v_max3_f32 v40, v40, v42, v43
	v_max3_f32 v40, v40, v44, v45
	v_cndmask_b32_e64 v100, v34, v190, s[8:9]
	v_cndmask_b32_e64 v101, v190, v35, s[10:11]
	v_max3_f32 v34, v40, v100, v101
	v_cndmask_b32_e64 v102, v36, v190, s[12:13]
	v_cndmask_b32_e64 v103, v37, v190, s[14:15]
	v_max3_f32 v34, v34, v102, v103
	ds_bpermute_b32 v35, v65, v34
	s_waitcnt lgkmcnt(0)
	v_max_f32_e32 v35, v35, v35
	v_max_f32_e32 v34, v34, v35
	ds_bpermute_b32 v35, v66, v34
	s_waitcnt lgkmcnt(0)
	v_max_f32_e32 v35, v35, v35
	v_max_f32_e32 v104, v34, v35
	v_sub_f32_e32 v35, v46, v104
	v_sub_f32_e32 v36, v41, v104
	v_sub_f32_e32 v39, v39, v104
	v_sub_f32_e32 v34, v38, v104
	v_exp_f32_e32 v34, v34
	v_exp_f32_e32 v36, v36
	v_exp_f32_e32 v37, v35
	v_exp_f32_e32 v35, v39
	v_sub_f32_e32 v50, v50, v104
	v_sub_f32_e32 v49, v49, v104
	v_sub_f32_e32 v48, v48, v104
	v_sub_f32_e32 v46, v47, v104
	v_exp_f32_e32 v46, v46
	v_exp_f32_e32 v47, v48
	v_exp_f32_e32 v48, v49
	v_exp_f32_e32 v49, v50
	v_sub_f32_e32 v50, v54, v104
	v_sub_f32_e32 v53, v53, v104
	v_sub_f32_e32 v52, v52, v104
	v_sub_f32_e32 v51, v51, v104
	v_exp_f32_e32 v58, v51
	v_exp_f32_e32 v60, v53
	v_exp_f32_e32 v61, v50
	v_exp_f32_e32 v59, v52
	v_sub_f32_e32 v50, v84, v104
	v_sub_f32_e32 v51, v57, v104
	v_sub_f32_e32 v52, v56, v104
	v_sub_f32_e32 v53, v55, v104
	v_exp_f32_e32 v72, v53
	v_exp_f32_e32 v73, v52
	v_exp_f32_e32 v74, v51
	v_exp_f32_e32 v75, v50
	v_sub_f32_e32 v50, v88, v104
	v_sub_f32_e32 v51, v87, v104
	v_sub_f32_e32 v52, v86, v104
	v_sub_f32_e32 v53, v85, v104
	v_pk_add_f32 v[38:39], v[36:37], 0 op_sel_hi:[1,0]
	v_pk_add_f32 v[40:41], v[34:35], 0 op_sel_hi:[1,0]
	v_exp_f32_e32 v84, v53
	v_exp_f32_e32 v86, v51
	v_exp_f32_e32 v87, v50
	v_exp_f32_e32 v85, v52
	v_pk_add_f32 v[40:41], v[46:47], v[40:41]
	v_pk_add_f32 v[38:39], v[48:49], v[38:39]
	v_pk_add_f32 v[40:41], v[58:59], v[40:41]
	v_pk_add_f32 v[38:39], v[60:61], v[38:39]
	v_pk_add_f32 v[40:41], v[72:73], v[40:41]
	v_pk_add_f32 v[38:39], v[74:75], v[38:39]
	v_sub_f32_e32 v52, v76, v104
	v_pk_add_f32 v[50:51], v[86:87], v[38:39]
	v_pk_add_f32 v[38:39], v[84:85], v[40:41]
	v_sub_f32_e32 v41, v77, v104
	v_sub_f32_e32 v40, v79, v104
	v_exp_f32_e32 v89, v41
	v_sub_f32_e32 v41, v78, v104
	v_exp_f32_e32 v88, v52
	v_exp_f32_e32 v90, v41
	v_exp_f32_e32 v91, v40
	v_sub_f32_e32 v54, v83, v104
	v_sub_f32_e32 v55, v82, v104
	v_sub_f32_e32 v56, v81, v104
	v_sub_f32_e32 v57, v80, v104
	v_exp_f32_e32 v80, v55
	v_exp_f32_e32 v81, v54
	v_exp_f32_e32 v82, v57
	v_exp_f32_e32 v83, v56
	v_pk_add_f32 v[52:53], v[88:89], v[38:39]
	v_pk_add_f32 v[50:51], v[90:91], v[50:51]
	v_cvt_pk_bf16_f32 v34, v34, v35
	v_cvt_pk_bf16_f32 v35, v36, v37
	v_cvt_pk_bf16_f32 v36, v46, v47
	v_cvt_pk_bf16_f32 v37, v48, v49
	ds_read2_b64 v[38:41], v67 offset0:12 offset1:16
	ds_read2_b64 v[46:49], v68 offset0:44 offset1:48
	v_pk_add_f32 v[92:93], v[80:81], v[50:51]
	v_pk_add_f32 v[94:95], v[82:83], v[52:53]
	ds_read2_b64 v[50:53], v70 offset0:76 offset1:80
	ds_read2_b64 v[54:57], v69 offset0:108 offset1:112
	v_sub_f32_e32 v44, v44, v104
	v_sub_f32_e32 v43, v43, v104
	v_sub_f32_e32 v42, v42, v104
	v_sub_f32_e32 v99, v45, v104
	v_cvt_pk_bf16_f32 v58, v58, v59
	v_cvt_pk_bf16_f32 v59, v60, v61
	v_cvt_pk_bf16_f32 v60, v72, v73
	v_cvt_pk_bf16_f32 v61, v74, v75
	ds_read2_b64 v[72:75], v67 offset0:20 offset1:24
	v_exp_f32_e32 v96, v42
	v_exp_f32_e32 v97, v43
	v_exp_f32_e32 v98, v44
	ds_read2_b64 v[42:45], v70 offset0:84 offset1:88
	s_waitcnt lgkmcnt(5)
; __device__ __forceinline__ unsigned cvt_pk_bf16(float lo, float hi) { unsigned r; asm volatile("v_cvt_pk_bf16_f32 %0, %1, %2" : "=v"(r) : "v"(lo), "v"(hi)); return r; }
; #define LAS __attribute__((address_space(3)))
; __device__ __forceinline__ void attn_unit(LAS unsigned char* lds, bf16* Q, const bf16* Kg, const bf16* Vg, const float* snk, int unit, int tid) {
;     ...
;         for (int kb = 0; kb < 9; ++kb) { const LAS unsigned char* kp = lds + (16 * (mt + kb) + fr) * ATT_KP + 16 * fq;
;             const bf16x8_t k0 = *(const LAS bf16x8_t*)kp, k1 = *(const LAS bf16x8_t*)(kp + 64);
;             f32x4 z = {0.f, 0.f, 0.f, 0.f}; z = __builtin_amdgcn_mfma_f32_16x16x32_bf16(k0, qf[mt][0], z, 0, 0, 0); z = __builtin_amdgcn_mfma_f32_16x16x32_bf16(k1, qf[mt][1], z, 0, 0, 0); st[kb] = z; }
;     ...
;         for (int kp = 0; kp < 5; ++kp) {
;             v4u pw; pw.x = cvt_pk_bf16(st[2 * kp][0], st[2 * kp][1]); pw.y = cvt_pk_bf16(st[2 * kp][2], st[2 * kp][3]);
;             if (kp < 4) { pw.z = cvt_pk_bf16(st[(2 * kp + 1) % 9][0], st[(2 * kp + 1) % 9][1]); pw.w = cvt_pk_bf16(st[(2 * kp + 1) % 9][2], st[(2 * kp + 1) % 9][3]); } else { pw.z = 0u; pw.w = 0u; }
;             const bf16x8_t pb = __builtin_bit_cast(bf16x8_t, pw);
; #pragma unroll
;             for (int dt = 0; dt < 4; ++dt) { const LAS unsigned char* vp = lds + ATT_VOFF + (16 * dt + fr) * ATT_VP + (16 * (mt + 2 * kp) + 4 * fq) * 2;
;                 const v2u lo = *(const LAS v2u*)vp; v2u hi = {0u, 0u}; if (kp < 4) hi = *(const LAS v2u*)(vp + 32);
;                 v4u aw; aw.x = lo.x; aw.y = lo.y; aw.z = hi.x; aw.w = hi.y;
;                 o[dt] = __builtin_amdgcn_mfma_f32_16x16x32_bf16(__builtin_bit_cast(bf16x8_t, aw), pb, o[dt], 0, 0, 0); }
;         }
; #pragma unroll
;         for (int dt = 0; dt < 4; ++dt) { const f32x4 y = o[dt] * inv; v2u w; w.x = cvt_pk_bf16(y[0], y[1]); w.y = cvt_pk_bf16(y[2], y[3]); *(v2u*)(qbase + (size_t)mt * 16 * 1024 + 16 * dt + 4 * fq) = w; }
	v_mfma_f32_16x16x32_bf16 v[38:41], v[38:41], v[34:37], 0
	ds_read2_b64 v[76:79], v68 offset0:52 offset1:56
	v_exp_f32_e32 v99, v99
	s_waitcnt lgkmcnt(5)
	v_mfma_f32_16x16x32_bf16 v[46:49], v[46:49], v[34:37], 0
	s_waitcnt lgkmcnt(4)
	v_mfma_f32_16x16x32_bf16 v[50:53], v[50:53], v[34:37], 0
	s_waitcnt lgkmcnt(3)
	v_mfma_f32_16x16x32_bf16 v[34:37], v[54:57], v[34:37], 0
	ds_read2_b64 v[54:57], v69 offset0:116 offset1:120
	s_waitcnt lgkmcnt(3)
	v_mfma_f32_16x16x32_bf16 v[38:41], v[72:75], v[58:61], v[38:41]
	v_cvt_pk_bf16_f32 v72, v84, v85
	v_cvt_pk_bf16_f32 v73, v86, v87
	v_cvt_pk_bf16_f32 v74, v88, v89
	v_cvt_pk_bf16_f32 v75, v90, v91
	s_waitcnt lgkmcnt(2)
	v_mfma_f32_16x16x32_bf16 v[42:45], v[42:45], v[58:61], v[50:53]
	v_sub_f32_e32 v89, v103, v104
	v_sub_f32_e32 v90, v102, v104
	v_sub_f32_e32 v91, v101, v104
	ds_read2_b64 v[50:53], v68 offset0:60 offset1:64
	s_waitcnt lgkmcnt(2)
	v_mfma_f32_16x16x32_bf16 v[46:49], v[76:79], v[58:61], v[46:49]
	ds_read2_b64 v[76:79], v67 offset0:28 offset1:32
	v_pk_add_f32 v[84:85], v[96:97], v[94:95]
	v_pk_add_f32 v[86:87], v[98:99], v[92:93]
	s_waitcnt lgkmcnt(2)
	v_mfma_f32_16x16x32_bf16 v[34:37], v[54:57], v[58:61], v[34:37]
	ds_read2_b64 v[54:57], v70 offset0:92 offset1:96
	v_sub_f32_e32 v58, v100, v104
	v_exp_f32_e32 v88, v58
	s_waitcnt lgkmcnt(2)
	v_mfma_f32_16x16x32_bf16 v[46:49], v[50:53], v[72:75], v[46:49]
	ds_read2_b64 v[50:53], v69 offset0:124 offset1:128
	v_cvt_pk_bf16_f32 v58, v82, v83
	v_cvt_pk_bf16_f32 v59, v80, v81
	v_cvt_pk_bf16_f32 v60, v96, v97
	v_cvt_pk_bf16_f32 v61, v98, v99
	s_waitcnt lgkmcnt(1)
	v_mfma_f32_16x16x32_bf16 v[42:45], v[54:57], v[72:75], v[42:45]
	ds_read2_b64 v[54:57], v68 offset0:68 offset1:72
	v_exp_f32_e32 v80, v90
	v_exp_f32_e32 v81, v89
	v_mfma_f32_16x16x32_bf16 v[38:41], v[76:79], v[72:75], v[38:41]
	ds_read2_b64 v[76:79], v67 offset0:36 offset1:40
	v_exp_f32_e32 v89, v91
	s_waitcnt lgkmcnt(2)
	v_mfma_f32_16x16x32_bf16 v[34:37], v[50:53], v[72:75], v[34:37]
	ds_read2_b64 v[50:53], v70 offset0:100 offset1:104
	v_pk_add_f32 v[72:73], v[80:81], v[86:87]
	v_pk_add_f32 v[74:75], v[88:89], v[84:85]
	s_waitcnt lgkmcnt(2)
	v_mfma_f32_16x16x32_bf16 v[46:49], v[54:57], v[58:61], v[46:49]
	ds_read2_b64 v[54:57], v69 offset0:132 offset1:136
	s_waitcnt lgkmcnt(2)
	v_mfma_f32_16x16x32_bf16 v[38:41], v[76:79], v[58:61], v[38:41]
	v_pk_mov_b32 v[76:77], v[74:75], v[72:73] op_sel:[1,0]
	v_mov_b32_e32 v75, v73
	v_pk_add_f32 v[72:73], v[76:77], v[74:75]
	s_waitcnt lgkmcnt(1)
	v_mfma_f32_16x16x32_bf16 v[42:45], v[50:53], v[58:61], v[42:45]
	v_add_f32_e32 v72, v72, v73
	ds_bpermute_b32 v50, v65, v72
	v_mov_b32_e32 v52, v147
	s_waitcnt lgkmcnt(1)
	v_mfma_f32_16x16x32_bf16 v[34:37], v[54:57], v[58:61], v[34:37]
	v_mov_b32_e32 v56, v147
	v_mov_b32_e32 v57, v147
	s_waitcnt lgkmcnt(0)
	v_add_f32_e32 v78, v72, v50
	v_cvt_pk_bf16_f32 v50, v88, v89
	v_cvt_pk_bf16_f32 v51, v80, v81
	ds_read_b64 v[54:55], v179 offset:37216
	ds_read_b64 v[58:59], v179 offset:45664
	v_mov_b32_e32 v53, v147
	v_mov_b32_e32 v60, v147
	v_mov_b32_e32 v61, v147
	s_waitcnt lgkmcnt(1)
	v_mfma_f32_16x16x32_bf16 v[38:41], v[54:57], v[50:53], v[38:41]
	ds_bpermute_b32 v54, v66, v78
	v_fma_f32 v55, v64, s61, -v104
	v_exp_f32_e32 v55, v55
	ds_read_b64 v[72:73], v179 offset:54112
	ds_read_b64 v[76:77], v179 offset:62560
	v_mov_b32_e32 v74, v147
	s_waitcnt lgkmcnt(2)
	v_add_f32_e32 v54, v78, v54
	v_add_f32_e32 v54, v55, v54
	v_mov_b32_e32 v75, v147
	v_mov_b32_e32 v78, v147
	v_mov_b32_e32 v79, v147
	v_div_scale_f32 v55, s[68:69], v54, v54, 1.0
	v_rcp_f32_e32 v56, v55
	v_mfma_f32_16x16x32_bf16 v[46:49], v[58:61], v[50:53], v[46:49]
	s_waitcnt lgkmcnt(1)
	v_mfma_f32_16x16x32_bf16 v[42:45], v[72:75], v[50:53], v[42:45]
	s_waitcnt lgkmcnt(0)
	v_mfma_f32_16x16x32_bf16 v[34:37], v[76:79], v[50:53], v[34:37]
	v_fma_f32 v50, -v55, v56, 1.0
	v_fmac_f32_e32 v56, v50, v56
	v_div_scale_f32 v50, vcc, 1.0, v54, 1.0
	v_mul_f32_e32 v51, v50, v56
	v_fma_f32 v52, -v55, v51, v50
	v_fmac_f32_e32 v51, v52, v56
	v_fma_f32 v50, -v55, v51, v50
	v_div_fmas_f32 v50, v50, v56, v51
	v_div_fixup_f32 v50, v50, v54, 1.0
	v_pk_mul_f32 v[40:41], v[50:51], v[40:41] op_sel_hi:[0,1]
	v_pk_mul_f32 v[38:39], v[50:51], v[38:39] op_sel_hi:[0,1]
	v_add_co_u32_e32 v84, vcc, s54, v62
	v_cvt_pk_bf16_f32 v38, v38, v39
	v_cvt_pk_bf16_f32 v39, v40, v41
	v_pk_mul_f32 v[40:41], v[50:51], v[46:47] op_sel_hi:[0,1]
	s_nop 0
	v_addc_co_u32_e32 v85, vcc, 0, v63, vcc
	v_lshrrev_b32_e32 v110, 4, v0
	v_and_b32_e32 v110, 1, v110
	v_mul_u32_u24_e32 v110, 24, v110
	v_mov_b32_e32 v111, 0
	v_lshl_add_u64 v[118:119], v[84:85], 0, v[110:111]
	v_mov_b32_e32 v114, v38
	v_mov_b32_e32 v115, v39
	v_pk_mul_f32 v[38:39], v[50:51], v[48:49] op_sel_hi:[0,1]
	v_cvt_pk_bf16_f32 v40, v40, v41
	v_cvt_pk_bf16_f32 v41, v38, v39
	v_mov_b32_e32 v116, v40
	v_mov_b32_e32 v117, v41
	s_nop 1
	v_permlane16_swap_b32_e32 v114, v116
	v_permlane16_swap_b32_e32 v115, v117
	global_store_dwordx4 v[118:119], v[114:117], off
	v_pk_mul_f32 v[40:41], v[50:51], v[42:43] op_sel_hi:[0,1]
	v_pk_mul_f32 v[38:39], v[50:51], v[44:45] op_sel_hi:[0,1]
	v_cvt_pk_bf16_f32 v40, v40, v41
	v_cvt_pk_bf16_f32 v41, v38, v39
	v_pk_mul_f32 v[36:37], v[50:51], v[36:37] op_sel_hi:[0,1]
	v_pk_mul_f32 v[34:35], v[50:51], v[34:35] op_sel_hi:[0,1]
	v_mov_b32_e32 v126, v40
	v_mov_b32_e32 v127, v41
	v_cvt_pk_bf16_f32 v86, v34, v35
	v_cvt_pk_bf16_f32 v87, v36, v37
	ds_read_b128 v[34:37], v178 offset:9216
	ds_read_b128 v[38:41], v178 offset:9280
	s_waitcnt lgkmcnt(1)
	v_mfma_f32_16x16x32_bf16 v[34:37], v[34:37], v[26:29], 0
	ds_read_b128 v[42:45], v178 offset:11520
	ds_read_b128 v[46:49], v178 offset:13824
	ds_read_b128 v[50:53], v178 offset:16128
	s_waitcnt lgkmcnt(3)
; __device__ __forceinline__ void attn_unit(LAS unsigned char* lds, bf16* Q, const bf16* Kg, const bf16* Vg, const float* snk, int unit, int tid) {
;     ...
;         for (int kb = 0; kb < 9; ++kb) { const LAS unsigned char* kp = lds + (16 * (mt + kb) + fr) * ATT_KP + 16 * fq;
;             const bf16x8_t k0 = *(const LAS bf16x8_t*)kp, k1 = *(const LAS bf16x8_t*)(kp + 64);
;             f32x4 z = {0.f, 0.f, 0.f, 0.f}; z = __builtin_amdgcn_mfma_f32_16x16x32_bf16(k0, qf[mt][0], z, 0, 0, 0); z = __builtin_amdgcn_mfma_f32_16x16x32_bf16(k1, qf[mt][1], z, 0, 0, 0); st[kb] = z; }
;         float mx = sink;
; #pragma unroll
;         for (int kb = 0; kb < 9; ++kb) {
;             const bool tile_ok = (n > 0) || (mt + kb >= 8);
; #pragma unroll
;             for (int i = 0; i < 4; ++i) { const bool ok = tile_ok && (kb == 0 ? lo_ok[i] : (kb == 8 ? !lo_ok[i] : true));
;                 st[kb][i] = ok ? st[kb][i] : -INFINITY; mx = fmaxf(mx, st[kb][i]); }
;         }
;         mx = fmaxf(mx, __shfl_xor(mx, 16)); mx = fmaxf(mx, __shfl_xor(mx, 32));
;         f32x4 ls4 = {0.f, 0.f, 0.f, 0.f};
; #pragma unroll
;         for (int kb = 0; kb < 9; ++kb) { f32x4 d = st[kb] - mx;
; #pragma unroll
;             for (int i = 0; i < 4; ++i) d[i] = __builtin_amdgcn_exp2f(d[i]);
;             st[kb] = d; ls4 = ls4 + d; }
;         float ls = (ls4[0] + ls4[1]) + (ls4[2] + ls4[3]);
;         ls += __shfl_xor(ls, 16); ls += __shfl_xor(ls, 32);
;         const float inv = 1.f / (ls + __builtin_amdgcn_exp2f(sink - mx));
;         f32x4 o[4];
; #pragma unroll
;         for (int dt = 0; dt < 4; ++dt) o[dt] = (f32x4){0.f, 0.f, 0.f, 0.f};
; #pragma unroll
;         for (int kp = 0; kp < 5; ++kp) {
;             v4u pw; pw.x = cvt_pk_bf16(st[2 * kp][0], st[2 * kp][1]); pw.y = cvt_pk_bf16(st[2 * kp][2], st[2 * kp][3]);
;             if (kp < 4) { pw.z = cvt_pk_bf16(st[(2 * kp + 1) % 9][0], st[(2 * kp + 1) % 9][1]); pw.w = cvt_pk_bf16(st[(2 * kp + 1) % 9][2], st[(2 * kp + 1) % 9][3]); } else { pw.z = 0u; pw.w = 0u; }
;             const bf16x8_t pb = __builtin_bit_cast(bf16x8_t, pw);
; #pragma unroll
;             for (int dt = 0; dt < 4; ++dt) { const LAS unsigned char* vp = lds + ATT_VOFF + (16 * dt + fr) * ATT_VP + (16 * (mt + 2 * kp) + 4 * fq) * 2;
;                 const v2u lo = *(const LAS v2u*)vp; v2u hi = {0u, 0u}; if (kp < 4) hi = *(const LAS v2u*)(vp + 32);
	v_mfma_f32_16x16x32_bf16 v[38:41], v[38:41], v[30:33], v[34:37]
	ds_read_b128 v[54:57], v178 offset:18432
	ds_read_b128 v[58:61], v178 offset:20736
	ds_read_b128 v[72:75], v178 offset:23040
	ds_read_b128 v[34:37], v178 offset:11584
	s_waitcnt lgkmcnt(6)
	v_mfma_f32_16x16x32_bf16 v[42:45], v[42:45], v[26:29], 0
	ds_read_b128 v[76:79], v178 offset:25344
	ds_read_b128 v[80:83], v178 offset:27648
	v_mov_b32_e32 v128, v86
	v_mov_b32_e32 v129, v87
	s_nop 1
	v_permlane16_swap_b32_e32 v126, v128
	v_permlane16_swap_b32_e32 v127, v129
	global_store_dwordx4 v[118:119], v[126:129], off offset:64
	s_waitcnt lgkmcnt(2)
	v_mfma_f32_16x16x32_bf16 v[42:45], v[34:37], v[30:33], v[42:45]
	ds_read_b128 v[34:37], v178 offset:13888
	v_mfma_f32_16x16x32_bf16 v[46:49], v[46:49], v[26:29], 0
	s_waitcnt lgkmcnt(0)
	v_mfma_f32_16x16x32_bf16 v[46:49], v[34:37], v[30:33], v[46:49]
	ds_read_b128 v[34:37], v178 offset:16192
	v_mfma_f32_16x16x32_bf16 v[50:53], v[50:53], v[26:29], 0
	s_waitcnt lgkmcnt(0)
	v_mfma_f32_16x16x32_bf16 v[50:53], v[34:37], v[30:33], v[50:53]
	ds_read_b128 v[34:37], v178 offset:18496
	v_mfma_f32_16x16x32_bf16 v[54:57], v[54:57], v[26:29], 0
	s_waitcnt lgkmcnt(0)
	v_mfma_f32_16x16x32_bf16 v[54:57], v[34:37], v[30:33], v[54:57]
	ds_read_b128 v[34:37], v178 offset:20800
	v_mfma_f32_16x16x32_bf16 v[58:61], v[58:61], v[26:29], 0
	s_waitcnt lgkmcnt(0)
	v_mfma_f32_16x16x32_bf16 v[58:61], v[34:37], v[30:33], v[58:61]
	ds_read_b128 v[34:37], v178 offset:23104
	v_mfma_f32_16x16x32_bf16 v[72:75], v[72:75], v[26:29], 0
	s_waitcnt lgkmcnt(0)
	v_mfma_f32_16x16x32_bf16 v[72:75], v[34:37], v[30:33], v[72:75]
	ds_read_b128 v[34:37], v178 offset:25408
	v_mfma_f32_16x16x32_bf16 v[76:79], v[76:79], v[26:29], 0
	s_waitcnt lgkmcnt(0)
	v_mfma_f32_16x16x32_bf16 v[34:37], v[34:37], v[30:33], v[76:79]
	s_nop 5
	ds_read_b128 v[76:79], v178 offset:27712
	v_mfma_f32_16x16x32_bf16 v[26:29], v[80:83], v[26:29], 0
	s_waitcnt lgkmcnt(0)
	v_mfma_f32_16x16x32_bf16 v[26:29], v[76:79], v[30:33], v[26:29]
	v_cndmask_b32_e64 v31, v39, v190, s[10:11]
	v_cndmask_b32_e64 v30, v190, v38, s[20:21]
	v_cndmask_b32_e64 v31, v190, v31, s[16:17]
	v_max3_f32 v32, v71, v30, v31
	v_cndmask_b32_e64 v33, v190, v40, s[18:19]
	v_cndmask_b32_e64 v38, v190, v41, s[22:23]
	v_max3_f32 v32, v32, v33, v38
	v_cndmask_b32_e64 v39, v190, v42, s[16:17]
	v_cndmask_b32_e64 v40, v190, v43, s[16:17]
	v_max3_f32 v32, v32, v39, v40
	v_cndmask_b32_e64 v41, v190, v44, s[16:17]
	v_cndmask_b32_e64 v42, v190, v45, s[16:17]
	v_max3_f32 v32, v32, v41, v42
	v_cndmask_b32_e64 v43, v190, v46, s[16:17]
	v_cndmask_b32_e64 v44, v190, v47, s[16:17]
	v_max3_f32 v32, v32, v43, v44
	v_cndmask_b32_e64 v45, v190, v48, s[16:17]
	v_cndmask_b32_e64 v46, v190, v49, s[16:17]
	v_max3_f32 v32, v32, v45, v46
	v_cndmask_b32_e64 v47, v190, v50, s[16:17]
	v_cndmask_b32_e64 v48, v190, v51, s[16:17]
	v_max3_f32 v32, v32, v47, v48
	v_cndmask_b32_e64 v49, v190, v52, s[16:17]
	v_cndmask_b32_e64 v76, v190, v53, s[16:17]
	v_max3_f32 v32, v32, v49, v76
	v_max3_f32 v32, v32, v54, v55
	v_max3_f32 v32, v32, v56, v57
	v_max3_f32 v32, v32, v58, v59
	v_max3_f32 v32, v32, v60, v61
	v_max3_f32 v32, v32, v72, v73
	v_max3_f32 v32, v32, v74, v75
	v_max3_f32 v32, v32, v34, v35
	v_max3_f32 v32, v32, v36, v37
	v_cndmask_b32_e64 v92, v26, v190, s[8:9]
	v_cndmask_b32_e64 v93, v190, v27, s[10:11]
	v_max3_f32 v26, v32, v92, v93
	v_cndmask_b32_e64 v94, v28, v190, s[12:13]
	v_cndmask_b32_e64 v95, v29, v190, s[14:15]
	v_max3_f32 v26, v26, v94, v95
	ds_bpermute_b32 v27, v65, v26
	s_waitcnt lgkmcnt(0)
	v_max_f32_e32 v27, v27, v27
	v_max_f32_e32 v26, v26, v27
	ds_bpermute_b32 v27, v66, v26
	s_waitcnt lgkmcnt(0)
	v_max_f32_e32 v27, v27, v27
	v_max_f32_e32 v96, v26, v27
	v_sub_f32_e32 v27, v38, v96
	v_sub_f32_e32 v28, v33, v96
	v_sub_f32_e32 v31, v31, v96
	v_sub_f32_e32 v26, v30, v96
	v_exp_f32_e32 v26, v26
	v_exp_f32_e32 v28, v28
	v_exp_f32_e32 v29, v27
	v_exp_f32_e32 v27, v31
	v_sub_f32_e32 v42, v42, v96
	v_sub_f32_e32 v41, v41, v96
	v_sub_f32_e32 v40, v40, v96
	v_sub_f32_e32 v38, v39, v96
	v_exp_f32_e32 v38, v38
	v_exp_f32_e32 v39, v40
	v_exp_f32_e32 v40, v41
	v_exp_f32_e32 v41, v42
	v_sub_f32_e32 v42, v46, v96
	v_sub_f32_e32 v45, v45, v96
	v_sub_f32_e32 v44, v44, v96
	v_sub_f32_e32 v43, v43, v96
	v_exp_f32_e32 v50, v43
	v_exp_f32_e32 v52, v45
	v_exp_f32_e32 v53, v42
	v_exp_f32_e32 v51, v44
	v_sub_f32_e32 v42, v76, v96
	v_sub_f32_e32 v43, v49, v96
	v_sub_f32_e32 v44, v48, v96
	v_sub_f32_e32 v45, v47, v96
	v_exp_f32_e32 v76, v45
	v_exp_f32_e32 v77, v44
	v_exp_f32_e32 v78, v43
	v_exp_f32_e32 v79, v42
	v_sub_f32_e32 v42, v57, v96
	v_sub_f32_e32 v43, v56, v96
	v_sub_f32_e32 v44, v55, v96
	v_sub_f32_e32 v45, v54, v96
	v_pk_add_f32 v[30:31], v[28:29], 0 op_sel_hi:[1,0]
	v_pk_add_f32 v[32:33], v[26:27], 0 op_sel_hi:[1,0]
	v_exp_f32_e32 v80, v45
	v_exp_f32_e32 v82, v43
	v_exp_f32_e32 v83, v42
	v_exp_f32_e32 v81, v44
	v_pk_add_f32 v[32:33], v[38:39], v[32:33]
	v_pk_add_f32 v[30:31], v[40:41], v[30:31]
	v_pk_add_f32 v[32:33], v[50:51], v[32:33]
	v_pk_add_f32 v[30:31], v[52:53], v[30:31]
	v_pk_add_f32 v[32:33], v[76:77], v[32:33]
	v_pk_add_f32 v[30:31], v[78:79], v[30:31]
	v_sub_f32_e32 v44, v58, v96
	v_pk_add_f32 v[42:43], v[82:83], v[30:31]
	v_pk_add_f32 v[30:31], v[80:81], v[32:33]
	v_sub_f32_e32 v33, v59, v96
	v_sub_f32_e32 v32, v61, v96
	v_exp_f32_e32 v85, v33
	v_sub_f32_e32 v33, v60, v96
	v_exp_f32_e32 v84, v44
	v_exp_f32_e32 v86, v33
	v_exp_f32_e32 v87, v32
	v_sub_f32_e32 v46, v75, v96
	v_sub_f32_e32 v47, v74, v96
	v_sub_f32_e32 v48, v73, v96
	v_sub_f32_e32 v49, v72, v96
	v_exp_f32_e32 v72, v47
	v_exp_f32_e32 v73, v46
	v_exp_f32_e32 v74, v49
	v_exp_f32_e32 v75, v48
	v_pk_add_f32 v[44:45], v[84:85], v[30:31]
	v_pk_add_f32 v[42:43], v[86:87], v[42:43]
	v_cvt_pk_bf16_f32 v26, v26, v27
	v_cvt_pk_bf16_f32 v27, v28, v29
	v_cvt_pk_bf16_f32 v28, v38, v39
	v_cvt_pk_bf16_f32 v29, v40, v41
	ds_read2_b64 v[30:33], v67 offset0:16 offset1:20
	ds_read2_b64 v[38:41], v68 offset0:48 offset1:52
	v_pk_add_f32 v[88:89], v[72:73], v[42:43]
	v_pk_add_f32 v[90:91], v[74:75], v[44:45]
	ds_read2_b64 v[42:45], v70 offset0:80 offset1:84
	ds_read2_b64 v[46:49], v69 offset0:112 offset1:116
	v_sub_f32_e32 v36, v36, v96
	v_sub_f32_e32 v35, v35, v96
	v_sub_f32_e32 v34, v34, v96
	v_sub_f32_e32 v97, v37, v96
	v_cvt_pk_bf16_f32 v50, v50, v51
	v_cvt_pk_bf16_f32 v51, v52, v53
	v_cvt_pk_bf16_f32 v52, v76, v77
	v_cvt_pk_bf16_f32 v53, v78, v79
	ds_read2_b64 v[54:57], v67 offset0:24 offset1:28
	v_exp_f32_e32 v76, v34
	v_exp_f32_e32 v77, v35
	v_exp_f32_e32 v78, v36
	ds_read2_b64 v[34:37], v70 offset0:88 offset1:92
	s_waitcnt lgkmcnt(5)
; __device__ __forceinline__ unsigned cvt_pk_bf16(float lo, float hi) { unsigned r; asm volatile("v_cvt_pk_bf16_f32 %0, %1, %2" : "=v"(r) : "v"(lo), "v"(hi)); return r; }
; #define LAS __attribute__((address_space(3)))
; __device__ __forceinline__ void attn_unit(LAS unsigned char* lds, bf16* Q, const bf16* Kg, const bf16* Vg, const float* snk, int unit, int tid) {
;     ...
;         for (int kp = 0; kp < 5; ++kp) {
;             v4u pw; pw.x = cvt_pk_bf16(st[2 * kp][0], st[2 * kp][1]); pw.y = cvt_pk_bf16(st[2 * kp][2], st[2 * kp][3]);
;             if (kp < 4) { pw.z = cvt_pk_bf16(st[(2 * kp + 1) % 9][0], st[(2 * kp + 1) % 9][1]); pw.w = cvt_pk_bf16(st[(2 * kp + 1) % 9][2], st[(2 * kp + 1) % 9][3]); } else { pw.z = 0u; pw.w = 0u; }
;             const bf16x8_t pb = __builtin_bit_cast(bf16x8_t, pw);
; #pragma unroll
;             for (int dt = 0; dt < 4; ++dt) { const LAS unsigned char* vp = lds + ATT_VOFF + (16 * dt + fr) * ATT_VP + (16 * (mt + 2 * kp) + 4 * fq) * 2;
;                 const v2u lo = *(const LAS v2u*)vp; v2u hi = {0u, 0u}; if (kp < 4) hi = *(const LAS v2u*)(vp + 32);
;                 v4u aw; aw.x = lo.x; aw.y = lo.y; aw.z = hi.x; aw.w = hi.y;
;                 o[dt] = __builtin_amdgcn_mfma_f32_16x16x32_bf16(__builtin_bit_cast(bf16x8_t, aw), pb, o[dt], 0, 0, 0); }
;         }
; #pragma unroll
;         for (int dt = 0; dt < 4; ++dt) { const f32x4 y = o[dt] * inv; v2u w; w.x = cvt_pk_bf16(y[0], y[1]); w.y = cvt_pk_bf16(y[2], y[3]); *(v2u*)(qbase + (size_t)mt * 16 * 1024 + 16 * dt + 4 * fq) = w; }
	v_mfma_f32_16x16x32_bf16 v[30:33], v[30:33], v[26:29], 0
	ds_read2_b64 v[58:61], v68 offset0:56 offset1:60
	v_exp_f32_e32 v79, v97
	s_waitcnt lgkmcnt(5)
	v_mfma_f32_16x16x32_bf16 v[38:41], v[38:41], v[26:29], 0
	s_waitcnt lgkmcnt(4)
	v_mfma_f32_16x16x32_bf16 v[42:45], v[42:45], v[26:29], 0
	s_waitcnt lgkmcnt(3)
	v_mfma_f32_16x16x32_bf16 v[26:29], v[46:49], v[26:29], 0
	ds_read2_b64 v[46:49], v69 offset0:120 offset1:124
	s_waitcnt lgkmcnt(3)
	v_mfma_f32_16x16x32_bf16 v[30:33], v[54:57], v[50:53], v[30:33]
	v_cvt_pk_bf16_f32 v54, v80, v81
	v_cvt_pk_bf16_f32 v55, v82, v83
	v_cvt_pk_bf16_f32 v56, v84, v85
	v_cvt_pk_bf16_f32 v57, v86, v87
	s_waitcnt lgkmcnt(2)
	v_mfma_f32_16x16x32_bf16 v[34:37], v[34:37], v[50:53], v[42:45]
	v_sub_f32_e32 v85, v95, v96
	v_sub_f32_e32 v86, v94, v96
	v_sub_f32_e32 v87, v93, v96
	ds_read2_b64 v[42:45], v68 offset0:64 offset1:68
	s_waitcnt lgkmcnt(2)
	v_mfma_f32_16x16x32_bf16 v[38:41], v[58:61], v[50:53], v[38:41]
	ds_read2_b64 v[58:61], v67 offset0:32 offset1:36
	v_pk_add_f32 v[80:81], v[76:77], v[90:91]
	v_pk_add_f32 v[82:83], v[78:79], v[88:89]
	s_waitcnt lgkmcnt(2)
	v_mfma_f32_16x16x32_bf16 v[26:29], v[46:49], v[50:53], v[26:29]
	ds_read2_b64 v[46:49], v70 offset0:96 offset1:100
	v_sub_f32_e32 v50, v92, v96
	v_exp_f32_e32 v84, v50
	s_waitcnt lgkmcnt(2)
	v_mfma_f32_16x16x32_bf16 v[38:41], v[42:45], v[54:57], v[38:41]
	ds_read2_b64 v[42:45], v69 offset0:128 offset1:132
	v_cvt_pk_bf16_f32 v50, v74, v75
	v_cvt_pk_bf16_f32 v51, v72, v73
	v_cvt_pk_bf16_f32 v52, v76, v77
	v_cvt_pk_bf16_f32 v53, v78, v79
	s_waitcnt lgkmcnt(1)
	v_mfma_f32_16x16x32_bf16 v[34:37], v[46:49], v[54:57], v[34:37]
	ds_read2_b64 v[46:49], v68 offset0:72 offset1:76
	v_exp_f32_e32 v72, v86
	v_exp_f32_e32 v73, v85
	v_mfma_f32_16x16x32_bf16 v[30:33], v[58:61], v[54:57], v[30:33]
	ds_read2_b64 v[58:61], v67 offset0:40 offset1:44
	v_exp_f32_e32 v85, v87
	s_waitcnt lgkmcnt(2)
	v_mfma_f32_16x16x32_bf16 v[26:29], v[42:45], v[54:57], v[26:29]
	ds_read2_b64 v[42:45], v70 offset0:104 offset1:108
	v_pk_add_f32 v[54:55], v[72:73], v[82:83]
	v_pk_add_f32 v[56:57], v[84:85], v[80:81]
	s_waitcnt lgkmcnt(2)
	v_mfma_f32_16x16x32_bf16 v[38:41], v[46:49], v[50:53], v[38:41]
	ds_read2_b64 v[46:49], v69 offset0:136 offset1:140
	s_waitcnt lgkmcnt(2)
	v_mfma_f32_16x16x32_bf16 v[30:33], v[58:61], v[50:53], v[30:33]
	v_pk_mov_b32 v[58:59], v[56:57], v[54:55] op_sel:[1,0]
	v_mov_b32_e32 v57, v55
	v_pk_add_f32 v[54:55], v[58:59], v[56:57]
	s_waitcnt lgkmcnt(1)
	v_mfma_f32_16x16x32_bf16 v[34:37], v[42:45], v[50:53], v[34:37]
	v_add_f32_e32 v54, v54, v55
	ds_bpermute_b32 v42, v65, v54
	v_mov_b32_e32 v44, v147
	s_waitcnt lgkmcnt(1)
	v_mfma_f32_16x16x32_bf16 v[26:29], v[46:49], v[50:53], v[26:29]
	v_mov_b32_e32 v48, v147
	v_mov_b32_e32 v49, v147
	s_waitcnt lgkmcnt(0)
	v_add_f32_e32 v60, v54, v42
	v_cvt_pk_bf16_f32 v42, v84, v85
	v_cvt_pk_bf16_f32 v43, v72, v73
	ds_read_b64 v[46:47], v179 offset:37248
	ds_read_b64 v[50:51], v179 offset:45696
	v_mov_b32_e32 v45, v147
	v_mov_b32_e32 v52, v147
	v_mov_b32_e32 v53, v147
	s_waitcnt lgkmcnt(1)
	v_mfma_f32_16x16x32_bf16 v[30:33], v[46:49], v[42:45], v[30:33]
	ds_bpermute_b32 v46, v66, v60
	v_fma_f32 v47, v64, s61, -v96
	v_exp_f32_e32 v47, v47
	ds_read_b64 v[54:55], v179 offset:54144
	ds_read_b64 v[58:59], v179 offset:62592
	v_mov_b32_e32 v56, v147
	s_waitcnt lgkmcnt(2)
	v_add_f32_e32 v46, v60, v46
	v_add_f32_e32 v46, v47, v46
	v_mov_b32_e32 v57, v147
	v_mov_b32_e32 v60, v147
	v_mov_b32_e32 v61, v147
	v_div_scale_f32 v47, s[68:69], v46, v46, 1.0
	v_rcp_f32_e32 v48, v47
	v_mfma_f32_16x16x32_bf16 v[38:41], v[50:53], v[42:45], v[38:41]
	s_waitcnt lgkmcnt(1)
	v_mfma_f32_16x16x32_bf16 v[34:37], v[54:57], v[42:45], v[34:37]
	s_waitcnt lgkmcnt(0)
	v_mfma_f32_16x16x32_bf16 v[26:29], v[58:61], v[42:45], v[26:29]
	v_fma_f32 v42, -v47, v48, 1.0
	v_fmac_f32_e32 v48, v42, v48
	v_div_scale_f32 v42, vcc, 1.0, v46, 1.0
	v_mul_f32_e32 v43, v42, v48
	v_fma_f32 v44, -v47, v43, v42
	v_fmac_f32_e32 v43, v44, v48
	v_fma_f32 v42, -v47, v43, v42
	v_div_fmas_f32 v42, v42, v48, v43
	v_div_fixup_f32 v42, v42, v46, 1.0
	v_pk_mul_f32 v[32:33], v[42:43], v[32:33] op_sel_hi:[0,1]
	v_pk_mul_f32 v[30:31], v[42:43], v[30:31] op_sel_hi:[0,1]
	v_add_co_u32_e32 v76, vcc, s55, v62
	v_cvt_pk_bf16_f32 v30, v30, v31
	v_cvt_pk_bf16_f32 v31, v32, v33
	v_pk_mul_f32 v[32:33], v[42:43], v[38:39] op_sel_hi:[0,1]
	s_nop 0
	v_addc_co_u32_e32 v77, vcc, 0, v63, vcc
	v_lshrrev_b32_e32 v110, 4, v0
	v_and_b32_e32 v110, 1, v110
	v_mul_u32_u24_e32 v110, 24, v110
	v_mov_b32_e32 v111, 0
	v_lshl_add_u64 v[118:119], v[76:77], 0, v[110:111]
	v_mov_b32_e32 v114, v30
	v_mov_b32_e32 v115, v31
	v_pk_mul_f32 v[30:31], v[42:43], v[40:41] op_sel_hi:[0,1]
	v_cvt_pk_bf16_f32 v32, v32, v33
	v_cvt_pk_bf16_f32 v33, v30, v31
	v_mov_b32_e32 v116, v32
	v_mov_b32_e32 v117, v33
	s_nop 1
	v_permlane16_swap_b32_e32 v114, v116
	v_permlane16_swap_b32_e32 v115, v117
	global_store_dwordx4 v[118:119], v[114:117], off
	v_pk_mul_f32 v[32:33], v[42:43], v[34:35] op_sel_hi:[0,1]
	v_pk_mul_f32 v[30:31], v[42:43], v[36:37] op_sel_hi:[0,1]
	v_cvt_pk_bf16_f32 v32, v32, v33
	v_cvt_pk_bf16_f32 v33, v30, v31
	v_pk_mul_f32 v[28:29], v[42:43], v[28:29] op_sel_hi:[0,1]
	v_pk_mul_f32 v[26:27], v[42:43], v[26:27] op_sel_hi:[0,1]
	v_mov_b32_e32 v126, v32
	v_mov_b32_e32 v127, v33
	v_cvt_pk_bf16_f32 v78, v26, v27
	v_cvt_pk_bf16_f32 v79, v28, v29
	ds_read_b128 v[26:29], v178 offset:11520
	ds_read_b128 v[30:33], v178 offset:11584
	s_waitcnt lgkmcnt(1)
	v_mfma_f32_16x16x32_bf16 v[26:29], v[26:29], v[18:21], 0
	ds_read_b128 v[34:37], v178 offset:13824
	ds_read_b128 v[38:41], v178 offset:16128
	ds_read_b128 v[42:45], v178 offset:18432
	s_waitcnt lgkmcnt(3)
; __device__ __forceinline__ void attn_unit(LAS unsigned char* lds, bf16* Q, const bf16* Kg, const bf16* Vg, const float* snk, int unit, int tid) {
;     ...
;         for (int kb = 0; kb < 9; ++kb) { const LAS unsigned char* kp = lds + (16 * (mt + kb) + fr) * ATT_KP + 16 * fq;
;             const bf16x8_t k0 = *(const LAS bf16x8_t*)kp, k1 = *(const LAS bf16x8_t*)(kp + 64);
;             f32x4 z = {0.f, 0.f, 0.f, 0.f}; z = __builtin_amdgcn_mfma_f32_16x16x32_bf16(k0, qf[mt][0], z, 0, 0, 0); z = __builtin_amdgcn_mfma_f32_16x16x32_bf16(k1, qf[mt][1], z, 0, 0, 0); st[kb] = z; }
;         float mx = sink;
; #pragma unroll
;         for (int kb = 0; kb < 9; ++kb) {
;             const bool tile_ok = (n > 0) || (mt + kb >= 8);
; #pragma unroll
;             for (int i = 0; i < 4; ++i) { const bool ok = tile_ok && (kb == 0 ? lo_ok[i] : (kb == 8 ? !lo_ok[i] : true));
;                 st[kb][i] = ok ? st[kb][i] : -INFINITY; mx = fmaxf(mx, st[kb][i]); }
;         }
;         mx = fmaxf(mx, __shfl_xor(mx, 16)); mx = fmaxf(mx, __shfl_xor(mx, 32));
;         f32x4 ls4 = {0.f, 0.f, 0.f, 0.f};
; #pragma unroll
;         for (int kb = 0; kb < 9; ++kb) { f32x4 d = st[kb] - mx;
; #pragma unroll
;             for (int i = 0; i < 4; ++i) d[i] = __builtin_amdgcn_exp2f(d[i]);
;             st[kb] = d; ls4 = ls4 + d; }
;         float ls = (ls4[0] + ls4[1]) + (ls4[2] + ls4[3]);
;         ls += __shfl_xor(ls, 16); ls += __shfl_xor(ls, 32);
;         const float inv = 1.f / (ls + __builtin_amdgcn_exp2f(sink - mx));
;         f32x4 o[4];
; #pragma unroll
;         for (int dt = 0; dt < 4; ++dt) o[dt] = (f32x4){0.f, 0.f, 0.f, 0.f};
; #pragma unroll
;         for (int kp = 0; kp < 5; ++kp) {
;             v4u pw; pw.x = cvt_pk_bf16(st[2 * kp][0], st[2 * kp][1]); pw.y = cvt_pk_bf16(st[2 * kp][2], st[2 * kp][3]);
;             if (kp < 4) { pw.z = cvt_pk_bf16(st[(2 * kp + 1) % 9][0], st[(2 * kp + 1) % 9][1]); pw.w = cvt_pk_bf16(st[(2 * kp + 1) % 9][2], st[(2 * kp + 1) % 9][3]); } else { pw.z = 0u; pw.w = 0u; }
;             const bf16x8_t pb = __builtin_bit_cast(bf16x8_t, pw);
; #pragma unroll
;             for (int dt = 0; dt < 4; ++dt) { const LAS unsigned char* vp = lds + ATT_VOFF + (16 * dt + fr) * ATT_VP + (16 * (mt + 2 * kp) + 4 * fq) * 2;
;                 const v2u lo = *(const LAS v2u*)vp; v2u hi = {0u, 0u}; if (kp < 4) hi = *(const LAS v2u*)(vp + 32);
	v_mfma_f32_16x16x32_bf16 v[30:33], v[30:33], v[22:25], v[26:29]
	ds_read_b128 v[46:49], v178 offset:20736
	ds_read_b128 v[50:53], v178 offset:23040
	ds_read_b128 v[54:57], v178 offset:25344
	ds_read_b128 v[26:29], v178 offset:13888
	s_waitcnt lgkmcnt(6)
	v_mfma_f32_16x16x32_bf16 v[34:37], v[34:37], v[18:21], 0
	ds_read_b128 v[58:61], v178 offset:27648
	ds_read_b128 v[72:75], v178 offset:29952
	v_mov_b32_e32 v128, v78
	v_mov_b32_e32 v129, v79
	s_nop 1
	v_permlane16_swap_b32_e32 v126, v128
	v_permlane16_swap_b32_e32 v127, v129
	global_store_dwordx4 v[118:119], v[126:129], off offset:64
	s_waitcnt lgkmcnt(2)
	v_mfma_f32_16x16x32_bf16 v[34:37], v[26:29], v[22:25], v[34:37]
	ds_read_b128 v[26:29], v178 offset:16192
	v_mfma_f32_16x16x32_bf16 v[38:41], v[38:41], v[18:21], 0
	s_waitcnt lgkmcnt(0)
	v_mfma_f32_16x16x32_bf16 v[38:41], v[26:29], v[22:25], v[38:41]
	ds_read_b128 v[26:29], v178 offset:18496
	v_mfma_f32_16x16x32_bf16 v[42:45], v[42:45], v[18:21], 0
	s_waitcnt lgkmcnt(0)
	v_mfma_f32_16x16x32_bf16 v[42:45], v[26:29], v[22:25], v[42:45]
	ds_read_b128 v[26:29], v178 offset:20800
	v_mfma_f32_16x16x32_bf16 v[46:49], v[46:49], v[18:21], 0
	s_waitcnt lgkmcnt(0)
	v_mfma_f32_16x16x32_bf16 v[46:49], v[26:29], v[22:25], v[46:49]
	ds_read_b128 v[26:29], v178 offset:23104
	v_mfma_f32_16x16x32_bf16 v[50:53], v[50:53], v[18:21], 0
	s_waitcnt lgkmcnt(0)
	v_mfma_f32_16x16x32_bf16 v[50:53], v[26:29], v[22:25], v[50:53]
	ds_read_b128 v[26:29], v178 offset:25408
	v_mfma_f32_16x16x32_bf16 v[54:57], v[54:57], v[18:21], 0
	s_waitcnt lgkmcnt(0)
	v_mfma_f32_16x16x32_bf16 v[54:57], v[26:29], v[22:25], v[54:57]
	ds_read_b128 v[26:29], v178 offset:27712
	v_mfma_f32_16x16x32_bf16 v[58:61], v[58:61], v[18:21], 0
	s_waitcnt lgkmcnt(0)
	v_mfma_f32_16x16x32_bf16 v[26:29], v[26:29], v[22:25], v[58:61]
	s_nop 5
	ds_read_b128 v[58:61], v178 offset:30016
	v_mfma_f32_16x16x32_bf16 v[18:21], v[72:75], v[18:21], 0
	s_waitcnt lgkmcnt(0)
	v_mfma_f32_16x16x32_bf16 v[18:21], v[58:61], v[22:25], v[18:21]
	v_cndmask_b32_e64 v23, v31, v190, s[10:11]
	v_cndmask_b32_e64 v22, v190, v30, s[20:21]
	v_cndmask_b32_e64 v23, v190, v23, s[16:17]
	v_max3_f32 v24, v71, v22, v23
	v_cndmask_b32_e64 v25, v190, v32, s[18:19]
	v_cndmask_b32_e64 v30, v190, v33, s[22:23]
	v_max3_f32 v24, v24, v25, v30
	v_cndmask_b32_e64 v31, v190, v34, s[16:17]
	v_cndmask_b32_e64 v32, v190, v35, s[16:17]
	v_max3_f32 v24, v24, v31, v32
	v_cndmask_b32_e64 v33, v190, v36, s[16:17]
	v_cndmask_b32_e64 v34, v190, v37, s[16:17]
	v_max3_f32 v24, v24, v33, v34
	v_cndmask_b32_e64 v35, v190, v38, s[16:17]
	v_cndmask_b32_e64 v36, v190, v39, s[16:17]
	v_max3_f32 v24, v24, v35, v36
	v_cndmask_b32_e64 v37, v190, v40, s[16:17]
	v_cndmask_b32_e64 v38, v190, v41, s[16:17]
	v_max3_f32 v24, v24, v37, v38
	v_max3_f32 v24, v24, v42, v43
	v_max3_f32 v24, v24, v44, v45
	v_max3_f32 v24, v24, v46, v47
	v_max3_f32 v24, v24, v48, v49
	v_max3_f32 v24, v24, v50, v51
	v_max3_f32 v24, v24, v52, v53
	v_max3_f32 v24, v24, v54, v55
	v_max3_f32 v24, v24, v56, v57
	v_max3_f32 v24, v24, v26, v27
	v_max3_f32 v24, v24, v28, v29
	v_cndmask_b32_e64 v86, v18, v190, s[8:9]
	v_cndmask_b32_e64 v87, v190, v19, s[10:11]
	v_max3_f32 v18, v24, v86, v87
	v_cndmask_b32_e64 v88, v20, v190, s[12:13]
	v_cndmask_b32_e64 v89, v21, v190, s[14:15]
	v_max3_f32 v18, v18, v88, v89
	ds_bpermute_b32 v19, v65, v18
	s_waitcnt lgkmcnt(0)
	v_max_f32_e32 v19, v19, v19
	v_max_f32_e32 v18, v18, v19
	ds_bpermute_b32 v19, v66, v18
	s_waitcnt lgkmcnt(0)
	v_max_f32_e32 v19, v19, v19
	v_max_f32_e32 v90, v18, v19
	v_sub_f32_e32 v19, v30, v90
	v_sub_f32_e32 v20, v25, v90
	v_sub_f32_e32 v23, v23, v90
	v_sub_f32_e32 v18, v22, v90
	v_exp_f32_e32 v18, v18
	v_exp_f32_e32 v20, v20
	v_exp_f32_e32 v21, v19
	v_exp_f32_e32 v19, v23
	v_sub_f32_e32 v34, v34, v90
	v_sub_f32_e32 v33, v33, v90
	v_sub_f32_e32 v32, v32, v90
	v_sub_f32_e32 v30, v31, v90
	v_exp_f32_e32 v30, v30
	v_exp_f32_e32 v31, v32
	v_exp_f32_e32 v32, v33
	v_exp_f32_e32 v33, v34
	v_sub_f32_e32 v34, v38, v90
	v_sub_f32_e32 v37, v37, v90
	v_sub_f32_e32 v36, v36, v90
	v_sub_f32_e32 v35, v35, v90
	v_exp_f32_e32 v58, v35
	v_exp_f32_e32 v60, v37
	v_exp_f32_e32 v61, v34
	v_exp_f32_e32 v59, v36
	v_sub_f32_e32 v34, v45, v90
	v_sub_f32_e32 v35, v44, v90
	v_sub_f32_e32 v36, v43, v90
	v_sub_f32_e32 v37, v42, v90
	v_exp_f32_e32 v44, v37
	v_exp_f32_e32 v45, v36
	v_exp_f32_e32 v72, v35
	v_exp_f32_e32 v73, v34
	v_sub_f32_e32 v34, v49, v90
	v_sub_f32_e32 v35, v48, v90
	v_sub_f32_e32 v36, v47, v90
	v_sub_f32_e32 v37, v46, v90
	v_pk_add_f32 v[22:23], v[20:21], 0 op_sel_hi:[1,0]
	v_pk_add_f32 v[24:25], v[18:19], 0 op_sel_hi:[1,0]
	v_exp_f32_e32 v74, v37
	v_exp_f32_e32 v76, v35
	v_exp_f32_e32 v77, v34
	v_exp_f32_e32 v75, v36
	v_pk_add_f32 v[24:25], v[30:31], v[24:25]
	v_pk_add_f32 v[22:23], v[32:33], v[22:23]
	v_pk_add_f32 v[24:25], v[58:59], v[24:25]
	v_pk_add_f32 v[22:23], v[60:61], v[22:23]
	v_pk_add_f32 v[24:25], v[44:45], v[24:25]
	v_pk_add_f32 v[22:23], v[72:73], v[22:23]
	v_sub_f32_e32 v36, v50, v90
	v_pk_add_f32 v[34:35], v[76:77], v[22:23]
	v_pk_add_f32 v[22:23], v[74:75], v[24:25]
	v_sub_f32_e32 v25, v51, v90
	v_sub_f32_e32 v24, v53, v90
	v_exp_f32_e32 v79, v25
	v_sub_f32_e32 v25, v52, v90
	v_exp_f32_e32 v78, v36
	v_exp_f32_e32 v80, v25
	v_exp_f32_e32 v81, v24
	v_sub_f32_e32 v38, v57, v90
	v_sub_f32_e32 v39, v56, v90
	v_sub_f32_e32 v40, v55, v90
	v_sub_f32_e32 v41, v54, v90
	v_exp_f32_e32 v54, v39
	v_exp_f32_e32 v55, v38
	v_exp_f32_e32 v56, v41
	v_exp_f32_e32 v57, v40
	v_pk_add_f32 v[36:37], v[78:79], v[22:23]
	v_pk_add_f32 v[34:35], v[80:81], v[34:35]
	v_cvt_pk_bf16_f32 v18, v18, v19
	v_cvt_pk_bf16_f32 v19, v20, v21
	v_cvt_pk_bf16_f32 v20, v30, v31
	v_cvt_pk_bf16_f32 v21, v32, v33
	ds_read2_b64 v[22:25], v67 offset0:20 offset1:24
	ds_read2_b64 v[30:33], v68 offset0:52 offset1:56
	v_pk_add_f32 v[82:83], v[54:55], v[34:35]
	v_pk_add_f32 v[84:85], v[56:57], v[36:37]
	ds_read2_b64 v[34:37], v70 offset0:84 offset1:88
	ds_read2_b64 v[38:41], v69 offset0:116 offset1:120
	v_sub_f32_e32 v28, v28, v90
	v_sub_f32_e32 v27, v27, v90
	v_sub_f32_e32 v26, v26, v90
	v_sub_f32_e32 v91, v29, v90
	v_cvt_pk_bf16_f32 v42, v58, v59
	v_cvt_pk_bf16_f32 v43, v60, v61
	v_cvt_pk_bf16_f32 v44, v44, v45
	v_cvt_pk_bf16_f32 v45, v72, v73
	ds_read2_b64 v[46:49], v67 offset0:28 offset1:32
	v_exp_f32_e32 v58, v26
	v_exp_f32_e32 v59, v27
	v_exp_f32_e32 v60, v28
	ds_read2_b64 v[26:29], v70 offset0:92 offset1:96
	s_waitcnt lgkmcnt(5)
; __device__ __forceinline__ unsigned cvt_pk_bf16(float lo, float hi) { unsigned r; asm volatile("v_cvt_pk_bf16_f32 %0, %1, %2" : "=v"(r) : "v"(lo), "v"(hi)); return r; }
; #define LAS __attribute__((address_space(3)))
; __device__ __forceinline__ void attn_unit(LAS unsigned char* lds, bf16* Q, const bf16* Kg, const bf16* Vg, const float* snk, int unit, int tid) {
;     ...
;         for (int kp = 0; kp < 5; ++kp) {
;             v4u pw; pw.x = cvt_pk_bf16(st[2 * kp][0], st[2 * kp][1]); pw.y = cvt_pk_bf16(st[2 * kp][2], st[2 * kp][3]);
;             if (kp < 4) { pw.z = cvt_pk_bf16(st[(2 * kp + 1) % 9][0], st[(2 * kp + 1) % 9][1]); pw.w = cvt_pk_bf16(st[(2 * kp + 1) % 9][2], st[(2 * kp + 1) % 9][3]); } else { pw.z = 0u; pw.w = 0u; }
;             const bf16x8_t pb = __builtin_bit_cast(bf16x8_t, pw);
; #pragma unroll
;             for (int dt = 0; dt < 4; ++dt) { const LAS unsigned char* vp = lds + ATT_VOFF + (16 * dt + fr) * ATT_VP + (16 * (mt + 2 * kp) + 4 * fq) * 2;
;                 const v2u lo = *(const LAS v2u*)vp; v2u hi = {0u, 0u}; if (kp < 4) hi = *(const LAS v2u*)(vp + 32);
;                 v4u aw; aw.x = lo.x; aw.y = lo.y; aw.z = hi.x; aw.w = hi.y;
;                 o[dt] = __builtin_amdgcn_mfma_f32_16x16x32_bf16(__builtin_bit_cast(bf16x8_t, aw), pb, o[dt], 0, 0, 0); }
;         }
; #pragma unroll
;         for (int dt = 0; dt < 4; ++dt) { const f32x4 y = o[dt] * inv; v2u w; w.x = cvt_pk_bf16(y[0], y[1]); w.y = cvt_pk_bf16(y[2], y[3]); *(v2u*)(qbase + (size_t)mt * 16 * 1024 + 16 * dt + 4 * fq) = w; }
	v_mfma_f32_16x16x32_bf16 v[22:25], v[22:25], v[18:21], 0
	ds_read2_b64 v[50:53], v68 offset0:60 offset1:64
	v_exp_f32_e32 v61, v91
	v_pk_add_f32 v[72:73], v[58:59], v[84:85]
	s_waitcnt lgkmcnt(5)
	v_mfma_f32_16x16x32_bf16 v[30:33], v[30:33], v[18:21], 0
	s_waitcnt lgkmcnt(4)
	v_mfma_f32_16x16x32_bf16 v[34:37], v[34:37], v[18:21], 0
	s_waitcnt lgkmcnt(3)
	v_mfma_f32_16x16x32_bf16 v[18:21], v[38:41], v[18:21], 0
	ds_read2_b64 v[38:41], v69 offset0:124 offset1:128
	s_waitcnt lgkmcnt(3)
	v_mfma_f32_16x16x32_bf16 v[22:25], v[46:49], v[42:45], v[22:25]
	v_cvt_pk_bf16_f32 v46, v74, v75
	v_cvt_pk_bf16_f32 v47, v76, v77
	v_cvt_pk_bf16_f32 v48, v78, v79
	v_cvt_pk_bf16_f32 v49, v80, v81
	s_waitcnt lgkmcnt(2)
	v_mfma_f32_16x16x32_bf16 v[26:29], v[26:29], v[42:45], v[34:37]
	v_sub_f32_e32 v77, v89, v90
	v_sub_f32_e32 v78, v88, v90
	v_sub_f32_e32 v79, v87, v90
	ds_read2_b64 v[34:37], v68 offset0:68 offset1:72
	s_waitcnt lgkmcnt(2)
	v_mfma_f32_16x16x32_bf16 v[30:33], v[50:53], v[42:45], v[30:33]
	ds_read2_b64 v[50:53], v67 offset0:36 offset1:40
	v_pk_add_f32 v[74:75], v[60:61], v[82:83]
	s_waitcnt lgkmcnt(2)
	v_mfma_f32_16x16x32_bf16 v[18:21], v[38:41], v[42:45], v[18:21]
	ds_read2_b64 v[38:41], v70 offset0:100 offset1:104
	v_sub_f32_e32 v42, v86, v90
	v_exp_f32_e32 v76, v42
	s_waitcnt lgkmcnt(2)
	v_mfma_f32_16x16x32_bf16 v[30:33], v[34:37], v[46:49], v[30:33]
	ds_read2_b64 v[34:37], v69 offset0:132 offset1:136
	v_cvt_pk_bf16_f32 v42, v56, v57
	v_cvt_pk_bf16_f32 v43, v54, v55
	v_cvt_pk_bf16_f32 v44, v58, v59
	v_cvt_pk_bf16_f32 v45, v60, v61
	s_waitcnt lgkmcnt(1)
	v_mfma_f32_16x16x32_bf16 v[26:29], v[38:41], v[46:49], v[26:29]
	ds_read2_b64 v[38:41], v68 offset0:76 offset1:80
	v_exp_f32_e32 v54, v78
	v_exp_f32_e32 v55, v77
	v_mfma_f32_16x16x32_bf16 v[22:25], v[50:53], v[46:49], v[22:25]
	ds_read2_b64 v[50:53], v67 offset0:44 offset1:48
	v_exp_f32_e32 v77, v79
	s_waitcnt lgkmcnt(2)
	v_mfma_f32_16x16x32_bf16 v[18:21], v[34:37], v[46:49], v[18:21]
	ds_read2_b64 v[34:37], v70 offset0:108 offset1:112
	v_pk_add_f32 v[46:47], v[54:55], v[74:75]
	v_pk_add_f32 v[48:49], v[76:77], v[72:73]
	s_waitcnt lgkmcnt(2)
	v_mfma_f32_16x16x32_bf16 v[30:33], v[38:41], v[42:45], v[30:33]
	ds_read2_b64 v[38:41], v69 offset0:140 offset1:144
	s_waitcnt lgkmcnt(2)
	v_mfma_f32_16x16x32_bf16 v[22:25], v[50:53], v[42:45], v[22:25]
	v_pk_mov_b32 v[50:51], v[48:49], v[46:47] op_sel:[1,0]
	v_mov_b32_e32 v49, v47
	v_pk_add_f32 v[46:47], v[50:51], v[48:49]
	s_waitcnt lgkmcnt(1)
	v_mfma_f32_16x16x32_bf16 v[26:29], v[34:37], v[42:45], v[26:29]
	v_add_f32_e32 v46, v46, v47
	ds_bpermute_b32 v34, v65, v46
	v_mov_b32_e32 v36, v147
	s_waitcnt lgkmcnt(1)
	v_mfma_f32_16x16x32_bf16 v[18:21], v[38:41], v[42:45], v[18:21]
	v_mov_b32_e32 v40, v147
	v_mov_b32_e32 v41, v147
	s_waitcnt lgkmcnt(0)
	v_add_f32_e32 v52, v46, v34
	v_cvt_pk_bf16_f32 v34, v76, v77
	v_cvt_pk_bf16_f32 v35, v54, v55
	ds_read_b64 v[38:39], v179 offset:37280
	ds_read_b64 v[42:43], v179 offset:45728
	v_mov_b32_e32 v37, v147
	v_mov_b32_e32 v44, v147
	v_mov_b32_e32 v45, v147
	s_waitcnt lgkmcnt(1)
	v_mfma_f32_16x16x32_bf16 v[22:25], v[38:41], v[34:37], v[22:25]
	ds_bpermute_b32 v38, v66, v52
	v_fma_f32 v39, v64, s61, -v90
	v_exp_f32_e32 v39, v39
	ds_read_b64 v[46:47], v179 offset:54176
	ds_read_b64 v[50:51], v179 offset:62624
	v_mov_b32_e32 v48, v147
	s_waitcnt lgkmcnt(2)
	v_add_f32_e32 v38, v52, v38
	v_add_f32_e32 v38, v39, v38
	v_mov_b32_e32 v49, v147
	v_mov_b32_e32 v52, v147
	v_mov_b32_e32 v53, v147
	v_div_scale_f32 v39, s[68:69], v38, v38, 1.0
	v_rcp_f32_e32 v40, v39
	v_mfma_f32_16x16x32_bf16 v[30:33], v[42:45], v[34:37], v[30:33]
	s_waitcnt lgkmcnt(1)
	v_mfma_f32_16x16x32_bf16 v[26:29], v[46:49], v[34:37], v[26:29]
	s_waitcnt lgkmcnt(0)
	v_mfma_f32_16x16x32_bf16 v[18:21], v[50:53], v[34:37], v[18:21]
	v_fma_f32 v34, -v39, v40, 1.0
	v_fmac_f32_e32 v40, v34, v40
	v_div_scale_f32 v34, vcc, 1.0, v38, 1.0
	v_mul_f32_e32 v35, v34, v40
	v_fma_f32 v36, -v39, v35, v34
	v_fmac_f32_e32 v35, v36, v40
	v_fma_f32 v34, -v39, v35, v34
	v_div_fmas_f32 v34, v34, v40, v35
	v_div_fixup_f32 v34, v34, v38, 1.0
	v_pk_mul_f32 v[24:25], v[34:35], v[24:25] op_sel_hi:[0,1]
	v_pk_mul_f32 v[22:23], v[34:35], v[22:23] op_sel_hi:[0,1]
	v_add_co_u32_e32 v58, vcc, s56, v62
	v_cvt_pk_bf16_f32 v22, v22, v23
	v_cvt_pk_bf16_f32 v23, v24, v25
	v_pk_mul_f32 v[24:25], v[34:35], v[30:31] op_sel_hi:[0,1]
	s_nop 0
	v_addc_co_u32_e32 v59, vcc, 0, v63, vcc
	v_lshrrev_b32_e32 v110, 4, v0
	v_and_b32_e32 v110, 1, v110
	v_mul_u32_u24_e32 v110, 24, v110
	v_mov_b32_e32 v111, 0
	v_lshl_add_u64 v[118:119], v[58:59], 0, v[110:111]
	v_mov_b32_e32 v114, v22
	v_mov_b32_e32 v115, v23
	v_pk_mul_f32 v[22:23], v[34:35], v[32:33] op_sel_hi:[0,1]
	v_cvt_pk_bf16_f32 v24, v24, v25
	v_cvt_pk_bf16_f32 v25, v22, v23
	v_mov_b32_e32 v116, v24
	v_mov_b32_e32 v117, v25
	s_nop 1
	v_permlane16_swap_b32_e32 v114, v116
	v_permlane16_swap_b32_e32 v115, v117
	global_store_dwordx4 v[118:119], v[114:117], off
	v_pk_mul_f32 v[24:25], v[34:35], v[26:27] op_sel_hi:[0,1]
	v_pk_mul_f32 v[22:23], v[34:35], v[28:29] op_sel_hi:[0,1]
	v_cvt_pk_bf16_f32 v24, v24, v25
	v_cvt_pk_bf16_f32 v25, v22, v23
	v_pk_mul_f32 v[20:21], v[34:35], v[20:21] op_sel_hi:[0,1]
	v_pk_mul_f32 v[18:19], v[34:35], v[18:19] op_sel_hi:[0,1]
	v_mov_b32_e32 v126, v24
	v_mov_b32_e32 v127, v25
	v_cvt_pk_bf16_f32 v60, v18, v19
	v_cvt_pk_bf16_f32 v61, v20, v21
	ds_read_b128 v[18:21], v178 offset:13824
	ds_read_b128 v[22:25], v178 offset:13888
	s_waitcnt lgkmcnt(1)
	v_mfma_f32_16x16x32_bf16 v[18:21], v[18:21], v[10:13], 0
	ds_read_b128 v[26:29], v178 offset:16128
	ds_read_b128 v[30:33], v178 offset:18432
	ds_read_b128 v[34:37], v178 offset:20736
	s_waitcnt lgkmcnt(3)
; __device__ __forceinline__ void attn_unit(LAS unsigned char* lds, bf16* Q, const bf16* Kg, const bf16* Vg, const float* snk, int unit, int tid) {
;     ...
;         for (int kb = 0; kb < 9; ++kb) { const LAS unsigned char* kp = lds + (16 * (mt + kb) + fr) * ATT_KP + 16 * fq;
;             const bf16x8_t k0 = *(const LAS bf16x8_t*)kp, k1 = *(const LAS bf16x8_t*)(kp + 64);
;             f32x4 z = {0.f, 0.f, 0.f, 0.f}; z = __builtin_amdgcn_mfma_f32_16x16x32_bf16(k0, qf[mt][0], z, 0, 0, 0); z = __builtin_amdgcn_mfma_f32_16x16x32_bf16(k1, qf[mt][1], z, 0, 0, 0); st[kb] = z; }
;         float mx = sink;
; #pragma unroll
;         for (int kb = 0; kb < 9; ++kb) {
;             const bool tile_ok = (n > 0) || (mt + kb >= 8);
; #pragma unroll
;             for (int i = 0; i < 4; ++i) { const bool ok = tile_ok && (kb == 0 ? lo_ok[i] : (kb == 8 ? !lo_ok[i] : true));
;                 st[kb][i] = ok ? st[kb][i] : -INFINITY; mx = fmaxf(mx, st[kb][i]); }
;         }
;         mx = fmaxf(mx, __shfl_xor(mx, 16)); mx = fmaxf(mx, __shfl_xor(mx, 32));
;         f32x4 ls4 = {0.f, 0.f, 0.f, 0.f};
; #pragma unroll
;         for (int kb = 0; kb < 9; ++kb) { f32x4 d = st[kb] - mx;
; #pragma unroll
;             for (int i = 0; i < 4; ++i) d[i] = __builtin_amdgcn_exp2f(d[i]);
;             st[kb] = d; ls4 = ls4 + d; }
;         float ls = (ls4[0] + ls4[1]) + (ls4[2] + ls4[3]);
;         ls += __shfl_xor(ls, 16); ls += __shfl_xor(ls, 32);
;         const float inv = 1.f / (ls + __builtin_amdgcn_exp2f(sink - mx));
;         f32x4 o[4];
; #pragma unroll
;         for (int dt = 0; dt < 4; ++dt) o[dt] = (f32x4){0.f, 0.f, 0.f, 0.f};
; #pragma unroll
;         for (int kp = 0; kp < 5; ++kp) {
;             v4u pw; pw.x = cvt_pk_bf16(st[2 * kp][0], st[2 * kp][1]); pw.y = cvt_pk_bf16(st[2 * kp][2], st[2 * kp][3]);
;             if (kp < 4) { pw.z = cvt_pk_bf16(st[(2 * kp + 1) % 9][0], st[(2 * kp + 1) % 9][1]); pw.w = cvt_pk_bf16(st[(2 * kp + 1) % 9][2], st[(2 * kp + 1) % 9][3]); } else { pw.z = 0u; pw.w = 0u; }
;             const bf16x8_t pb = __builtin_bit_cast(bf16x8_t, pw);
; #pragma unroll
;             for (int dt = 0; dt < 4; ++dt) { const LAS unsigned char* vp = lds + ATT_VOFF + (16 * dt + fr) * ATT_VP + (16 * (mt + 2 * kp) + 4 * fq) * 2;
;                 const v2u lo = *(const LAS v2u*)vp; v2u hi = {0u, 0u}; if (kp < 4) hi = *(const LAS v2u*)(vp + 32);
	v_mfma_f32_16x16x32_bf16 v[22:25], v[22:25], v[14:17], v[18:21]
	ds_read_b128 v[38:41], v178 offset:23040
	ds_read_b128 v[42:45], v178 offset:25344
	ds_read_b128 v[46:49], v178 offset:27648
	ds_read_b128 v[18:21], v178 offset:16192
	s_waitcnt lgkmcnt(6)
	v_mfma_f32_16x16x32_bf16 v[26:29], v[26:29], v[10:13], 0
	ds_read_b128 v[50:53], v178 offset:29952
	ds_read_b128 v[54:57], v178 offset:32256
	v_mov_b32_e32 v128, v60
	v_mov_b32_e32 v129, v61
	s_nop 1
	v_permlane16_swap_b32_e32 v126, v128
	v_permlane16_swap_b32_e32 v127, v129
	global_store_dwordx4 v[118:119], v[126:129], off offset:64
	s_waitcnt lgkmcnt(2)
	v_mfma_f32_16x16x32_bf16 v[26:29], v[18:21], v[14:17], v[26:29]
	ds_read_b128 v[18:21], v178 offset:18496
	v_mfma_f32_16x16x32_bf16 v[30:33], v[30:33], v[10:13], 0
	s_waitcnt lgkmcnt(0)
	v_mfma_f32_16x16x32_bf16 v[30:33], v[18:21], v[14:17], v[30:33]
	ds_read_b128 v[18:21], v178 offset:20800
	v_mfma_f32_16x16x32_bf16 v[34:37], v[34:37], v[10:13], 0
	s_waitcnt lgkmcnt(0)
	v_mfma_f32_16x16x32_bf16 v[34:37], v[18:21], v[14:17], v[34:37]
	ds_read_b128 v[18:21], v178 offset:23104
	v_mfma_f32_16x16x32_bf16 v[38:41], v[38:41], v[10:13], 0
	s_waitcnt lgkmcnt(0)
	v_mfma_f32_16x16x32_bf16 v[38:41], v[18:21], v[14:17], v[38:41]
	ds_read_b128 v[18:21], v178 offset:25408
	v_mfma_f32_16x16x32_bf16 v[42:45], v[42:45], v[10:13], 0
	s_waitcnt lgkmcnt(0)
	v_mfma_f32_16x16x32_bf16 v[42:45], v[18:21], v[14:17], v[42:45]
	ds_read_b128 v[18:21], v178 offset:27712
	v_mfma_f32_16x16x32_bf16 v[46:49], v[46:49], v[10:13], 0
	s_waitcnt lgkmcnt(0)
	v_mfma_f32_16x16x32_bf16 v[46:49], v[18:21], v[14:17], v[46:49]
	ds_read_b128 v[18:21], v178 offset:30016
	v_mfma_f32_16x16x32_bf16 v[50:53], v[50:53], v[10:13], 0
	s_waitcnt lgkmcnt(0)
	v_mfma_f32_16x16x32_bf16 v[18:21], v[18:21], v[14:17], v[50:53]
	s_nop 5
	ds_read_b128 v[50:53], v178 offset:32320
	v_mfma_f32_16x16x32_bf16 v[10:13], v[54:57], v[10:13], 0
	s_waitcnt lgkmcnt(0)
	v_mfma_f32_16x16x32_bf16 v[10:13], v[50:53], v[14:17], v[10:13]
	v_cndmask_b32_e64 v15, v23, v190, s[10:11]
	v_cndmask_b32_e64 v14, v190, v22, s[20:21]
	v_cndmask_b32_e64 v15, v190, v15, s[16:17]
	v_max3_f32 v16, v71, v14, v15
	v_cndmask_b32_e64 v17, v190, v24, s[18:19]
	v_cndmask_b32_e64 v22, v190, v25, s[22:23]
	v_max3_f32 v16, v16, v17, v22
	v_cndmask_b32_e64 v23, v190, v26, s[16:17]
	v_cndmask_b32_e64 v24, v190, v27, s[16:17]
	v_max3_f32 v16, v16, v23, v24
	v_cndmask_b32_e64 v25, v190, v28, s[16:17]
	v_cndmask_b32_e64 v26, v190, v29, s[16:17]
	v_max3_f32 v16, v16, v25, v26
	v_max3_f32 v16, v16, v30, v31
	v_max3_f32 v16, v16, v32, v33
	v_max3_f32 v16, v16, v34, v35
	v_max3_f32 v16, v16, v36, v37
	v_max3_f32 v16, v16, v38, v39
	v_max3_f32 v16, v16, v40, v41
	v_max3_f32 v16, v16, v42, v43
	v_max3_f32 v16, v16, v44, v45
	v_max3_f32 v16, v16, v46, v47
	v_max3_f32 v16, v16, v48, v49
	v_max3_f32 v16, v16, v18, v19
	v_max3_f32 v16, v16, v20, v21
	v_cndmask_b32_e64 v78, v10, v190, s[8:9]
	v_cndmask_b32_e64 v79, v190, v11, s[10:11]
	v_max3_f32 v10, v16, v78, v79
	v_cndmask_b32_e64 v80, v12, v190, s[12:13]
	v_cndmask_b32_e64 v81, v13, v190, s[14:15]
	v_max3_f32 v10, v10, v80, v81
	ds_bpermute_b32 v11, v65, v10
	s_waitcnt lgkmcnt(0)
	v_max_f32_e32 v11, v11, v11
	v_max_f32_e32 v10, v10, v11
	ds_bpermute_b32 v11, v66, v10
	s_waitcnt lgkmcnt(0)
	v_max_f32_e32 v11, v11, v11
	v_max_f32_e32 v82, v10, v11
	v_sub_f32_e32 v11, v22, v82
	v_sub_f32_e32 v12, v17, v82
	v_sub_f32_e32 v15, v15, v82
	v_sub_f32_e32 v10, v14, v82
	v_exp_f32_e32 v10, v10
	v_exp_f32_e32 v12, v12
	v_exp_f32_e32 v13, v11
	v_exp_f32_e32 v11, v15
	v_sub_f32_e32 v26, v26, v82
	v_sub_f32_e32 v25, v25, v82
	v_sub_f32_e32 v24, v24, v82
	v_sub_f32_e32 v22, v23, v82
	v_exp_f32_e32 v22, v22
	v_exp_f32_e32 v23, v24
	v_exp_f32_e32 v24, v25
	v_exp_f32_e32 v25, v26
	v_sub_f32_e32 v26, v33, v82
	v_sub_f32_e32 v27, v32, v82
	v_sub_f32_e32 v28, v31, v82
	v_sub_f32_e32 v29, v30, v82
	v_exp_f32_e32 v50, v29
	v_exp_f32_e32 v52, v27
	v_exp_f32_e32 v53, v26
	v_exp_f32_e32 v51, v28
	v_sub_f32_e32 v26, v37, v82
	v_sub_f32_e32 v27, v36, v82
	v_sub_f32_e32 v28, v35, v82
	v_sub_f32_e32 v29, v34, v82
	v_exp_f32_e32 v36, v29
	v_exp_f32_e32 v37, v28
	v_exp_f32_e32 v54, v27
	v_exp_f32_e32 v55, v26
	v_sub_f32_e32 v26, v41, v82
	v_sub_f32_e32 v27, v40, v82
	v_sub_f32_e32 v28, v39, v82
	v_sub_f32_e32 v29, v38, v82
	v_pk_add_f32 v[14:15], v[12:13], 0 op_sel_hi:[1,0]
	v_pk_add_f32 v[16:17], v[10:11], 0 op_sel_hi:[1,0]
	v_exp_f32_e32 v56, v29
	v_exp_f32_e32 v58, v27
	v_exp_f32_e32 v59, v26
	v_exp_f32_e32 v57, v28
	v_pk_add_f32 v[16:17], v[22:23], v[16:17]
	v_pk_add_f32 v[14:15], v[24:25], v[14:15]
	v_pk_add_f32 v[16:17], v[50:51], v[16:17]
	v_pk_add_f32 v[14:15], v[52:53], v[14:15]
	v_pk_add_f32 v[16:17], v[36:37], v[16:17]
	v_pk_add_f32 v[14:15], v[54:55], v[14:15]
	v_sub_f32_e32 v28, v42, v82
	v_pk_add_f32 v[26:27], v[58:59], v[14:15]
	v_pk_add_f32 v[14:15], v[56:57], v[16:17]
	v_sub_f32_e32 v17, v43, v82
	v_sub_f32_e32 v16, v45, v82
	v_exp_f32_e32 v61, v17
	v_sub_f32_e32 v17, v44, v82
	v_exp_f32_e32 v60, v28
	v_exp_f32_e32 v72, v17
	v_exp_f32_e32 v73, v16
	v_sub_f32_e32 v30, v49, v82
	v_sub_f32_e32 v31, v48, v82
	v_sub_f32_e32 v32, v47, v82
	v_sub_f32_e32 v33, v46, v82
	v_exp_f32_e32 v46, v31
	v_exp_f32_e32 v47, v30
	v_exp_f32_e32 v48, v33
	v_exp_f32_e32 v49, v32
	v_pk_add_f32 v[28:29], v[60:61], v[14:15]
	v_pk_add_f32 v[26:27], v[72:73], v[26:27]
	v_cvt_pk_bf16_f32 v10, v10, v11
	v_cvt_pk_bf16_f32 v11, v12, v13
	v_cvt_pk_bf16_f32 v12, v22, v23
	v_cvt_pk_bf16_f32 v13, v24, v25
	ds_read2_b64 v[14:17], v67 offset0:24 offset1:28
	ds_read2_b64 v[22:25], v68 offset0:56 offset1:60
	v_pk_add_f32 v[74:75], v[46:47], v[26:27]
	v_pk_add_f32 v[76:77], v[48:49], v[28:29]
	ds_read2_b64 v[26:29], v70 offset0:88 offset1:92
	ds_read2_b64 v[30:33], v69 offset0:120 offset1:124
	v_sub_f32_e32 v20, v20, v82
	v_sub_f32_e32 v19, v19, v82
	v_sub_f32_e32 v18, v18, v82
	v_sub_f32_e32 v83, v21, v82
	v_cvt_pk_bf16_f32 v34, v50, v51
	v_cvt_pk_bf16_f32 v35, v52, v53
	v_cvt_pk_bf16_f32 v36, v36, v37
	v_cvt_pk_bf16_f32 v37, v54, v55
	ds_read2_b64 v[38:41], v67 offset0:32 offset1:36
	v_exp_f32_e32 v50, v18
	v_exp_f32_e32 v51, v19
	v_exp_f32_e32 v52, v20
	ds_read2_b64 v[18:21], v70 offset0:96 offset1:100
	s_waitcnt lgkmcnt(5)
; __device__ __forceinline__ unsigned cvt_pk_bf16(float lo, float hi) { unsigned r; asm volatile("v_cvt_pk_bf16_f32 %0, %1, %2" : "=v"(r) : "v"(lo), "v"(hi)); return r; }
; #define LAS __attribute__((address_space(3)))
; __device__ __forceinline__ void attn_unit(LAS unsigned char* lds, bf16* Q, const bf16* Kg, const bf16* Vg, const float* snk, int unit, int tid) {
;     ...
;         for (int kp = 0; kp < 5; ++kp) {
;             v4u pw; pw.x = cvt_pk_bf16(st[2 * kp][0], st[2 * kp][1]); pw.y = cvt_pk_bf16(st[2 * kp][2], st[2 * kp][3]);
;             if (kp < 4) { pw.z = cvt_pk_bf16(st[(2 * kp + 1) % 9][0], st[(2 * kp + 1) % 9][1]); pw.w = cvt_pk_bf16(st[(2 * kp + 1) % 9][2], st[(2 * kp + 1) % 9][3]); } else { pw.z = 0u; pw.w = 0u; }
;             const bf16x8_t pb = __builtin_bit_cast(bf16x8_t, pw);
; #pragma unroll
;             for (int dt = 0; dt < 4; ++dt) { const LAS unsigned char* vp = lds + ATT_VOFF + (16 * dt + fr) * ATT_VP + (16 * (mt + 2 * kp) + 4 * fq) * 2;
;                 const v2u lo = *(const LAS v2u*)vp; v2u hi = {0u, 0u}; if (kp < 4) hi = *(const LAS v2u*)(vp + 32);
;                 v4u aw; aw.x = lo.x; aw.y = lo.y; aw.z = hi.x; aw.w = hi.y;
;                 o[dt] = __builtin_amdgcn_mfma_f32_16x16x32_bf16(__builtin_bit_cast(bf16x8_t, aw), pb, o[dt], 0, 0, 0); }
;         }
; #pragma unroll
;         for (int dt = 0; dt < 4; ++dt) { const f32x4 y = o[dt] * inv; v2u w; w.x = cvt_pk_bf16(y[0], y[1]); w.y = cvt_pk_bf16(y[2], y[3]); *(v2u*)(qbase + (size_t)mt * 16 * 1024 + 16 * dt + 4 * fq) = w; }
	v_mfma_f32_16x16x32_bf16 v[14:17], v[14:17], v[10:13], 0
	ds_read2_b64 v[42:45], v68 offset0:64 offset1:68
	v_exp_f32_e32 v53, v83
	v_pk_add_f32 v[54:55], v[50:51], v[76:77]
	s_waitcnt lgkmcnt(5)
	v_mfma_f32_16x16x32_bf16 v[22:25], v[22:25], v[10:13], 0
	s_waitcnt lgkmcnt(4)
	v_mfma_f32_16x16x32_bf16 v[26:29], v[26:29], v[10:13], 0
	s_waitcnt lgkmcnt(3)
	v_mfma_f32_16x16x32_bf16 v[10:13], v[30:33], v[10:13], 0
	ds_read2_b64 v[30:33], v69 offset0:128 offset1:132
	s_waitcnt lgkmcnt(3)
	v_mfma_f32_16x16x32_bf16 v[14:17], v[38:41], v[34:37], v[14:17]
	v_cvt_pk_bf16_f32 v38, v56, v57
	v_cvt_pk_bf16_f32 v39, v58, v59
	v_cvt_pk_bf16_f32 v40, v60, v61
	v_cvt_pk_bf16_f32 v41, v72, v73
	s_waitcnt lgkmcnt(2)
	v_mfma_f32_16x16x32_bf16 v[18:21], v[18:21], v[34:37], v[26:29]
	v_sub_f32_e32 v59, v81, v82
	v_sub_f32_e32 v60, v80, v82
	v_sub_f32_e32 v61, v79, v82
	ds_read2_b64 v[26:29], v68 offset0:72 offset1:76
	s_waitcnt lgkmcnt(2)
	v_mfma_f32_16x16x32_bf16 v[22:25], v[42:45], v[34:37], v[22:25]
	ds_read2_b64 v[42:45], v67 offset0:40 offset1:44
	v_pk_add_f32 v[56:57], v[52:53], v[74:75]
	s_waitcnt lgkmcnt(2)
	v_mfma_f32_16x16x32_bf16 v[10:13], v[30:33], v[34:37], v[10:13]
	ds_read2_b64 v[30:33], v70 offset0:104 offset1:108
	v_sub_f32_e32 v34, v78, v82
	v_exp_f32_e32 v58, v34
	s_waitcnt lgkmcnt(2)
	v_mfma_f32_16x16x32_bf16 v[22:25], v[26:29], v[38:41], v[22:25]
	ds_read2_b64 v[26:29], v69 offset0:136 offset1:140
	v_cvt_pk_bf16_f32 v34, v48, v49
	v_cvt_pk_bf16_f32 v35, v46, v47
	v_cvt_pk_bf16_f32 v36, v50, v51
	v_cvt_pk_bf16_f32 v37, v52, v53
	s_waitcnt lgkmcnt(1)
	v_mfma_f32_16x16x32_bf16 v[18:21], v[30:33], v[38:41], v[18:21]
	ds_read2_b64 v[30:33], v68 offset0:80 offset1:84
	v_exp_f32_e32 v46, v60
	v_exp_f32_e32 v47, v59
	v_mfma_f32_16x16x32_bf16 v[14:17], v[42:45], v[38:41], v[14:17]
	ds_read2_b64 v[42:45], v67 offset0:48 offset1:52
	v_exp_f32_e32 v59, v61
	s_waitcnt lgkmcnt(2)
	v_mfma_f32_16x16x32_bf16 v[10:13], v[26:29], v[38:41], v[10:13]
	ds_read2_b64 v[26:29], v70 offset0:112 offset1:116
	v_pk_add_f32 v[38:39], v[46:47], v[56:57]
	v_pk_add_f32 v[40:41], v[58:59], v[54:55]
	s_waitcnt lgkmcnt(2)
	v_mfma_f32_16x16x32_bf16 v[22:25], v[30:33], v[34:37], v[22:25]
	ds_read2_b64 v[30:33], v69 offset0:144 offset1:148
	s_waitcnt lgkmcnt(2)
	v_mfma_f32_16x16x32_bf16 v[14:17], v[42:45], v[34:37], v[14:17]
	v_pk_mov_b32 v[42:43], v[40:41], v[38:39] op_sel:[1,0]
	v_mov_b32_e32 v41, v39
	v_pk_add_f32 v[38:39], v[42:43], v[40:41]
	s_waitcnt lgkmcnt(1)
	v_mfma_f32_16x16x32_bf16 v[18:21], v[26:29], v[34:37], v[18:21]
	v_add_f32_e32 v38, v38, v39
	ds_bpermute_b32 v26, v65, v38
	v_mov_b32_e32 v28, v147
	s_waitcnt lgkmcnt(1)
	v_mfma_f32_16x16x32_bf16 v[10:13], v[30:33], v[34:37], v[10:13]
	v_mov_b32_e32 v32, v147
	v_mov_b32_e32 v33, v147
	s_waitcnt lgkmcnt(0)
	v_add_f32_e32 v44, v38, v26
	v_cvt_pk_bf16_f32 v26, v58, v59
	v_cvt_pk_bf16_f32 v27, v46, v47
	ds_read_b64 v[30:31], v179 offset:37312
	ds_read_b64 v[34:35], v179 offset:45760
	v_mov_b32_e32 v29, v147
	v_mov_b32_e32 v36, v147
	v_mov_b32_e32 v37, v147
	s_waitcnt lgkmcnt(1)
	v_mfma_f32_16x16x32_bf16 v[14:17], v[30:33], v[26:29], v[14:17]
	ds_bpermute_b32 v30, v66, v44
	v_fma_f32 v31, v64, s61, -v82
	v_exp_f32_e32 v31, v31
	ds_read_b64 v[38:39], v179 offset:54208
	ds_read_b64 v[42:43], v179 offset:62656
	v_mov_b32_e32 v40, v147
	s_waitcnt lgkmcnt(2)
	v_add_f32_e32 v30, v44, v30
	v_add_f32_e32 v30, v31, v30
	v_mov_b32_e32 v41, v147
	v_mov_b32_e32 v44, v147
	v_mov_b32_e32 v45, v147
	v_div_scale_f32 v31, s[68:69], v30, v30, 1.0
	v_rcp_f32_e32 v32, v31
	v_mfma_f32_16x16x32_bf16 v[22:25], v[34:37], v[26:29], v[22:25]
	s_waitcnt lgkmcnt(1)
	v_mfma_f32_16x16x32_bf16 v[18:21], v[38:41], v[26:29], v[18:21]
	s_waitcnt lgkmcnt(0)
	v_mfma_f32_16x16x32_bf16 v[10:13], v[42:45], v[26:29], v[10:13]
	v_fma_f32 v26, -v31, v32, 1.0
	v_fmac_f32_e32 v32, v26, v32
	v_div_scale_f32 v26, vcc, 1.0, v30, 1.0
	v_mul_f32_e32 v27, v26, v32
	v_fma_f32 v28, -v31, v27, v26
	v_fmac_f32_e32 v27, v28, v32
	v_fma_f32 v26, -v31, v27, v26
	v_div_fmas_f32 v26, v26, v32, v27
	v_div_fixup_f32 v26, v26, v30, 1.0
	v_pk_mul_f32 v[16:17], v[26:27], v[16:17] op_sel_hi:[0,1]
	v_pk_mul_f32 v[14:15], v[26:27], v[14:15] op_sel_hi:[0,1]
	v_add_co_u32_e32 v50, vcc, s57, v62
	v_cvt_pk_bf16_f32 v14, v14, v15
	v_cvt_pk_bf16_f32 v15, v16, v17
	v_pk_mul_f32 v[16:17], v[26:27], v[22:23] op_sel_hi:[0,1]
	s_nop 0
	v_addc_co_u32_e32 v51, vcc, 0, v63, vcc
	v_lshrrev_b32_e32 v110, 4, v0
	v_and_b32_e32 v110, 1, v110
	v_mul_u32_u24_e32 v110, 24, v110
	v_mov_b32_e32 v111, 0
	v_lshl_add_u64 v[118:119], v[50:51], 0, v[110:111]
	v_mov_b32_e32 v114, v14
	v_mov_b32_e32 v115, v15
	v_pk_mul_f32 v[14:15], v[26:27], v[24:25] op_sel_hi:[0,1]
	v_cvt_pk_bf16_f32 v16, v16, v17
	v_cvt_pk_bf16_f32 v17, v14, v15
	v_mov_b32_e32 v116, v16
	v_mov_b32_e32 v117, v17
	s_nop 1
	v_permlane16_swap_b32_e32 v114, v116
	v_permlane16_swap_b32_e32 v115, v117
	global_store_dwordx4 v[118:119], v[114:117], off
	v_pk_mul_f32 v[16:17], v[26:27], v[18:19] op_sel_hi:[0,1]
	v_pk_mul_f32 v[14:15], v[26:27], v[20:21] op_sel_hi:[0,1]
	v_cvt_pk_bf16_f32 v16, v16, v17
	v_cvt_pk_bf16_f32 v17, v14, v15
	v_pk_mul_f32 v[12:13], v[26:27], v[12:13] op_sel_hi:[0,1]
	v_pk_mul_f32 v[10:11], v[26:27], v[10:11] op_sel_hi:[0,1]
	v_mov_b32_e32 v126, v16
	v_mov_b32_e32 v127, v17
	v_cvt_pk_bf16_f32 v52, v10, v11
	v_cvt_pk_bf16_f32 v53, v12, v13
	ds_read_b128 v[10:13], v178 offset:16128
	ds_read_b128 v[14:17], v178 offset:16192
	s_waitcnt lgkmcnt(1)
	v_mfma_f32_16x16x32_bf16 v[10:13], v[10:13], v[2:5], 0
	ds_read_b128 v[18:21], v178 offset:18432
	ds_read_b128 v[22:25], v178 offset:20736
	ds_read_b128 v[26:29], v178 offset:23040
	s_waitcnt lgkmcnt(3)
; __device__ __forceinline__ void attn_unit(LAS unsigned char* lds, bf16* Q, const bf16* Kg, const bf16* Vg, const float* snk, int unit, int tid) {
;     ...
;         for (int kb = 0; kb < 9; ++kb) { const LAS unsigned char* kp = lds + (16 * (mt + kb) + fr) * ATT_KP + 16 * fq;
;             const bf16x8_t k0 = *(const LAS bf16x8_t*)kp, k1 = *(const LAS bf16x8_t*)(kp + 64);
;             f32x4 z = {0.f, 0.f, 0.f, 0.f}; z = __builtin_amdgcn_mfma_f32_16x16x32_bf16(k0, qf[mt][0], z, 0, 0, 0); z = __builtin_amdgcn_mfma_f32_16x16x32_bf16(k1, qf[mt][1], z, 0, 0, 0); st[kb] = z; }
;         float mx = sink;
; #pragma unroll
;         for (int kb = 0; kb < 9; ++kb) {
;             const bool tile_ok = (n > 0) || (mt + kb >= 8);
; #pragma unroll
;             for (int i = 0; i < 4; ++i) { const bool ok = tile_ok && (kb == 0 ? lo_ok[i] : (kb == 8 ? !lo_ok[i] : true));
;                 st[kb][i] = ok ? st[kb][i] : -INFINITY; mx = fmaxf(mx, st[kb][i]); }
;         }
;         mx = fmaxf(mx, __shfl_xor(mx, 16)); mx = fmaxf(mx, __shfl_xor(mx, 32));
;         f32x4 ls4 = {0.f, 0.f, 0.f, 0.f};
; #pragma unroll
;         for (int kb = 0; kb < 9; ++kb) { f32x4 d = st[kb] - mx;
; #pragma unroll
;             for (int i = 0; i < 4; ++i) d[i] = __builtin_amdgcn_exp2f(d[i]);
;             st[kb] = d; ls4 = ls4 + d; }
;         float ls = (ls4[0] + ls4[1]) + (ls4[2] + ls4[3]);
;         ls += __shfl_xor(ls, 16); ls += __shfl_xor(ls, 32);
;         const float inv = 1.f / (ls + __builtin_amdgcn_exp2f(sink - mx));
;         f32x4 o[4];
; #pragma unroll
;         for (int dt = 0; dt < 4; ++dt) o[dt] = (f32x4){0.f, 0.f, 0.f, 0.f};
; #pragma unroll
;         for (int kp = 0; kp < 5; ++kp) {
;             v4u pw; pw.x = cvt_pk_bf16(st[2 * kp][0], st[2 * kp][1]); pw.y = cvt_pk_bf16(st[2 * kp][2], st[2 * kp][3]);
;             if (kp < 4) { pw.z = cvt_pk_bf16(st[(2 * kp + 1) % 9][0], st[(2 * kp + 1) % 9][1]); pw.w = cvt_pk_bf16(st[(2 * kp + 1) % 9][2], st[(2 * kp + 1) % 9][3]); } else { pw.z = 0u; pw.w = 0u; }
;             const bf16x8_t pb = __builtin_bit_cast(bf16x8_t, pw);
; #pragma unroll
;             for (int dt = 0; dt < 4; ++dt) { const LAS unsigned char* vp = lds + ATT_VOFF + (16 * dt + fr) * ATT_VP + (16 * (mt + 2 * kp) + 4 * fq) * 2;
;                 const v2u lo = *(const LAS v2u*)vp; v2u hi = {0u, 0u}; if (kp < 4) hi = *(const LAS v2u*)(vp + 32);
	v_mfma_f32_16x16x32_bf16 v[14:17], v[14:17], v[6:9], v[10:13]
	ds_read_b128 v[30:33], v178 offset:25344
	ds_read_b128 v[34:37], v178 offset:27648
	ds_read_b128 v[38:41], v178 offset:29952
	ds_read_b128 v[10:13], v178 offset:18496
	s_waitcnt lgkmcnt(6)
	v_mfma_f32_16x16x32_bf16 v[18:21], v[18:21], v[2:5], 0
	ds_read_b128 v[42:45], v178 offset:32256
	ds_read_b128 v[46:49], v178 offset:34560
	v_mov_b32_e32 v128, v52
	v_mov_b32_e32 v129, v53
	s_nop 1
	v_permlane16_swap_b32_e32 v126, v128
	v_permlane16_swap_b32_e32 v127, v129
	global_store_dwordx4 v[118:119], v[126:129], off offset:64
	s_waitcnt lgkmcnt(2)
	v_mfma_f32_16x16x32_bf16 v[18:21], v[10:13], v[6:9], v[18:21]
	ds_read_b128 v[10:13], v178 offset:20800
	v_mfma_f32_16x16x32_bf16 v[22:25], v[22:25], v[2:5], 0
	s_waitcnt lgkmcnt(0)
	v_mfma_f32_16x16x32_bf16 v[22:25], v[10:13], v[6:9], v[22:25]
	ds_read_b128 v[10:13], v178 offset:23104
	v_mfma_f32_16x16x32_bf16 v[26:29], v[26:29], v[2:5], 0
	s_waitcnt lgkmcnt(0)
	v_mfma_f32_16x16x32_bf16 v[26:29], v[10:13], v[6:9], v[26:29]
	ds_read_b128 v[10:13], v178 offset:25408
	v_mfma_f32_16x16x32_bf16 v[30:33], v[30:33], v[2:5], 0
	s_waitcnt lgkmcnt(0)
	v_mfma_f32_16x16x32_bf16 v[30:33], v[10:13], v[6:9], v[30:33]
	ds_read_b128 v[10:13], v178 offset:27712
	v_mfma_f32_16x16x32_bf16 v[34:37], v[34:37], v[2:5], 0
	s_waitcnt lgkmcnt(0)
	v_mfma_f32_16x16x32_bf16 v[34:37], v[10:13], v[6:9], v[34:37]
	ds_read_b128 v[10:13], v178 offset:30016
	v_mfma_f32_16x16x32_bf16 v[38:41], v[38:41], v[2:5], 0
	s_waitcnt lgkmcnt(0)
	v_mfma_f32_16x16x32_bf16 v[38:41], v[10:13], v[6:9], v[38:41]
	ds_read_b128 v[10:13], v178 offset:32320
	v_mfma_f32_16x16x32_bf16 v[42:45], v[42:45], v[2:5], 0
	s_waitcnt lgkmcnt(0)
	v_mfma_f32_16x16x32_bf16 v[10:13], v[10:13], v[6:9], v[42:45]
	s_nop 5
	ds_read_b128 v[42:45], v178 offset:34624
	v_mfma_f32_16x16x32_bf16 v[2:5], v[46:49], v[2:5], 0
	s_waitcnt lgkmcnt(0)
	v_mfma_f32_16x16x32_bf16 v[2:5], v[42:45], v[6:9], v[2:5]
	v_cndmask_b32_e64 v7, v15, v190, s[10:11]
	v_cndmask_b32_e64 v6, v190, v14, s[20:21]
	v_cndmask_b32_e64 v7, v190, v7, s[16:17]
	v_max3_f32 v8, v71, v6, v7
	v_cndmask_b32_e64 v9, v190, v16, s[18:19]
	v_cndmask_b32_e64 v14, v190, v17, s[22:23]
	v_max3_f32 v8, v8, v9, v14
	v_max3_f32 v8, v8, v18, v19
	v_max3_f32 v8, v8, v20, v21
	v_max3_f32 v8, v8, v22, v23
	v_max3_f32 v8, v8, v24, v25
	v_max3_f32 v8, v8, v26, v27
	v_max3_f32 v8, v8, v28, v29
	v_max3_f32 v8, v8, v30, v31
	v_max3_f32 v8, v8, v32, v33
	v_max3_f32 v8, v8, v34, v35
	v_max3_f32 v8, v8, v36, v37
	v_max3_f32 v8, v8, v38, v39
	v_max3_f32 v8, v8, v40, v41
	v_max3_f32 v8, v8, v10, v11
	v_max3_f32 v8, v8, v12, v13
	v_cndmask_b32_e64 v60, v2, v190, s[8:9]
	v_cndmask_b32_e64 v61, v190, v3, s[10:11]
	v_max3_f32 v2, v8, v60, v61
	v_cndmask_b32_e64 v71, v4, v190, s[12:13]
	v_cndmask_b32_e64 v72, v5, v190, s[14:15]
	v_max3_f32 v2, v2, v71, v72
	ds_bpermute_b32 v3, v65, v2
	s_waitcnt lgkmcnt(0)
	v_max_f32_e32 v3, v3, v3
	v_max_f32_e32 v2, v2, v3
	ds_bpermute_b32 v3, v66, v2
	s_waitcnt lgkmcnt(0)
	v_max_f32_e32 v3, v3, v3
	v_max_f32_e32 v73, v2, v3
	v_sub_f32_e32 v3, v14, v73
	v_sub_f32_e32 v4, v9, v73
	v_sub_f32_e32 v7, v7, v73
	v_sub_f32_e32 v2, v6, v73
	v_exp_f32_e32 v2, v2
	v_exp_f32_e32 v4, v4
	v_exp_f32_e32 v5, v3
	v_exp_f32_e32 v3, v7
	v_sub_f32_e32 v17, v21, v73
	v_sub_f32_e32 v16, v20, v73
	v_sub_f32_e32 v15, v19, v73
	v_sub_f32_e32 v14, v18, v73
	v_exp_f32_e32 v14, v14
	v_exp_f32_e32 v15, v15
	v_exp_f32_e32 v16, v16
	v_exp_f32_e32 v17, v17
	v_sub_f32_e32 v18, v25, v73
	v_sub_f32_e32 v19, v24, v73
	v_sub_f32_e32 v20, v23, v73
	v_sub_f32_e32 v21, v22, v73
	v_exp_f32_e32 v42, v21
	v_exp_f32_e32 v44, v19
	v_exp_f32_e32 v45, v18
	v_exp_f32_e32 v43, v20
	v_sub_f32_e32 v18, v29, v73
	v_sub_f32_e32 v19, v28, v73
	v_sub_f32_e32 v20, v27, v73
	v_sub_f32_e32 v21, v26, v73
	v_exp_f32_e32 v28, v21
	v_exp_f32_e32 v29, v20
	v_exp_f32_e32 v46, v19
	v_exp_f32_e32 v47, v18
	v_sub_f32_e32 v18, v33, v73
	v_sub_f32_e32 v19, v32, v73
	v_sub_f32_e32 v20, v31, v73
	v_sub_f32_e32 v21, v30, v73
	v_pk_add_f32 v[6:7], v[4:5], 0 op_sel_hi:[1,0]
	v_pk_add_f32 v[8:9], v[2:3], 0 op_sel_hi:[1,0]
	v_exp_f32_e32 v48, v21
	v_exp_f32_e32 v50, v19
	v_exp_f32_e32 v51, v18
	v_exp_f32_e32 v49, v20
	v_pk_add_f32 v[8:9], v[14:15], v[8:9]
	v_pk_add_f32 v[6:7], v[16:17], v[6:7]
	v_pk_add_f32 v[8:9], v[42:43], v[8:9]
	v_pk_add_f32 v[6:7], v[44:45], v[6:7]
	v_pk_add_f32 v[8:9], v[28:29], v[8:9]
	v_pk_add_f32 v[6:7], v[46:47], v[6:7]
	v_sub_f32_e32 v20, v34, v73
	v_pk_add_f32 v[18:19], v[50:51], v[6:7]
	v_pk_add_f32 v[6:7], v[48:49], v[8:9]
	v_sub_f32_e32 v9, v35, v73
	v_sub_f32_e32 v8, v37, v73
	v_exp_f32_e32 v53, v9
	v_sub_f32_e32 v9, v36, v73
	v_exp_f32_e32 v52, v20
	v_exp_f32_e32 v54, v9
	v_exp_f32_e32 v55, v8
	v_sub_f32_e32 v22, v41, v73
	v_sub_f32_e32 v23, v40, v73
	v_sub_f32_e32 v24, v39, v73
	v_sub_f32_e32 v25, v38, v73
	v_exp_f32_e32 v38, v23
	v_exp_f32_e32 v39, v22
	v_exp_f32_e32 v40, v25
	v_exp_f32_e32 v41, v24
	v_pk_add_f32 v[20:21], v[52:53], v[6:7]
	v_pk_add_f32 v[18:19], v[54:55], v[18:19]
	v_cvt_pk_bf16_f32 v2, v2, v3
	v_cvt_pk_bf16_f32 v3, v4, v5
	v_cvt_pk_bf16_f32 v4, v14, v15
	v_cvt_pk_bf16_f32 v5, v16, v17
	ds_read2_b64 v[6:9], v67 offset0:28 offset1:32
	ds_read2_b64 v[14:17], v68 offset0:60 offset1:64
	v_pk_add_f32 v[56:57], v[38:39], v[18:19]
	v_pk_add_f32 v[58:59], v[40:41], v[20:21]
	ds_read2_b64 v[18:21], v70 offset0:92 offset1:96
	ds_read2_b64 v[22:25], v69 offset0:124 offset1:128
	v_sub_f32_e32 v12, v12, v73
	v_sub_f32_e32 v11, v11, v73
	v_sub_f32_e32 v10, v10, v73
	v_sub_f32_e32 v74, v13, v73
	v_cvt_pk_bf16_f32 v26, v42, v43
	v_cvt_pk_bf16_f32 v27, v44, v45
	v_cvt_pk_bf16_f32 v28, v28, v29
	v_cvt_pk_bf16_f32 v29, v46, v47
	ds_read2_b64 v[30:33], v67 offset0:36 offset1:40
	v_exp_f32_e32 v42, v10
	v_exp_f32_e32 v43, v11
	v_exp_f32_e32 v44, v12
	ds_read2_b64 v[10:13], v70 offset0:100 offset1:104
	s_waitcnt lgkmcnt(5)
; __device__ __forceinline__ unsigned cvt_pk_bf16(float lo, float hi) { unsigned r; asm volatile("v_cvt_pk_bf16_f32 %0, %1, %2" : "=v"(r) : "v"(lo), "v"(hi)); return r; }
; #define LAS __attribute__((address_space(3)))
; __device__ __forceinline__ void attn_unit(LAS unsigned char* lds, bf16* Q, const bf16* Kg, const bf16* Vg, const float* snk, int unit, int tid) {
;     ...
;         for (int kp = 0; kp < 5; ++kp) {
;             v4u pw; pw.x = cvt_pk_bf16(st[2 * kp][0], st[2 * kp][1]); pw.y = cvt_pk_bf16(st[2 * kp][2], st[2 * kp][3]);
;             if (kp < 4) { pw.z = cvt_pk_bf16(st[(2 * kp + 1) % 9][0], st[(2 * kp + 1) % 9][1]); pw.w = cvt_pk_bf16(st[(2 * kp + 1) % 9][2], st[(2 * kp + 1) % 9][3]); } else { pw.z = 0u; pw.w = 0u; }
;             const bf16x8_t pb = __builtin_bit_cast(bf16x8_t, pw);
; #pragma unroll
;             for (int dt = 0; dt < 4; ++dt) { const LAS unsigned char* vp = lds + ATT_VOFF + (16 * dt + fr) * ATT_VP + (16 * (mt + 2 * kp) + 4 * fq) * 2;
;                 const v2u lo = *(const LAS v2u*)vp; v2u hi = {0u, 0u}; if (kp < 4) hi = *(const LAS v2u*)(vp + 32);
;                 v4u aw; aw.x = lo.x; aw.y = lo.y; aw.z = hi.x; aw.w = hi.y;
;                 o[dt] = __builtin_amdgcn_mfma_f32_16x16x32_bf16(__builtin_bit_cast(bf16x8_t, aw), pb, o[dt], 0, 0, 0); }
;         }
; #pragma unroll
;         for (int dt = 0; dt < 4; ++dt) { const f32x4 y = o[dt] * inv; v2u w; w.x = cvt_pk_bf16(y[0], y[1]); w.y = cvt_pk_bf16(y[2], y[3]); *(v2u*)(qbase + (size_t)mt * 16 * 1024 + 16 * dt + 4 * fq) = w; }
;     }
;     __syncthreads();
	v_mfma_f32_16x16x32_bf16 v[6:9], v[6:9], v[2:5], 0
	ds_read2_b64 v[34:37], v68 offset0:68 offset1:72
	v_exp_f32_e32 v45, v74
	v_pk_add_f32 v[46:47], v[42:43], v[58:59]
	s_waitcnt lgkmcnt(5)
	v_mfma_f32_16x16x32_bf16 v[14:17], v[14:17], v[2:5], 0
	s_waitcnt lgkmcnt(4)
	v_mfma_f32_16x16x32_bf16 v[18:21], v[18:21], v[2:5], 0
	s_waitcnt lgkmcnt(3)
	v_mfma_f32_16x16x32_bf16 v[2:5], v[22:25], v[2:5], 0
	ds_read2_b64 v[22:25], v69 offset0:132 offset1:136
	s_waitcnt lgkmcnt(3)
	v_mfma_f32_16x16x32_bf16 v[6:9], v[30:33], v[26:29], v[6:9]
	v_cvt_pk_bf16_f32 v30, v48, v49
	v_cvt_pk_bf16_f32 v31, v50, v51
	v_cvt_pk_bf16_f32 v32, v52, v53
	v_cvt_pk_bf16_f32 v33, v54, v55
	s_waitcnt lgkmcnt(2)
	v_mfma_f32_16x16x32_bf16 v[10:13], v[10:13], v[26:29], v[18:21]
	v_sub_f32_e32 v51, v72, v73
	v_sub_f32_e32 v52, v71, v73
	v_sub_f32_e32 v53, v61, v73
	ds_read2_b64 v[18:21], v68 offset0:76 offset1:80
	s_waitcnt lgkmcnt(2)
	v_mfma_f32_16x16x32_bf16 v[14:17], v[34:37], v[26:29], v[14:17]
	ds_read2_b64 v[34:37], v67 offset0:44 offset1:48
	v_pk_add_f32 v[48:49], v[44:45], v[56:57]
	s_waitcnt lgkmcnt(2)
	v_mfma_f32_16x16x32_bf16 v[2:5], v[22:25], v[26:29], v[2:5]
	ds_read2_b64 v[22:25], v70 offset0:108 offset1:112
	v_sub_f32_e32 v26, v60, v73
	v_exp_f32_e32 v50, v26
	s_waitcnt lgkmcnt(2)
	v_mfma_f32_16x16x32_bf16 v[14:17], v[18:21], v[30:33], v[14:17]
	ds_read2_b64 v[18:21], v69 offset0:140 offset1:144
	v_cvt_pk_bf16_f32 v26, v40, v41
	v_cvt_pk_bf16_f32 v27, v38, v39
	v_cvt_pk_bf16_f32 v28, v42, v43
	v_cvt_pk_bf16_f32 v29, v44, v45
	s_waitcnt lgkmcnt(1)
	v_mfma_f32_16x16x32_bf16 v[10:13], v[22:25], v[30:33], v[10:13]
	ds_read2_b64 v[22:25], v68 offset0:84 offset1:88
	v_exp_f32_e32 v38, v52
	v_exp_f32_e32 v39, v51
	v_mfma_f32_16x16x32_bf16 v[6:9], v[34:37], v[30:33], v[6:9]
	ds_read2_b64 v[34:37], v67 offset0:52 offset1:56
	v_exp_f32_e32 v51, v53
	s_waitcnt lgkmcnt(2)
	v_mfma_f32_16x16x32_bf16 v[2:5], v[18:21], v[30:33], v[2:5]
	ds_read2_b64 v[18:21], v70 offset0:116 offset1:120
	v_pk_add_f32 v[30:31], v[38:39], v[48:49]
	v_pk_add_f32 v[32:33], v[50:51], v[46:47]
	s_waitcnt lgkmcnt(2)
	v_mfma_f32_16x16x32_bf16 v[14:17], v[22:25], v[26:29], v[14:17]
	ds_read2_b64 v[22:25], v69 offset0:148 offset1:152
	s_waitcnt lgkmcnt(2)
	v_mfma_f32_16x16x32_bf16 v[6:9], v[34:37], v[26:29], v[6:9]
	v_pk_mov_b32 v[34:35], v[32:33], v[30:31] op_sel:[1,0]
	v_mov_b32_e32 v33, v31
	v_pk_add_f32 v[30:31], v[34:35], v[32:33]
	s_waitcnt lgkmcnt(1)
	v_mfma_f32_16x16x32_bf16 v[10:13], v[18:21], v[26:29], v[10:13]
	v_add_f32_e32 v30, v30, v31
	ds_bpermute_b32 v18, v65, v30
	v_mov_b32_e32 v20, v147
	s_waitcnt lgkmcnt(1)
	v_mfma_f32_16x16x32_bf16 v[2:5], v[22:25], v[26:29], v[2:5]
	v_mov_b32_e32 v24, v147
	v_mov_b32_e32 v25, v147
	s_waitcnt lgkmcnt(0)
	v_add_f32_e32 v36, v30, v18
	v_cvt_pk_bf16_f32 v18, v50, v51
	v_cvt_pk_bf16_f32 v19, v38, v39
	ds_read_b64 v[22:23], v179 offset:37344
	ds_read_b64 v[26:27], v179 offset:45792
	v_mov_b32_e32 v21, v147
	v_mov_b32_e32 v28, v147
	v_mov_b32_e32 v29, v147
	s_waitcnt lgkmcnt(1)
	v_mfma_f32_16x16x32_bf16 v[6:9], v[22:25], v[18:21], v[6:9]
	ds_bpermute_b32 v22, v66, v36
	v_fma_f32 v23, v64, s61, -v73
	v_exp_f32_e32 v23, v23
	ds_read_b64 v[30:31], v179 offset:54240
	ds_read_b64 v[34:35], v179 offset:62688
	v_mov_b32_e32 v32, v147
	s_waitcnt lgkmcnt(2)
	v_add_f32_e32 v22, v36, v22
	v_add_f32_e32 v22, v23, v22
	v_mov_b32_e32 v33, v147
	v_mov_b32_e32 v36, v147
	v_mov_b32_e32 v37, v147
	v_div_scale_f32 v23, s[16:17], v22, v22, 1.0
	v_rcp_f32_e32 v24, v23
	v_mfma_f32_16x16x32_bf16 v[14:17], v[26:29], v[18:21], v[14:17]
	s_waitcnt lgkmcnt(1)
	v_mfma_f32_16x16x32_bf16 v[10:13], v[30:33], v[18:21], v[10:13]
	s_waitcnt lgkmcnt(0)
	v_mfma_f32_16x16x32_bf16 v[2:5], v[34:37], v[18:21], v[2:5]
	v_fma_f32 v18, -v23, v24, 1.0
	v_fmac_f32_e32 v24, v18, v24
	v_div_scale_f32 v18, vcc, 1.0, v22, 1.0
	v_mul_f32_e32 v19, v18, v24
	v_fma_f32 v20, -v23, v19, v18
	v_fmac_f32_e32 v19, v20, v24
	v_fma_f32 v18, -v23, v19, v18
	v_div_fmas_f32 v18, v18, v24, v19
	v_div_fixup_f32 v18, v18, v22, 1.0
	v_pk_mul_f32 v[8:9], v[18:19], v[8:9] op_sel_hi:[0,1]
	v_pk_mul_f32 v[6:7], v[18:19], v[6:7] op_sel_hi:[0,1]
	v_cvt_pk_bf16_f32 v6, v6, v7
	v_cvt_pk_bf16_f32 v7, v8, v9
	v_add_co_u32_e32 v8, vcc, s58, v62
	v_pk_mul_f32 v[14:15], v[18:19], v[14:15] op_sel_hi:[0,1]
	s_nop 0
	v_addc_co_u32_e32 v9, vcc, 0, v63, vcc
	v_lshrrev_b32_e32 v110, 4, v0
	v_and_b32_e32 v110, 1, v110
	v_mul_u32_u24_e32 v110, 24, v110
	v_mov_b32_e32 v111, 0
	v_lshl_add_u64 v[118:119], v[8:9], 0, v[110:111]
	v_mov_b32_e32 v114, v6
	v_mov_b32_e32 v115, v7
	v_pk_mul_f32 v[6:7], v[18:19], v[16:17] op_sel_hi:[0,1]
	v_pk_mul_f32 v[10:11], v[18:19], v[10:11] op_sel_hi:[0,1]
	v_pk_mul_f32 v[2:3], v[18:19], v[2:3] op_sel_hi:[0,1]
	v_cvt_pk_bf16_f32 v14, v14, v15
	v_cvt_pk_bf16_f32 v15, v6, v7
	v_mov_b32_e32 v116, v14
	v_mov_b32_e32 v117, v15
	s_nop 1
	v_permlane16_swap_b32_e32 v114, v116
	v_permlane16_swap_b32_e32 v115, v117
	global_store_dwordx4 v[118:119], v[114:117], off
	v_pk_mul_f32 v[6:7], v[18:19], v[12:13] op_sel_hi:[0,1]
	v_cvt_pk_bf16_f32 v10, v10, v11
	v_cvt_pk_bf16_f32 v11, v6, v7
	v_mov_b32_e32 v126, v10
	v_mov_b32_e32 v127, v11
	v_pk_mul_f32 v[4:5], v[18:19], v[4:5] op_sel_hi:[0,1]
	v_cvt_pk_bf16_f32 v2, v2, v3
	v_cvt_pk_bf16_f32 v3, v4, v5
	v_mov_b32_e32 v128, v2
	v_mov_b32_e32 v129, v3
	s_nop 1
	v_permlane16_swap_b32_e32 v126, v128
	v_permlane16_swap_b32_e32 v127, v129
	global_store_dwordx4 v[118:119], v[126:129], off offset:64
	s_barrier
